# GEMM MFMA segments start right at the barrier (priority flips and the already-satisfied lgkmcnt wait removed) + barrier XGEN-first
# speedup vs baseline: 1.0084x; 1.0060x over previous
; #define PG8_STAGE(bufoff, gbase, voff) do { _Pragma("unroll") for (int _i = 0; _i < 2; ++_i) \
;         __builtin_amdgcn_global_load_lds((const unsigned*)((const char*)(gbase) + (voff)[_i]), (LAS unsigned*)(lds + (bufoff) + ldsw + _i * 8192), 16, 0, 0); } while (0)
; #define PG8_LDA(dst, b, h) do { _Pragma("unroll") for (int m = 0; m < 4; ++m) _Pragma("unroll") for (int k = 0; k < 2; ++k) dst[m][k] = *(const LAS bf16x8*)(lds + PG8_SA(b, h) + aoff + m * 2048 + k * 1024); } while (0)
; #define PG8_LDB(dst, b, h) do { _Pragma("unroll") for (int n = 0; n < 2; ++n) _Pragma("unroll") for (int k = 0; k < 2; ++k) dst[n][k] = *(const LAS bf16x8*)(lds + PG8_SB(b, h) + boff + n * 2048 + k * 1024); } while (0)
; #define PG8_MMA(ai, bj, At, Bt) do { __builtin_amdgcn_s_setprio(1); _Pragma("unroll") for (int m = 0; m < 4; ++m) _Pragma("unroll") for (int n = 0; n < 2; ++n) _Pragma("unroll") for (int k = 0; k < 2; ++k) \
;         acc[ai][bj][m][n] = __builtin_amdgcn_mfma_f32_16x16x32_bf16(Bt[n][k], At[m][k], acc[ai][bj][m][n], 0, 0, 0); __builtin_amdgcn_s_setprio(0); } while (0)
; #define PG8_WAIT_V(n) asm volatile("s_waitcnt vmcnt(" #n ")" ::: "memory")
; #define PG8_WAIT_L(n) asm volatile("s_waitcnt lgkmcnt(" #n ")" ::: "memory")
; #define PG8_BAR __builtin_amdgcn_s_barrier()
; template <class Epi, class Sched, bool ABLK = false, bool ALIGN_EPI = true, bool SP2 = true, bool BBLK = true>
; __device__ __forceinline__ void gemm_phase(LAS unsigned char* lds, const Gemm g, const Sched& S, const Epi& E) {
;     ...
;             const bool last = (t == nt - 2);
;             const char* a1 = a_tile(uA, tbA + t + 1);
;             const char* a2 = last ? a_tile(nuA, ntbA) : a_tile(uA, tbA + t + 2); const char* b2 = last ? nB : cB + (size_t)(t + 2) * kstepB;
;             const char* a3 = last ? a_tile(nuA, ntbA + 1) : a_tile(uA, tbA + t + 3); const char* b3 = b2 + kstepB;
;             if (last && has_next) S.a_ready(nxt);
;             if constexpr (SP2) {
;             PG8_LDB(B0, 0, 0); PG8_LDB(B1, 0, 1); PG8_SCHED; PG8_LDA(At, 0, 0); PG8_STAGE(PG8_SA(1, 1), a1 + hstepA, voffA);
;             PG8_WAIT_V(8); PG8_WAIT_L(0); PG8_BAR; PG8_MMA(0, 0, At, B0); PG8_MMA(0, 1, At, B1); PG8_BAR; PG8_SCHED;
;             PG8_LDA(At, 0, 1); PG8_STAGE(PG8_SB(0, 0), b2, voffB); PG8_STAGE(PG8_SB(0, 1), b2 + hstepB, voffB); PG8_STAGE(PG8_SA(0, 0), a2, voffA);
.LBB0_350:
	ds_read_b128 v[152:155], v148
	ds_read_b128 v[156:159], v148 offset:1024
	ds_read_b128 v[160:163], v148 offset:2048
	ds_read_b128 v[164:167], v148 offset:3072
	ds_read_b128 v[168:171], v149
	ds_read_b128 v[172:175], v149 offset:1024
	ds_read_b128 v[176:179], v149 offset:2048
	ds_read_b128 v[180:183], v149 offset:3072
	s_add_u32 s28, s24, s26
	s_addc_u32 s29, s25, s27
	s_add_u32 s34, s28, 0x100
	s_addc_u32 s35, s29, 0
	s_add_u32 s28, s28, 0x180
	s_addc_u32 s29, s29, 0
	s_cmpk_eq_i32 s26, 0xf00
	s_cselect_b32 s29, s51, s29
	s_cselect_b32 s28, s50, s28
	s_cselect_b32 s31, s9, s53
	s_cselect_b32 s30, s11, s52
	s_cselect_b32 s35, s4, s35
	s_cselect_b32 s34, s5, s34
	s_mov_b32 m0, s49
	v_lshl_add_u64 v[216:217], v[142:143], 0, s[26:27]
	ds_read_b128 v[184:187], v150
	ds_read_b128 v[188:191], v150 offset:1024
	ds_read_b128 v[192:195], v150 offset:2048
	ds_read_b128 v[196:199], v150 offset:3072
	ds_read_b128 v[200:203], v150 offset:4096
	ds_read_b128 v[204:207], v150 offset:5120
	ds_read_b128 v[208:211], v150 offset:6144
	ds_read_b128 v[212:215], v150 offset:7168
	global_load_lds_dwordx4 v[216:217], off
	v_lshl_add_u64 v[216:217], v[144:145], 0, s[26:27]
	s_add_i32 m0, s21, 0xe000
	s_nop 0
	global_load_lds_dwordx4 v[216:217], off
	s_waitcnt vmcnt(8)
	s_waitcnt lgkmcnt(0)
	s_barrier
	v_mfma_f32_16x16x32_bf16 v[122:125], v[152:155], v[184:187], v[122:125]
	v_mfma_f32_16x16x32_bf16 v[118:121], v[160:163], v[184:187], v[118:121]
	v_mfma_f32_16x16x32_bf16 v[106:109], v[152:155], v[192:195], v[106:109]
	v_mfma_f32_16x16x32_bf16 v[102:105], v[160:163], v[192:195], v[102:105]
	v_mfma_f32_16x16x32_bf16 v[90:93], v[152:155], v[200:203], v[90:93]
	v_mfma_f32_16x16x32_bf16 v[86:89], v[160:163], v[200:203], v[86:89]
	v_mfma_f32_16x16x32_bf16 v[74:77], v[152:155], v[208:211], v[74:77]
	v_mfma_f32_16x16x32_bf16 v[70:73], v[160:163], v[208:211], v[70:73]
	v_mfma_f32_16x16x32_bf16 v[122:125], v[156:159], v[188:191], v[122:125]
	v_mfma_f32_16x16x32_bf16 v[118:121], v[164:167], v[188:191], v[118:121]
	v_mfma_f32_16x16x32_bf16 v[106:109], v[156:159], v[196:199], v[106:109]
	v_mfma_f32_16x16x32_bf16 v[102:105], v[164:167], v[196:199], v[102:105]
	v_mfma_f32_16x16x32_bf16 v[90:93], v[156:159], v[204:207], v[90:93]
	v_mfma_f32_16x16x32_bf16 v[86:89], v[164:167], v[204:207], v[86:89]
	v_mfma_f32_16x16x32_bf16 v[74:77], v[156:159], v[212:215], v[74:77]
	v_mfma_f32_16x16x32_bf16 v[70:73], v[164:167], v[212:215], v[70:73]
	v_mfma_f32_16x16x32_bf16 v[126:129], v[168:171], v[184:187], v[126:129]
	v_mfma_f32_16x16x32_bf16 v[114:117], v[176:179], v[184:187], v[114:117]
	v_mfma_f32_16x16x32_bf16 v[110:113], v[168:171], v[192:195], v[110:113]
	v_mfma_f32_16x16x32_bf16 v[98:101], v[176:179], v[192:195], v[98:101]
	v_mfma_f32_16x16x32_bf16 v[94:97], v[168:171], v[200:203], v[94:97]
	v_mfma_f32_16x16x32_bf16 v[82:85], v[176:179], v[200:203], v[82:85]
	v_mfma_f32_16x16x32_bf16 v[78:81], v[168:171], v[208:211], v[78:81]
	v_mfma_f32_16x16x32_bf16 v[66:69], v[176:179], v[208:211], v[66:69]
	v_mfma_f32_16x16x32_bf16 v[126:129], v[172:175], v[188:191], v[126:129]
	v_mfma_f32_16x16x32_bf16 v[114:117], v[180:183], v[188:191], v[114:117]
	v_mfma_f32_16x16x32_bf16 v[110:113], v[172:175], v[196:199], v[110:113]
	v_mfma_f32_16x16x32_bf16 v[98:101], v[180:183], v[196:199], v[98:101]
	v_mfma_f32_16x16x32_bf16 v[94:97], v[172:175], v[204:207], v[94:97]
	v_mfma_f32_16x16x32_bf16 v[82:85], v[180:183], v[204:207], v[82:85]
	v_mfma_f32_16x16x32_bf16 v[78:81], v[172:175], v[212:215], v[78:81]
	v_mfma_f32_16x16x32_bf16 v[66:69], v[180:183], v[212:215], v[66:69]
	s_barrier
	s_add_i32 s55, s44, s33
	v_lshl_add_u64 v[216:217], s[30:31], 0, v[134:135]
	s_mov_b32 m0, s55
	ds_read_b128 v[184:187], v150 offset:16384
	ds_read_b128 v[188:191], v150 offset:17408
	ds_read_b128 v[192:195], v150 offset:18432
	ds_read_b128 v[196:199], v150 offset:19456
	ds_read_b128 v[200:203], v150 offset:20480
	ds_read_b128 v[204:207], v150 offset:21504
	ds_read_b128 v[208:211], v150 offset:22528
	ds_read_b128 v[212:215], v150 offset:23552
	global_load_lds_dwordx4 v[216:217], off
	s_add_i32 m0, s55, 0x2000
	s_add_u32 s56, s30, 0x4000
	v_lshl_add_u64 v[216:217], s[30:31], 0, v[130:131]
	s_addc_u32 s57, s31, 0
	s_add_i32 s55, s45, s33
	global_load_lds_dwordx4 v[216:217], off
	v_lshl_add_u64 v[216:217], s[56:57], 0, v[134:135]
	s_mov_b32 m0, s55
	s_nop 0
	global_load_lds_dwordx4 v[216:217], off
	v_lshl_add_u64 v[216:217], s[56:57], 0, v[130:131]
	s_add_i32 m0, s55, 0x2000
	s_nop 0
	global_load_lds_dwordx4 v[216:217], off
	v_lshl_add_u64 v[216:217], s[34:35], 0, v[136:137]
	s_mov_b32 m0, s21
	s_nop 0
	global_load_lds_dwordx4 v[216:217], off
	v_lshl_add_u64 v[216:217], s[34:35], 0, v[132:133]
	s_mov_b32 m0, s23
	s_nop 0
	global_load_lds_dwordx4 v[216:217], off
	s_waitcnt vmcnt(8)
	s_waitcnt lgkmcnt(0)
	s_barrier
; #define PG8_STAGE(bufoff, gbase, voff) do { _Pragma("unroll") for (int _i = 0; _i < 2; ++_i) \
;         __builtin_amdgcn_global_load_lds((const unsigned*)((const char*)(gbase) + (voff)[_i]), (LAS unsigned*)(lds + (bufoff) + ldsw + _i * 8192), 16, 0, 0); } while (0)
; #define PG8_LDA(dst, b, h) do { _Pragma("unroll") for (int m = 0; m < 4; ++m) _Pragma("unroll") for (int k = 0; k < 2; ++k) dst[m][k] = *(const LAS bf16x8*)(lds + PG8_SA(b, h) + aoff + m * 2048 + k * 1024); } while (0)
; #define PG8_LDB(dst, b, h) do { _Pragma("unroll") for (int n = 0; n < 2; ++n) _Pragma("unroll") for (int k = 0; k < 2; ++k) dst[n][k] = *(const LAS bf16x8*)(lds + PG8_SB(b, h) + boff + n * 2048 + k * 1024); } while (0)
; #define PG8_MMA(ai, bj, At, Bt) do { __builtin_amdgcn_s_setprio(1); _Pragma("unroll") for (int m = 0; m < 4; ++m) _Pragma("unroll") for (int n = 0; n < 2; ++n) _Pragma("unroll") for (int k = 0; k < 2; ++k) \
;         acc[ai][bj][m][n] = __builtin_amdgcn_mfma_f32_16x16x32_bf16(Bt[n][k], At[m][k], acc[ai][bj][m][n], 0, 0, 0); __builtin_amdgcn_s_setprio(0); } while (0)
; #define PG8_WAIT_V(n) asm volatile("s_waitcnt vmcnt(" #n ")" ::: "memory")
; #define PG8_WAIT_L(n) asm volatile("s_waitcnt lgkmcnt(" #n ")" ::: "memory")
; #define PG8_BAR __builtin_amdgcn_s_barrier()
; #define PG8_SCHED __builtin_amdgcn_sched_barrier(0)
; template <class Epi, class Sched, bool ABLK = false, bool ALIGN_EPI = true, bool SP2 = true, bool BBLK = true>
; __device__ __forceinline__ void gemm_phase(LAS unsigned char* lds, const Gemm g, const Sched& S, const Epi& E) {
;     ...
;             PG8_WAIT_V(8); PG8_WAIT_L(0); PG8_BAR; PG8_MMA(1, 0, At, B0); PG8_MMA(1, 1, At, B1); PG8_BAR; PG8_SCHED;
;             PG8_LDB(B0, 1, 0); PG8_LDB(B1, 1, 1); PG8_SCHED; PG8_LDA(At, 1, 0); PG8_STAGE(PG8_SA(0, 1), a2 + hstepA, voffA);
;             PG8_WAIT_V(8); PG8_WAIT_L(0); PG8_BAR; PG8_MMA(0, 0, At, B0); PG8_MMA(0, 1, At, B1); PG8_BAR; PG8_SCHED;
	v_mfma_f32_16x16x32_bf16 v[58:61], v[152:155], v[184:187], v[58:61]
	v_mfma_f32_16x16x32_bf16 v[54:57], v[160:163], v[184:187], v[54:57]
	v_mfma_f32_16x16x32_bf16 v[42:45], v[152:155], v[192:195], v[42:45]
	v_mfma_f32_16x16x32_bf16 v[38:41], v[160:163], v[192:195], v[38:41]
	v_mfma_f32_16x16x32_bf16 v[26:29], v[152:155], v[200:203], v[26:29]
	v_mfma_f32_16x16x32_bf16 v[22:25], v[160:163], v[200:203], v[22:25]
	v_mfma_f32_16x16x32_bf16 v[10:13], v[152:155], v[208:211], v[10:13]
	v_mfma_f32_16x16x32_bf16 v[6:9], v[160:163], v[208:211], v[6:9]
	v_mfma_f32_16x16x32_bf16 v[58:61], v[156:159], v[188:191], v[58:61]
	v_mfma_f32_16x16x32_bf16 v[54:57], v[164:167], v[188:191], v[54:57]
	v_mfma_f32_16x16x32_bf16 v[42:45], v[156:159], v[196:199], v[42:45]
	v_mfma_f32_16x16x32_bf16 v[38:41], v[164:167], v[196:199], v[38:41]
	v_mfma_f32_16x16x32_bf16 v[26:29], v[156:159], v[204:207], v[26:29]
	v_mfma_f32_16x16x32_bf16 v[22:25], v[164:167], v[204:207], v[22:25]
	v_mfma_f32_16x16x32_bf16 v[10:13], v[156:159], v[212:215], v[10:13]
	v_mfma_f32_16x16x32_bf16 v[6:9], v[164:167], v[212:215], v[6:9]
	v_mfma_f32_16x16x32_bf16 v[62:65], v[168:171], v[184:187], v[62:65]
	v_mfma_f32_16x16x32_bf16 v[50:53], v[176:179], v[184:187], v[50:53]
	v_mfma_f32_16x16x32_bf16 v[46:49], v[168:171], v[192:195], v[46:49]
	v_mfma_f32_16x16x32_bf16 v[34:37], v[176:179], v[192:195], v[34:37]
	v_mfma_f32_16x16x32_bf16 v[30:33], v[168:171], v[200:203], v[30:33]
	v_mfma_f32_16x16x32_bf16 v[18:21], v[176:179], v[200:203], v[18:21]
	v_mfma_f32_16x16x32_bf16 v[14:17], v[168:171], v[208:211], v[14:17]
	v_mfma_f32_16x16x32_bf16 v[2:5], v[176:179], v[208:211], v[2:5]
	v_mfma_f32_16x16x32_bf16 v[62:65], v[172:175], v[188:191], v[62:65]
	v_mfma_f32_16x16x32_bf16 v[50:53], v[180:183], v[188:191], v[50:53]
	v_mfma_f32_16x16x32_bf16 v[46:49], v[172:175], v[196:199], v[46:49]
	v_mfma_f32_16x16x32_bf16 v[34:37], v[180:183], v[196:199], v[34:37]
	v_mfma_f32_16x16x32_bf16 v[30:33], v[172:175], v[204:207], v[30:33]
	v_mfma_f32_16x16x32_bf16 v[18:21], v[180:183], v[204:207], v[18:21]
	v_mfma_f32_16x16x32_bf16 v[14:17], v[172:175], v[212:215], v[14:17]
	v_mfma_f32_16x16x32_bf16 v[2:5], v[180:183], v[212:215], v[2:5]
	s_barrier
	s_add_i32 s55, 0, 0x18000
	v_add_u32_e32 v151, s55, v146
	s_add_i32 s56, 0, 0x1c000
	ds_read_b128 v[152:155], v151
	ds_read_b128 v[156:159], v151 offset:1024
	ds_read_b128 v[160:163], v151 offset:2048
	ds_read_b128 v[164:167], v151 offset:3072
	v_add_u32_e32 v151, s56, v146
	ds_read_b128 v[168:171], v151
	ds_read_b128 v[172:175], v151 offset:1024
	ds_read_b128 v[176:179], v151 offset:2048
	ds_read_b128 v[180:183], v151 offset:3072
	s_add_u32 s34, s34, 0x80000
	s_addc_u32 s35, s35, 0
	s_mov_b32 m0, s39
	v_lshl_add_u64 v[216:217], s[34:35], 0, v[136:137]
	ds_read_b128 v[184:187], v150 offset:32768
	ds_read_b128 v[188:191], v150 offset:33792
	ds_read_b128 v[192:195], v150 offset:34816
	ds_read_b128 v[196:199], v150 offset:35840
	ds_read_b128 v[200:203], v150 offset:36864
	ds_read_b128 v[204:207], v150 offset:37888
	ds_read_b128 v[208:211], v150 offset:38912
	ds_read_b128 v[212:215], v150 offset:39936
	global_load_lds_dwordx4 v[216:217], off
	v_lshl_add_u64 v[216:217], s[34:35], 0, v[132:133]
	s_mov_b32 m0, s40
	s_nop 0
	global_load_lds_dwordx4 v[216:217], off
	s_waitcnt vmcnt(8)
	s_waitcnt lgkmcnt(0)
	s_barrier
	v_mfma_f32_16x16x32_bf16 v[122:125], v[152:155], v[184:187], v[122:125]
	v_mfma_f32_16x16x32_bf16 v[118:121], v[160:163], v[184:187], v[118:121]
	v_mfma_f32_16x16x32_bf16 v[106:109], v[152:155], v[192:195], v[106:109]
	v_mfma_f32_16x16x32_bf16 v[102:105], v[160:163], v[192:195], v[102:105]
	v_mfma_f32_16x16x32_bf16 v[90:93], v[152:155], v[200:203], v[90:93]
	v_mfma_f32_16x16x32_bf16 v[86:89], v[160:163], v[200:203], v[86:89]
	v_mfma_f32_16x16x32_bf16 v[74:77], v[152:155], v[208:211], v[74:77]
	v_mfma_f32_16x16x32_bf16 v[70:73], v[160:163], v[208:211], v[70:73]
	v_mfma_f32_16x16x32_bf16 v[122:125], v[156:159], v[188:191], v[122:125]
	v_mfma_f32_16x16x32_bf16 v[118:121], v[164:167], v[188:191], v[118:121]
	v_mfma_f32_16x16x32_bf16 v[106:109], v[156:159], v[196:199], v[106:109]
	v_mfma_f32_16x16x32_bf16 v[102:105], v[164:167], v[196:199], v[102:105]
	v_mfma_f32_16x16x32_bf16 v[90:93], v[156:159], v[204:207], v[90:93]
	v_mfma_f32_16x16x32_bf16 v[86:89], v[164:167], v[204:207], v[86:89]
	v_mfma_f32_16x16x32_bf16 v[74:77], v[156:159], v[212:215], v[74:77]
	v_mfma_f32_16x16x32_bf16 v[70:73], v[164:167], v[212:215], v[70:73]
	v_mfma_f32_16x16x32_bf16 v[126:129], v[168:171], v[184:187], v[126:129]
	v_mfma_f32_16x16x32_bf16 v[114:117], v[176:179], v[184:187], v[114:117]
	v_mfma_f32_16x16x32_bf16 v[110:113], v[168:171], v[192:195], v[110:113]
	v_mfma_f32_16x16x32_bf16 v[98:101], v[176:179], v[192:195], v[98:101]
	v_mfma_f32_16x16x32_bf16 v[94:97], v[168:171], v[200:203], v[94:97]
	v_mfma_f32_16x16x32_bf16 v[82:85], v[176:179], v[200:203], v[82:85]
	v_mfma_f32_16x16x32_bf16 v[78:81], v[168:171], v[208:211], v[78:81]
	v_mfma_f32_16x16x32_bf16 v[66:69], v[176:179], v[208:211], v[66:69]
	v_mfma_f32_16x16x32_bf16 v[126:129], v[172:175], v[188:191], v[126:129]
	v_mfma_f32_16x16x32_bf16 v[114:117], v[180:183], v[188:191], v[114:117]
	v_mfma_f32_16x16x32_bf16 v[110:113], v[172:175], v[196:199], v[110:113]
	v_mfma_f32_16x16x32_bf16 v[98:101], v[180:183], v[196:199], v[98:101]
	v_mfma_f32_16x16x32_bf16 v[94:97], v[172:175], v[204:207], v[94:97]
	v_mfma_f32_16x16x32_bf16 v[82:85], v[180:183], v[204:207], v[82:85]
	v_mfma_f32_16x16x32_bf16 v[78:81], v[172:175], v[212:215], v[78:81]
	v_mfma_f32_16x16x32_bf16 v[66:69], v[180:183], v[212:215], v[66:69]
	s_barrier
; #define PG8_STAGE(bufoff, gbase, voff) do { _Pragma("unroll") for (int _i = 0; _i < 2; ++_i) \
;         __builtin_amdgcn_global_load_lds((const unsigned*)((const char*)(gbase) + (voff)[_i]), (LAS unsigned*)(lds + (bufoff) + ldsw + _i * 8192), 16, 0, 0); } while (0)
; #define PG8_LDA(dst, b, h) do { _Pragma("unroll") for (int m = 0; m < 4; ++m) _Pragma("unroll") for (int k = 0; k < 2; ++k) dst[m][k] = *(const LAS bf16x8*)(lds + PG8_SA(b, h) + aoff + m * 2048 + k * 1024); } while (0)
; #define PG8_MMA(ai, bj, At, Bt) do { __builtin_amdgcn_s_setprio(1); _Pragma("unroll") for (int m = 0; m < 4; ++m) _Pragma("unroll") for (int n = 0; n < 2; ++n) _Pragma("unroll") for (int k = 0; k < 2; ++k) \
;         acc[ai][bj][m][n] = __builtin_amdgcn_mfma_f32_16x16x32_bf16(Bt[n][k], At[m][k], acc[ai][bj][m][n], 0, 0, 0); __builtin_amdgcn_s_setprio(0); } while (0)
; #define PG8_WAIT_V(n) asm volatile("s_waitcnt vmcnt(" #n ")" ::: "memory")
; #define PG8_WAIT_L(n) asm volatile("s_waitcnt lgkmcnt(" #n ")" ::: "memory")
; #define PG8_BAR __builtin_amdgcn_s_barrier()
; #define PG8_SCHED __builtin_amdgcn_sched_barrier(0)
; template <class Epi, class Sched, bool ABLK = false, bool ALIGN_EPI = true, bool SP2 = true, bool BBLK = true>
; __device__ __forceinline__ void gemm_phase(LAS unsigned char* lds, const Gemm g, const Sched& S, const Epi& E) {
;     ...
;             PG8_LDA(At, 1, 1); PG8_STAGE(PG8_SB(1, 0), b3, voffB); PG8_STAGE(PG8_SB(1, 1), b3 + hstepB, voffB); PG8_STAGE(PG8_SA(1, 0), a3, voffA);
;             PG8_WAIT_V(8); PG8_WAIT_L(0); PG8_BAR; PG8_MMA(1, 0, At, B0); PG8_MMA(1, 1, At, B1); PG8_BAR; PG8_SCHED;
;     ...
;         if constexpr (ALIGN_EPI) { if (wr == 0) PG8_BAR; }
	s_add_u32 s34, s30, 0x8000
	s_addc_u32 s35, s31, 0
	s_add_i32 s55, s55, s33
	v_lshl_add_u64 v[216:217], s[34:35], 0, v[134:135]
	s_mov_b32 m0, s55
	ds_read_b128 v[184:187], v150 offset:49152
	ds_read_b128 v[188:191], v150 offset:50176
	ds_read_b128 v[192:195], v150 offset:51200
	ds_read_b128 v[196:199], v150 offset:52224
	ds_read_b128 v[200:203], v150 offset:53248
	ds_read_b128 v[204:207], v150 offset:54272
	ds_read_b128 v[208:211], v150 offset:55296
	ds_read_b128 v[212:215], v150 offset:56320
	global_load_lds_dwordx4 v[216:217], off
	s_add_i32 m0, s55, 0x2000
	s_add_u32 s30, s30, 0xc000
	v_lshl_add_u64 v[216:217], s[34:35], 0, v[130:131]
	s_addc_u32 s31, s31, 0
	s_add_i32 s34, s56, s33
	global_load_lds_dwordx4 v[216:217], off
	v_lshl_add_u64 v[216:217], s[30:31], 0, v[134:135]
	s_mov_b32 m0, s34
	s_nop 0
	global_load_lds_dwordx4 v[216:217], off
	v_lshl_add_u64 v[216:217], s[30:31], 0, v[130:131]
	s_add_i32 m0, s34, 0x2000
	s_nop 0
	global_load_lds_dwordx4 v[216:217], off
	v_lshl_add_u64 v[216:217], s[28:29], 0, v[136:137]
	s_mov_b32 m0, s42
	s_nop 0
	global_load_lds_dwordx4 v[216:217], off
	v_lshl_add_u64 v[216:217], s[28:29], 0, v[132:133]
	s_mov_b32 m0, s43
	s_nop 0
	global_load_lds_dwordx4 v[216:217], off
	s_waitcnt vmcnt(8)
	s_waitcnt lgkmcnt(0)
	s_barrier
	v_mfma_f32_16x16x32_bf16 v[58:61], v[152:155], v[184:187], v[58:61]
	v_mfma_f32_16x16x32_bf16 v[54:57], v[160:163], v[184:187], v[54:57]
	v_mfma_f32_16x16x32_bf16 v[42:45], v[152:155], v[192:195], v[42:45]
	v_mfma_f32_16x16x32_bf16 v[38:41], v[160:163], v[192:195], v[38:41]
	v_mfma_f32_16x16x32_bf16 v[26:29], v[152:155], v[200:203], v[26:29]
	v_mfma_f32_16x16x32_bf16 v[22:25], v[160:163], v[200:203], v[22:25]
	v_mfma_f32_16x16x32_bf16 v[10:13], v[152:155], v[208:211], v[10:13]
	v_mfma_f32_16x16x32_bf16 v[6:9], v[160:163], v[208:211], v[6:9]
	v_mfma_f32_16x16x32_bf16 v[58:61], v[156:159], v[188:191], v[58:61]
	v_mfma_f32_16x16x32_bf16 v[54:57], v[164:167], v[188:191], v[54:57]
	v_mfma_f32_16x16x32_bf16 v[42:45], v[156:159], v[196:199], v[42:45]
	v_mfma_f32_16x16x32_bf16 v[38:41], v[164:167], v[196:199], v[38:41]
	v_mfma_f32_16x16x32_bf16 v[26:29], v[156:159], v[204:207], v[26:29]
	v_mfma_f32_16x16x32_bf16 v[22:25], v[164:167], v[204:207], v[22:25]
	v_mfma_f32_16x16x32_bf16 v[10:13], v[156:159], v[212:215], v[10:13]
	v_mfma_f32_16x16x32_bf16 v[6:9], v[164:167], v[212:215], v[6:9]
	v_mfma_f32_16x16x32_bf16 v[62:65], v[168:171], v[184:187], v[62:65]
	v_mfma_f32_16x16x32_bf16 v[50:53], v[176:179], v[184:187], v[50:53]
	v_mfma_f32_16x16x32_bf16 v[46:49], v[168:171], v[192:195], v[46:49]
	v_mfma_f32_16x16x32_bf16 v[34:37], v[176:179], v[192:195], v[34:37]
	v_mfma_f32_16x16x32_bf16 v[30:33], v[168:171], v[200:203], v[30:33]
	v_mfma_f32_16x16x32_bf16 v[18:21], v[176:179], v[200:203], v[18:21]
	v_mfma_f32_16x16x32_bf16 v[14:17], v[168:171], v[208:211], v[14:17]
	v_mfma_f32_16x16x32_bf16 v[2:5], v[176:179], v[208:211], v[2:5]
	v_mfma_f32_16x16x32_bf16 v[62:65], v[172:175], v[188:191], v[62:65]
	v_mfma_f32_16x16x32_bf16 v[50:53], v[180:183], v[188:191], v[50:53]
	v_mfma_f32_16x16x32_bf16 v[46:49], v[172:175], v[196:199], v[46:49]
	v_mfma_f32_16x16x32_bf16 v[34:37], v[180:183], v[196:199], v[34:37]
	v_mfma_f32_16x16x32_bf16 v[30:33], v[172:175], v[204:207], v[30:33]
	v_mfma_f32_16x16x32_bf16 v[18:21], v[180:183], v[204:207], v[18:21]
	v_mfma_f32_16x16x32_bf16 v[14:17], v[172:175], v[212:215], v[14:17]
	v_mfma_f32_16x16x32_bf16 v[2:5], v[180:183], v[212:215], v[2:5]
	s_barrier
	s_add_i32 s54, s54, 2
	s_add_u32 s26, s26, 0x100
	s_addc_u32 s27, s27, 0
	s_add_u32 s52, s52, 0x10000
	s_addc_u32 s53, s53, 0
	s_cmp_gt_u32 s54, 29
	s_cbranch_scc0 .LBB0_350
	s_and_b64 vcc, exec, s[6:7]
	s_cbranch_vccz .LBB0_353
	s_barrier

; #define PG8_STAGE(bufoff, gbase, voff) do { _Pragma("unroll") for (int _i = 0; _i < 2; ++_i) \
;         __builtin_amdgcn_global_load_lds((const unsigned*)((const char*)(gbase) + (voff)[_i]), (LAS unsigned*)(lds + (bufoff) + ldsw + _i * 8192), 16, 0, 0); } while (0)
; #define PG8_LDA(dst, b, h) do { _Pragma("unroll") for (int m = 0; m < 4; ++m) _Pragma("unroll") for (int k = 0; k < 2; ++k) dst[m][k] = *(const LAS bf16x8*)(lds + PG8_SA(b, h) + aoff + m * 2048 + k * 1024); } while (0)
; #define PG8_LDB(dst, b, h) do { _Pragma("unroll") for (int n = 0; n < 2; ++n) _Pragma("unroll") for (int k = 0; k < 2; ++k) dst[n][k] = *(const LAS bf16x8*)(lds + PG8_SB(b, h) + boff + n * 2048 + k * 1024); } while (0)
; #define PG8_MMA(ai, bj, At, Bt) do { __builtin_amdgcn_s_setprio(1); _Pragma("unroll") for (int m = 0; m < 4; ++m) _Pragma("unroll") for (int n = 0; n < 2; ++n) _Pragma("unroll") for (int k = 0; k < 2; ++k) \
;         acc[ai][bj][m][n] = __builtin_amdgcn_mfma_f32_16x16x32_bf16(Bt[n][k], At[m][k], acc[ai][bj][m][n], 0, 0, 0); __builtin_amdgcn_s_setprio(0); } while (0)
; #define PG8_WAIT_V(n) asm volatile("s_waitcnt vmcnt(" #n ")" ::: "memory")
; #define PG8_WAIT_L(n) asm volatile("s_waitcnt lgkmcnt(" #n ")" ::: "memory")
; #define PG8_BAR __builtin_amdgcn_s_barrier()
; template <class Epi, class Sched, bool ABLK = false, bool ALIGN_EPI = true, bool SP2 = true, bool BBLK = true>
; __device__ __forceinline__ void gemm_phase(LAS unsigned char* lds, const Gemm g, const Sched& S, const Epi& E) {
;     ...
;             const bool last = (t == nt - 2);
;             const char* a1 = a_tile(uA, tbA + t + 1);
;             const char* a2 = last ? a_tile(nuA, ntbA) : a_tile(uA, tbA + t + 2); const char* b2 = last ? nB : cB + (size_t)(t + 2) * kstepB;
;             const char* a3 = last ? a_tile(nuA, ntbA + 1) : a_tile(uA, tbA + t + 3); const char* b3 = b2 + kstepB;
;             if (last && has_next) S.a_ready(nxt);
;             if constexpr (SP2) {
;             PG8_LDB(B0, 0, 0); PG8_LDB(B1, 0, 1); PG8_SCHED; PG8_LDA(At, 0, 0); PG8_STAGE(PG8_SA(1, 1), a1 + hstepA, voffA);
;             PG8_WAIT_V(8); PG8_WAIT_L(0); PG8_BAR; PG8_MMA(0, 0, At, B0); PG8_MMA(0, 1, At, B1); PG8_BAR; PG8_SCHED;
;             PG8_LDA(At, 0, 1); PG8_STAGE(PG8_SB(0, 0), b2, voffB); PG8_STAGE(PG8_SB(0, 1), b2 + hstepB, voffB); PG8_STAGE(PG8_SA(0, 0), a2, voffA);
.LBB0_475:
	ds_read_b128 v[172:175], v168
	ds_read_b128 v[176:179], v168 offset:1024
	ds_read_b128 v[180:183], v168 offset:2048
	ds_read_b128 v[184:187], v168 offset:3072
	ds_read_b128 v[188:191], v169
	ds_read_b128 v[192:195], v169 offset:1024
	ds_read_b128 v[196:199], v169 offset:2048
	ds_read_b128 v[200:203], v169 offset:3072
	s_add_u32 s30, s26, s28
	s_addc_u32 s31, s27, s29
	s_add_u32 s36, s30, 0x100
	s_addc_u32 s37, s31, 0
	s_add_u32 s30, s30, 0x180
	s_addc_u32 s31, s31, 0
	s_cmpk_eq_i32 s28, 0xf00
	s_cselect_b32 s31, s57, s31
	s_cselect_b32 s30, s23, s30
	s_cselect_b32 s35, s11, s59
	s_cselect_b32 s34, s13, s58
	s_cselect_b32 s37, s4, s37
	s_cselect_b32 s36, s5, s36
	s_mov_b32 m0, s53
	v_lshl_add_u64 v[236:237], v[164:165], 0, s[28:29]
	ds_read_b128 v[204:207], v170
	ds_read_b128 v[208:211], v170 offset:1024
	ds_read_b128 v[212:215], v170 offset:2048
	ds_read_b128 v[216:219], v170 offset:3072
	ds_read_b128 v[220:223], v170 offset:4096
	ds_read_b128 v[224:227], v170 offset:5120
	ds_read_b128 v[228:231], v170 offset:6144
	ds_read_b128 v[232:235], v170 offset:7168
	global_load_lds_dwordx4 v[236:237], off
	v_lshl_add_u64 v[236:237], v[166:167], 0, s[28:29]
	s_mov_b32 m0, s54
	s_nop 0
	global_load_lds_dwordx4 v[236:237], off
	s_waitcnt vmcnt(8)
	s_waitcnt lgkmcnt(0)
	s_barrier
	v_mfma_f32_16x16x32_bf16 v[126:129], v[172:175], v[204:207], v[126:129]
	v_mfma_f32_16x16x32_bf16 v[122:125], v[180:183], v[204:207], v[122:125]
	v_mfma_f32_16x16x32_bf16 v[110:113], v[172:175], v[212:215], v[110:113]
	v_mfma_f32_16x16x32_bf16 v[106:109], v[180:183], v[212:215], v[106:109]
	v_mfma_f32_16x16x32_bf16 v[94:97], v[172:175], v[220:223], v[94:97]
	v_mfma_f32_16x16x32_bf16 v[90:93], v[180:183], v[220:223], v[90:93]
	v_mfma_f32_16x16x32_bf16 v[78:81], v[172:175], v[228:231], v[78:81]
	v_mfma_f32_16x16x32_bf16 v[74:77], v[180:183], v[228:231], v[74:77]
	v_mfma_f32_16x16x32_bf16 v[126:129], v[176:179], v[208:211], v[126:129]
	v_mfma_f32_16x16x32_bf16 v[122:125], v[184:187], v[208:211], v[122:125]
	v_mfma_f32_16x16x32_bf16 v[110:113], v[176:179], v[216:219], v[110:113]
	v_mfma_f32_16x16x32_bf16 v[106:109], v[184:187], v[216:219], v[106:109]
	v_mfma_f32_16x16x32_bf16 v[94:97], v[176:179], v[224:227], v[94:97]
	v_mfma_f32_16x16x32_bf16 v[90:93], v[184:187], v[224:227], v[90:93]
	v_mfma_f32_16x16x32_bf16 v[78:81], v[176:179], v[232:235], v[78:81]
	v_mfma_f32_16x16x32_bf16 v[74:77], v[184:187], v[232:235], v[74:77]
	v_mfma_f32_16x16x32_bf16 v[118:121], v[188:191], v[204:207], v[118:121]
	v_mfma_f32_16x16x32_bf16 v[114:117], v[196:199], v[204:207], v[114:117]
	v_mfma_f32_16x16x32_bf16 v[102:105], v[188:191], v[212:215], v[102:105]
	v_mfma_f32_16x16x32_bf16 v[98:101], v[196:199], v[212:215], v[98:101]
	v_mfma_f32_16x16x32_bf16 v[86:89], v[188:191], v[220:223], v[86:89]
	v_mfma_f32_16x16x32_bf16 v[82:85], v[196:199], v[220:223], v[82:85]
	v_mfma_f32_16x16x32_bf16 v[70:73], v[188:191], v[228:231], v[70:73]
	v_mfma_f32_16x16x32_bf16 v[66:69], v[196:199], v[228:231], v[66:69]
	v_mfma_f32_16x16x32_bf16 v[118:121], v[192:195], v[208:211], v[118:121]
	v_mfma_f32_16x16x32_bf16 v[114:117], v[200:203], v[208:211], v[114:117]
	v_mfma_f32_16x16x32_bf16 v[102:105], v[192:195], v[216:219], v[102:105]
	v_mfma_f32_16x16x32_bf16 v[98:101], v[200:203], v[216:219], v[98:101]
	v_mfma_f32_16x16x32_bf16 v[86:89], v[192:195], v[224:227], v[86:89]
	v_mfma_f32_16x16x32_bf16 v[82:85], v[200:203], v[224:227], v[82:85]
	v_mfma_f32_16x16x32_bf16 v[70:73], v[192:195], v[232:235], v[70:73]
	v_mfma_f32_16x16x32_bf16 v[66:69], v[200:203], v[232:235], v[66:69]
	s_barrier
	s_mov_b32 m0, s55
	v_lshl_add_u64 v[236:237], s[34:35], 0, v[134:135]
	s_add_u32 s62, s34, 0x4000
	ds_read_b128 v[204:207], v170 offset:16384
	ds_read_b128 v[208:211], v170 offset:17408
	ds_read_b128 v[212:215], v170 offset:18432
	ds_read_b128 v[216:219], v170 offset:19456
	ds_read_b128 v[220:223], v170 offset:20480
	ds_read_b128 v[224:227], v170 offset:21504
	ds_read_b128 v[228:231], v170 offset:22528
	ds_read_b128 v[232:235], v170 offset:23552
	global_load_lds_dwordx4 v[236:237], off
	v_lshl_add_u64 v[236:237], s[34:35], 0, v[130:131]
	s_mov_b32 m0, s56
	s_addc_u32 s63, s35, 0
	s_add_i32 s61, s52, s40
	global_load_lds_dwordx4 v[236:237], off
	v_lshl_add_u64 v[236:237], s[62:63], 0, v[134:135]
	s_mov_b32 m0, s61
	s_nop 0
	global_load_lds_dwordx4 v[236:237], off
	v_lshl_add_u64 v[236:237], s[62:63], 0, v[130:131]
	s_add_i32 m0, s61, 0x2000
	s_nop 0
	global_load_lds_dwordx4 v[236:237], off
	v_lshl_add_u64 v[236:237], s[36:37], 0, v[136:137]
	s_mov_b32 m0, s25
	s_nop 0
	global_load_lds_dwordx4 v[236:237], off
	v_lshl_add_u64 v[236:237], s[36:37], 0, v[132:133]
	s_mov_b32 m0, s43
	s_nop 0
	global_load_lds_dwordx4 v[236:237], off
	s_waitcnt vmcnt(8)
	s_waitcnt lgkmcnt(0)
	s_barrier
; #define PG8_STAGE(bufoff, gbase, voff) do { _Pragma("unroll") for (int _i = 0; _i < 2; ++_i) \
;         __builtin_amdgcn_global_load_lds((const unsigned*)((const char*)(gbase) + (voff)[_i]), (LAS unsigned*)(lds + (bufoff) + ldsw + _i * 8192), 16, 0, 0); } while (0)
; #define PG8_LDA(dst, b, h) do { _Pragma("unroll") for (int m = 0; m < 4; ++m) _Pragma("unroll") for (int k = 0; k < 2; ++k) dst[m][k] = *(const LAS bf16x8*)(lds + PG8_SA(b, h) + aoff + m * 2048 + k * 1024); } while (0)
; #define PG8_LDB(dst, b, h) do { _Pragma("unroll") for (int n = 0; n < 2; ++n) _Pragma("unroll") for (int k = 0; k < 2; ++k) dst[n][k] = *(const LAS bf16x8*)(lds + PG8_SB(b, h) + boff + n * 2048 + k * 1024); } while (0)
; #define PG8_MMA(ai, bj, At, Bt) do { __builtin_amdgcn_s_setprio(1); _Pragma("unroll") for (int m = 0; m < 4; ++m) _Pragma("unroll") for (int n = 0; n < 2; ++n) _Pragma("unroll") for (int k = 0; k < 2; ++k) \
;         acc[ai][bj][m][n] = __builtin_amdgcn_mfma_f32_16x16x32_bf16(Bt[n][k], At[m][k], acc[ai][bj][m][n], 0, 0, 0); __builtin_amdgcn_s_setprio(0); } while (0)
; #define PG8_WAIT_V(n) asm volatile("s_waitcnt vmcnt(" #n ")" ::: "memory")
; #define PG8_WAIT_L(n) asm volatile("s_waitcnt lgkmcnt(" #n ")" ::: "memory")
; #define PG8_BAR __builtin_amdgcn_s_barrier()
; #define PG8_SCHED __builtin_amdgcn_sched_barrier(0)
; template <class Epi, class Sched, bool ABLK = false, bool ALIGN_EPI = true, bool SP2 = true, bool BBLK = true>
; __device__ __forceinline__ void gemm_phase(LAS unsigned char* lds, const Gemm g, const Sched& S, const Epi& E) {
;     ...
;             PG8_WAIT_V(8); PG8_WAIT_L(0); PG8_BAR; PG8_MMA(1, 0, At, B0); PG8_MMA(1, 1, At, B1); PG8_BAR; PG8_SCHED;
;             PG8_LDB(B0, 1, 0); PG8_LDB(B1, 1, 1); PG8_SCHED; PG8_LDA(At, 1, 0); PG8_STAGE(PG8_SA(0, 1), a2 + hstepA, voffA);
;             PG8_WAIT_V(8); PG8_WAIT_L(0); PG8_BAR; PG8_MMA(0, 0, At, B0); PG8_MMA(0, 1, At, B1); PG8_BAR; PG8_SCHED;
	v_mfma_f32_16x16x32_bf16 v[62:65], v[172:175], v[204:207], v[62:65]
	v_mfma_f32_16x16x32_bf16 v[58:61], v[180:183], v[204:207], v[58:61]
	v_mfma_f32_16x16x32_bf16 v[46:49], v[172:175], v[212:215], v[46:49]
	v_mfma_f32_16x16x32_bf16 v[42:45], v[180:183], v[212:215], v[42:45]
	v_mfma_f32_16x16x32_bf16 v[30:33], v[172:175], v[220:223], v[30:33]
	v_mfma_f32_16x16x32_bf16 v[26:29], v[180:183], v[220:223], v[26:29]
	v_mfma_f32_16x16x32_bf16 v[14:17], v[172:175], v[228:231], v[14:17]
	v_mfma_f32_16x16x32_bf16 v[10:13], v[180:183], v[228:231], v[10:13]
	v_mfma_f32_16x16x32_bf16 v[62:65], v[176:179], v[208:211], v[62:65]
	v_mfma_f32_16x16x32_bf16 v[58:61], v[184:187], v[208:211], v[58:61]
	v_mfma_f32_16x16x32_bf16 v[46:49], v[176:179], v[216:219], v[46:49]
	v_mfma_f32_16x16x32_bf16 v[42:45], v[184:187], v[216:219], v[42:45]
	v_mfma_f32_16x16x32_bf16 v[30:33], v[176:179], v[224:227], v[30:33]
	v_mfma_f32_16x16x32_bf16 v[26:29], v[184:187], v[224:227], v[26:29]
	v_mfma_f32_16x16x32_bf16 v[14:17], v[176:179], v[232:235], v[14:17]
	v_mfma_f32_16x16x32_bf16 v[10:13], v[184:187], v[232:235], v[10:13]
	v_mfma_f32_16x16x32_bf16 v[54:57], v[188:191], v[204:207], v[54:57]
	v_mfma_f32_16x16x32_bf16 v[50:53], v[196:199], v[204:207], v[50:53]
	v_mfma_f32_16x16x32_bf16 v[38:41], v[188:191], v[212:215], v[38:41]
	v_mfma_f32_16x16x32_bf16 v[34:37], v[196:199], v[212:215], v[34:37]
	v_mfma_f32_16x16x32_bf16 v[22:25], v[188:191], v[220:223], v[22:25]
	v_mfma_f32_16x16x32_bf16 v[18:21], v[196:199], v[220:223], v[18:21]
	v_mfma_f32_16x16x32_bf16 v[6:9], v[188:191], v[228:231], v[6:9]
	v_mfma_f32_16x16x32_bf16 v[2:5], v[196:199], v[228:231], v[2:5]
	v_mfma_f32_16x16x32_bf16 v[54:57], v[192:195], v[208:211], v[54:57]
	v_mfma_f32_16x16x32_bf16 v[50:53], v[200:203], v[208:211], v[50:53]
	v_mfma_f32_16x16x32_bf16 v[38:41], v[192:195], v[216:219], v[38:41]
	v_mfma_f32_16x16x32_bf16 v[34:37], v[200:203], v[216:219], v[34:37]
	v_mfma_f32_16x16x32_bf16 v[22:25], v[192:195], v[224:227], v[22:25]
	v_mfma_f32_16x16x32_bf16 v[18:21], v[200:203], v[224:227], v[18:21]
	v_mfma_f32_16x16x32_bf16 v[6:9], v[192:195], v[232:235], v[6:9]
	v_mfma_f32_16x16x32_bf16 v[2:5], v[200:203], v[232:235], v[2:5]
	s_barrier
	s_add_i32 s61, 0, 0x18000
	v_add_u32_e32 v171, s61, v1
	s_add_i32 s62, 0, 0x1c000
	ds_read_b128 v[172:175], v171
	ds_read_b128 v[176:179], v171 offset:1024
	ds_read_b128 v[180:183], v171 offset:2048
	ds_read_b128 v[184:187], v171 offset:3072
	v_add_u32_e32 v171, s62, v1
	ds_read_b128 v[188:191], v171
	ds_read_b128 v[192:195], v171 offset:1024
	ds_read_b128 v[196:199], v171 offset:2048
	ds_read_b128 v[200:203], v171 offset:3072
	s_add_u32 s36, s36, 0x80000
	s_addc_u32 s37, s37, 0
	s_mov_b32 m0, s46
	v_lshl_add_u64 v[236:237], s[36:37], 0, v[136:137]
	ds_read_b128 v[204:207], v170 offset:32768
	ds_read_b128 v[208:211], v170 offset:33792
	ds_read_b128 v[212:215], v170 offset:34816
	ds_read_b128 v[216:219], v170 offset:35840
	ds_read_b128 v[220:223], v170 offset:36864
	ds_read_b128 v[224:227], v170 offset:37888
	ds_read_b128 v[228:231], v170 offset:38912
	ds_read_b128 v[232:235], v170 offset:39936
	global_load_lds_dwordx4 v[236:237], off
	v_lshl_add_u64 v[236:237], s[36:37], 0, v[132:133]
	s_mov_b32 m0, s47
	s_nop 0
	global_load_lds_dwordx4 v[236:237], off
	s_waitcnt vmcnt(8)
	s_waitcnt lgkmcnt(0)
	s_barrier
	v_mfma_f32_16x16x32_bf16 v[126:129], v[172:175], v[204:207], v[126:129]
	v_mfma_f32_16x16x32_bf16 v[122:125], v[180:183], v[204:207], v[122:125]
	v_mfma_f32_16x16x32_bf16 v[110:113], v[172:175], v[212:215], v[110:113]
	v_mfma_f32_16x16x32_bf16 v[106:109], v[180:183], v[212:215], v[106:109]
	v_mfma_f32_16x16x32_bf16 v[94:97], v[172:175], v[220:223], v[94:97]
	v_mfma_f32_16x16x32_bf16 v[90:93], v[180:183], v[220:223], v[90:93]
	v_mfma_f32_16x16x32_bf16 v[78:81], v[172:175], v[228:231], v[78:81]
	v_mfma_f32_16x16x32_bf16 v[74:77], v[180:183], v[228:231], v[74:77]
	v_mfma_f32_16x16x32_bf16 v[126:129], v[176:179], v[208:211], v[126:129]
	v_mfma_f32_16x16x32_bf16 v[122:125], v[184:187], v[208:211], v[122:125]
	v_mfma_f32_16x16x32_bf16 v[110:113], v[176:179], v[216:219], v[110:113]
	v_mfma_f32_16x16x32_bf16 v[106:109], v[184:187], v[216:219], v[106:109]
	v_mfma_f32_16x16x32_bf16 v[94:97], v[176:179], v[224:227], v[94:97]
	v_mfma_f32_16x16x32_bf16 v[90:93], v[184:187], v[224:227], v[90:93]
	v_mfma_f32_16x16x32_bf16 v[78:81], v[176:179], v[232:235], v[78:81]
	v_mfma_f32_16x16x32_bf16 v[74:77], v[184:187], v[232:235], v[74:77]
	v_mfma_f32_16x16x32_bf16 v[118:121], v[188:191], v[204:207], v[118:121]
	v_mfma_f32_16x16x32_bf16 v[114:117], v[196:199], v[204:207], v[114:117]
	v_mfma_f32_16x16x32_bf16 v[102:105], v[188:191], v[212:215], v[102:105]
	v_mfma_f32_16x16x32_bf16 v[98:101], v[196:199], v[212:215], v[98:101]
	v_mfma_f32_16x16x32_bf16 v[86:89], v[188:191], v[220:223], v[86:89]
	v_mfma_f32_16x16x32_bf16 v[82:85], v[196:199], v[220:223], v[82:85]
	v_mfma_f32_16x16x32_bf16 v[70:73], v[188:191], v[228:231], v[70:73]
	v_mfma_f32_16x16x32_bf16 v[66:69], v[196:199], v[228:231], v[66:69]
	v_mfma_f32_16x16x32_bf16 v[118:121], v[192:195], v[208:211], v[118:121]
	v_mfma_f32_16x16x32_bf16 v[114:117], v[200:203], v[208:211], v[114:117]
	v_mfma_f32_16x16x32_bf16 v[102:105], v[192:195], v[216:219], v[102:105]
	v_mfma_f32_16x16x32_bf16 v[98:101], v[200:203], v[216:219], v[98:101]
	v_mfma_f32_16x16x32_bf16 v[86:89], v[192:195], v[224:227], v[86:89]
	v_mfma_f32_16x16x32_bf16 v[82:85], v[200:203], v[224:227], v[82:85]
	v_mfma_f32_16x16x32_bf16 v[70:73], v[192:195], v[232:235], v[70:73]
	v_mfma_f32_16x16x32_bf16 v[66:69], v[200:203], v[232:235], v[66:69]
	s_barrier
; #define PG8_STAGE(bufoff, gbase, voff) do { _Pragma("unroll") for (int _i = 0; _i < 2; ++_i) \
;         __builtin_amdgcn_global_load_lds((const unsigned*)((const char*)(gbase) + (voff)[_i]), (LAS unsigned*)(lds + (bufoff) + ldsw + _i * 8192), 16, 0, 0); } while (0)
; #define PG8_LDA(dst, b, h) do { _Pragma("unroll") for (int m = 0; m < 4; ++m) _Pragma("unroll") for (int k = 0; k < 2; ++k) dst[m][k] = *(const LAS bf16x8*)(lds + PG8_SA(b, h) + aoff + m * 2048 + k * 1024); } while (0)
; #define PG8_MMA(ai, bj, At, Bt) do { __builtin_amdgcn_s_setprio(1); _Pragma("unroll") for (int m = 0; m < 4; ++m) _Pragma("unroll") for (int n = 0; n < 2; ++n) _Pragma("unroll") for (int k = 0; k < 2; ++k) \
;         acc[ai][bj][m][n] = __builtin_amdgcn_mfma_f32_16x16x32_bf16(Bt[n][k], At[m][k], acc[ai][bj][m][n], 0, 0, 0); __builtin_amdgcn_s_setprio(0); } while (0)
; #define PG8_WAIT_V(n) asm volatile("s_waitcnt vmcnt(" #n ")" ::: "memory")
; #define PG8_WAIT_L(n) asm volatile("s_waitcnt lgkmcnt(" #n ")" ::: "memory")
; #define PG8_BAR __builtin_amdgcn_s_barrier()
; #define PG8_SCHED __builtin_amdgcn_sched_barrier(0)
; template <class Epi, class Sched, bool ABLK = false, bool ALIGN_EPI = true, bool SP2 = true, bool BBLK = true>
; __device__ __forceinline__ void gemm_phase(LAS unsigned char* lds, const Gemm g, const Sched& S, const Epi& E) {
;     ...
;             PG8_LDA(At, 1, 1); PG8_STAGE(PG8_SB(1, 0), b3, voffB); PG8_STAGE(PG8_SB(1, 1), b3 + hstepB, voffB); PG8_STAGE(PG8_SA(1, 0), a3, voffA);
;             PG8_WAIT_V(8); PG8_WAIT_L(0); PG8_BAR; PG8_MMA(1, 0, At, B0); PG8_MMA(1, 1, At, B1); PG8_BAR; PG8_SCHED;
;     ...
;         if constexpr (ALIGN_EPI) { if (wr == 0) PG8_BAR; }
	s_add_u32 s36, s34, 0x8000
	s_addc_u32 s37, s35, 0
	s_add_i32 s61, s61, s40
	v_lshl_add_u64 v[236:237], s[36:37], 0, v[134:135]
	s_mov_b32 m0, s61
	ds_read_b128 v[204:207], v170 offset:49152
	ds_read_b128 v[208:211], v170 offset:50176
	ds_read_b128 v[212:215], v170 offset:51200
	ds_read_b128 v[216:219], v170 offset:52224
	ds_read_b128 v[220:223], v170 offset:53248
	ds_read_b128 v[224:227], v170 offset:54272
	ds_read_b128 v[228:231], v170 offset:55296
	ds_read_b128 v[232:235], v170 offset:56320
	global_load_lds_dwordx4 v[236:237], off
	s_add_i32 m0, s61, 0x2000
	s_add_u32 s34, s34, 0xc000
	v_lshl_add_u64 v[236:237], s[36:37], 0, v[130:131]
	s_addc_u32 s35, s35, 0
	s_add_i32 s36, s62, s40
	global_load_lds_dwordx4 v[236:237], off
	v_lshl_add_u64 v[236:237], s[34:35], 0, v[134:135]
	s_mov_b32 m0, s36
	s_nop 0
	global_load_lds_dwordx4 v[236:237], off
	v_lshl_add_u64 v[236:237], s[34:35], 0, v[130:131]
	s_add_i32 m0, s36, 0x2000
	s_nop 0
	global_load_lds_dwordx4 v[236:237], off
	v_lshl_add_u64 v[236:237], s[30:31], 0, v[136:137]
	s_mov_b32 m0, s50
	s_nop 0
	global_load_lds_dwordx4 v[236:237], off
	v_lshl_add_u64 v[236:237], s[30:31], 0, v[132:133]
	s_mov_b32 m0, s51
	s_nop 0
	global_load_lds_dwordx4 v[236:237], off
	s_waitcnt vmcnt(8)
	s_waitcnt lgkmcnt(0)
	s_barrier
	v_mfma_f32_16x16x32_bf16 v[62:65], v[172:175], v[204:207], v[62:65]
	v_mfma_f32_16x16x32_bf16 v[58:61], v[180:183], v[204:207], v[58:61]
	v_mfma_f32_16x16x32_bf16 v[46:49], v[172:175], v[212:215], v[46:49]
	v_mfma_f32_16x16x32_bf16 v[42:45], v[180:183], v[212:215], v[42:45]
	v_mfma_f32_16x16x32_bf16 v[30:33], v[172:175], v[220:223], v[30:33]
	v_mfma_f32_16x16x32_bf16 v[26:29], v[180:183], v[220:223], v[26:29]
	v_mfma_f32_16x16x32_bf16 v[14:17], v[172:175], v[228:231], v[14:17]
	v_mfma_f32_16x16x32_bf16 v[10:13], v[180:183], v[228:231], v[10:13]
	v_mfma_f32_16x16x32_bf16 v[62:65], v[176:179], v[208:211], v[62:65]
	v_mfma_f32_16x16x32_bf16 v[58:61], v[184:187], v[208:211], v[58:61]
	v_mfma_f32_16x16x32_bf16 v[46:49], v[176:179], v[216:219], v[46:49]
	v_mfma_f32_16x16x32_bf16 v[42:45], v[184:187], v[216:219], v[42:45]
	v_mfma_f32_16x16x32_bf16 v[30:33], v[176:179], v[224:227], v[30:33]
	v_mfma_f32_16x16x32_bf16 v[26:29], v[184:187], v[224:227], v[26:29]
	v_mfma_f32_16x16x32_bf16 v[14:17], v[176:179], v[232:235], v[14:17]
	v_mfma_f32_16x16x32_bf16 v[10:13], v[184:187], v[232:235], v[10:13]
	v_mfma_f32_16x16x32_bf16 v[54:57], v[188:191], v[204:207], v[54:57]
	v_mfma_f32_16x16x32_bf16 v[50:53], v[196:199], v[204:207], v[50:53]
	v_mfma_f32_16x16x32_bf16 v[38:41], v[188:191], v[212:215], v[38:41]
	v_mfma_f32_16x16x32_bf16 v[34:37], v[196:199], v[212:215], v[34:37]
	v_mfma_f32_16x16x32_bf16 v[22:25], v[188:191], v[220:223], v[22:25]
	v_mfma_f32_16x16x32_bf16 v[18:21], v[196:199], v[220:223], v[18:21]
	v_mfma_f32_16x16x32_bf16 v[6:9], v[188:191], v[228:231], v[6:9]
	v_mfma_f32_16x16x32_bf16 v[2:5], v[196:199], v[228:231], v[2:5]
	v_mfma_f32_16x16x32_bf16 v[54:57], v[192:195], v[208:211], v[54:57]
	v_mfma_f32_16x16x32_bf16 v[50:53], v[200:203], v[208:211], v[50:53]
	v_mfma_f32_16x16x32_bf16 v[38:41], v[192:195], v[216:219], v[38:41]
	v_mfma_f32_16x16x32_bf16 v[34:37], v[200:203], v[216:219], v[34:37]
	v_mfma_f32_16x16x32_bf16 v[22:25], v[192:195], v[224:227], v[22:25]
	v_mfma_f32_16x16x32_bf16 v[18:21], v[200:203], v[224:227], v[18:21]
	v_mfma_f32_16x16x32_bf16 v[6:9], v[192:195], v[232:235], v[6:9]
	v_mfma_f32_16x16x32_bf16 v[2:5], v[200:203], v[232:235], v[2:5]
	s_barrier
	s_add_i32 s60, s60, 2
	s_add_u32 s28, s28, 0x100
	s_addc_u32 s29, s29, 0
	s_add_u32 s58, s58, 0x10000
	s_addc_u32 s59, s59, 0
	s_cmp_gt_u32 s60, 29
	s_cbranch_scc0 .LBB0_475
	s_and_b64 vcc, exec, s[8:9]
	s_cbranch_vccz .LBB0_478
	s_barrier

; #define PG8_STAGE(bufoff, gbase, voff) do { _Pragma("unroll") for (int _i = 0; _i < 2; ++_i) \
;         __builtin_amdgcn_global_load_lds((const unsigned*)((const char*)(gbase) + (voff)[_i]), (LAS unsigned*)(lds + (bufoff) + ldsw + _i * 8192), 16, 0, 0); } while (0)
; #define PG8_LDA(dst, b, h) do { _Pragma("unroll") for (int m = 0; m < 4; ++m) _Pragma("unroll") for (int k = 0; k < 2; ++k) dst[m][k] = *(const LAS bf16x8*)(lds + PG8_SA(b, h) + aoff + m * 2048 + k * 1024); } while (0)
; #define PG8_LDB(dst, b, h) do { _Pragma("unroll") for (int n = 0; n < 2; ++n) _Pragma("unroll") for (int k = 0; k < 2; ++k) dst[n][k] = *(const LAS bf16x8*)(lds + PG8_SB(b, h) + boff + n * 2048 + k * 1024); } while (0)
; #define PG8_MMA(ai, bj, At, Bt) do { __builtin_amdgcn_s_setprio(1); _Pragma("unroll") for (int m = 0; m < 4; ++m) _Pragma("unroll") for (int n = 0; n < 2; ++n) _Pragma("unroll") for (int k = 0; k < 2; ++k) \
;         acc[ai][bj][m][n] = __builtin_amdgcn_mfma_f32_16x16x32_bf16(Bt[n][k], At[m][k], acc[ai][bj][m][n], 0, 0, 0); __builtin_amdgcn_s_setprio(0); } while (0)
; #define PG8_WAIT_V(n) asm volatile("s_waitcnt vmcnt(" #n ")" ::: "memory")
; #define PG8_WAIT_L(n) asm volatile("s_waitcnt lgkmcnt(" #n ")" ::: "memory")
; #define PG8_BAR __builtin_amdgcn_s_barrier()
; template <class Epi, class Sched, bool ABLK = false, bool ALIGN_EPI = true, bool SP2 = true, bool BBLK = true>
; __device__ __forceinline__ void gemm_phase(LAS unsigned char* lds, const Gemm g, const Sched& S, const Epi& E) {
;     ...
;             const bool last = (t == nt - 2);
;             const char* a1 = a_tile(uA, tbA + t + 1);
;             const char* a2 = last ? a_tile(nuA, ntbA) : a_tile(uA, tbA + t + 2); const char* b2 = last ? nB : cB + (size_t)(t + 2) * kstepB;
;             const char* a3 = last ? a_tile(nuA, ntbA + 1) : a_tile(uA, tbA + t + 3); const char* b3 = b2 + kstepB;
;             if (last && has_next) S.a_ready(nxt);
;             if constexpr (SP2) {
;             PG8_LDB(B0, 0, 0); PG8_LDB(B1, 0, 1); PG8_SCHED; PG8_LDA(At, 0, 0); PG8_STAGE(PG8_SA(1, 1), a1 + hstepA, voffA);
;             PG8_WAIT_V(8); PG8_WAIT_L(0); PG8_BAR; PG8_MMA(0, 0, At, B0); PG8_MMA(0, 1, At, B1); PG8_BAR; PG8_SCHED;
;             PG8_LDA(At, 0, 1); PG8_STAGE(PG8_SB(0, 0), b2, voffB); PG8_STAGE(PG8_SB(0, 1), b2 + hstepB, voffB); PG8_STAGE(PG8_SA(0, 0), a2, voffA);
.LBB0_540:
	ds_read_b128 v[152:155], v148
	ds_read_b128 v[156:159], v148 offset:1024
	ds_read_b128 v[160:163], v148 offset:2048
	ds_read_b128 v[164:167], v148 offset:3072
	ds_read_b128 v[168:171], v149
	ds_read_b128 v[172:175], v149 offset:1024
	ds_read_b128 v[176:179], v149 offset:2048
	ds_read_b128 v[180:183], v149 offset:3072
	s_add_u32 s42, s75, s40
	s_addc_u32 s43, s76, s41
	s_add_u32 s48, s42, 0x10000
	s_addc_u32 s49, s43, 0
	s_add_i32 s79, s79, 2
	s_add_u32 s46, s66, s40
	s_addc_u32 s47, s67, s41
	s_add_u32 s42, s42, 0x18000
	s_addc_u32 s43, s43, 0
	s_cmp_eq_u32 s77, s40
	s_cselect_b32 s43, s65, s43
	s_cselect_b32 s42, s64, s42
	s_cselect_b32 s47, s4, s47
	s_cselect_b32 s46, s5, s46
	s_cselect_b32 s49, s63, s49
	s_cselect_b32 s48, s35, s48
	v_lshl_add_u64 v[216:217], v[142:143], 0, s[40:41]
	s_add_i32 m0, s52, 0xc000
	ds_read_b128 v[184:187], v150
	ds_read_b128 v[188:191], v150 offset:1024
	ds_read_b128 v[192:195], v150 offset:2048
	ds_read_b128 v[196:199], v150 offset:3072
	ds_read_b128 v[200:203], v150 offset:4096
	ds_read_b128 v[204:207], v150 offset:5120
	ds_read_b128 v[208:211], v150 offset:6144
	ds_read_b128 v[212:215], v150 offset:7168
	global_load_lds_dwordx4 v[216:217], off
	v_lshl_add_u64 v[216:217], v[144:145], 0, s[40:41]
	s_add_i32 m0, s52, 0xe000
	s_nop 0
	global_load_lds_dwordx4 v[216:217], off
	s_waitcnt vmcnt(8)
	s_waitcnt lgkmcnt(0)
	s_barrier
	v_mfma_f32_16x16x32_bf16 v[126:129], v[152:155], v[184:187], v[126:129]
	v_mfma_f32_16x16x32_bf16 v[122:125], v[160:163], v[184:187], v[122:125]
	v_mfma_f32_16x16x32_bf16 v[110:113], v[152:155], v[192:195], v[110:113]
	v_mfma_f32_16x16x32_bf16 v[106:109], v[160:163], v[192:195], v[106:109]
	v_mfma_f32_16x16x32_bf16 v[94:97], v[152:155], v[200:203], v[94:97]
	v_mfma_f32_16x16x32_bf16 v[90:93], v[160:163], v[200:203], v[90:93]
	v_mfma_f32_16x16x32_bf16 v[78:81], v[152:155], v[208:211], v[78:81]
	v_mfma_f32_16x16x32_bf16 v[74:77], v[160:163], v[208:211], v[74:77]
	v_mfma_f32_16x16x32_bf16 v[126:129], v[156:159], v[188:191], v[126:129]
	v_mfma_f32_16x16x32_bf16 v[122:125], v[164:167], v[188:191], v[122:125]
	v_mfma_f32_16x16x32_bf16 v[110:113], v[156:159], v[196:199], v[110:113]
	v_mfma_f32_16x16x32_bf16 v[106:109], v[164:167], v[196:199], v[106:109]
	v_mfma_f32_16x16x32_bf16 v[94:97], v[156:159], v[204:207], v[94:97]
	v_mfma_f32_16x16x32_bf16 v[90:93], v[164:167], v[204:207], v[90:93]
	v_mfma_f32_16x16x32_bf16 v[78:81], v[156:159], v[212:215], v[78:81]
	v_mfma_f32_16x16x32_bf16 v[74:77], v[164:167], v[212:215], v[74:77]
	v_mfma_f32_16x16x32_bf16 v[118:121], v[168:171], v[184:187], v[118:121]
	v_mfma_f32_16x16x32_bf16 v[114:117], v[176:179], v[184:187], v[114:117]
	v_mfma_f32_16x16x32_bf16 v[102:105], v[168:171], v[192:195], v[102:105]
	v_mfma_f32_16x16x32_bf16 v[98:101], v[176:179], v[192:195], v[98:101]
	v_mfma_f32_16x16x32_bf16 v[86:89], v[168:171], v[200:203], v[86:89]
	v_mfma_f32_16x16x32_bf16 v[82:85], v[176:179], v[200:203], v[82:85]
	v_mfma_f32_16x16x32_bf16 v[70:73], v[168:171], v[208:211], v[70:73]
	v_mfma_f32_16x16x32_bf16 v[66:69], v[176:179], v[208:211], v[66:69]
	v_mfma_f32_16x16x32_bf16 v[118:121], v[172:175], v[188:191], v[118:121]
	v_mfma_f32_16x16x32_bf16 v[114:117], v[180:183], v[188:191], v[114:117]
	v_mfma_f32_16x16x32_bf16 v[102:105], v[172:175], v[196:199], v[102:105]
	v_mfma_f32_16x16x32_bf16 v[98:101], v[180:183], v[196:199], v[98:101]
	v_mfma_f32_16x16x32_bf16 v[86:89], v[172:175], v[204:207], v[86:89]
	v_mfma_f32_16x16x32_bf16 v[82:85], v[180:183], v[204:207], v[82:85]
	v_mfma_f32_16x16x32_bf16 v[70:73], v[172:175], v[212:215], v[70:73]
	v_mfma_f32_16x16x32_bf16 v[66:69], v[180:183], v[212:215], v[66:69]
	s_barrier
	s_add_i32 s60, s72, s51
	v_lshl_add_u64 v[216:217], s[46:47], 0, v[130:131]
	s_mov_b32 m0, s60
	ds_read_b128 v[184:187], v150 offset:16384
	ds_read_b128 v[188:191], v150 offset:17408
	ds_read_b128 v[192:195], v150 offset:18432
	ds_read_b128 v[196:199], v150 offset:19456
	ds_read_b128 v[200:203], v150 offset:20480
	ds_read_b128 v[204:207], v150 offset:21504
	ds_read_b128 v[208:211], v150 offset:22528
	ds_read_b128 v[212:215], v150 offset:23552
	global_load_lds_dwordx4 v[216:217], off
	s_add_i32 m0, s60, 0x2000
	s_add_u32 s60, s46, 0x4000
	v_lshl_add_u64 v[216:217], s[46:47], 0, v[132:133]
	s_addc_u32 s61, s47, 0
	s_add_i32 s81, s73, s51
	global_load_lds_dwordx4 v[216:217], off
	v_lshl_add_u64 v[216:217], s[60:61], 0, v[130:131]
	s_mov_b32 m0, s81
	s_nop 0
	global_load_lds_dwordx4 v[216:217], off
	v_lshl_add_u64 v[216:217], s[60:61], 0, v[132:133]
	s_add_i32 m0, s81, 0x2000
	s_nop 0
	global_load_lds_dwordx4 v[216:217], off
	v_lshl_add_u64 v[216:217], s[48:49], 0, v[130:131]
	s_mov_b32 m0, s52
	s_nop 0
	global_load_lds_dwordx4 v[216:217], off
	v_lshl_add_u64 v[216:217], s[48:49], 0, v[132:133]
	s_mov_b32 m0, s53
	s_nop 0
	global_load_lds_dwordx4 v[216:217], off
	s_waitcnt vmcnt(8)
	s_waitcnt lgkmcnt(0)
	s_barrier
; #define PG8_STAGE(bufoff, gbase, voff) do { _Pragma("unroll") for (int _i = 0; _i < 2; ++_i) \
;         __builtin_amdgcn_global_load_lds((const unsigned*)((const char*)(gbase) + (voff)[_i]), (LAS unsigned*)(lds + (bufoff) + ldsw + _i * 8192), 16, 0, 0); } while (0)
; #define PG8_LDA(dst, b, h) do { _Pragma("unroll") for (int m = 0; m < 4; ++m) _Pragma("unroll") for (int k = 0; k < 2; ++k) dst[m][k] = *(const LAS bf16x8*)(lds + PG8_SA(b, h) + aoff + m * 2048 + k * 1024); } while (0)
; #define PG8_LDB(dst, b, h) do { _Pragma("unroll") for (int n = 0; n < 2; ++n) _Pragma("unroll") for (int k = 0; k < 2; ++k) dst[n][k] = *(const LAS bf16x8*)(lds + PG8_SB(b, h) + boff + n * 2048 + k * 1024); } while (0)
; #define PG8_MMA(ai, bj, At, Bt) do { __builtin_amdgcn_s_setprio(1); _Pragma("unroll") for (int m = 0; m < 4; ++m) _Pragma("unroll") for (int n = 0; n < 2; ++n) _Pragma("unroll") for (int k = 0; k < 2; ++k) \
;         acc[ai][bj][m][n] = __builtin_amdgcn_mfma_f32_16x16x32_bf16(Bt[n][k], At[m][k], acc[ai][bj][m][n], 0, 0, 0); __builtin_amdgcn_s_setprio(0); } while (0)
; #define PG8_WAIT_V(n) asm volatile("s_waitcnt vmcnt(" #n ")" ::: "memory")
; #define PG8_WAIT_L(n) asm volatile("s_waitcnt lgkmcnt(" #n ")" ::: "memory")
; #define PG8_BAR __builtin_amdgcn_s_barrier()
; #define PG8_SCHED __builtin_amdgcn_sched_barrier(0)
; template <class Epi, class Sched, bool ABLK = false, bool ALIGN_EPI = true, bool SP2 = true, bool BBLK = true>
; __device__ __forceinline__ void gemm_phase(LAS unsigned char* lds, const Gemm g, const Sched& S, const Epi& E) {
;     ...
;             PG8_WAIT_V(8); PG8_WAIT_L(0); PG8_BAR; PG8_MMA(1, 0, At, B0); PG8_MMA(1, 1, At, B1); PG8_BAR; PG8_SCHED;
;             PG8_LDB(B0, 1, 0); PG8_LDB(B1, 1, 1); PG8_SCHED; PG8_LDA(At, 1, 0); PG8_STAGE(PG8_SA(0, 1), a2 + hstepA, voffA);
;             PG8_WAIT_V(8); PG8_WAIT_L(0); PG8_BAR; PG8_MMA(0, 0, At, B0); PG8_MMA(0, 1, At, B1); PG8_BAR; PG8_SCHED;
	v_mfma_f32_16x16x32_bf16 v[62:65], v[152:155], v[184:187], v[62:65]
	v_mfma_f32_16x16x32_bf16 v[58:61], v[160:163], v[184:187], v[58:61]
	v_mfma_f32_16x16x32_bf16 v[46:49], v[152:155], v[192:195], v[46:49]
	v_mfma_f32_16x16x32_bf16 v[42:45], v[160:163], v[192:195], v[42:45]
	v_mfma_f32_16x16x32_bf16 v[30:33], v[152:155], v[200:203], v[30:33]
	v_mfma_f32_16x16x32_bf16 v[26:29], v[160:163], v[200:203], v[26:29]
	v_mfma_f32_16x16x32_bf16 v[14:17], v[152:155], v[208:211], v[14:17]
	v_mfma_f32_16x16x32_bf16 v[10:13], v[160:163], v[208:211], v[10:13]
	v_mfma_f32_16x16x32_bf16 v[62:65], v[156:159], v[188:191], v[62:65]
	v_mfma_f32_16x16x32_bf16 v[58:61], v[164:167], v[188:191], v[58:61]
	v_mfma_f32_16x16x32_bf16 v[46:49], v[156:159], v[196:199], v[46:49]
	v_mfma_f32_16x16x32_bf16 v[42:45], v[164:167], v[196:199], v[42:45]
	v_mfma_f32_16x16x32_bf16 v[30:33], v[156:159], v[204:207], v[30:33]
	v_mfma_f32_16x16x32_bf16 v[26:29], v[164:167], v[204:207], v[26:29]
	v_mfma_f32_16x16x32_bf16 v[14:17], v[156:159], v[212:215], v[14:17]
	v_mfma_f32_16x16x32_bf16 v[10:13], v[164:167], v[212:215], v[10:13]
	v_mfma_f32_16x16x32_bf16 v[54:57], v[168:171], v[184:187], v[54:57]
	v_mfma_f32_16x16x32_bf16 v[50:53], v[176:179], v[184:187], v[50:53]
	v_mfma_f32_16x16x32_bf16 v[38:41], v[168:171], v[192:195], v[38:41]
	v_mfma_f32_16x16x32_bf16 v[34:37], v[176:179], v[192:195], v[34:37]
	v_mfma_f32_16x16x32_bf16 v[22:25], v[168:171], v[200:203], v[22:25]
	v_mfma_f32_16x16x32_bf16 v[18:21], v[176:179], v[200:203], v[18:21]
	v_mfma_f32_16x16x32_bf16 v[6:9], v[168:171], v[208:211], v[6:9]
	v_mfma_f32_16x16x32_bf16 v[2:5], v[176:179], v[208:211], v[2:5]
	v_mfma_f32_16x16x32_bf16 v[54:57], v[172:175], v[188:191], v[54:57]
	v_mfma_f32_16x16x32_bf16 v[50:53], v[180:183], v[188:191], v[50:53]
	v_mfma_f32_16x16x32_bf16 v[38:41], v[172:175], v[196:199], v[38:41]
	v_mfma_f32_16x16x32_bf16 v[34:37], v[180:183], v[196:199], v[34:37]
	v_mfma_f32_16x16x32_bf16 v[22:25], v[172:175], v[204:207], v[22:25]
	v_mfma_f32_16x16x32_bf16 v[18:21], v[180:183], v[204:207], v[18:21]
	v_mfma_f32_16x16x32_bf16 v[6:9], v[172:175], v[212:215], v[6:9]
	v_mfma_f32_16x16x32_bf16 v[2:5], v[180:183], v[212:215], v[2:5]
	s_barrier
	s_add_i32 s60, 0, 0x18000
	v_add_u32_e32 v151, s60, v146
	s_add_i32 s61, 0, 0x1c000
	ds_read_b128 v[152:155], v151
	ds_read_b128 v[156:159], v151 offset:1024
	ds_read_b128 v[160:163], v151 offset:2048
	ds_read_b128 v[164:167], v151 offset:3072
	v_add_u32_e32 v151, s61, v146
	ds_read_b128 v[168:171], v151
	ds_read_b128 v[172:175], v151 offset:1024
	ds_read_b128 v[176:179], v151 offset:2048
	ds_read_b128 v[180:183], v151 offset:3072
	s_add_u32 s48, s48, 0x4000
	s_addc_u32 s49, s49, 0
	s_mov_b32 m0, s54
	v_lshl_add_u64 v[216:217], s[48:49], 0, v[130:131]
	ds_read_b128 v[184:187], v150 offset:32768
	ds_read_b128 v[188:191], v150 offset:33792
	ds_read_b128 v[192:195], v150 offset:34816
	ds_read_b128 v[196:199], v150 offset:35840
	ds_read_b128 v[200:203], v150 offset:36864
	ds_read_b128 v[204:207], v150 offset:37888
	ds_read_b128 v[208:211], v150 offset:38912
	ds_read_b128 v[212:215], v150 offset:39936
	global_load_lds_dwordx4 v[216:217], off
	v_lshl_add_u64 v[216:217], s[48:49], 0, v[132:133]
	s_mov_b32 m0, s55
	s_nop 0
	global_load_lds_dwordx4 v[216:217], off
	s_waitcnt vmcnt(8)
	s_waitcnt lgkmcnt(0)
	s_barrier
	v_mfma_f32_16x16x32_bf16 v[126:129], v[152:155], v[184:187], v[126:129]
	v_mfma_f32_16x16x32_bf16 v[122:125], v[160:163], v[184:187], v[122:125]
	v_mfma_f32_16x16x32_bf16 v[110:113], v[152:155], v[192:195], v[110:113]
	v_mfma_f32_16x16x32_bf16 v[106:109], v[160:163], v[192:195], v[106:109]
	v_mfma_f32_16x16x32_bf16 v[94:97], v[152:155], v[200:203], v[94:97]
	v_mfma_f32_16x16x32_bf16 v[90:93], v[160:163], v[200:203], v[90:93]
	v_mfma_f32_16x16x32_bf16 v[78:81], v[152:155], v[208:211], v[78:81]
	v_mfma_f32_16x16x32_bf16 v[74:77], v[160:163], v[208:211], v[74:77]
	v_mfma_f32_16x16x32_bf16 v[126:129], v[156:159], v[188:191], v[126:129]
	v_mfma_f32_16x16x32_bf16 v[122:125], v[164:167], v[188:191], v[122:125]
	v_mfma_f32_16x16x32_bf16 v[110:113], v[156:159], v[196:199], v[110:113]
	v_mfma_f32_16x16x32_bf16 v[106:109], v[164:167], v[196:199], v[106:109]
	v_mfma_f32_16x16x32_bf16 v[94:97], v[156:159], v[204:207], v[94:97]
	v_mfma_f32_16x16x32_bf16 v[90:93], v[164:167], v[204:207], v[90:93]
	v_mfma_f32_16x16x32_bf16 v[78:81], v[156:159], v[212:215], v[78:81]
	v_mfma_f32_16x16x32_bf16 v[74:77], v[164:167], v[212:215], v[74:77]
	v_mfma_f32_16x16x32_bf16 v[118:121], v[168:171], v[184:187], v[118:121]
	v_mfma_f32_16x16x32_bf16 v[114:117], v[176:179], v[184:187], v[114:117]
	v_mfma_f32_16x16x32_bf16 v[102:105], v[168:171], v[192:195], v[102:105]
	v_mfma_f32_16x16x32_bf16 v[98:101], v[176:179], v[192:195], v[98:101]
	v_mfma_f32_16x16x32_bf16 v[86:89], v[168:171], v[200:203], v[86:89]
	v_mfma_f32_16x16x32_bf16 v[82:85], v[176:179], v[200:203], v[82:85]
	v_mfma_f32_16x16x32_bf16 v[70:73], v[168:171], v[208:211], v[70:73]
	v_mfma_f32_16x16x32_bf16 v[66:69], v[176:179], v[208:211], v[66:69]
	v_mfma_f32_16x16x32_bf16 v[118:121], v[172:175], v[188:191], v[118:121]
	v_mfma_f32_16x16x32_bf16 v[114:117], v[180:183], v[188:191], v[114:117]
	v_mfma_f32_16x16x32_bf16 v[102:105], v[172:175], v[196:199], v[102:105]
	v_mfma_f32_16x16x32_bf16 v[98:101], v[180:183], v[196:199], v[98:101]
	v_mfma_f32_16x16x32_bf16 v[86:89], v[172:175], v[204:207], v[86:89]
	v_mfma_f32_16x16x32_bf16 v[82:85], v[180:183], v[204:207], v[82:85]
	v_mfma_f32_16x16x32_bf16 v[70:73], v[172:175], v[212:215], v[70:73]
	v_mfma_f32_16x16x32_bf16 v[66:69], v[180:183], v[212:215], v[66:69]
	s_barrier
; #define PG8_STAGE(bufoff, gbase, voff) do { _Pragma("unroll") for (int _i = 0; _i < 2; ++_i) \
;         __builtin_amdgcn_global_load_lds((const unsigned*)((const char*)(gbase) + (voff)[_i]), (LAS unsigned*)(lds + (bufoff) + ldsw + _i * 8192), 16, 0, 0); } while (0)
; #define PG8_LDA(dst, b, h) do { _Pragma("unroll") for (int m = 0; m < 4; ++m) _Pragma("unroll") for (int k = 0; k < 2; ++k) dst[m][k] = *(const LAS bf16x8*)(lds + PG8_SA(b, h) + aoff + m * 2048 + k * 1024); } while (0)
; #define PG8_MMA(ai, bj, At, Bt) do { __builtin_amdgcn_s_setprio(1); _Pragma("unroll") for (int m = 0; m < 4; ++m) _Pragma("unroll") for (int n = 0; n < 2; ++n) _Pragma("unroll") for (int k = 0; k < 2; ++k) \
;         acc[ai][bj][m][n] = __builtin_amdgcn_mfma_f32_16x16x32_bf16(Bt[n][k], At[m][k], acc[ai][bj][m][n], 0, 0, 0); __builtin_amdgcn_s_setprio(0); } while (0)
; #define PG8_WAIT_V(n) asm volatile("s_waitcnt vmcnt(" #n ")" ::: "memory")
; #define PG8_WAIT_L(n) asm volatile("s_waitcnt lgkmcnt(" #n ")" ::: "memory")
; #define PG8_BAR __builtin_amdgcn_s_barrier()
; #define PG8_SCHED __builtin_amdgcn_sched_barrier(0)
; template <class Epi, class Sched, bool ABLK = false, bool ALIGN_EPI = true, bool SP2 = true, bool BBLK = true>
; __device__ __forceinline__ void gemm_phase(LAS unsigned char* lds, const Gemm g, const Sched& S, const Epi& E) {
;     ...
;             PG8_LDA(At, 1, 1); PG8_STAGE(PG8_SB(1, 0), b3, voffB); PG8_STAGE(PG8_SB(1, 1), b3 + hstepB, voffB); PG8_STAGE(PG8_SA(1, 0), a3, voffA);
;             PG8_WAIT_V(8); PG8_WAIT_L(0); PG8_BAR; PG8_MMA(1, 0, At, B0); PG8_MMA(1, 1, At, B1); PG8_BAR; PG8_SCHED;
;     ...
;         if constexpr (ALIGN_EPI) { if (wr == 0) PG8_BAR; }
	s_add_u32 s48, s46, 0x8000
	s_addc_u32 s49, s47, 0
	s_add_i32 s81, s60, s51
	v_lshl_add_u64 v[216:217], s[48:49], 0, v[130:131]
	s_mov_b32 m0, s81
	ds_read_b128 v[184:187], v150 offset:49152
	ds_read_b128 v[188:191], v150 offset:50176
	ds_read_b128 v[192:195], v150 offset:51200
	ds_read_b128 v[196:199], v150 offset:52224
	ds_read_b128 v[200:203], v150 offset:53248
	ds_read_b128 v[204:207], v150 offset:54272
	ds_read_b128 v[208:211], v150 offset:55296
	ds_read_b128 v[212:215], v150 offset:56320
	global_load_lds_dwordx4 v[216:217], off
	s_add_i32 m0, s81, 0x2000
	s_add_u32 s46, s46, 0xc000
	v_lshl_add_u64 v[216:217], s[48:49], 0, v[132:133]
	s_addc_u32 s47, s47, 0
	s_add_i32 s48, s61, s51
	global_load_lds_dwordx4 v[216:217], off
	v_lshl_add_u64 v[216:217], s[46:47], 0, v[130:131]
	s_mov_b32 m0, s48
	s_nop 0
	global_load_lds_dwordx4 v[216:217], off
	v_lshl_add_u64 v[216:217], s[46:47], 0, v[132:133]
	s_add_i32 m0, s48, 0x2000
	s_nop 0
	global_load_lds_dwordx4 v[216:217], off
	v_lshl_add_u64 v[216:217], s[42:43], 0, v[130:131]
	s_mov_b32 m0, s56
	s_nop 0
	global_load_lds_dwordx4 v[216:217], off
	v_lshl_add_u64 v[216:217], s[42:43], 0, v[132:133]
	s_mov_b32 m0, s57
	s_nop 0
	global_load_lds_dwordx4 v[216:217], off
	s_waitcnt vmcnt(8)
	s_waitcnt lgkmcnt(0)
	s_barrier
	v_mfma_f32_16x16x32_bf16 v[62:65], v[152:155], v[184:187], v[62:65]
	v_mfma_f32_16x16x32_bf16 v[58:61], v[160:163], v[184:187], v[58:61]
	v_mfma_f32_16x16x32_bf16 v[46:49], v[152:155], v[192:195], v[46:49]
	v_mfma_f32_16x16x32_bf16 v[42:45], v[160:163], v[192:195], v[42:45]
	v_mfma_f32_16x16x32_bf16 v[30:33], v[152:155], v[200:203], v[30:33]
	v_mfma_f32_16x16x32_bf16 v[26:29], v[160:163], v[200:203], v[26:29]
	v_mfma_f32_16x16x32_bf16 v[14:17], v[152:155], v[208:211], v[14:17]
	v_mfma_f32_16x16x32_bf16 v[10:13], v[160:163], v[208:211], v[10:13]
	v_mfma_f32_16x16x32_bf16 v[62:65], v[156:159], v[188:191], v[62:65]
	v_mfma_f32_16x16x32_bf16 v[58:61], v[164:167], v[188:191], v[58:61]
	v_mfma_f32_16x16x32_bf16 v[46:49], v[156:159], v[196:199], v[46:49]
	v_mfma_f32_16x16x32_bf16 v[42:45], v[164:167], v[196:199], v[42:45]
	v_mfma_f32_16x16x32_bf16 v[30:33], v[156:159], v[204:207], v[30:33]
	v_mfma_f32_16x16x32_bf16 v[26:29], v[164:167], v[204:207], v[26:29]
	v_mfma_f32_16x16x32_bf16 v[14:17], v[156:159], v[212:215], v[14:17]
	v_mfma_f32_16x16x32_bf16 v[10:13], v[164:167], v[212:215], v[10:13]
	v_mfma_f32_16x16x32_bf16 v[54:57], v[168:171], v[184:187], v[54:57]
	v_mfma_f32_16x16x32_bf16 v[50:53], v[176:179], v[184:187], v[50:53]
	v_mfma_f32_16x16x32_bf16 v[38:41], v[168:171], v[192:195], v[38:41]
	v_mfma_f32_16x16x32_bf16 v[34:37], v[176:179], v[192:195], v[34:37]
	v_mfma_f32_16x16x32_bf16 v[22:25], v[168:171], v[200:203], v[22:25]
	v_mfma_f32_16x16x32_bf16 v[18:21], v[176:179], v[200:203], v[18:21]
	v_mfma_f32_16x16x32_bf16 v[6:9], v[168:171], v[208:211], v[6:9]
	v_mfma_f32_16x16x32_bf16 v[2:5], v[176:179], v[208:211], v[2:5]
	v_mfma_f32_16x16x32_bf16 v[54:57], v[172:175], v[188:191], v[54:57]
	v_mfma_f32_16x16x32_bf16 v[50:53], v[180:183], v[188:191], v[50:53]
	v_mfma_f32_16x16x32_bf16 v[38:41], v[172:175], v[196:199], v[38:41]
	v_mfma_f32_16x16x32_bf16 v[34:37], v[180:183], v[196:199], v[34:37]
	v_mfma_f32_16x16x32_bf16 v[22:25], v[172:175], v[204:207], v[22:25]
	v_mfma_f32_16x16x32_bf16 v[18:21], v[180:183], v[204:207], v[18:21]
	v_mfma_f32_16x16x32_bf16 v[6:9], v[172:175], v[212:215], v[6:9]
	v_mfma_f32_16x16x32_bf16 v[2:5], v[180:183], v[212:215], v[2:5]
	s_barrier
	s_add_u32 s40, s40, 0x10000
	s_addc_u32 s41, s41, 0
	s_cmp_ge_u32 s79, s59
	s_cbranch_scc0 .LBB0_540
	s_and_b64 vcc, exec, s[12:13]
	s_cbranch_vccz .LBB0_543
	s_barrier

; #define PG8_STAGE(bufoff, gbase, voff) do { _Pragma("unroll") for (int _i = 0; _i < 2; ++_i) \
;         __builtin_amdgcn_global_load_lds((const unsigned*)((const char*)(gbase) + (voff)[_i]), (LAS unsigned*)(lds + (bufoff) + ldsw + _i * 8192), 16, 0, 0); } while (0)
; #define PG8_LDA(dst, b, h) do { _Pragma("unroll") for (int m = 0; m < 4; ++m) _Pragma("unroll") for (int k = 0; k < 2; ++k) dst[m][k] = *(const LAS bf16x8*)(lds + PG8_SA(b, h) + aoff + m * 2048 + k * 1024); } while (0)
; #define PG8_LDB(dst, b, h) do { _Pragma("unroll") for (int n = 0; n < 2; ++n) _Pragma("unroll") for (int k = 0; k < 2; ++k) dst[n][k] = *(const LAS bf16x8*)(lds + PG8_SB(b, h) + boff + n * 2048 + k * 1024); } while (0)
; #define PG8_MMA(ai, bj, At, Bt) do { __builtin_amdgcn_s_setprio(1); _Pragma("unroll") for (int m = 0; m < 4; ++m) _Pragma("unroll") for (int n = 0; n < 2; ++n) _Pragma("unroll") for (int k = 0; k < 2; ++k) \
;         acc[ai][bj][m][n] = __builtin_amdgcn_mfma_f32_16x16x32_bf16(Bt[n][k], At[m][k], acc[ai][bj][m][n], 0, 0, 0); __builtin_amdgcn_s_setprio(0); } while (0)
; #define PG8_WAIT_V(n) asm volatile("s_waitcnt vmcnt(" #n ")" ::: "memory")
; #define PG8_WAIT_L(n) asm volatile("s_waitcnt lgkmcnt(" #n ")" ::: "memory")
; #define PG8_BAR __builtin_amdgcn_s_barrier()
; template <class Epi, class Sched, bool ABLK = false, bool ALIGN_EPI = true, bool SP2 = true, bool BBLK = true>
; __device__ __forceinline__ void gemm_phase(LAS unsigned char* lds, const Gemm g, const Sched& S, const Epi& E) {
;     ...
;             const bool last = (t == nt - 2);
;             const char* a1 = a_tile(uA, tbA + t + 1);
;             const char* a2 = last ? a_tile(nuA, ntbA) : a_tile(uA, tbA + t + 2); const char* b2 = last ? nB : cB + (size_t)(t + 2) * kstepB;
;             const char* a3 = last ? a_tile(nuA, ntbA + 1) : a_tile(uA, tbA + t + 3); const char* b3 = b2 + kstepB;
;             if (last && has_next) S.a_ready(nxt);
;             if constexpr (SP2) {
;             PG8_LDB(B0, 0, 0); PG8_LDB(B1, 0, 1); PG8_SCHED; PG8_LDA(At, 0, 0); PG8_STAGE(PG8_SA(1, 1), a1 + hstepA, voffA);
;             PG8_WAIT_V(8); PG8_WAIT_L(0); PG8_BAR; PG8_MMA(0, 0, At, B0); PG8_MMA(0, 1, At, B1); PG8_BAR; PG8_SCHED;
;             PG8_LDA(At, 0, 1); PG8_STAGE(PG8_SB(0, 0), b2, voffB); PG8_STAGE(PG8_SB(0, 1), b2 + hstepB, voffB); PG8_STAGE(PG8_SA(0, 0), a2, voffA);
.LBB0_668:
	ds_read_b128 v[184:187], v153
	ds_read_b128 v[188:191], v153 offset:1024
	ds_read_b128 v[192:195], v153 offset:2048
	ds_read_b128 v[196:199], v153 offset:3072
	ds_read_b128 v[200:203], v157
	ds_read_b128 v[204:207], v157 offset:1024
	ds_read_b128 v[208:211], v157 offset:2048
	ds_read_b128 v[212:215], v157 offset:3072
	s_add_u32 s30, s26, s28
	s_addc_u32 s31, s27, s29
	s_add_u32 s36, s30, 0x100
	s_addc_u32 s37, s31, 0
	s_add_u32 s30, s30, 0x180
	s_addc_u32 s31, s31, 0
	s_cmpk_eq_i32 s28, 0xf00
	s_cselect_b32 s31, s17, s31
	s_cselect_b32 s30, s15, s30
	s_cselect_b32 s35, s5, s53
	s_cselect_b32 s34, s9, s52
	s_cselect_b32 s37, s2, s37
	s_cselect_b32 s36, s4, s36
	v_lshl_add_u64 v[248:249], v[180:181], 0, s[28:29]
	s_add_i32 m0, s25, 0xc000
	ds_read_b128 v[216:219], v149
	ds_read_b128 v[220:223], v149 offset:1024
	ds_read_b128 v[224:227], v149 offset:2048
	ds_read_b128 v[228:231], v149 offset:3072
	ds_read_b128 v[232:235], v149 offset:4096
	ds_read_b128 v[236:239], v149 offset:5120
	ds_read_b128 v[240:243], v149 offset:6144
	ds_read_b128 v[244:247], v149 offset:7168
	global_load_lds_dwordx4 v[248:249], off
	v_lshl_add_u64 v[248:249], v[182:183], 0, s[28:29]
	s_add_i32 m0, s25, 0xe000
	s_nop 0
	global_load_lds_dwordx4 v[248:249], off
	s_waitcnt vmcnt(8)
	s_waitcnt lgkmcnt(0)
	s_barrier
	v_mfma_f32_16x16x32_bf16 v[126:129], v[184:187], v[216:219], v[126:129]
	v_mfma_f32_16x16x32_bf16 v[122:125], v[192:195], v[216:219], v[122:125]
	v_mfma_f32_16x16x32_bf16 v[110:113], v[184:187], v[224:227], v[110:113]
	v_mfma_f32_16x16x32_bf16 v[106:109], v[192:195], v[224:227], v[106:109]
	v_mfma_f32_16x16x32_bf16 v[94:97], v[184:187], v[232:235], v[94:97]
	v_mfma_f32_16x16x32_bf16 v[90:93], v[192:195], v[232:235], v[90:93]
	v_mfma_f32_16x16x32_bf16 v[78:81], v[184:187], v[240:243], v[78:81]
	v_mfma_f32_16x16x32_bf16 v[74:77], v[192:195], v[240:243], v[74:77]
	v_mfma_f32_16x16x32_bf16 v[126:129], v[188:191], v[220:223], v[126:129]
	v_mfma_f32_16x16x32_bf16 v[122:125], v[196:199], v[220:223], v[122:125]
	v_mfma_f32_16x16x32_bf16 v[110:113], v[188:191], v[228:231], v[110:113]
	v_mfma_f32_16x16x32_bf16 v[106:109], v[196:199], v[228:231], v[106:109]
	v_mfma_f32_16x16x32_bf16 v[94:97], v[188:191], v[236:239], v[94:97]
	v_mfma_f32_16x16x32_bf16 v[90:93], v[196:199], v[236:239], v[90:93]
	v_mfma_f32_16x16x32_bf16 v[78:81], v[188:191], v[244:247], v[78:81]
	v_mfma_f32_16x16x32_bf16 v[74:77], v[196:199], v[244:247], v[74:77]
	v_mfma_f32_16x16x32_bf16 v[118:121], v[200:203], v[216:219], v[118:121]
	v_mfma_f32_16x16x32_bf16 v[114:117], v[208:211], v[216:219], v[114:117]
	v_mfma_f32_16x16x32_bf16 v[102:105], v[200:203], v[224:227], v[102:105]
	v_mfma_f32_16x16x32_bf16 v[98:101], v[208:211], v[224:227], v[98:101]
	v_mfma_f32_16x16x32_bf16 v[86:89], v[200:203], v[232:235], v[86:89]
	v_mfma_f32_16x16x32_bf16 v[82:85], v[208:211], v[232:235], v[82:85]
	v_mfma_f32_16x16x32_bf16 v[70:73], v[200:203], v[240:243], v[70:73]
	v_mfma_f32_16x16x32_bf16 v[66:69], v[208:211], v[240:243], v[66:69]
	v_mfma_f32_16x16x32_bf16 v[118:121], v[204:207], v[220:223], v[118:121]
	v_mfma_f32_16x16x32_bf16 v[114:117], v[212:215], v[220:223], v[114:117]
	v_mfma_f32_16x16x32_bf16 v[102:105], v[204:207], v[228:231], v[102:105]
	v_mfma_f32_16x16x32_bf16 v[98:101], v[212:215], v[228:231], v[98:101]
	v_mfma_f32_16x16x32_bf16 v[86:89], v[204:207], v[236:239], v[86:89]
	v_mfma_f32_16x16x32_bf16 v[82:85], v[212:215], v[236:239], v[82:85]
	v_mfma_f32_16x16x32_bf16 v[70:73], v[204:207], v[244:247], v[70:73]
	v_mfma_f32_16x16x32_bf16 v[66:69], v[212:215], v[244:247], v[66:69]
	s_barrier
	s_add_i32 s55, s72, s41
	v_lshl_add_u64 v[248:249], s[34:35], 0, v[132:133]
	s_mov_b32 m0, s55
	ds_read_b128 v[216:219], v149 offset:16384
	ds_read_b128 v[220:223], v149 offset:17408
	ds_read_b128 v[224:227], v149 offset:18432
	ds_read_b128 v[228:231], v149 offset:19456
	ds_read_b128 v[232:235], v149 offset:20480
	ds_read_b128 v[236:239], v149 offset:21504
	ds_read_b128 v[240:243], v149 offset:22528
	ds_read_b128 v[244:247], v149 offset:23552
	global_load_lds_dwordx4 v[248:249], off
	s_add_i32 m0, s55, 0x2000
	s_add_u32 s56, s34, 0x4000
	v_lshl_add_u64 v[248:249], s[34:35], 0, v[136:137]
	s_addc_u32 s57, s35, 0
	s_add_i32 s55, s73, s41
	global_load_lds_dwordx4 v[248:249], off
	v_lshl_add_u64 v[248:249], s[56:57], 0, v[132:133]
	s_mov_b32 m0, s55
	s_nop 0
	global_load_lds_dwordx4 v[248:249], off
	v_lshl_add_u64 v[248:249], s[56:57], 0, v[136:137]
	s_add_i32 m0, s55, 0x2000
	s_nop 0
	global_load_lds_dwordx4 v[248:249], off
	v_lshl_add_u64 v[248:249], s[36:37], 0, v[130:131]
	s_mov_b32 m0, s25
	s_nop 0
	global_load_lds_dwordx4 v[248:249], off
	v_lshl_add_u64 v[248:249], s[36:37], 0, v[134:135]
	s_mov_b32 m0, s42
	s_nop 0
	global_load_lds_dwordx4 v[248:249], off
	s_waitcnt vmcnt(8)
	s_waitcnt lgkmcnt(0)
	s_barrier
; #define PG8_STAGE(bufoff, gbase, voff) do { _Pragma("unroll") for (int _i = 0; _i < 2; ++_i) \
;         __builtin_amdgcn_global_load_lds((const unsigned*)((const char*)(gbase) + (voff)[_i]), (LAS unsigned*)(lds + (bufoff) + ldsw + _i * 8192), 16, 0, 0); } while (0)
; #define PG8_LDA(dst, b, h) do { _Pragma("unroll") for (int m = 0; m < 4; ++m) _Pragma("unroll") for (int k = 0; k < 2; ++k) dst[m][k] = *(const LAS bf16x8*)(lds + PG8_SA(b, h) + aoff + m * 2048 + k * 1024); } while (0)
; #define PG8_LDB(dst, b, h) do { _Pragma("unroll") for (int n = 0; n < 2; ++n) _Pragma("unroll") for (int k = 0; k < 2; ++k) dst[n][k] = *(const LAS bf16x8*)(lds + PG8_SB(b, h) + boff + n * 2048 + k * 1024); } while (0)
; #define PG8_MMA(ai, bj, At, Bt) do { __builtin_amdgcn_s_setprio(1); _Pragma("unroll") for (int m = 0; m < 4; ++m) _Pragma("unroll") for (int n = 0; n < 2; ++n) _Pragma("unroll") for (int k = 0; k < 2; ++k) \
;         acc[ai][bj][m][n] = __builtin_amdgcn_mfma_f32_16x16x32_bf16(Bt[n][k], At[m][k], acc[ai][bj][m][n], 0, 0, 0); __builtin_amdgcn_s_setprio(0); } while (0)
; #define PG8_WAIT_V(n) asm volatile("s_waitcnt vmcnt(" #n ")" ::: "memory")
; #define PG8_WAIT_L(n) asm volatile("s_waitcnt lgkmcnt(" #n ")" ::: "memory")
; #define PG8_BAR __builtin_amdgcn_s_barrier()
; #define PG8_SCHED __builtin_amdgcn_sched_barrier(0)
; template <class Epi, class Sched, bool ABLK = false, bool ALIGN_EPI = true, bool SP2 = true, bool BBLK = true>
; __device__ __forceinline__ void gemm_phase(LAS unsigned char* lds, const Gemm g, const Sched& S, const Epi& E) {
;     ...
;             PG8_WAIT_V(8); PG8_WAIT_L(0); PG8_BAR; PG8_MMA(1, 0, At, B0); PG8_MMA(1, 1, At, B1); PG8_BAR; PG8_SCHED;
;             PG8_LDB(B0, 1, 0); PG8_LDB(B1, 1, 1); PG8_SCHED; PG8_LDA(At, 1, 0); PG8_STAGE(PG8_SA(0, 1), a2 + hstepA, voffA);
;             PG8_WAIT_V(8); PG8_WAIT_L(0); PG8_BAR; PG8_MMA(0, 0, At, B0); PG8_MMA(0, 1, At, B1); PG8_BAR; PG8_SCHED;
	v_mfma_f32_16x16x32_bf16 v[62:65], v[184:187], v[216:219], v[62:65]
	v_mfma_f32_16x16x32_bf16 v[58:61], v[192:195], v[216:219], v[58:61]
	v_mfma_f32_16x16x32_bf16 v[46:49], v[184:187], v[224:227], v[46:49]
	v_mfma_f32_16x16x32_bf16 v[42:45], v[192:195], v[224:227], v[42:45]
	v_mfma_f32_16x16x32_bf16 v[30:33], v[184:187], v[232:235], v[30:33]
	v_mfma_f32_16x16x32_bf16 v[26:29], v[192:195], v[232:235], v[26:29]
	v_mfma_f32_16x16x32_bf16 v[14:17], v[184:187], v[240:243], v[14:17]
	v_mfma_f32_16x16x32_bf16 v[10:13], v[192:195], v[240:243], v[10:13]
	v_mfma_f32_16x16x32_bf16 v[62:65], v[188:191], v[220:223], v[62:65]
	v_mfma_f32_16x16x32_bf16 v[58:61], v[196:199], v[220:223], v[58:61]
	v_mfma_f32_16x16x32_bf16 v[46:49], v[188:191], v[228:231], v[46:49]
	v_mfma_f32_16x16x32_bf16 v[42:45], v[196:199], v[228:231], v[42:45]
	v_mfma_f32_16x16x32_bf16 v[30:33], v[188:191], v[236:239], v[30:33]
	v_mfma_f32_16x16x32_bf16 v[26:29], v[196:199], v[236:239], v[26:29]
	v_mfma_f32_16x16x32_bf16 v[14:17], v[188:191], v[244:247], v[14:17]
	v_mfma_f32_16x16x32_bf16 v[10:13], v[196:199], v[244:247], v[10:13]
	v_mfma_f32_16x16x32_bf16 v[54:57], v[200:203], v[216:219], v[54:57]
	v_mfma_f32_16x16x32_bf16 v[50:53], v[208:211], v[216:219], v[50:53]
	v_mfma_f32_16x16x32_bf16 v[38:41], v[200:203], v[224:227], v[38:41]
	v_mfma_f32_16x16x32_bf16 v[34:37], v[208:211], v[224:227], v[34:37]
	v_mfma_f32_16x16x32_bf16 v[22:25], v[200:203], v[232:235], v[22:25]
	v_mfma_f32_16x16x32_bf16 v[18:21], v[208:211], v[232:235], v[18:21]
	v_mfma_f32_16x16x32_bf16 v[6:9], v[200:203], v[240:243], v[6:9]
	v_mfma_f32_16x16x32_bf16 v[2:5], v[208:211], v[240:243], v[2:5]
	v_mfma_f32_16x16x32_bf16 v[54:57], v[204:207], v[220:223], v[54:57]
	v_mfma_f32_16x16x32_bf16 v[50:53], v[212:215], v[220:223], v[50:53]
	v_mfma_f32_16x16x32_bf16 v[38:41], v[204:207], v[228:231], v[38:41]
	v_mfma_f32_16x16x32_bf16 v[34:37], v[212:215], v[228:231], v[34:37]
	v_mfma_f32_16x16x32_bf16 v[22:25], v[204:207], v[236:239], v[22:25]
	v_mfma_f32_16x16x32_bf16 v[18:21], v[212:215], v[236:239], v[18:21]
	v_mfma_f32_16x16x32_bf16 v[6:9], v[204:207], v[244:247], v[6:9]
	v_mfma_f32_16x16x32_bf16 v[2:5], v[212:215], v[244:247], v[2:5]
	s_barrier
	v_add_u32_e32 v138, s60, v1
	ds_read_b128 v[184:187], v138
	ds_read_b128 v[188:191], v138 offset:1024
	ds_read_b128 v[192:195], v138 offset:2048
	ds_read_b128 v[196:199], v138 offset:3072
	v_add_u32_e32 v138, s61, v1
	ds_read_b128 v[200:203], v138
	ds_read_b128 v[204:207], v138 offset:1024
	ds_read_b128 v[208:211], v138 offset:2048
	ds_read_b128 v[212:215], v138 offset:3072
	s_add_u32 s36, s36, 0x80000
	s_addc_u32 s37, s37, 0
	s_mov_b32 m0, s43
	v_lshl_add_u64 v[248:249], s[36:37], 0, v[130:131]
	ds_read_b128 v[216:219], v149 offset:32768
	ds_read_b128 v[220:223], v149 offset:33792
	ds_read_b128 v[224:227], v149 offset:34816
	ds_read_b128 v[228:231], v149 offset:35840
	ds_read_b128 v[232:235], v149 offset:36864
	ds_read_b128 v[236:239], v149 offset:37888
	ds_read_b128 v[240:243], v149 offset:38912
	ds_read_b128 v[244:247], v149 offset:39936
	global_load_lds_dwordx4 v[248:249], off
	v_lshl_add_u64 v[248:249], s[36:37], 0, v[134:135]
	s_mov_b32 m0, s46
	s_nop 0
	global_load_lds_dwordx4 v[248:249], off
	s_waitcnt vmcnt(8)
	s_waitcnt lgkmcnt(0)
	s_barrier
	v_mfma_f32_16x16x32_bf16 v[126:129], v[184:187], v[216:219], v[126:129]
	v_mfma_f32_16x16x32_bf16 v[122:125], v[192:195], v[216:219], v[122:125]
	v_mfma_f32_16x16x32_bf16 v[110:113], v[184:187], v[224:227], v[110:113]
	v_mfma_f32_16x16x32_bf16 v[106:109], v[192:195], v[224:227], v[106:109]
	v_mfma_f32_16x16x32_bf16 v[94:97], v[184:187], v[232:235], v[94:97]
	v_mfma_f32_16x16x32_bf16 v[90:93], v[192:195], v[232:235], v[90:93]
	v_mfma_f32_16x16x32_bf16 v[78:81], v[184:187], v[240:243], v[78:81]
	v_mfma_f32_16x16x32_bf16 v[74:77], v[192:195], v[240:243], v[74:77]
	v_mfma_f32_16x16x32_bf16 v[126:129], v[188:191], v[220:223], v[126:129]
	v_mfma_f32_16x16x32_bf16 v[122:125], v[196:199], v[220:223], v[122:125]
	v_mfma_f32_16x16x32_bf16 v[110:113], v[188:191], v[228:231], v[110:113]
	v_mfma_f32_16x16x32_bf16 v[106:109], v[196:199], v[228:231], v[106:109]
	v_mfma_f32_16x16x32_bf16 v[94:97], v[188:191], v[236:239], v[94:97]
	v_mfma_f32_16x16x32_bf16 v[90:93], v[196:199], v[236:239], v[90:93]
	v_mfma_f32_16x16x32_bf16 v[78:81], v[188:191], v[244:247], v[78:81]
	v_mfma_f32_16x16x32_bf16 v[74:77], v[196:199], v[244:247], v[74:77]
	v_mfma_f32_16x16x32_bf16 v[118:121], v[200:203], v[216:219], v[118:121]
	v_mfma_f32_16x16x32_bf16 v[114:117], v[208:211], v[216:219], v[114:117]
	v_mfma_f32_16x16x32_bf16 v[102:105], v[200:203], v[224:227], v[102:105]
	v_mfma_f32_16x16x32_bf16 v[98:101], v[208:211], v[224:227], v[98:101]
	v_mfma_f32_16x16x32_bf16 v[86:89], v[200:203], v[232:235], v[86:89]
	v_mfma_f32_16x16x32_bf16 v[82:85], v[208:211], v[232:235], v[82:85]
	v_mfma_f32_16x16x32_bf16 v[70:73], v[200:203], v[240:243], v[70:73]
	v_mfma_f32_16x16x32_bf16 v[66:69], v[208:211], v[240:243], v[66:69]
	v_mfma_f32_16x16x32_bf16 v[118:121], v[204:207], v[220:223], v[118:121]
	v_mfma_f32_16x16x32_bf16 v[114:117], v[212:215], v[220:223], v[114:117]
	v_mfma_f32_16x16x32_bf16 v[102:105], v[204:207], v[228:231], v[102:105]
	v_mfma_f32_16x16x32_bf16 v[98:101], v[212:215], v[228:231], v[98:101]
	v_mfma_f32_16x16x32_bf16 v[86:89], v[204:207], v[236:239], v[86:89]
	v_mfma_f32_16x16x32_bf16 v[82:85], v[212:215], v[236:239], v[82:85]
	v_mfma_f32_16x16x32_bf16 v[70:73], v[204:207], v[244:247], v[70:73]
	v_mfma_f32_16x16x32_bf16 v[66:69], v[212:215], v[244:247], v[66:69]
	s_barrier
; #define PG8_STAGE(bufoff, gbase, voff) do { _Pragma("unroll") for (int _i = 0; _i < 2; ++_i) \
;         __builtin_amdgcn_global_load_lds((const unsigned*)((const char*)(gbase) + (voff)[_i]), (LAS unsigned*)(lds + (bufoff) + ldsw + _i * 8192), 16, 0, 0); } while (0)
; #define PG8_LDA(dst, b, h) do { _Pragma("unroll") for (int m = 0; m < 4; ++m) _Pragma("unroll") for (int k = 0; k < 2; ++k) dst[m][k] = *(const LAS bf16x8*)(lds + PG8_SA(b, h) + aoff + m * 2048 + k * 1024); } while (0)
; #define PG8_MMA(ai, bj, At, Bt) do { __builtin_amdgcn_s_setprio(1); _Pragma("unroll") for (int m = 0; m < 4; ++m) _Pragma("unroll") for (int n = 0; n < 2; ++n) _Pragma("unroll") for (int k = 0; k < 2; ++k) \
;         acc[ai][bj][m][n] = __builtin_amdgcn_mfma_f32_16x16x32_bf16(Bt[n][k], At[m][k], acc[ai][bj][m][n], 0, 0, 0); __builtin_amdgcn_s_setprio(0); } while (0)
; #define PG8_WAIT_V(n) asm volatile("s_waitcnt vmcnt(" #n ")" ::: "memory")
; #define PG8_WAIT_L(n) asm volatile("s_waitcnt lgkmcnt(" #n ")" ::: "memory")
; #define PG8_BAR __builtin_amdgcn_s_barrier()
; #define PG8_SCHED __builtin_amdgcn_sched_barrier(0)
; template <class Epi, class Sched, bool ABLK = false, bool ALIGN_EPI = true, bool SP2 = true, bool BBLK = true>
; __device__ __forceinline__ void gemm_phase(LAS unsigned char* lds, const Gemm g, const Sched& S, const Epi& E) {
;     ...
;             PG8_LDA(At, 1, 1); PG8_STAGE(PG8_SB(1, 0), b3, voffB); PG8_STAGE(PG8_SB(1, 1), b3 + hstepB, voffB); PG8_STAGE(PG8_SA(1, 0), a3, voffA);
;             PG8_WAIT_V(8); PG8_WAIT_L(0); PG8_BAR; PG8_MMA(1, 0, At, B0); PG8_MMA(1, 1, At, B1); PG8_BAR; PG8_SCHED;
;     ...
;         if constexpr (ALIGN_EPI) { if (wr == 0) PG8_BAR; }
	s_add_u32 s36, s34, 0x8000
	s_addc_u32 s37, s35, 0
	s_add_i32 s55, s60, s41
	v_lshl_add_u64 v[248:249], s[36:37], 0, v[132:133]
	s_mov_b32 m0, s55
	ds_read_b128 v[216:219], v149 offset:49152
	ds_read_b128 v[220:223], v149 offset:50176
	ds_read_b128 v[224:227], v149 offset:51200
	ds_read_b128 v[228:231], v149 offset:52224
	ds_read_b128 v[232:235], v149 offset:53248
	ds_read_b128 v[236:239], v149 offset:54272
	ds_read_b128 v[240:243], v149 offset:55296
	ds_read_b128 v[244:247], v149 offset:56320
	global_load_lds_dwordx4 v[248:249], off
	s_add_i32 m0, s55, 0x2000
	s_add_u32 s34, s34, 0xc000
	v_lshl_add_u64 v[248:249], s[36:37], 0, v[136:137]
	s_addc_u32 s35, s35, 0
	s_add_i32 s36, s61, s41
	global_load_lds_dwordx4 v[248:249], off
	v_lshl_add_u64 v[248:249], s[34:35], 0, v[132:133]
	s_mov_b32 m0, s36
	s_nop 0
	global_load_lds_dwordx4 v[248:249], off
	v_lshl_add_u64 v[248:249], s[34:35], 0, v[136:137]
	s_add_i32 m0, s36, 0x2000
	s_nop 0
	global_load_lds_dwordx4 v[248:249], off
	v_lshl_add_u64 v[248:249], s[30:31], 0, v[130:131]
	s_mov_b32 m0, s47
	s_nop 0
	global_load_lds_dwordx4 v[248:249], off
	v_lshl_add_u64 v[248:249], s[30:31], 0, v[134:135]
	s_mov_b32 m0, s48
	s_nop 0
	global_load_lds_dwordx4 v[248:249], off
	s_waitcnt vmcnt(8)
	s_waitcnt lgkmcnt(0)
	s_barrier
	v_mfma_f32_16x16x32_bf16 v[62:65], v[184:187], v[216:219], v[62:65]
	v_mfma_f32_16x16x32_bf16 v[58:61], v[192:195], v[216:219], v[58:61]
	v_mfma_f32_16x16x32_bf16 v[46:49], v[184:187], v[224:227], v[46:49]
	v_mfma_f32_16x16x32_bf16 v[42:45], v[192:195], v[224:227], v[42:45]
	v_mfma_f32_16x16x32_bf16 v[30:33], v[184:187], v[232:235], v[30:33]
	v_mfma_f32_16x16x32_bf16 v[26:29], v[192:195], v[232:235], v[26:29]
	v_mfma_f32_16x16x32_bf16 v[14:17], v[184:187], v[240:243], v[14:17]
	v_mfma_f32_16x16x32_bf16 v[10:13], v[192:195], v[240:243], v[10:13]
	v_mfma_f32_16x16x32_bf16 v[62:65], v[188:191], v[220:223], v[62:65]
	v_mfma_f32_16x16x32_bf16 v[58:61], v[196:199], v[220:223], v[58:61]
	v_mfma_f32_16x16x32_bf16 v[46:49], v[188:191], v[228:231], v[46:49]
	v_mfma_f32_16x16x32_bf16 v[42:45], v[196:199], v[228:231], v[42:45]
	v_mfma_f32_16x16x32_bf16 v[30:33], v[188:191], v[236:239], v[30:33]
	v_mfma_f32_16x16x32_bf16 v[26:29], v[196:199], v[236:239], v[26:29]
	v_mfma_f32_16x16x32_bf16 v[14:17], v[188:191], v[244:247], v[14:17]
	v_mfma_f32_16x16x32_bf16 v[10:13], v[196:199], v[244:247], v[10:13]
	v_mfma_f32_16x16x32_bf16 v[54:57], v[200:203], v[216:219], v[54:57]
	v_mfma_f32_16x16x32_bf16 v[50:53], v[208:211], v[216:219], v[50:53]
	v_mfma_f32_16x16x32_bf16 v[38:41], v[200:203], v[224:227], v[38:41]
	v_mfma_f32_16x16x32_bf16 v[34:37], v[208:211], v[224:227], v[34:37]
	v_mfma_f32_16x16x32_bf16 v[22:25], v[200:203], v[232:235], v[22:25]
	v_mfma_f32_16x16x32_bf16 v[18:21], v[208:211], v[232:235], v[18:21]
	v_mfma_f32_16x16x32_bf16 v[6:9], v[200:203], v[240:243], v[6:9]
	v_mfma_f32_16x16x32_bf16 v[2:5], v[208:211], v[240:243], v[2:5]
	v_mfma_f32_16x16x32_bf16 v[54:57], v[204:207], v[220:223], v[54:57]
	v_mfma_f32_16x16x32_bf16 v[50:53], v[212:215], v[220:223], v[50:53]
	v_mfma_f32_16x16x32_bf16 v[38:41], v[204:207], v[228:231], v[38:41]
	v_mfma_f32_16x16x32_bf16 v[34:37], v[212:215], v[228:231], v[34:37]
	v_mfma_f32_16x16x32_bf16 v[22:25], v[204:207], v[236:239], v[22:25]
	v_mfma_f32_16x16x32_bf16 v[18:21], v[212:215], v[236:239], v[18:21]
	v_mfma_f32_16x16x32_bf16 v[6:9], v[204:207], v[244:247], v[6:9]
	v_mfma_f32_16x16x32_bf16 v[2:5], v[212:215], v[244:247], v[2:5]
	s_barrier
	s_add_i32 s54, s54, 2
	s_add_u32 s28, s28, 0x100
	s_addc_u32 s29, s29, 0
	s_add_u32 s52, s52, 0x10000
	s_addc_u32 s53, s53, 0
	s_cmp_gt_u32 s54, 29
	s_cbranch_scc0 .LBB0_668
	s_and_b64 vcc, exec, s[12:13]
	s_cbranch_vccz .LBB0_671
	s_barrier

; #define PG8_STAGE(bufoff, gbase, voff) do { _Pragma("unroll") for (int _i = 0; _i < 2; ++_i) \
;         __builtin_amdgcn_global_load_lds((const unsigned*)((const char*)(gbase) + (voff)[_i]), (LAS unsigned*)(lds + (bufoff) + ldsw + _i * 8192), 16, 0, 0); } while (0)
; #define PG8_LDA(dst, b, h) do { _Pragma("unroll") for (int m = 0; m < 4; ++m) _Pragma("unroll") for (int k = 0; k < 2; ++k) dst[m][k] = *(const LAS bf16x8*)(lds + PG8_SA(b, h) + aoff + m * 2048 + k * 1024); } while (0)
; #define PG8_LDB(dst, b, h) do { _Pragma("unroll") for (int n = 0; n < 2; ++n) _Pragma("unroll") for (int k = 0; k < 2; ++k) dst[n][k] = *(const LAS bf16x8*)(lds + PG8_SB(b, h) + boff + n * 2048 + k * 1024); } while (0)
; #define PG8_MMA(ai, bj, At, Bt) do { __builtin_amdgcn_s_setprio(1); _Pragma("unroll") for (int m = 0; m < 4; ++m) _Pragma("unroll") for (int n = 0; n < 2; ++n) _Pragma("unroll") for (int k = 0; k < 2; ++k) \
;         acc[ai][bj][m][n] = __builtin_amdgcn_mfma_f32_16x16x32_bf16(Bt[n][k], At[m][k], acc[ai][bj][m][n], 0, 0, 0); __builtin_amdgcn_s_setprio(0); } while (0)
; #define PG8_WAIT_V(n) asm volatile("s_waitcnt vmcnt(" #n ")" ::: "memory")
; #define PG8_WAIT_L(n) asm volatile("s_waitcnt lgkmcnt(" #n ")" ::: "memory")
; #define PG8_BAR __builtin_amdgcn_s_barrier()
; template <class Epi, class Sched, bool ABLK = false, bool ALIGN_EPI = true, bool SP2 = true, bool BBLK = true>
; __device__ __forceinline__ void gemm_phase(LAS unsigned char* lds, const Gemm g, const Sched& S, const Epi& E) {
;     ...
;             const bool last = (t == nt - 2);
;             const char* a1 = a_tile(uA, tbA + t + 1);
;             const char* a2 = last ? a_tile(nuA, ntbA) : a_tile(uA, tbA + t + 2); const char* b2 = last ? nB : cB + (size_t)(t + 2) * kstepB;
;             const char* a3 = last ? a_tile(nuA, ntbA + 1) : a_tile(uA, tbA + t + 3); const char* b3 = b2 + kstepB;
;             if (last && has_next) S.a_ready(nxt);
;             if constexpr (SP2) {
;             PG8_LDB(B0, 0, 0); PG8_LDB(B1, 0, 1); PG8_SCHED; PG8_LDA(At, 0, 0); PG8_STAGE(PG8_SA(1, 1), a1 + hstepA, voffA);
;             PG8_WAIT_V(8); PG8_WAIT_L(0); PG8_BAR; PG8_MMA(0, 0, At, B0); PG8_MMA(0, 1, At, B1); PG8_BAR; PG8_SCHED;
;             PG8_LDA(At, 0, 1); PG8_STAGE(PG8_SB(0, 0), b2, voffB); PG8_STAGE(PG8_SB(0, 1), b2 + hstepB, voffB); PG8_STAGE(PG8_SA(0, 0), a2, voffA);
.LBB0_1038:
	ds_read_b128 v[156:159], v153
	ds_read_b128 v[160:163], v153 offset:1024
	ds_read_b128 v[164:167], v153 offset:2048
	ds_read_b128 v[168:171], v153 offset:3072
	ds_read_b128 v[172:175], v154
	ds_read_b128 v[176:179], v154 offset:1024
	ds_read_b128 v[180:183], v154 offset:2048
	ds_read_b128 v[184:187], v154 offset:3072
	s_add_u32 s22, s56, s20
	s_addc_u32 s23, s57, s21
	s_add_u32 s26, s22, 0x100
	s_addc_u32 s27, s23, 0
	s_add_i32 s65, s65, 2
	s_add_u32 s22, s22, 0x180
	s_addc_u32 s23, s23, 0
	s_cmp_eq_u32 s64, s20
	s_cselect_b32 s23, s50, s23
	s_cselect_b32 s22, s49, s22
	s_cselect_b32 s25, s4, s55
	s_cselect_b32 s24, s5, s51
	s_cselect_b32 s27, s48, s27
	s_cselect_b32 s26, s17, s26
	v_lshl_add_u64 v[220:221], v[146:147], 0, s[20:21]
	s_add_i32 m0, s35, 0xc000
	ds_read_b128 v[188:191], v155
	ds_read_b128 v[192:195], v155 offset:1024
	ds_read_b128 v[196:199], v155 offset:2048
	ds_read_b128 v[200:203], v155 offset:3072
	ds_read_b128 v[204:207], v155 offset:4096
	ds_read_b128 v[208:211], v155 offset:5120
	ds_read_b128 v[212:215], v155 offset:6144
	ds_read_b128 v[216:219], v155 offset:7168
	global_load_lds_dwordx4 v[220:221], off
	v_lshl_add_u64 v[220:221], v[148:149], 0, s[20:21]
	s_add_i32 m0, s35, 0xe000
	s_nop 0
	global_load_lds_dwordx4 v[220:221], off
	s_waitcnt vmcnt(8)
	s_waitcnt lgkmcnt(0)
	s_barrier
	v_mfma_f32_16x16x32_bf16 v[126:129], v[156:159], v[188:191], v[126:129]
	v_mfma_f32_16x16x32_bf16 v[122:125], v[164:167], v[188:191], v[122:125]
	v_mfma_f32_16x16x32_bf16 v[110:113], v[156:159], v[196:199], v[110:113]
	v_mfma_f32_16x16x32_bf16 v[106:109], v[164:167], v[196:199], v[106:109]
	v_mfma_f32_16x16x32_bf16 v[94:97], v[156:159], v[204:207], v[94:97]
	v_mfma_f32_16x16x32_bf16 v[90:93], v[164:167], v[204:207], v[90:93]
	v_mfma_f32_16x16x32_bf16 v[78:81], v[156:159], v[212:215], v[78:81]
	v_mfma_f32_16x16x32_bf16 v[74:77], v[164:167], v[212:215], v[74:77]
	v_mfma_f32_16x16x32_bf16 v[126:129], v[160:163], v[192:195], v[126:129]
	v_mfma_f32_16x16x32_bf16 v[122:125], v[168:171], v[192:195], v[122:125]
	v_mfma_f32_16x16x32_bf16 v[110:113], v[160:163], v[200:203], v[110:113]
	v_mfma_f32_16x16x32_bf16 v[106:109], v[168:171], v[200:203], v[106:109]
	v_mfma_f32_16x16x32_bf16 v[94:97], v[160:163], v[208:211], v[94:97]
	v_mfma_f32_16x16x32_bf16 v[90:93], v[168:171], v[208:211], v[90:93]
	v_mfma_f32_16x16x32_bf16 v[78:81], v[160:163], v[216:219], v[78:81]
	v_mfma_f32_16x16x32_bf16 v[74:77], v[168:171], v[216:219], v[74:77]
	v_mfma_f32_16x16x32_bf16 v[118:121], v[172:175], v[188:191], v[118:121]
	v_mfma_f32_16x16x32_bf16 v[114:117], v[180:183], v[188:191], v[114:117]
	v_mfma_f32_16x16x32_bf16 v[102:105], v[172:175], v[196:199], v[102:105]
	v_mfma_f32_16x16x32_bf16 v[98:101], v[180:183], v[196:199], v[98:101]
	v_mfma_f32_16x16x32_bf16 v[86:89], v[172:175], v[204:207], v[86:89]
	v_mfma_f32_16x16x32_bf16 v[82:85], v[180:183], v[204:207], v[82:85]
	v_mfma_f32_16x16x32_bf16 v[70:73], v[172:175], v[212:215], v[70:73]
	v_mfma_f32_16x16x32_bf16 v[66:69], v[180:183], v[212:215], v[66:69]
	v_mfma_f32_16x16x32_bf16 v[118:121], v[176:179], v[192:195], v[118:121]
	v_mfma_f32_16x16x32_bf16 v[114:117], v[184:187], v[192:195], v[114:117]
	v_mfma_f32_16x16x32_bf16 v[102:105], v[176:179], v[200:203], v[102:105]
	v_mfma_f32_16x16x32_bf16 v[98:101], v[184:187], v[200:203], v[98:101]
	v_mfma_f32_16x16x32_bf16 v[86:89], v[176:179], v[208:211], v[86:89]
	v_mfma_f32_16x16x32_bf16 v[82:85], v[184:187], v[208:211], v[82:85]
	v_mfma_f32_16x16x32_bf16 v[70:73], v[176:179], v[216:219], v[70:73]
	v_mfma_f32_16x16x32_bf16 v[66:69], v[184:187], v[216:219], v[66:69]
	s_barrier
	s_add_i32 s66, s72, s34
	v_lshl_add_u64 v[220:221], s[24:25], 0, v[132:133]
	s_mov_b32 m0, s66
	ds_read_b128 v[188:191], v155 offset:16384
	ds_read_b128 v[192:195], v155 offset:17408
	ds_read_b128 v[196:199], v155 offset:18432
	ds_read_b128 v[200:203], v155 offset:19456
	ds_read_b128 v[204:207], v155 offset:20480
	ds_read_b128 v[208:211], v155 offset:21504
	ds_read_b128 v[212:215], v155 offset:22528
	ds_read_b128 v[216:219], v155 offset:23552
	global_load_lds_dwordx4 v[220:221], off
	s_add_i32 m0, s66, 0x2000
	s_add_u32 s66, s24, 0x4000
	v_lshl_add_u64 v[220:221], s[24:25], 0, v[136:137]
	s_addc_u32 s67, s25, 0
	s_add_i32 s75, s73, s34
	global_load_lds_dwordx4 v[220:221], off
	v_lshl_add_u64 v[220:221], s[66:67], 0, v[132:133]
	s_mov_b32 m0, s75
	s_nop 0
	global_load_lds_dwordx4 v[220:221], off
	v_lshl_add_u64 v[220:221], s[66:67], 0, v[136:137]
	s_add_i32 m0, s75, 0x2000
	s_nop 0
	global_load_lds_dwordx4 v[220:221], off
	v_lshl_add_u64 v[220:221], s[26:27], 0, v[130:131]
	s_mov_b32 m0, s35
	s_nop 0
	global_load_lds_dwordx4 v[220:221], off
	v_lshl_add_u64 v[220:221], s[26:27], 0, v[134:135]
	s_mov_b32 m0, s36
	s_nop 0
	global_load_lds_dwordx4 v[220:221], off
	s_waitcnt vmcnt(8)
	s_waitcnt lgkmcnt(0)
	s_barrier
; #define PG8_STAGE(bufoff, gbase, voff) do { _Pragma("unroll") for (int _i = 0; _i < 2; ++_i) \
;         __builtin_amdgcn_global_load_lds((const unsigned*)((const char*)(gbase) + (voff)[_i]), (LAS unsigned*)(lds + (bufoff) + ldsw + _i * 8192), 16, 0, 0); } while (0)
; #define PG8_LDA(dst, b, h) do { _Pragma("unroll") for (int m = 0; m < 4; ++m) _Pragma("unroll") for (int k = 0; k < 2; ++k) dst[m][k] = *(const LAS bf16x8*)(lds + PG8_SA(b, h) + aoff + m * 2048 + k * 1024); } while (0)
; #define PG8_LDB(dst, b, h) do { _Pragma("unroll") for (int n = 0; n < 2; ++n) _Pragma("unroll") for (int k = 0; k < 2; ++k) dst[n][k] = *(const LAS bf16x8*)(lds + PG8_SB(b, h) + boff + n * 2048 + k * 1024); } while (0)
; #define PG8_MMA(ai, bj, At, Bt) do { __builtin_amdgcn_s_setprio(1); _Pragma("unroll") for (int m = 0; m < 4; ++m) _Pragma("unroll") for (int n = 0; n < 2; ++n) _Pragma("unroll") for (int k = 0; k < 2; ++k) \
;         acc[ai][bj][m][n] = __builtin_amdgcn_mfma_f32_16x16x32_bf16(Bt[n][k], At[m][k], acc[ai][bj][m][n], 0, 0, 0); __builtin_amdgcn_s_setprio(0); } while (0)
; #define PG8_WAIT_V(n) asm volatile("s_waitcnt vmcnt(" #n ")" ::: "memory")
; #define PG8_WAIT_L(n) asm volatile("s_waitcnt lgkmcnt(" #n ")" ::: "memory")
; #define PG8_BAR __builtin_amdgcn_s_barrier()
; #define PG8_SCHED __builtin_amdgcn_sched_barrier(0)
; template <class Epi, class Sched, bool ABLK = false, bool ALIGN_EPI = true, bool SP2 = true, bool BBLK = true>
; __device__ __forceinline__ void gemm_phase(LAS unsigned char* lds, const Gemm g, const Sched& S, const Epi& E) {
;     ...
;             PG8_WAIT_V(8); PG8_WAIT_L(0); PG8_BAR; PG8_MMA(1, 0, At, B0); PG8_MMA(1, 1, At, B1); PG8_BAR; PG8_SCHED;
;             PG8_LDB(B0, 1, 0); PG8_LDB(B1, 1, 1); PG8_SCHED; PG8_LDA(At, 1, 0); PG8_STAGE(PG8_SA(0, 1), a2 + hstepA, voffA);
;             PG8_WAIT_V(8); PG8_WAIT_L(0); PG8_BAR; PG8_MMA(0, 0, At, B0); PG8_MMA(0, 1, At, B1); PG8_BAR; PG8_SCHED;
	v_mfma_f32_16x16x32_bf16 v[62:65], v[156:159], v[188:191], v[62:65]
	v_mfma_f32_16x16x32_bf16 v[58:61], v[164:167], v[188:191], v[58:61]
	v_mfma_f32_16x16x32_bf16 v[46:49], v[156:159], v[196:199], v[46:49]
	v_mfma_f32_16x16x32_bf16 v[42:45], v[164:167], v[196:199], v[42:45]
	v_mfma_f32_16x16x32_bf16 v[30:33], v[156:159], v[204:207], v[30:33]
	v_mfma_f32_16x16x32_bf16 v[26:29], v[164:167], v[204:207], v[26:29]
	v_mfma_f32_16x16x32_bf16 v[14:17], v[156:159], v[212:215], v[14:17]
	v_mfma_f32_16x16x32_bf16 v[10:13], v[164:167], v[212:215], v[10:13]
	v_mfma_f32_16x16x32_bf16 v[62:65], v[160:163], v[192:195], v[62:65]
	v_mfma_f32_16x16x32_bf16 v[58:61], v[168:171], v[192:195], v[58:61]
	v_mfma_f32_16x16x32_bf16 v[46:49], v[160:163], v[200:203], v[46:49]
	v_mfma_f32_16x16x32_bf16 v[42:45], v[168:171], v[200:203], v[42:45]
	v_mfma_f32_16x16x32_bf16 v[30:33], v[160:163], v[208:211], v[30:33]
	v_mfma_f32_16x16x32_bf16 v[26:29], v[168:171], v[208:211], v[26:29]
	v_mfma_f32_16x16x32_bf16 v[14:17], v[160:163], v[216:219], v[14:17]
	v_mfma_f32_16x16x32_bf16 v[10:13], v[168:171], v[216:219], v[10:13]
	v_mfma_f32_16x16x32_bf16 v[54:57], v[172:175], v[188:191], v[54:57]
	v_mfma_f32_16x16x32_bf16 v[50:53], v[180:183], v[188:191], v[50:53]
	v_mfma_f32_16x16x32_bf16 v[38:41], v[172:175], v[196:199], v[38:41]
	v_mfma_f32_16x16x32_bf16 v[34:37], v[180:183], v[196:199], v[34:37]
	v_mfma_f32_16x16x32_bf16 v[22:25], v[172:175], v[204:207], v[22:25]
	v_mfma_f32_16x16x32_bf16 v[18:21], v[180:183], v[204:207], v[18:21]
	v_mfma_f32_16x16x32_bf16 v[6:9], v[172:175], v[212:215], v[6:9]
	v_mfma_f32_16x16x32_bf16 v[2:5], v[180:183], v[212:215], v[2:5]
	v_mfma_f32_16x16x32_bf16 v[54:57], v[176:179], v[192:195], v[54:57]
	v_mfma_f32_16x16x32_bf16 v[50:53], v[184:187], v[192:195], v[50:53]
	v_mfma_f32_16x16x32_bf16 v[38:41], v[176:179], v[200:203], v[38:41]
	v_mfma_f32_16x16x32_bf16 v[34:37], v[184:187], v[200:203], v[34:37]
	v_mfma_f32_16x16x32_bf16 v[22:25], v[176:179], v[208:211], v[22:25]
	v_mfma_f32_16x16x32_bf16 v[18:21], v[184:187], v[208:211], v[18:21]
	v_mfma_f32_16x16x32_bf16 v[6:9], v[176:179], v[216:219], v[6:9]
	v_mfma_f32_16x16x32_bf16 v[2:5], v[184:187], v[216:219], v[2:5]
	s_barrier
	v_add_u32_e32 v168, s60, v151
	v_add_u32_e32 v184, s61, v151
	ds_read_b128 v[156:159], v168
	ds_read_b128 v[160:163], v168 offset:1024
	ds_read_b128 v[164:167], v168 offset:2048
	ds_read_b128 v[168:171], v168 offset:3072
	ds_read_b128 v[172:175], v184
	ds_read_b128 v[176:179], v184 offset:1024
	ds_read_b128 v[180:183], v184 offset:2048
	ds_read_b128 v[184:187], v184 offset:3072
	s_add_u32 s26, s26, 0x80000
	s_addc_u32 s27, s27, 0
	s_mov_b32 m0, s37
	v_lshl_add_u64 v[220:221], s[26:27], 0, v[130:131]
	ds_read_b128 v[188:191], v155 offset:32768
	ds_read_b128 v[192:195], v155 offset:33792
	ds_read_b128 v[196:199], v155 offset:34816
	ds_read_b128 v[200:203], v155 offset:35840
	ds_read_b128 v[204:207], v155 offset:36864
	ds_read_b128 v[208:211], v155 offset:37888
	ds_read_b128 v[212:215], v155 offset:38912
	ds_read_b128 v[216:219], v155 offset:39936
	global_load_lds_dwordx4 v[220:221], off
	v_lshl_add_u64 v[220:221], s[26:27], 0, v[134:135]
	s_mov_b32 m0, s40
	s_nop 0
	global_load_lds_dwordx4 v[220:221], off
	s_waitcnt vmcnt(8)
	s_waitcnt lgkmcnt(0)
	s_barrier
	v_mfma_f32_16x16x32_bf16 v[126:129], v[156:159], v[188:191], v[126:129]
	v_mfma_f32_16x16x32_bf16 v[122:125], v[164:167], v[188:191], v[122:125]
	v_mfma_f32_16x16x32_bf16 v[110:113], v[156:159], v[196:199], v[110:113]
	v_mfma_f32_16x16x32_bf16 v[106:109], v[164:167], v[196:199], v[106:109]
	v_mfma_f32_16x16x32_bf16 v[94:97], v[156:159], v[204:207], v[94:97]
	v_mfma_f32_16x16x32_bf16 v[90:93], v[164:167], v[204:207], v[90:93]
	v_mfma_f32_16x16x32_bf16 v[78:81], v[156:159], v[212:215], v[78:81]
	v_mfma_f32_16x16x32_bf16 v[74:77], v[164:167], v[212:215], v[74:77]
	v_mfma_f32_16x16x32_bf16 v[126:129], v[160:163], v[192:195], v[126:129]
	v_mfma_f32_16x16x32_bf16 v[122:125], v[168:171], v[192:195], v[122:125]
	v_mfma_f32_16x16x32_bf16 v[110:113], v[160:163], v[200:203], v[110:113]
	v_mfma_f32_16x16x32_bf16 v[106:109], v[168:171], v[200:203], v[106:109]
	v_mfma_f32_16x16x32_bf16 v[94:97], v[160:163], v[208:211], v[94:97]
	v_mfma_f32_16x16x32_bf16 v[90:93], v[168:171], v[208:211], v[90:93]
	v_mfma_f32_16x16x32_bf16 v[78:81], v[160:163], v[216:219], v[78:81]
	v_mfma_f32_16x16x32_bf16 v[74:77], v[168:171], v[216:219], v[74:77]
	v_mfma_f32_16x16x32_bf16 v[118:121], v[172:175], v[188:191], v[118:121]
	v_mfma_f32_16x16x32_bf16 v[114:117], v[180:183], v[188:191], v[114:117]
	v_mfma_f32_16x16x32_bf16 v[102:105], v[172:175], v[196:199], v[102:105]
	v_mfma_f32_16x16x32_bf16 v[98:101], v[180:183], v[196:199], v[98:101]
	v_mfma_f32_16x16x32_bf16 v[86:89], v[172:175], v[204:207], v[86:89]
	v_mfma_f32_16x16x32_bf16 v[82:85], v[180:183], v[204:207], v[82:85]
	v_mfma_f32_16x16x32_bf16 v[70:73], v[172:175], v[212:215], v[70:73]
	v_mfma_f32_16x16x32_bf16 v[66:69], v[180:183], v[212:215], v[66:69]
	v_mfma_f32_16x16x32_bf16 v[118:121], v[176:179], v[192:195], v[118:121]
	v_mfma_f32_16x16x32_bf16 v[114:117], v[184:187], v[192:195], v[114:117]
	v_mfma_f32_16x16x32_bf16 v[102:105], v[176:179], v[200:203], v[102:105]
	v_mfma_f32_16x16x32_bf16 v[98:101], v[184:187], v[200:203], v[98:101]
	v_mfma_f32_16x16x32_bf16 v[86:89], v[176:179], v[208:211], v[86:89]
	v_mfma_f32_16x16x32_bf16 v[82:85], v[184:187], v[208:211], v[82:85]
	v_mfma_f32_16x16x32_bf16 v[70:73], v[176:179], v[216:219], v[70:73]
	v_mfma_f32_16x16x32_bf16 v[66:69], v[184:187], v[216:219], v[66:69]
	s_barrier
; #define PG8_STAGE(bufoff, gbase, voff) do { _Pragma("unroll") for (int _i = 0; _i < 2; ++_i) \
;         __builtin_amdgcn_global_load_lds((const unsigned*)((const char*)(gbase) + (voff)[_i]), (LAS unsigned*)(lds + (bufoff) + ldsw + _i * 8192), 16, 0, 0); } while (0)
; #define PG8_LDA(dst, b, h) do { _Pragma("unroll") for (int m = 0; m < 4; ++m) _Pragma("unroll") for (int k = 0; k < 2; ++k) dst[m][k] = *(const LAS bf16x8*)(lds + PG8_SA(b, h) + aoff + m * 2048 + k * 1024); } while (0)
; #define PG8_MMA(ai, bj, At, Bt) do { __builtin_amdgcn_s_setprio(1); _Pragma("unroll") for (int m = 0; m < 4; ++m) _Pragma("unroll") for (int n = 0; n < 2; ++n) _Pragma("unroll") for (int k = 0; k < 2; ++k) \
;         acc[ai][bj][m][n] = __builtin_amdgcn_mfma_f32_16x16x32_bf16(Bt[n][k], At[m][k], acc[ai][bj][m][n], 0, 0, 0); __builtin_amdgcn_s_setprio(0); } while (0)
; #define PG8_WAIT_V(n) asm volatile("s_waitcnt vmcnt(" #n ")" ::: "memory")
; #define PG8_WAIT_L(n) asm volatile("s_waitcnt lgkmcnt(" #n ")" ::: "memory")
; #define PG8_BAR __builtin_amdgcn_s_barrier()
; #define PG8_SCHED __builtin_amdgcn_sched_barrier(0)
; template <class Epi, class Sched, bool ABLK = false, bool ALIGN_EPI = true, bool SP2 = true, bool BBLK = true>
; __device__ __forceinline__ void gemm_phase(LAS unsigned char* lds, const Gemm g, const Sched& S, const Epi& E) {
;     ...
;             PG8_LDA(At, 1, 1); PG8_STAGE(PG8_SB(1, 0), b3, voffB); PG8_STAGE(PG8_SB(1, 1), b3 + hstepB, voffB); PG8_STAGE(PG8_SA(1, 0), a3, voffA);
;             PG8_WAIT_V(8); PG8_WAIT_L(0); PG8_BAR; PG8_MMA(1, 0, At, B0); PG8_MMA(1, 1, At, B1); PG8_BAR; PG8_SCHED;
;     ...
;         if constexpr (ALIGN_EPI) { if (wr == 0) PG8_BAR; }
	s_add_u32 s26, s24, 0x8000
	s_addc_u32 s27, s25, 0
	s_add_i32 s66, s60, s34
	v_lshl_add_u64 v[220:221], s[26:27], 0, v[132:133]
	s_mov_b32 m0, s66
	ds_read_b128 v[188:191], v155 offset:49152
	ds_read_b128 v[192:195], v155 offset:50176
	ds_read_b128 v[196:199], v155 offset:51200
	ds_read_b128 v[200:203], v155 offset:52224
	ds_read_b128 v[204:207], v155 offset:53248
	ds_read_b128 v[208:211], v155 offset:54272
	ds_read_b128 v[212:215], v155 offset:55296
	ds_read_b128 v[216:219], v155 offset:56320
	global_load_lds_dwordx4 v[220:221], off
	s_add_i32 m0, s66, 0x2000
	s_add_u32 s24, s24, 0xc000
	v_lshl_add_u64 v[220:221], s[26:27], 0, v[136:137]
	s_addc_u32 s25, s25, 0
	s_add_i32 s26, s61, s34
	global_load_lds_dwordx4 v[220:221], off
	v_lshl_add_u64 v[220:221], s[24:25], 0, v[132:133]
	s_mov_b32 m0, s26
	s_nop 0
	global_load_lds_dwordx4 v[220:221], off
	v_lshl_add_u64 v[220:221], s[24:25], 0, v[136:137]
	s_add_i32 m0, s26, 0x2000
	s_nop 0
	global_load_lds_dwordx4 v[220:221], off
	v_lshl_add_u64 v[220:221], s[22:23], 0, v[130:131]
	s_mov_b32 m0, s41
	s_nop 0
	global_load_lds_dwordx4 v[220:221], off
	v_lshl_add_u64 v[220:221], s[22:23], 0, v[134:135]
	s_mov_b32 m0, s42
	s_nop 0
	global_load_lds_dwordx4 v[220:221], off
	s_waitcnt vmcnt(8)
	s_waitcnt lgkmcnt(0)
	s_barrier
	v_mfma_f32_16x16x32_bf16 v[62:65], v[156:159], v[188:191], v[62:65]
	v_mfma_f32_16x16x32_bf16 v[58:61], v[164:167], v[188:191], v[58:61]
	v_mfma_f32_16x16x32_bf16 v[46:49], v[156:159], v[196:199], v[46:49]
	v_mfma_f32_16x16x32_bf16 v[42:45], v[164:167], v[196:199], v[42:45]
	v_mfma_f32_16x16x32_bf16 v[30:33], v[156:159], v[204:207], v[30:33]
	v_mfma_f32_16x16x32_bf16 v[26:29], v[164:167], v[204:207], v[26:29]
	v_mfma_f32_16x16x32_bf16 v[14:17], v[156:159], v[212:215], v[14:17]
	v_mfma_f32_16x16x32_bf16 v[10:13], v[164:167], v[212:215], v[10:13]
	v_mfma_f32_16x16x32_bf16 v[62:65], v[160:163], v[192:195], v[62:65]
	v_mfma_f32_16x16x32_bf16 v[58:61], v[168:171], v[192:195], v[58:61]
	v_mfma_f32_16x16x32_bf16 v[46:49], v[160:163], v[200:203], v[46:49]
	v_mfma_f32_16x16x32_bf16 v[42:45], v[168:171], v[200:203], v[42:45]
	v_mfma_f32_16x16x32_bf16 v[30:33], v[160:163], v[208:211], v[30:33]
	v_mfma_f32_16x16x32_bf16 v[26:29], v[168:171], v[208:211], v[26:29]
	v_mfma_f32_16x16x32_bf16 v[14:17], v[160:163], v[216:219], v[14:17]
	v_mfma_f32_16x16x32_bf16 v[10:13], v[168:171], v[216:219], v[10:13]
	v_mfma_f32_16x16x32_bf16 v[54:57], v[172:175], v[188:191], v[54:57]
	v_mfma_f32_16x16x32_bf16 v[50:53], v[180:183], v[188:191], v[50:53]
	v_mfma_f32_16x16x32_bf16 v[38:41], v[172:175], v[196:199], v[38:41]
	v_mfma_f32_16x16x32_bf16 v[34:37], v[180:183], v[196:199], v[34:37]
	v_mfma_f32_16x16x32_bf16 v[22:25], v[172:175], v[204:207], v[22:25]
	v_mfma_f32_16x16x32_bf16 v[18:21], v[180:183], v[204:207], v[18:21]
	v_mfma_f32_16x16x32_bf16 v[6:9], v[172:175], v[212:215], v[6:9]
	v_mfma_f32_16x16x32_bf16 v[2:5], v[180:183], v[212:215], v[2:5]
	v_mfma_f32_16x16x32_bf16 v[54:57], v[176:179], v[192:195], v[54:57]
	v_mfma_f32_16x16x32_bf16 v[50:53], v[184:187], v[192:195], v[50:53]
	v_mfma_f32_16x16x32_bf16 v[38:41], v[176:179], v[200:203], v[38:41]
	v_mfma_f32_16x16x32_bf16 v[34:37], v[184:187], v[200:203], v[34:37]
	v_mfma_f32_16x16x32_bf16 v[22:25], v[176:179], v[208:211], v[22:25]
	v_mfma_f32_16x16x32_bf16 v[18:21], v[184:187], v[208:211], v[18:21]
	v_mfma_f32_16x16x32_bf16 v[6:9], v[176:179], v[216:219], v[6:9]
	v_mfma_f32_16x16x32_bf16 v[2:5], v[184:187], v[216:219], v[2:5]
	s_barrier
	s_add_u32 s51, s51, 0x10000
	s_addc_u32 s55, s55, 0
	s_add_u32 s20, s20, 0x100
	s_addc_u32 s21, s21, 0
	s_cmp_ge_u32 s65, s46
	s_cbranch_scc0 .LBB0_1038
	s_and_b64 vcc, exec, s[10:11]
	s_cbranch_vccz .LBB0_1041
	s_barrier

; #define PG8_STAGE(bufoff, gbase, voff) do { _Pragma("unroll") for (int _i = 0; _i < 2; ++_i) \
;         __builtin_amdgcn_global_load_lds((const unsigned*)((const char*)(gbase) + (voff)[_i]), (LAS unsigned*)(lds + (bufoff) + ldsw + _i * 8192), 16, 0, 0); } while (0)
; #define PG8_LDA(dst, b, h) do { _Pragma("unroll") for (int m = 0; m < 4; ++m) _Pragma("unroll") for (int k = 0; k < 2; ++k) dst[m][k] = *(const LAS bf16x8*)(lds + PG8_SA(b, h) + aoff + m * 2048 + k * 1024); } while (0)
; #define PG8_LDB(dst, b, h) do { _Pragma("unroll") for (int n = 0; n < 2; ++n) _Pragma("unroll") for (int k = 0; k < 2; ++k) dst[n][k] = *(const LAS bf16x8*)(lds + PG8_SB(b, h) + boff + n * 2048 + k * 1024); } while (0)
; #define PG8_MMA(ai, bj, At, Bt) do { __builtin_amdgcn_s_setprio(1); _Pragma("unroll") for (int m = 0; m < 4; ++m) _Pragma("unroll") for (int n = 0; n < 2; ++n) _Pragma("unroll") for (int k = 0; k < 2; ++k) \
;         acc[ai][bj][m][n] = __builtin_amdgcn_mfma_f32_16x16x32_bf16(Bt[n][k], At[m][k], acc[ai][bj][m][n], 0, 0, 0); __builtin_amdgcn_s_setprio(0); } while (0)
; #define PG8_WAIT_V(n) asm volatile("s_waitcnt vmcnt(" #n ")" ::: "memory")
; #define PG8_WAIT_L(n) asm volatile("s_waitcnt lgkmcnt(" #n ")" ::: "memory")
; #define PG8_BAR __builtin_amdgcn_s_barrier()
; template <class Epi, class Sched, bool ABLK = false, bool ALIGN_EPI = true, bool SP2 = true, bool BBLK = true>
; __device__ __forceinline__ void gemm_phase(LAS unsigned char* lds, const Gemm g, const Sched& S, const Epi& E) {
;     ...
;             const bool last = (t == nt - 2);
;             const char* a1 = a_tile(uA, tbA + t + 1);
;             const char* a2 = last ? a_tile(nuA, ntbA) : a_tile(uA, tbA + t + 2); const char* b2 = last ? nB : cB + (size_t)(t + 2) * kstepB;
;             const char* a3 = last ? a_tile(nuA, ntbA + 1) : a_tile(uA, tbA + t + 3); const char* b3 = b2 + kstepB;
;             if (last && has_next) S.a_ready(nxt);
;             if constexpr (SP2) {
;             PG8_LDB(B0, 0, 0); PG8_LDB(B1, 0, 1); PG8_SCHED; PG8_LDA(At, 0, 0); PG8_STAGE(PG8_SA(1, 1), a1 + hstepA, voffA);
;             PG8_WAIT_V(8); PG8_WAIT_L(0); PG8_BAR; PG8_MMA(0, 0, At, B0); PG8_MMA(0, 1, At, B1); PG8_BAR; PG8_SCHED;
;             PG8_LDA(At, 0, 1); PG8_STAGE(PG8_SB(0, 0), b2, voffB); PG8_STAGE(PG8_SB(0, 1), b2 + hstepB, voffB); PG8_STAGE(PG8_SA(0, 0), a2, voffA);
.LBB0_1164:
	ds_read_b128 v[172:175], v169
	ds_read_b128 v[176:179], v169 offset:1024
	ds_read_b128 v[180:183], v169 offset:2048
	ds_read_b128 v[184:187], v169 offset:3072
	ds_read_b128 v[188:191], v170
	ds_read_b128 v[192:195], v170 offset:1024
	ds_read_b128 v[196:199], v170 offset:2048
	ds_read_b128 v[200:203], v170 offset:3072
	s_add_u32 s30, s26, s28
	s_addc_u32 s31, s27, s29
	s_add_u32 s36, s30, 0x100
	s_addc_u32 s37, s31, 0
	s_add_u32 s30, s30, 0x180
	s_addc_u32 s31, s31, 0
	s_cmpk_eq_i32 s28, 0xf00
	s_cselect_b32 s31, s57, s31
	s_cselect_b32 s30, s23, s30
	s_cselect_b32 s35, s11, s65
	s_cselect_b32 s34, s15, s64
	s_cselect_b32 s37, s4, s37
	s_cselect_b32 s36, s5, s36
	s_mov_b32 m0, s50
	v_lshl_add_u64 v[236:237], v[164:165], 0, s[28:29]
	ds_read_b128 v[204:207], v171
	ds_read_b128 v[208:211], v171 offset:1024
	ds_read_b128 v[212:215], v171 offset:2048
	ds_read_b128 v[216:219], v171 offset:3072
	ds_read_b128 v[220:223], v171 offset:4096
	ds_read_b128 v[224:227], v171 offset:5120
	ds_read_b128 v[228:231], v171 offset:6144
	ds_read_b128 v[232:235], v171 offset:7168
	global_load_lds_dwordx4 v[236:237], off
	v_lshl_add_u64 v[236:237], v[166:167], 0, s[28:29]
	s_mov_b32 m0, s51
	s_nop 0
	global_load_lds_dwordx4 v[236:237], off
	s_waitcnt vmcnt(8)
	s_waitcnt lgkmcnt(0)
	s_barrier
	v_mfma_f32_16x16x32_bf16 v[126:129], v[172:175], v[204:207], v[126:129]
	v_mfma_f32_16x16x32_bf16 v[122:125], v[180:183], v[204:207], v[122:125]
	v_mfma_f32_16x16x32_bf16 v[110:113], v[172:175], v[212:215], v[110:113]
	v_mfma_f32_16x16x32_bf16 v[106:109], v[180:183], v[212:215], v[106:109]
	v_mfma_f32_16x16x32_bf16 v[94:97], v[172:175], v[220:223], v[94:97]
	v_mfma_f32_16x16x32_bf16 v[90:93], v[180:183], v[220:223], v[90:93]
	v_mfma_f32_16x16x32_bf16 v[78:81], v[172:175], v[228:231], v[78:81]
	v_mfma_f32_16x16x32_bf16 v[74:77], v[180:183], v[228:231], v[74:77]
	v_mfma_f32_16x16x32_bf16 v[126:129], v[176:179], v[208:211], v[126:129]
	v_mfma_f32_16x16x32_bf16 v[122:125], v[184:187], v[208:211], v[122:125]
	v_mfma_f32_16x16x32_bf16 v[110:113], v[176:179], v[216:219], v[110:113]
	v_mfma_f32_16x16x32_bf16 v[106:109], v[184:187], v[216:219], v[106:109]
	v_mfma_f32_16x16x32_bf16 v[94:97], v[176:179], v[224:227], v[94:97]
	v_mfma_f32_16x16x32_bf16 v[90:93], v[184:187], v[224:227], v[90:93]
	v_mfma_f32_16x16x32_bf16 v[78:81], v[176:179], v[232:235], v[78:81]
	v_mfma_f32_16x16x32_bf16 v[74:77], v[184:187], v[232:235], v[74:77]
	v_mfma_f32_16x16x32_bf16 v[118:121], v[188:191], v[204:207], v[118:121]
	v_mfma_f32_16x16x32_bf16 v[114:117], v[196:199], v[204:207], v[114:117]
	v_mfma_f32_16x16x32_bf16 v[102:105], v[188:191], v[212:215], v[102:105]
	v_mfma_f32_16x16x32_bf16 v[98:101], v[196:199], v[212:215], v[98:101]
	v_mfma_f32_16x16x32_bf16 v[86:89], v[188:191], v[220:223], v[86:89]
	v_mfma_f32_16x16x32_bf16 v[82:85], v[196:199], v[220:223], v[82:85]
	v_mfma_f32_16x16x32_bf16 v[70:73], v[188:191], v[228:231], v[70:73]
	v_mfma_f32_16x16x32_bf16 v[66:69], v[196:199], v[228:231], v[66:69]
	v_mfma_f32_16x16x32_bf16 v[118:121], v[192:195], v[208:211], v[118:121]
	v_mfma_f32_16x16x32_bf16 v[114:117], v[200:203], v[208:211], v[114:117]
	v_mfma_f32_16x16x32_bf16 v[102:105], v[192:195], v[216:219], v[102:105]
	v_mfma_f32_16x16x32_bf16 v[98:101], v[200:203], v[216:219], v[98:101]
	v_mfma_f32_16x16x32_bf16 v[86:89], v[192:195], v[224:227], v[86:89]
	v_mfma_f32_16x16x32_bf16 v[82:85], v[200:203], v[224:227], v[82:85]
	v_mfma_f32_16x16x32_bf16 v[70:73], v[192:195], v[232:235], v[70:73]
	v_mfma_f32_16x16x32_bf16 v[66:69], v[200:203], v[232:235], v[66:69]
	s_barrier
	s_mov_b32 m0, s55
	v_lshl_add_u64 v[236:237], s[34:35], 0, v[134:135]
	s_add_u32 s76, s34, 0x4000
	ds_read_b128 v[204:207], v171 offset:16384
	ds_read_b128 v[208:211], v171 offset:17408
	ds_read_b128 v[212:215], v171 offset:18432
	ds_read_b128 v[216:219], v171 offset:19456
	ds_read_b128 v[220:223], v171 offset:20480
	ds_read_b128 v[224:227], v171 offset:21504
	ds_read_b128 v[228:231], v171 offset:22528
	ds_read_b128 v[232:235], v171 offset:23552
	global_load_lds_dwordx4 v[236:237], off
	v_lshl_add_u64 v[236:237], s[34:35], 0, v[130:131]
	s_mov_b32 m0, s56
	s_addc_u32 s77, s35, 0
	s_add_i32 s67, s73, s42
	global_load_lds_dwordx4 v[236:237], off
	v_lshl_add_u64 v[236:237], s[76:77], 0, v[134:135]
	s_mov_b32 m0, s67
	s_nop 0
	global_load_lds_dwordx4 v[236:237], off
	v_lshl_add_u64 v[236:237], s[76:77], 0, v[130:131]
	s_add_i32 m0, s67, 0x2000
	s_nop 0
	global_load_lds_dwordx4 v[236:237], off
	v_lshl_add_u64 v[236:237], s[36:37], 0, v[136:137]
	s_mov_b32 m0, s25
	s_nop 0
	global_load_lds_dwordx4 v[236:237], off
	v_lshl_add_u64 v[236:237], s[36:37], 0, v[132:133]
	s_mov_b32 m0, s43
	s_nop 0
	global_load_lds_dwordx4 v[236:237], off
	s_waitcnt vmcnt(8)
	s_waitcnt lgkmcnt(0)
	s_barrier
; #define PG8_STAGE(bufoff, gbase, voff) do { _Pragma("unroll") for (int _i = 0; _i < 2; ++_i) \
;         __builtin_amdgcn_global_load_lds((const unsigned*)((const char*)(gbase) + (voff)[_i]), (LAS unsigned*)(lds + (bufoff) + ldsw + _i * 8192), 16, 0, 0); } while (0)
; #define PG8_LDA(dst, b, h) do { _Pragma("unroll") for (int m = 0; m < 4; ++m) _Pragma("unroll") for (int k = 0; k < 2; ++k) dst[m][k] = *(const LAS bf16x8*)(lds + PG8_SA(b, h) + aoff + m * 2048 + k * 1024); } while (0)
; #define PG8_LDB(dst, b, h) do { _Pragma("unroll") for (int n = 0; n < 2; ++n) _Pragma("unroll") for (int k = 0; k < 2; ++k) dst[n][k] = *(const LAS bf16x8*)(lds + PG8_SB(b, h) + boff + n * 2048 + k * 1024); } while (0)
; #define PG8_MMA(ai, bj, At, Bt) do { __builtin_amdgcn_s_setprio(1); _Pragma("unroll") for (int m = 0; m < 4; ++m) _Pragma("unroll") for (int n = 0; n < 2; ++n) _Pragma("unroll") for (int k = 0; k < 2; ++k) \
;         acc[ai][bj][m][n] = __builtin_amdgcn_mfma_f32_16x16x32_bf16(Bt[n][k], At[m][k], acc[ai][bj][m][n], 0, 0, 0); __builtin_amdgcn_s_setprio(0); } while (0)
; #define PG8_WAIT_V(n) asm volatile("s_waitcnt vmcnt(" #n ")" ::: "memory")
; #define PG8_WAIT_L(n) asm volatile("s_waitcnt lgkmcnt(" #n ")" ::: "memory")
; #define PG8_BAR __builtin_amdgcn_s_barrier()
; #define PG8_SCHED __builtin_amdgcn_sched_barrier(0)
; template <class Epi, class Sched, bool ABLK = false, bool ALIGN_EPI = true, bool SP2 = true, bool BBLK = true>
; __device__ __forceinline__ void gemm_phase(LAS unsigned char* lds, const Gemm g, const Sched& S, const Epi& E) {
;     ...
;             PG8_WAIT_V(8); PG8_WAIT_L(0); PG8_BAR; PG8_MMA(1, 0, At, B0); PG8_MMA(1, 1, At, B1); PG8_BAR; PG8_SCHED;
;             PG8_LDB(B0, 1, 0); PG8_LDB(B1, 1, 1); PG8_SCHED; PG8_LDA(At, 1, 0); PG8_STAGE(PG8_SA(0, 1), a2 + hstepA, voffA);
;             PG8_WAIT_V(8); PG8_WAIT_L(0); PG8_BAR; PG8_MMA(0, 0, At, B0); PG8_MMA(0, 1, At, B1); PG8_BAR; PG8_SCHED;
	v_mfma_f32_16x16x32_bf16 v[62:65], v[172:175], v[204:207], v[62:65]
	v_mfma_f32_16x16x32_bf16 v[58:61], v[180:183], v[204:207], v[58:61]
	v_mfma_f32_16x16x32_bf16 v[46:49], v[172:175], v[212:215], v[46:49]
	v_mfma_f32_16x16x32_bf16 v[42:45], v[180:183], v[212:215], v[42:45]
	v_mfma_f32_16x16x32_bf16 v[30:33], v[172:175], v[220:223], v[30:33]
	v_mfma_f32_16x16x32_bf16 v[26:29], v[180:183], v[220:223], v[26:29]
	v_mfma_f32_16x16x32_bf16 v[14:17], v[172:175], v[228:231], v[14:17]
	v_mfma_f32_16x16x32_bf16 v[10:13], v[180:183], v[228:231], v[10:13]
	v_mfma_f32_16x16x32_bf16 v[62:65], v[176:179], v[208:211], v[62:65]
	v_mfma_f32_16x16x32_bf16 v[58:61], v[184:187], v[208:211], v[58:61]
	v_mfma_f32_16x16x32_bf16 v[46:49], v[176:179], v[216:219], v[46:49]
	v_mfma_f32_16x16x32_bf16 v[42:45], v[184:187], v[216:219], v[42:45]
	v_mfma_f32_16x16x32_bf16 v[30:33], v[176:179], v[224:227], v[30:33]
	v_mfma_f32_16x16x32_bf16 v[26:29], v[184:187], v[224:227], v[26:29]
	v_mfma_f32_16x16x32_bf16 v[14:17], v[176:179], v[232:235], v[14:17]
	v_mfma_f32_16x16x32_bf16 v[10:13], v[184:187], v[232:235], v[10:13]
	v_mfma_f32_16x16x32_bf16 v[54:57], v[188:191], v[204:207], v[54:57]
	v_mfma_f32_16x16x32_bf16 v[50:53], v[196:199], v[204:207], v[50:53]
	v_mfma_f32_16x16x32_bf16 v[38:41], v[188:191], v[212:215], v[38:41]
	v_mfma_f32_16x16x32_bf16 v[34:37], v[196:199], v[212:215], v[34:37]
	v_mfma_f32_16x16x32_bf16 v[22:25], v[188:191], v[220:223], v[22:25]
	v_mfma_f32_16x16x32_bf16 v[18:21], v[196:199], v[220:223], v[18:21]
	v_mfma_f32_16x16x32_bf16 v[6:9], v[188:191], v[228:231], v[6:9]
	v_mfma_f32_16x16x32_bf16 v[2:5], v[196:199], v[228:231], v[2:5]
	v_mfma_f32_16x16x32_bf16 v[54:57], v[192:195], v[208:211], v[54:57]
	v_mfma_f32_16x16x32_bf16 v[50:53], v[200:203], v[208:211], v[50:53]
	v_mfma_f32_16x16x32_bf16 v[38:41], v[192:195], v[216:219], v[38:41]
	v_mfma_f32_16x16x32_bf16 v[34:37], v[200:203], v[216:219], v[34:37]
	v_mfma_f32_16x16x32_bf16 v[22:25], v[192:195], v[224:227], v[22:25]
	v_mfma_f32_16x16x32_bf16 v[18:21], v[200:203], v[224:227], v[18:21]
	v_mfma_f32_16x16x32_bf16 v[6:9], v[192:195], v[232:235], v[6:9]
	v_mfma_f32_16x16x32_bf16 v[2:5], v[200:203], v[232:235], v[2:5]
	s_barrier
	v_add_u32_e32 v184, s60, v168
	v_add_u32_e32 v200, s61, v168
	ds_read_b128 v[172:175], v184
	ds_read_b128 v[176:179], v184 offset:1024
	ds_read_b128 v[180:183], v184 offset:2048
	ds_read_b128 v[184:187], v184 offset:3072
	ds_read_b128 v[188:191], v200
	ds_read_b128 v[192:195], v200 offset:1024
	ds_read_b128 v[196:199], v200 offset:2048
	ds_read_b128 v[200:203], v200 offset:3072
	s_add_u32 s36, s36, 0x80000
	s_addc_u32 s37, s37, 0
	s_mov_b32 m0, s44
	v_lshl_add_u64 v[236:237], s[36:37], 0, v[136:137]
	ds_read_b128 v[204:207], v171 offset:32768
	ds_read_b128 v[208:211], v171 offset:33792
	ds_read_b128 v[212:215], v171 offset:34816
	ds_read_b128 v[216:219], v171 offset:35840
	ds_read_b128 v[220:223], v171 offset:36864
	ds_read_b128 v[224:227], v171 offset:37888
	ds_read_b128 v[228:231], v171 offset:38912
	ds_read_b128 v[232:235], v171 offset:39936
	global_load_lds_dwordx4 v[236:237], off
	v_lshl_add_u64 v[236:237], s[36:37], 0, v[132:133]
	s_mov_b32 m0, s45
	s_nop 0
	global_load_lds_dwordx4 v[236:237], off
	s_waitcnt vmcnt(8)
	s_waitcnt lgkmcnt(0)
	s_barrier
	v_mfma_f32_16x16x32_bf16 v[126:129], v[172:175], v[204:207], v[126:129]
	v_mfma_f32_16x16x32_bf16 v[122:125], v[180:183], v[204:207], v[122:125]
	v_mfma_f32_16x16x32_bf16 v[110:113], v[172:175], v[212:215], v[110:113]
	v_mfma_f32_16x16x32_bf16 v[106:109], v[180:183], v[212:215], v[106:109]
	v_mfma_f32_16x16x32_bf16 v[94:97], v[172:175], v[220:223], v[94:97]
	v_mfma_f32_16x16x32_bf16 v[90:93], v[180:183], v[220:223], v[90:93]
	v_mfma_f32_16x16x32_bf16 v[78:81], v[172:175], v[228:231], v[78:81]
	v_mfma_f32_16x16x32_bf16 v[74:77], v[180:183], v[228:231], v[74:77]
	v_mfma_f32_16x16x32_bf16 v[126:129], v[176:179], v[208:211], v[126:129]
	v_mfma_f32_16x16x32_bf16 v[122:125], v[184:187], v[208:211], v[122:125]
	v_mfma_f32_16x16x32_bf16 v[110:113], v[176:179], v[216:219], v[110:113]
	v_mfma_f32_16x16x32_bf16 v[106:109], v[184:187], v[216:219], v[106:109]
	v_mfma_f32_16x16x32_bf16 v[94:97], v[176:179], v[224:227], v[94:97]
	v_mfma_f32_16x16x32_bf16 v[90:93], v[184:187], v[224:227], v[90:93]
	v_mfma_f32_16x16x32_bf16 v[78:81], v[176:179], v[232:235], v[78:81]
	v_mfma_f32_16x16x32_bf16 v[74:77], v[184:187], v[232:235], v[74:77]
	v_mfma_f32_16x16x32_bf16 v[118:121], v[188:191], v[204:207], v[118:121]
	v_mfma_f32_16x16x32_bf16 v[114:117], v[196:199], v[204:207], v[114:117]
	v_mfma_f32_16x16x32_bf16 v[102:105], v[188:191], v[212:215], v[102:105]
	v_mfma_f32_16x16x32_bf16 v[98:101], v[196:199], v[212:215], v[98:101]
	v_mfma_f32_16x16x32_bf16 v[86:89], v[188:191], v[220:223], v[86:89]
	v_mfma_f32_16x16x32_bf16 v[82:85], v[196:199], v[220:223], v[82:85]
	v_mfma_f32_16x16x32_bf16 v[70:73], v[188:191], v[228:231], v[70:73]
	v_mfma_f32_16x16x32_bf16 v[66:69], v[196:199], v[228:231], v[66:69]
	v_mfma_f32_16x16x32_bf16 v[118:121], v[192:195], v[208:211], v[118:121]
	v_mfma_f32_16x16x32_bf16 v[114:117], v[200:203], v[208:211], v[114:117]
	v_mfma_f32_16x16x32_bf16 v[102:105], v[192:195], v[216:219], v[102:105]
	v_mfma_f32_16x16x32_bf16 v[98:101], v[200:203], v[216:219], v[98:101]
	v_mfma_f32_16x16x32_bf16 v[86:89], v[192:195], v[224:227], v[86:89]
	v_mfma_f32_16x16x32_bf16 v[82:85], v[200:203], v[224:227], v[82:85]
	v_mfma_f32_16x16x32_bf16 v[70:73], v[192:195], v[232:235], v[70:73]
	v_mfma_f32_16x16x32_bf16 v[66:69], v[200:203], v[232:235], v[66:69]
	s_barrier
; #define PG8_STAGE(bufoff, gbase, voff) do { _Pragma("unroll") for (int _i = 0; _i < 2; ++_i) \
;         __builtin_amdgcn_global_load_lds((const unsigned*)((const char*)(gbase) + (voff)[_i]), (LAS unsigned*)(lds + (bufoff) + ldsw + _i * 8192), 16, 0, 0); } while (0)
; #define PG8_LDA(dst, b, h) do { _Pragma("unroll") for (int m = 0; m < 4; ++m) _Pragma("unroll") for (int k = 0; k < 2; ++k) dst[m][k] = *(const LAS bf16x8*)(lds + PG8_SA(b, h) + aoff + m * 2048 + k * 1024); } while (0)
; #define PG8_MMA(ai, bj, At, Bt) do { __builtin_amdgcn_s_setprio(1); _Pragma("unroll") for (int m = 0; m < 4; ++m) _Pragma("unroll") for (int n = 0; n < 2; ++n) _Pragma("unroll") for (int k = 0; k < 2; ++k) \
;         acc[ai][bj][m][n] = __builtin_amdgcn_mfma_f32_16x16x32_bf16(Bt[n][k], At[m][k], acc[ai][bj][m][n], 0, 0, 0); __builtin_amdgcn_s_setprio(0); } while (0)
; #define PG8_WAIT_V(n) asm volatile("s_waitcnt vmcnt(" #n ")" ::: "memory")
; #define PG8_WAIT_L(n) asm volatile("s_waitcnt lgkmcnt(" #n ")" ::: "memory")
; #define PG8_BAR __builtin_amdgcn_s_barrier()
; #define PG8_SCHED __builtin_amdgcn_sched_barrier(0)
; template <class Epi, class Sched, bool ABLK = false, bool ALIGN_EPI = true, bool SP2 = true, bool BBLK = true>
; __device__ __forceinline__ void gemm_phase(LAS unsigned char* lds, const Gemm g, const Sched& S, const Epi& E) {
;     ...
;             PG8_LDA(At, 1, 1); PG8_STAGE(PG8_SB(1, 0), b3, voffB); PG8_STAGE(PG8_SB(1, 1), b3 + hstepB, voffB); PG8_STAGE(PG8_SA(1, 0), a3, voffA);
;             PG8_WAIT_V(8); PG8_WAIT_L(0); PG8_BAR; PG8_MMA(1, 0, At, B0); PG8_MMA(1, 1, At, B1); PG8_BAR; PG8_SCHED;
;     ...
;         if constexpr (ALIGN_EPI) { if (wr == 0) PG8_BAR; }
	s_add_u32 s36, s34, 0x8000
	s_addc_u32 s37, s35, 0
	s_add_i32 s67, s60, s42
	v_lshl_add_u64 v[236:237], s[36:37], 0, v[134:135]
	s_mov_b32 m0, s67
	ds_read_b128 v[204:207], v171 offset:49152
	ds_read_b128 v[208:211], v171 offset:50176
	ds_read_b128 v[212:215], v171 offset:51200
	ds_read_b128 v[216:219], v171 offset:52224
	ds_read_b128 v[220:223], v171 offset:53248
	ds_read_b128 v[224:227], v171 offset:54272
	ds_read_b128 v[228:231], v171 offset:55296
	ds_read_b128 v[232:235], v171 offset:56320
	global_load_lds_dwordx4 v[236:237], off
	s_add_i32 m0, s67, 0x2000
	s_add_u32 s34, s34, 0xc000
	v_lshl_add_u64 v[236:237], s[36:37], 0, v[130:131]
	s_addc_u32 s35, s35, 0
	s_add_i32 s36, s61, s42
	global_load_lds_dwordx4 v[236:237], off
	v_lshl_add_u64 v[236:237], s[34:35], 0, v[134:135]
	s_mov_b32 m0, s36
	s_nop 0
	global_load_lds_dwordx4 v[236:237], off
	v_lshl_add_u64 v[236:237], s[34:35], 0, v[130:131]
	s_add_i32 m0, s36, 0x2000
	s_nop 0
	global_load_lds_dwordx4 v[236:237], off
	v_lshl_add_u64 v[236:237], s[30:31], 0, v[136:137]
	s_mov_b32 m0, s48
	s_nop 0
	global_load_lds_dwordx4 v[236:237], off
	v_lshl_add_u64 v[236:237], s[30:31], 0, v[132:133]
	s_mov_b32 m0, s49
	s_nop 0
	global_load_lds_dwordx4 v[236:237], off
	s_waitcnt vmcnt(8)
	s_waitcnt lgkmcnt(0)
	s_barrier
	v_mfma_f32_16x16x32_bf16 v[62:65], v[172:175], v[204:207], v[62:65]
	v_mfma_f32_16x16x32_bf16 v[58:61], v[180:183], v[204:207], v[58:61]
	v_mfma_f32_16x16x32_bf16 v[46:49], v[172:175], v[212:215], v[46:49]
	v_mfma_f32_16x16x32_bf16 v[42:45], v[180:183], v[212:215], v[42:45]
	v_mfma_f32_16x16x32_bf16 v[30:33], v[172:175], v[220:223], v[30:33]
	v_mfma_f32_16x16x32_bf16 v[26:29], v[180:183], v[220:223], v[26:29]
	v_mfma_f32_16x16x32_bf16 v[14:17], v[172:175], v[228:231], v[14:17]
	v_mfma_f32_16x16x32_bf16 v[10:13], v[180:183], v[228:231], v[10:13]
	v_mfma_f32_16x16x32_bf16 v[62:65], v[176:179], v[208:211], v[62:65]
	v_mfma_f32_16x16x32_bf16 v[58:61], v[184:187], v[208:211], v[58:61]
	v_mfma_f32_16x16x32_bf16 v[46:49], v[176:179], v[216:219], v[46:49]
	v_mfma_f32_16x16x32_bf16 v[42:45], v[184:187], v[216:219], v[42:45]
	v_mfma_f32_16x16x32_bf16 v[30:33], v[176:179], v[224:227], v[30:33]
	v_mfma_f32_16x16x32_bf16 v[26:29], v[184:187], v[224:227], v[26:29]
	v_mfma_f32_16x16x32_bf16 v[14:17], v[176:179], v[232:235], v[14:17]
	v_mfma_f32_16x16x32_bf16 v[10:13], v[184:187], v[232:235], v[10:13]
	v_mfma_f32_16x16x32_bf16 v[54:57], v[188:191], v[204:207], v[54:57]
	v_mfma_f32_16x16x32_bf16 v[50:53], v[196:199], v[204:207], v[50:53]
	v_mfma_f32_16x16x32_bf16 v[38:41], v[188:191], v[212:215], v[38:41]
	v_mfma_f32_16x16x32_bf16 v[34:37], v[196:199], v[212:215], v[34:37]
	v_mfma_f32_16x16x32_bf16 v[22:25], v[188:191], v[220:223], v[22:25]
	v_mfma_f32_16x16x32_bf16 v[18:21], v[196:199], v[220:223], v[18:21]
	v_mfma_f32_16x16x32_bf16 v[6:9], v[188:191], v[228:231], v[6:9]
	v_mfma_f32_16x16x32_bf16 v[2:5], v[196:199], v[228:231], v[2:5]
	v_mfma_f32_16x16x32_bf16 v[54:57], v[192:195], v[208:211], v[54:57]
	v_mfma_f32_16x16x32_bf16 v[50:53], v[200:203], v[208:211], v[50:53]
	v_mfma_f32_16x16x32_bf16 v[38:41], v[192:195], v[216:219], v[38:41]
	v_mfma_f32_16x16x32_bf16 v[34:37], v[200:203], v[216:219], v[34:37]
	v_mfma_f32_16x16x32_bf16 v[22:25], v[192:195], v[224:227], v[22:25]
	v_mfma_f32_16x16x32_bf16 v[18:21], v[200:203], v[224:227], v[18:21]
	v_mfma_f32_16x16x32_bf16 v[6:9], v[192:195], v[232:235], v[6:9]
	v_mfma_f32_16x16x32_bf16 v[2:5], v[200:203], v[232:235], v[2:5]
	s_barrier
	s_add_i32 s66, s66, 2
	s_add_u32 s28, s28, 0x100
	s_addc_u32 s29, s29, 0
	s_add_u32 s64, s64, 0x10000
	s_addc_u32 s65, s65, 0
	s_cmp_gt_u32 s66, 29
	s_cbranch_scc0 .LBB0_1164
	s_and_b64 vcc, exec, s[6:7]
	s_cbranch_vccz .LBB0_1167
	s_barrier

; #define PG8_STAGE(bufoff, gbase, voff) do { _Pragma("unroll") for (int _i = 0; _i < 2; ++_i) \
;         __builtin_amdgcn_global_load_lds((const unsigned*)((const char*)(gbase) + (voff)[_i]), (LAS unsigned*)(lds + (bufoff) + ldsw + _i * 8192), 16, 0, 0); } while (0)
; #define PG8_LDA(dst, b, h) do { _Pragma("unroll") for (int m = 0; m < 4; ++m) _Pragma("unroll") for (int k = 0; k < 2; ++k) dst[m][k] = *(const LAS bf16x8*)(lds + PG8_SA(b, h) + aoff + m * 2048 + k * 1024); } while (0)
; #define PG8_LDB(dst, b, h) do { _Pragma("unroll") for (int n = 0; n < 2; ++n) _Pragma("unroll") for (int k = 0; k < 2; ++k) dst[n][k] = *(const LAS bf16x8*)(lds + PG8_SB(b, h) + boff + n * 2048 + k * 1024); } while (0)
; #define PG8_MMA(ai, bj, At, Bt) do { __builtin_amdgcn_s_setprio(1); _Pragma("unroll") for (int m = 0; m < 4; ++m) _Pragma("unroll") for (int n = 0; n < 2; ++n) _Pragma("unroll") for (int k = 0; k < 2; ++k) \
;         acc[ai][bj][m][n] = __builtin_amdgcn_mfma_f32_16x16x32_bf16(Bt[n][k], At[m][k], acc[ai][bj][m][n], 0, 0, 0); __builtin_amdgcn_s_setprio(0); } while (0)
; #define PG8_WAIT_V(n) asm volatile("s_waitcnt vmcnt(" #n ")" ::: "memory")
; #define PG8_WAIT_L(n) asm volatile("s_waitcnt lgkmcnt(" #n ")" ::: "memory")
; #define PG8_BAR __builtin_amdgcn_s_barrier()
; template <class Epi, class Sched, bool ABLK = false, bool ALIGN_EPI = true, bool SP2 = true, bool BBLK = true>
; __device__ __forceinline__ void gemm_phase(LAS unsigned char* lds, const Gemm g, const Sched& S, const Epi& E) {
;     ...
;             const bool last = (t == nt - 2);
;             const char* a1 = a_tile(uA, tbA + t + 1);
;             const char* a2 = last ? a_tile(nuA, ntbA) : a_tile(uA, tbA + t + 2); const char* b2 = last ? nB : cB + (size_t)(t + 2) * kstepB;
;             const char* a3 = last ? a_tile(nuA, ntbA + 1) : a_tile(uA, tbA + t + 3); const char* b3 = b2 + kstepB;
;             if (last && has_next) S.a_ready(nxt);
;             if constexpr (SP2) {
;             PG8_LDB(B0, 0, 0); PG8_LDB(B1, 0, 1); PG8_SCHED; PG8_LDA(At, 0, 0); PG8_STAGE(PG8_SA(1, 1), a1 + hstepA, voffA);
;             PG8_WAIT_V(8); PG8_WAIT_L(0); PG8_BAR; PG8_MMA(0, 0, At, B0); PG8_MMA(0, 1, At, B1); PG8_BAR; PG8_SCHED;
;             PG8_LDA(At, 0, 1); PG8_STAGE(PG8_SB(0, 0), b2, voffB); PG8_STAGE(PG8_SB(0, 1), b2 + hstepB, voffB); PG8_STAGE(PG8_SA(0, 0), a2, voffA);
.LBB0_1229:
	ds_read_b128 v[152:155], v149
	ds_read_b128 v[156:159], v149 offset:1024
	ds_read_b128 v[160:163], v149 offset:2048
	ds_read_b128 v[164:167], v149 offset:3072
	ds_read_b128 v[168:171], v150
	ds_read_b128 v[172:175], v150 offset:1024
	ds_read_b128 v[176:179], v150 offset:2048
	ds_read_b128 v[180:183], v150 offset:3072
	s_add_u32 s24, s51, s22
	s_addc_u32 s25, s55, s23
	s_add_u32 s28, s24, 0x10000
	s_addc_u32 s29, s25, 0
	s_add_i32 s57, s57, 2
	s_add_u32 s26, s49, s22
	s_addc_u32 s27, s50, s23
	s_add_u32 s24, s24, 0x18000
	s_addc_u32 s25, s25, 0
	s_cmp_eq_u32 s56, s22
	s_cselect_b32 s25, s48, s25
	s_cselect_b32 s24, s47, s24
	s_cselect_b32 s27, s4, s27
	s_cselect_b32 s26, s5, s26
	s_cselect_b32 s29, s46, s29
	s_cselect_b32 s28, s19, s28
	v_lshl_add_u64 v[216:217], v[142:143], 0, s[22:23]
	s_add_i32 m0, s35, 0xc000
	ds_read_b128 v[184:187], v151
	ds_read_b128 v[188:191], v151 offset:1024
	ds_read_b128 v[192:195], v151 offset:2048
	ds_read_b128 v[196:199], v151 offset:3072
	ds_read_b128 v[200:203], v151 offset:4096
	ds_read_b128 v[204:207], v151 offset:5120
	ds_read_b128 v[208:211], v151 offset:6144
	ds_read_b128 v[212:215], v151 offset:7168
	global_load_lds_dwordx4 v[216:217], off
	v_lshl_add_u64 v[216:217], v[144:145], 0, s[22:23]
	s_add_i32 m0, s35, 0xe000
	s_nop 0
	global_load_lds_dwordx4 v[216:217], off
	s_waitcnt vmcnt(8)
	s_waitcnt lgkmcnt(0)
	s_barrier
	v_mfma_f32_16x16x32_bf16 v[126:129], v[152:155], v[184:187], v[126:129]
	v_mfma_f32_16x16x32_bf16 v[122:125], v[160:163], v[184:187], v[122:125]
	v_mfma_f32_16x16x32_bf16 v[110:113], v[152:155], v[192:195], v[110:113]
	v_mfma_f32_16x16x32_bf16 v[106:109], v[160:163], v[192:195], v[106:109]
	v_mfma_f32_16x16x32_bf16 v[94:97], v[152:155], v[200:203], v[94:97]
	v_mfma_f32_16x16x32_bf16 v[90:93], v[160:163], v[200:203], v[90:93]
	v_mfma_f32_16x16x32_bf16 v[78:81], v[152:155], v[208:211], v[78:81]
	v_mfma_f32_16x16x32_bf16 v[74:77], v[160:163], v[208:211], v[74:77]
	v_mfma_f32_16x16x32_bf16 v[126:129], v[156:159], v[188:191], v[126:129]
	v_mfma_f32_16x16x32_bf16 v[122:125], v[164:167], v[188:191], v[122:125]
	v_mfma_f32_16x16x32_bf16 v[110:113], v[156:159], v[196:199], v[110:113]
	v_mfma_f32_16x16x32_bf16 v[106:109], v[164:167], v[196:199], v[106:109]
	v_mfma_f32_16x16x32_bf16 v[94:97], v[156:159], v[204:207], v[94:97]
	v_mfma_f32_16x16x32_bf16 v[90:93], v[164:167], v[204:207], v[90:93]
	v_mfma_f32_16x16x32_bf16 v[78:81], v[156:159], v[212:215], v[78:81]
	v_mfma_f32_16x16x32_bf16 v[74:77], v[164:167], v[212:215], v[74:77]
	v_mfma_f32_16x16x32_bf16 v[118:121], v[168:171], v[184:187], v[118:121]
	v_mfma_f32_16x16x32_bf16 v[114:117], v[176:179], v[184:187], v[114:117]
	v_mfma_f32_16x16x32_bf16 v[102:105], v[168:171], v[192:195], v[102:105]
	v_mfma_f32_16x16x32_bf16 v[98:101], v[176:179], v[192:195], v[98:101]
	v_mfma_f32_16x16x32_bf16 v[86:89], v[168:171], v[200:203], v[86:89]
	v_mfma_f32_16x16x32_bf16 v[82:85], v[176:179], v[200:203], v[82:85]
	v_mfma_f32_16x16x32_bf16 v[70:73], v[168:171], v[208:211], v[70:73]
	v_mfma_f32_16x16x32_bf16 v[66:69], v[176:179], v[208:211], v[66:69]
	v_mfma_f32_16x16x32_bf16 v[118:121], v[172:175], v[188:191], v[118:121]
	v_mfma_f32_16x16x32_bf16 v[114:117], v[180:183], v[188:191], v[114:117]
	v_mfma_f32_16x16x32_bf16 v[102:105], v[172:175], v[196:199], v[102:105]
	v_mfma_f32_16x16x32_bf16 v[98:101], v[180:183], v[196:199], v[98:101]
	v_mfma_f32_16x16x32_bf16 v[86:89], v[172:175], v[204:207], v[86:89]
	v_mfma_f32_16x16x32_bf16 v[82:85], v[180:183], v[204:207], v[82:85]
	v_mfma_f32_16x16x32_bf16 v[70:73], v[172:175], v[212:215], v[70:73]
	v_mfma_f32_16x16x32_bf16 v[66:69], v[180:183], v[212:215], v[66:69]
	s_barrier
	s_add_i32 s59, s72, s34
	v_lshl_add_u64 v[216:217], s[26:27], 0, v[130:131]
	s_mov_b32 m0, s59
	ds_read_b128 v[184:187], v151 offset:16384
	ds_read_b128 v[188:191], v151 offset:17408
	ds_read_b128 v[192:195], v151 offset:18432
	ds_read_b128 v[196:199], v151 offset:19456
	ds_read_b128 v[200:203], v151 offset:20480
	ds_read_b128 v[204:207], v151 offset:21504
	ds_read_b128 v[208:211], v151 offset:22528
	ds_read_b128 v[212:215], v151 offset:23552
	global_load_lds_dwordx4 v[216:217], off
	s_add_i32 m0, s59, 0x2000
	s_add_u32 s64, s26, 0x4000
	v_lshl_add_u64 v[216:217], s[26:27], 0, v[132:133]
	s_addc_u32 s65, s27, 0
	s_add_i32 s59, s73, s34
	global_load_lds_dwordx4 v[216:217], off
	v_lshl_add_u64 v[216:217], s[64:65], 0, v[130:131]
	s_mov_b32 m0, s59
	s_nop 0
	global_load_lds_dwordx4 v[216:217], off
	v_lshl_add_u64 v[216:217], s[64:65], 0, v[132:133]
	s_add_i32 m0, s59, 0x2000
	s_nop 0
	global_load_lds_dwordx4 v[216:217], off
	v_lshl_add_u64 v[216:217], s[28:29], 0, v[130:131]
	s_mov_b32 m0, s35
	s_nop 0
	global_load_lds_dwordx4 v[216:217], off
	v_lshl_add_u64 v[216:217], s[28:29], 0, v[132:133]
	s_mov_b32 m0, s36
	s_nop 0
	global_load_lds_dwordx4 v[216:217], off
	s_waitcnt vmcnt(8)
	s_waitcnt lgkmcnt(0)
	s_barrier
; #define PG8_STAGE(bufoff, gbase, voff) do { _Pragma("unroll") for (int _i = 0; _i < 2; ++_i) \
;         __builtin_amdgcn_global_load_lds((const unsigned*)((const char*)(gbase) + (voff)[_i]), (LAS unsigned*)(lds + (bufoff) + ldsw + _i * 8192), 16, 0, 0); } while (0)
; #define PG8_LDA(dst, b, h) do { _Pragma("unroll") for (int m = 0; m < 4; ++m) _Pragma("unroll") for (int k = 0; k < 2; ++k) dst[m][k] = *(const LAS bf16x8*)(lds + PG8_SA(b, h) + aoff + m * 2048 + k * 1024); } while (0)
; #define PG8_LDB(dst, b, h) do { _Pragma("unroll") for (int n = 0; n < 2; ++n) _Pragma("unroll") for (int k = 0; k < 2; ++k) dst[n][k] = *(const LAS bf16x8*)(lds + PG8_SB(b, h) + boff + n * 2048 + k * 1024); } while (0)
; #define PG8_MMA(ai, bj, At, Bt) do { __builtin_amdgcn_s_setprio(1); _Pragma("unroll") for (int m = 0; m < 4; ++m) _Pragma("unroll") for (int n = 0; n < 2; ++n) _Pragma("unroll") for (int k = 0; k < 2; ++k) \
;         acc[ai][bj][m][n] = __builtin_amdgcn_mfma_f32_16x16x32_bf16(Bt[n][k], At[m][k], acc[ai][bj][m][n], 0, 0, 0); __builtin_amdgcn_s_setprio(0); } while (0)
; #define PG8_WAIT_V(n) asm volatile("s_waitcnt vmcnt(" #n ")" ::: "memory")
; #define PG8_WAIT_L(n) asm volatile("s_waitcnt lgkmcnt(" #n ")" ::: "memory")
; #define PG8_BAR __builtin_amdgcn_s_barrier()
; #define PG8_SCHED __builtin_amdgcn_sched_barrier(0)
; template <class Epi, class Sched, bool ABLK = false, bool ALIGN_EPI = true, bool SP2 = true, bool BBLK = true>
; __device__ __forceinline__ void gemm_phase(LAS unsigned char* lds, const Gemm g, const Sched& S, const Epi& E) {
;     ...
;             PG8_WAIT_V(8); PG8_WAIT_L(0); PG8_BAR; PG8_MMA(1, 0, At, B0); PG8_MMA(1, 1, At, B1); PG8_BAR; PG8_SCHED;
;             PG8_LDB(B0, 1, 0); PG8_LDB(B1, 1, 1); PG8_SCHED; PG8_LDA(At, 1, 0); PG8_STAGE(PG8_SA(0, 1), a2 + hstepA, voffA);
;             PG8_WAIT_V(8); PG8_WAIT_L(0); PG8_BAR; PG8_MMA(0, 0, At, B0); PG8_MMA(0, 1, At, B1); PG8_BAR; PG8_SCHED;
	v_mfma_f32_16x16x32_bf16 v[62:65], v[152:155], v[184:187], v[62:65]
	v_mfma_f32_16x16x32_bf16 v[58:61], v[160:163], v[184:187], v[58:61]
	v_mfma_f32_16x16x32_bf16 v[46:49], v[152:155], v[192:195], v[46:49]
	v_mfma_f32_16x16x32_bf16 v[42:45], v[160:163], v[192:195], v[42:45]
	v_mfma_f32_16x16x32_bf16 v[30:33], v[152:155], v[200:203], v[30:33]
	v_mfma_f32_16x16x32_bf16 v[26:29], v[160:163], v[200:203], v[26:29]
	v_mfma_f32_16x16x32_bf16 v[14:17], v[152:155], v[208:211], v[14:17]
	v_mfma_f32_16x16x32_bf16 v[10:13], v[160:163], v[208:211], v[10:13]
	v_mfma_f32_16x16x32_bf16 v[62:65], v[156:159], v[188:191], v[62:65]
	v_mfma_f32_16x16x32_bf16 v[58:61], v[164:167], v[188:191], v[58:61]
	v_mfma_f32_16x16x32_bf16 v[46:49], v[156:159], v[196:199], v[46:49]
	v_mfma_f32_16x16x32_bf16 v[42:45], v[164:167], v[196:199], v[42:45]
	v_mfma_f32_16x16x32_bf16 v[30:33], v[156:159], v[204:207], v[30:33]
	v_mfma_f32_16x16x32_bf16 v[26:29], v[164:167], v[204:207], v[26:29]
	v_mfma_f32_16x16x32_bf16 v[14:17], v[156:159], v[212:215], v[14:17]
	v_mfma_f32_16x16x32_bf16 v[10:13], v[164:167], v[212:215], v[10:13]
	v_mfma_f32_16x16x32_bf16 v[54:57], v[168:171], v[184:187], v[54:57]
	v_mfma_f32_16x16x32_bf16 v[50:53], v[176:179], v[184:187], v[50:53]
	v_mfma_f32_16x16x32_bf16 v[38:41], v[168:171], v[192:195], v[38:41]
	v_mfma_f32_16x16x32_bf16 v[34:37], v[176:179], v[192:195], v[34:37]
	v_mfma_f32_16x16x32_bf16 v[22:25], v[168:171], v[200:203], v[22:25]
	v_mfma_f32_16x16x32_bf16 v[18:21], v[176:179], v[200:203], v[18:21]
	v_mfma_f32_16x16x32_bf16 v[6:9], v[168:171], v[208:211], v[6:9]
	v_mfma_f32_16x16x32_bf16 v[2:5], v[176:179], v[208:211], v[2:5]
	v_mfma_f32_16x16x32_bf16 v[54:57], v[172:175], v[188:191], v[54:57]
	v_mfma_f32_16x16x32_bf16 v[50:53], v[180:183], v[188:191], v[50:53]
	v_mfma_f32_16x16x32_bf16 v[38:41], v[172:175], v[196:199], v[38:41]
	v_mfma_f32_16x16x32_bf16 v[34:37], v[180:183], v[196:199], v[34:37]
	v_mfma_f32_16x16x32_bf16 v[22:25], v[172:175], v[204:207], v[22:25]
	v_mfma_f32_16x16x32_bf16 v[18:21], v[180:183], v[204:207], v[18:21]
	v_mfma_f32_16x16x32_bf16 v[6:9], v[172:175], v[212:215], v[6:9]
	v_mfma_f32_16x16x32_bf16 v[2:5], v[180:183], v[212:215], v[2:5]
	s_barrier
	v_add_u32_e32 v164, s60, v147
	v_add_u32_e32 v180, s61, v147
	ds_read_b128 v[152:155], v164
	ds_read_b128 v[156:159], v164 offset:1024
	ds_read_b128 v[160:163], v164 offset:2048
	ds_read_b128 v[164:167], v164 offset:3072
	ds_read_b128 v[168:171], v180
	ds_read_b128 v[172:175], v180 offset:1024
	ds_read_b128 v[176:179], v180 offset:2048
	ds_read_b128 v[180:183], v180 offset:3072
	s_add_u32 s28, s28, 0x4000
	s_addc_u32 s29, s29, 0
	s_mov_b32 m0, s37
	v_lshl_add_u64 v[216:217], s[28:29], 0, v[130:131]
	ds_read_b128 v[184:187], v151 offset:32768
	ds_read_b128 v[188:191], v151 offset:33792
	ds_read_b128 v[192:195], v151 offset:34816
	ds_read_b128 v[196:199], v151 offset:35840
	ds_read_b128 v[200:203], v151 offset:36864
	ds_read_b128 v[204:207], v151 offset:37888
	ds_read_b128 v[208:211], v151 offset:38912
	ds_read_b128 v[212:215], v151 offset:39936
	global_load_lds_dwordx4 v[216:217], off
	v_lshl_add_u64 v[216:217], s[28:29], 0, v[132:133]
	s_mov_b32 m0, s40
	s_nop 0
	global_load_lds_dwordx4 v[216:217], off
	s_waitcnt vmcnt(8)
	s_waitcnt lgkmcnt(0)
	s_barrier
	v_mfma_f32_16x16x32_bf16 v[126:129], v[152:155], v[184:187], v[126:129]
	v_mfma_f32_16x16x32_bf16 v[122:125], v[160:163], v[184:187], v[122:125]
	v_mfma_f32_16x16x32_bf16 v[110:113], v[152:155], v[192:195], v[110:113]
	v_mfma_f32_16x16x32_bf16 v[106:109], v[160:163], v[192:195], v[106:109]
	v_mfma_f32_16x16x32_bf16 v[94:97], v[152:155], v[200:203], v[94:97]
	v_mfma_f32_16x16x32_bf16 v[90:93], v[160:163], v[200:203], v[90:93]
	v_mfma_f32_16x16x32_bf16 v[78:81], v[152:155], v[208:211], v[78:81]
	v_mfma_f32_16x16x32_bf16 v[74:77], v[160:163], v[208:211], v[74:77]
	v_mfma_f32_16x16x32_bf16 v[126:129], v[156:159], v[188:191], v[126:129]
	v_mfma_f32_16x16x32_bf16 v[122:125], v[164:167], v[188:191], v[122:125]
	v_mfma_f32_16x16x32_bf16 v[110:113], v[156:159], v[196:199], v[110:113]
	v_mfma_f32_16x16x32_bf16 v[106:109], v[164:167], v[196:199], v[106:109]
	v_mfma_f32_16x16x32_bf16 v[94:97], v[156:159], v[204:207], v[94:97]
	v_mfma_f32_16x16x32_bf16 v[90:93], v[164:167], v[204:207], v[90:93]
	v_mfma_f32_16x16x32_bf16 v[78:81], v[156:159], v[212:215], v[78:81]
	v_mfma_f32_16x16x32_bf16 v[74:77], v[164:167], v[212:215], v[74:77]
	v_mfma_f32_16x16x32_bf16 v[118:121], v[168:171], v[184:187], v[118:121]
	v_mfma_f32_16x16x32_bf16 v[114:117], v[176:179], v[184:187], v[114:117]
	v_mfma_f32_16x16x32_bf16 v[102:105], v[168:171], v[192:195], v[102:105]
	v_mfma_f32_16x16x32_bf16 v[98:101], v[176:179], v[192:195], v[98:101]
	v_mfma_f32_16x16x32_bf16 v[86:89], v[168:171], v[200:203], v[86:89]
	v_mfma_f32_16x16x32_bf16 v[82:85], v[176:179], v[200:203], v[82:85]
	v_mfma_f32_16x16x32_bf16 v[70:73], v[168:171], v[208:211], v[70:73]
	v_mfma_f32_16x16x32_bf16 v[66:69], v[176:179], v[208:211], v[66:69]
	v_mfma_f32_16x16x32_bf16 v[118:121], v[172:175], v[188:191], v[118:121]
	v_mfma_f32_16x16x32_bf16 v[114:117], v[180:183], v[188:191], v[114:117]
	v_mfma_f32_16x16x32_bf16 v[102:105], v[172:175], v[196:199], v[102:105]
	v_mfma_f32_16x16x32_bf16 v[98:101], v[180:183], v[196:199], v[98:101]
	v_mfma_f32_16x16x32_bf16 v[86:89], v[172:175], v[204:207], v[86:89]
	v_mfma_f32_16x16x32_bf16 v[82:85], v[180:183], v[204:207], v[82:85]
	v_mfma_f32_16x16x32_bf16 v[70:73], v[172:175], v[212:215], v[70:73]
	v_mfma_f32_16x16x32_bf16 v[66:69], v[180:183], v[212:215], v[66:69]
	s_barrier
; #define PG8_STAGE(bufoff, gbase, voff) do { _Pragma("unroll") for (int _i = 0; _i < 2; ++_i) \
;         __builtin_amdgcn_global_load_lds((const unsigned*)((const char*)(gbase) + (voff)[_i]), (LAS unsigned*)(lds + (bufoff) + ldsw + _i * 8192), 16, 0, 0); } while (0)
; #define PG8_LDA(dst, b, h) do { _Pragma("unroll") for (int m = 0; m < 4; ++m) _Pragma("unroll") for (int k = 0; k < 2; ++k) dst[m][k] = *(const LAS bf16x8*)(lds + PG8_SA(b, h) + aoff + m * 2048 + k * 1024); } while (0)
; #define PG8_MMA(ai, bj, At, Bt) do { __builtin_amdgcn_s_setprio(1); _Pragma("unroll") for (int m = 0; m < 4; ++m) _Pragma("unroll") for (int n = 0; n < 2; ++n) _Pragma("unroll") for (int k = 0; k < 2; ++k) \
;         acc[ai][bj][m][n] = __builtin_amdgcn_mfma_f32_16x16x32_bf16(Bt[n][k], At[m][k], acc[ai][bj][m][n], 0, 0, 0); __builtin_amdgcn_s_setprio(0); } while (0)
; #define PG8_WAIT_V(n) asm volatile("s_waitcnt vmcnt(" #n ")" ::: "memory")
; #define PG8_WAIT_L(n) asm volatile("s_waitcnt lgkmcnt(" #n ")" ::: "memory")
; #define PG8_BAR __builtin_amdgcn_s_barrier()
; #define PG8_SCHED __builtin_amdgcn_sched_barrier(0)
; template <class Epi, class Sched, bool ABLK = false, bool ALIGN_EPI = true, bool SP2 = true, bool BBLK = true>
; __device__ __forceinline__ void gemm_phase(LAS unsigned char* lds, const Gemm g, const Sched& S, const Epi& E) {
;     ...
;             PG8_LDA(At, 1, 1); PG8_STAGE(PG8_SB(1, 0), b3, voffB); PG8_STAGE(PG8_SB(1, 1), b3 + hstepB, voffB); PG8_STAGE(PG8_SA(1, 0), a3, voffA);
;             PG8_WAIT_V(8); PG8_WAIT_L(0); PG8_BAR; PG8_MMA(1, 0, At, B0); PG8_MMA(1, 1, At, B1); PG8_BAR; PG8_SCHED;
;     ...
;         if constexpr (ALIGN_EPI) { if (wr == 0) PG8_BAR; }
	s_add_u32 s28, s26, 0x8000
	s_addc_u32 s29, s27, 0
	s_add_i32 s59, s60, s34
	v_lshl_add_u64 v[216:217], s[28:29], 0, v[130:131]
	s_mov_b32 m0, s59
	ds_read_b128 v[184:187], v151 offset:49152
	ds_read_b128 v[188:191], v151 offset:50176
	ds_read_b128 v[192:195], v151 offset:51200
	ds_read_b128 v[196:199], v151 offset:52224
	ds_read_b128 v[200:203], v151 offset:53248
	ds_read_b128 v[204:207], v151 offset:54272
	ds_read_b128 v[208:211], v151 offset:55296
	ds_read_b128 v[212:215], v151 offset:56320
	global_load_lds_dwordx4 v[216:217], off
	s_add_i32 m0, s59, 0x2000
	s_add_u32 s26, s26, 0xc000
	v_lshl_add_u64 v[216:217], s[28:29], 0, v[132:133]
	s_addc_u32 s27, s27, 0
	s_add_i32 s28, s61, s34
	global_load_lds_dwordx4 v[216:217], off
	v_lshl_add_u64 v[216:217], s[26:27], 0, v[130:131]
	s_mov_b32 m0, s28
	s_nop 0
	global_load_lds_dwordx4 v[216:217], off
	v_lshl_add_u64 v[216:217], s[26:27], 0, v[132:133]
	s_add_i32 m0, s28, 0x2000
	s_nop 0
	global_load_lds_dwordx4 v[216:217], off
	v_lshl_add_u64 v[216:217], s[24:25], 0, v[130:131]
	s_mov_b32 m0, s41
	s_nop 0
	global_load_lds_dwordx4 v[216:217], off
	v_lshl_add_u64 v[216:217], s[24:25], 0, v[132:133]
	s_mov_b32 m0, s42
	s_nop 0
	global_load_lds_dwordx4 v[216:217], off
	s_waitcnt vmcnt(8)
	s_waitcnt lgkmcnt(0)
	s_barrier
	v_mfma_f32_16x16x32_bf16 v[62:65], v[152:155], v[184:187], v[62:65]
	v_mfma_f32_16x16x32_bf16 v[58:61], v[160:163], v[184:187], v[58:61]
	v_mfma_f32_16x16x32_bf16 v[46:49], v[152:155], v[192:195], v[46:49]
	v_mfma_f32_16x16x32_bf16 v[42:45], v[160:163], v[192:195], v[42:45]
	v_mfma_f32_16x16x32_bf16 v[30:33], v[152:155], v[200:203], v[30:33]
	v_mfma_f32_16x16x32_bf16 v[26:29], v[160:163], v[200:203], v[26:29]
	v_mfma_f32_16x16x32_bf16 v[14:17], v[152:155], v[208:211], v[14:17]
	v_mfma_f32_16x16x32_bf16 v[10:13], v[160:163], v[208:211], v[10:13]
	v_mfma_f32_16x16x32_bf16 v[62:65], v[156:159], v[188:191], v[62:65]
	v_mfma_f32_16x16x32_bf16 v[58:61], v[164:167], v[188:191], v[58:61]
	v_mfma_f32_16x16x32_bf16 v[46:49], v[156:159], v[196:199], v[46:49]
	v_mfma_f32_16x16x32_bf16 v[42:45], v[164:167], v[196:199], v[42:45]
	v_mfma_f32_16x16x32_bf16 v[30:33], v[156:159], v[204:207], v[30:33]
	v_mfma_f32_16x16x32_bf16 v[26:29], v[164:167], v[204:207], v[26:29]
	v_mfma_f32_16x16x32_bf16 v[14:17], v[156:159], v[212:215], v[14:17]
	v_mfma_f32_16x16x32_bf16 v[10:13], v[164:167], v[212:215], v[10:13]
	v_mfma_f32_16x16x32_bf16 v[54:57], v[168:171], v[184:187], v[54:57]
	v_mfma_f32_16x16x32_bf16 v[50:53], v[176:179], v[184:187], v[50:53]
	v_mfma_f32_16x16x32_bf16 v[38:41], v[168:171], v[192:195], v[38:41]
	v_mfma_f32_16x16x32_bf16 v[34:37], v[176:179], v[192:195], v[34:37]
	v_mfma_f32_16x16x32_bf16 v[22:25], v[168:171], v[200:203], v[22:25]
	v_mfma_f32_16x16x32_bf16 v[18:21], v[176:179], v[200:203], v[18:21]
	v_mfma_f32_16x16x32_bf16 v[6:9], v[168:171], v[208:211], v[6:9]
	v_mfma_f32_16x16x32_bf16 v[2:5], v[176:179], v[208:211], v[2:5]
	v_mfma_f32_16x16x32_bf16 v[54:57], v[172:175], v[188:191], v[54:57]
	v_mfma_f32_16x16x32_bf16 v[50:53], v[180:183], v[188:191], v[50:53]
	v_mfma_f32_16x16x32_bf16 v[38:41], v[172:175], v[196:199], v[38:41]
	v_mfma_f32_16x16x32_bf16 v[34:37], v[180:183], v[196:199], v[34:37]
	v_mfma_f32_16x16x32_bf16 v[22:25], v[172:175], v[204:207], v[22:25]
	v_mfma_f32_16x16x32_bf16 v[18:21], v[180:183], v[204:207], v[18:21]
	v_mfma_f32_16x16x32_bf16 v[6:9], v[172:175], v[212:215], v[6:9]
	v_mfma_f32_16x16x32_bf16 v[2:5], v[180:183], v[212:215], v[2:5]
	s_barrier
	s_add_u32 s22, s22, 0x10000
	s_addc_u32 s23, s23, 0
	s_cmp_ge_u32 s57, s44
	s_cbranch_scc0 .LBB0_1229
	s_and_b64 vcc, exec, s[6:7]
	s_cbranch_vccz .LBB0_1232
	s_barrier

; #define PG8_STAGE(bufoff, gbase, voff) do { _Pragma("unroll") for (int _i = 0; _i < 2; ++_i) \
;         __builtin_amdgcn_global_load_lds((const unsigned*)((const char*)(gbase) + (voff)[_i]), (LAS unsigned*)(lds + (bufoff) + ldsw + _i * 8192), 16, 0, 0); } while (0)
; #define PG8_LDA(dst, b, h) do { _Pragma("unroll") for (int m = 0; m < 4; ++m) _Pragma("unroll") for (int k = 0; k < 2; ++k) dst[m][k] = *(const LAS bf16x8*)(lds + PG8_SA(b, h) + aoff + m * 2048 + k * 1024); } while (0)
; #define PG8_LDB(dst, b, h) do { _Pragma("unroll") for (int n = 0; n < 2; ++n) _Pragma("unroll") for (int k = 0; k < 2; ++k) dst[n][k] = *(const LAS bf16x8*)(lds + PG8_SB(b, h) + boff + n * 2048 + k * 1024); } while (0)
; #define PG8_MMA(ai, bj, At, Bt) do { __builtin_amdgcn_s_setprio(1); _Pragma("unroll") for (int m = 0; m < 4; ++m) _Pragma("unroll") for (int n = 0; n < 2; ++n) _Pragma("unroll") for (int k = 0; k < 2; ++k) \
;         acc[ai][bj][m][n] = __builtin_amdgcn_mfma_f32_16x16x32_bf16(Bt[n][k], At[m][k], acc[ai][bj][m][n], 0, 0, 0); __builtin_amdgcn_s_setprio(0); } while (0)
; #define PG8_WAIT_V(n) asm volatile("s_waitcnt vmcnt(" #n ")" ::: "memory")
; #define PG8_BAR __builtin_amdgcn_s_barrier()
; template <class Epi, class Sched, bool ABLK = false, bool ALIGN_EPI = true, bool SP2 = true, bool BBLK = true>
; __device__ __forceinline__ void gemm_phase(LAS unsigned char* lds, const Gemm g, const Sched& S, const Epi& E) {
;     ...
;             const bool last = (t == nt - 2);
;             const char* a1 = a_tile(uA, tbA + t + 1);
;             const char* a2 = last ? a_tile(nuA, ntbA) : a_tile(uA, tbA + t + 2); const char* b2 = last ? nB : cB + (size_t)(t + 2) * kstepB;
;             const char* a3 = last ? a_tile(nuA, ntbA + 1) : a_tile(uA, tbA + t + 3); const char* b3 = b2 + kstepB;
;             if (last && has_next) S.a_ready(nxt);
;             if constexpr (SP2) {
;             PG8_LDB(B0, 0, 0); PG8_LDB(B1, 0, 1); PG8_SCHED; PG8_LDA(At, 0, 0); PG8_STAGE(PG8_SA(1, 1), a1 + hstepA, voffA);
;             PG8_WAIT_V(8); PG8_WAIT_L(0); PG8_BAR; PG8_MMA(0, 0, At, B0); PG8_MMA(0, 1, At, B1); PG8_BAR; PG8_SCHED;
;             PG8_LDA(At, 0, 1); PG8_STAGE(PG8_SB(0, 0), b2, voffB); PG8_STAGE(PG8_SB(0, 1), b2 + hstepB, voffB); PG8_STAGE(PG8_SA(0, 0), a2, voffA);
;             PG8_WAIT_V(8); PG8_WAIT_L(0); PG8_BAR; PG8_MMA(1, 0, At, B0); PG8_MMA(1, 1, At, B1); PG8_BAR; PG8_SCHED;
.LBB0_1355:
	ds_read_b128 v[152:155], v163
	ds_read_b128 v[156:159], v163 offset:1024
	ds_read_b128 v[166:169], v163 offset:2048
	ds_read_b128 v[170:173], v163 offset:3072
	ds_read_b128 v[174:177], v164
	ds_read_b128 v[178:181], v164 offset:1024
	ds_read_b128 v[182:185], v164 offset:2048
	ds_read_b128 v[186:189], v164 offset:3072
	s_add_u32 s42, s36, s40
	s_addc_u32 s43, s37, s41
	s_add_u32 s46, s42, 0x100
	s_addc_u32 s47, s43, 0
	s_add_u32 s42, s42, 0x180
	s_addc_u32 s43, s43, 0
	s_cmpk_eq_i32 s40, 0xf00
	s_cselect_b32 s43, s57, s43
	s_cselect_b32 s42, s56, s42
	s_cselect_b32 s45, s21, s64
	s_cselect_b32 s44, s23, s59
	s_cselect_b32 s47, s4, s47
	s_cselect_b32 s46, s5, s46
	v_lshl_add_u64 v[222:223], v[148:149], 0, s[40:41]
	s_add_i32 m0, s31, 0xc000
	ds_read_b128 v[190:193], v165
	ds_read_b128 v[194:197], v165 offset:1024
	ds_read_b128 v[198:201], v165 offset:2048
	ds_read_b128 v[202:205], v165 offset:3072
	ds_read_b128 v[206:209], v165 offset:4096
	ds_read_b128 v[210:213], v165 offset:5120
	ds_read_b128 v[214:217], v165 offset:6144
	ds_read_b128 v[218:221], v165 offset:7168
	global_load_lds_dwordx4 v[222:223], off
	v_lshl_add_u64 v[222:223], v[150:151], 0, s[40:41]
	s_add_i32 m0, s31, 0xe000
	s_nop 0
	global_load_lds_dwordx4 v[222:223], off
	s_waitcnt vmcnt(8)
	s_waitcnt lgkmcnt(0)
	s_barrier
	v_mfma_f32_16x16x32_bf16 v[126:129], v[152:155], v[190:193], v[126:129]
	v_mfma_f32_16x16x32_bf16 v[122:125], v[166:169], v[190:193], v[122:125]
	v_mfma_f32_16x16x32_bf16 v[110:113], v[152:155], v[198:201], v[110:113]
	v_mfma_f32_16x16x32_bf16 v[106:109], v[166:169], v[198:201], v[106:109]
	v_mfma_f32_16x16x32_bf16 v[94:97], v[152:155], v[206:209], v[94:97]
	v_mfma_f32_16x16x32_bf16 v[90:93], v[166:169], v[206:209], v[90:93]
	v_mfma_f32_16x16x32_bf16 v[78:81], v[152:155], v[214:217], v[78:81]
	v_mfma_f32_16x16x32_bf16 v[74:77], v[166:169], v[214:217], v[74:77]
	v_mfma_f32_16x16x32_bf16 v[126:129], v[156:159], v[194:197], v[126:129]
	v_mfma_f32_16x16x32_bf16 v[122:125], v[170:173], v[194:197], v[122:125]
	v_mfma_f32_16x16x32_bf16 v[110:113], v[156:159], v[202:205], v[110:113]
	v_mfma_f32_16x16x32_bf16 v[106:109], v[170:173], v[202:205], v[106:109]
	v_mfma_f32_16x16x32_bf16 v[94:97], v[156:159], v[210:213], v[94:97]
	v_mfma_f32_16x16x32_bf16 v[90:93], v[170:173], v[210:213], v[90:93]
	v_mfma_f32_16x16x32_bf16 v[78:81], v[156:159], v[218:221], v[78:81]
	v_mfma_f32_16x16x32_bf16 v[74:77], v[170:173], v[218:221], v[74:77]
	v_mfma_f32_16x16x32_bf16 v[118:121], v[174:177], v[190:193], v[118:121]
	v_mfma_f32_16x16x32_bf16 v[114:117], v[182:185], v[190:193], v[114:117]
	v_mfma_f32_16x16x32_bf16 v[102:105], v[174:177], v[198:201], v[102:105]
	v_mfma_f32_16x16x32_bf16 v[98:101], v[182:185], v[198:201], v[98:101]
	v_mfma_f32_16x16x32_bf16 v[86:89], v[174:177], v[206:209], v[86:89]
	v_mfma_f32_16x16x32_bf16 v[82:85], v[182:185], v[206:209], v[82:85]
	v_mfma_f32_16x16x32_bf16 v[70:73], v[174:177], v[214:217], v[70:73]
	v_mfma_f32_16x16x32_bf16 v[66:69], v[182:185], v[214:217], v[66:69]
	v_mfma_f32_16x16x32_bf16 v[118:121], v[178:181], v[194:197], v[118:121]
	v_mfma_f32_16x16x32_bf16 v[114:117], v[186:189], v[194:197], v[114:117]
	v_mfma_f32_16x16x32_bf16 v[102:105], v[178:181], v[202:205], v[102:105]
	v_mfma_f32_16x16x32_bf16 v[98:101], v[186:189], v[202:205], v[98:101]
	v_mfma_f32_16x16x32_bf16 v[86:89], v[178:181], v[210:213], v[86:89]
	v_mfma_f32_16x16x32_bf16 v[82:85], v[186:189], v[210:213], v[82:85]
	v_mfma_f32_16x16x32_bf16 v[70:73], v[178:181], v[218:221], v[70:73]
	v_mfma_f32_16x16x32_bf16 v[66:69], v[186:189], v[218:221], v[66:69]
	s_barrier
	s_add_i32 s66, s72, s49
	v_lshl_add_u64 v[222:223], s[44:45], 0, v[134:135]
	s_mov_b32 m0, s66
	ds_read_b128 v[190:193], v165 offset:16384
	ds_read_b128 v[194:197], v165 offset:17408
	ds_read_b128 v[198:201], v165 offset:18432
	ds_read_b128 v[202:205], v165 offset:19456
	ds_read_b128 v[206:209], v165 offset:20480
	ds_read_b128 v[210:213], v165 offset:21504
	ds_read_b128 v[214:217], v165 offset:22528
	ds_read_b128 v[218:221], v165 offset:23552
	global_load_lds_dwordx4 v[222:223], off
	s_add_i32 m0, s66, 0x2000
	s_add_u32 s66, s44, 0x4000
	v_lshl_add_u64 v[222:223], s[44:45], 0, v[130:131]
	s_addc_u32 s67, s45, 0
	s_add_i32 s75, s73, s49
	global_load_lds_dwordx4 v[222:223], off
	v_lshl_add_u64 v[222:223], s[66:67], 0, v[134:135]
	s_mov_b32 m0, s75
	s_nop 0
	global_load_lds_dwordx4 v[222:223], off
	v_lshl_add_u64 v[222:223], s[66:67], 0, v[130:131]
	s_add_i32 m0, s75, 0x2000
	s_nop 0
	global_load_lds_dwordx4 v[222:223], off
	v_lshl_add_u64 v[222:223], s[46:47], 0, v[136:137]
	s_mov_b32 m0, s31
	s_nop 0
	global_load_lds_dwordx4 v[222:223], off
	v_lshl_add_u64 v[222:223], s[46:47], 0, v[132:133]
	s_mov_b32 m0, s35
	s_nop 0
	global_load_lds_dwordx4 v[222:223], off
	s_waitcnt vmcnt(8)
	s_waitcnt lgkmcnt(0)
	s_barrier
; #define PG8_STAGE(bufoff, gbase, voff) do { _Pragma("unroll") for (int _i = 0; _i < 2; ++_i) \
;         __builtin_amdgcn_global_load_lds((const unsigned*)((const char*)(gbase) + (voff)[_i]), (LAS unsigned*)(lds + (bufoff) + ldsw + _i * 8192), 16, 0, 0); } while (0)
; #define PG8_LDA(dst, b, h) do { _Pragma("unroll") for (int m = 0; m < 4; ++m) _Pragma("unroll") for (int k = 0; k < 2; ++k) dst[m][k] = *(const LAS bf16x8*)(lds + PG8_SA(b, h) + aoff + m * 2048 + k * 1024); } while (0)
; #define PG8_LDB(dst, b, h) do { _Pragma("unroll") for (int n = 0; n < 2; ++n) _Pragma("unroll") for (int k = 0; k < 2; ++k) dst[n][k] = *(const LAS bf16x8*)(lds + PG8_SB(b, h) + boff + n * 2048 + k * 1024); } while (0)
; #define PG8_MMA(ai, bj, At, Bt) do { __builtin_amdgcn_s_setprio(1); _Pragma("unroll") for (int m = 0; m < 4; ++m) _Pragma("unroll") for (int n = 0; n < 2; ++n) _Pragma("unroll") for (int k = 0; k < 2; ++k) \
;         acc[ai][bj][m][n] = __builtin_amdgcn_mfma_f32_16x16x32_bf16(Bt[n][k], At[m][k], acc[ai][bj][m][n], 0, 0, 0); __builtin_amdgcn_s_setprio(0); } while (0)
; #define PG8_WAIT_V(n) asm volatile("s_waitcnt vmcnt(" #n ")" ::: "memory")
; #define PG8_WAIT_L(n) asm volatile("s_waitcnt lgkmcnt(" #n ")" ::: "memory")
; #define PG8_BAR __builtin_amdgcn_s_barrier()
; #define PG8_SCHED __builtin_amdgcn_sched_barrier(0)
; template <class Epi, class Sched, bool ABLK = false, bool ALIGN_EPI = true, bool SP2 = true, bool BBLK = true>
; __device__ __forceinline__ void gemm_phase(LAS unsigned char* lds, const Gemm g, const Sched& S, const Epi& E) {
;     ...
;             PG8_WAIT_V(8); PG8_WAIT_L(0); PG8_BAR; PG8_MMA(1, 0, At, B0); PG8_MMA(1, 1, At, B1); PG8_BAR; PG8_SCHED;
;             PG8_LDB(B0, 1, 0); PG8_LDB(B1, 1, 1); PG8_SCHED; PG8_LDA(At, 1, 0); PG8_STAGE(PG8_SA(0, 1), a2 + hstepA, voffA);
;             PG8_WAIT_V(8); PG8_WAIT_L(0); PG8_BAR; PG8_MMA(0, 0, At, B0); PG8_MMA(0, 1, At, B1); PG8_BAR; PG8_SCHED;
	v_mfma_f32_16x16x32_bf16 v[62:65], v[152:155], v[190:193], v[62:65]
	v_mfma_f32_16x16x32_bf16 v[58:61], v[166:169], v[190:193], v[58:61]
	v_mfma_f32_16x16x32_bf16 v[46:49], v[152:155], v[198:201], v[46:49]
	v_mfma_f32_16x16x32_bf16 v[42:45], v[166:169], v[198:201], v[42:45]
	v_mfma_f32_16x16x32_bf16 v[30:33], v[152:155], v[206:209], v[30:33]
	v_mfma_f32_16x16x32_bf16 v[26:29], v[166:169], v[206:209], v[26:29]
	v_mfma_f32_16x16x32_bf16 v[14:17], v[152:155], v[214:217], v[14:17]
	v_mfma_f32_16x16x32_bf16 v[10:13], v[166:169], v[214:217], v[10:13]
	v_mfma_f32_16x16x32_bf16 v[62:65], v[156:159], v[194:197], v[62:65]
	v_mfma_f32_16x16x32_bf16 v[58:61], v[170:173], v[194:197], v[58:61]
	v_mfma_f32_16x16x32_bf16 v[46:49], v[156:159], v[202:205], v[46:49]
	v_mfma_f32_16x16x32_bf16 v[42:45], v[170:173], v[202:205], v[42:45]
	v_mfma_f32_16x16x32_bf16 v[30:33], v[156:159], v[210:213], v[30:33]
	v_mfma_f32_16x16x32_bf16 v[26:29], v[170:173], v[210:213], v[26:29]
	v_mfma_f32_16x16x32_bf16 v[14:17], v[156:159], v[218:221], v[14:17]
	v_mfma_f32_16x16x32_bf16 v[10:13], v[170:173], v[218:221], v[10:13]
	v_mfma_f32_16x16x32_bf16 v[54:57], v[174:177], v[190:193], v[54:57]
	v_mfma_f32_16x16x32_bf16 v[50:53], v[182:185], v[190:193], v[50:53]
	v_mfma_f32_16x16x32_bf16 v[38:41], v[174:177], v[198:201], v[38:41]
	v_mfma_f32_16x16x32_bf16 v[34:37], v[182:185], v[198:201], v[34:37]
	v_mfma_f32_16x16x32_bf16 v[22:25], v[174:177], v[206:209], v[22:25]
	v_mfma_f32_16x16x32_bf16 v[18:21], v[182:185], v[206:209], v[18:21]
	v_mfma_f32_16x16x32_bf16 v[6:9], v[174:177], v[214:217], v[6:9]
	v_mfma_f32_16x16x32_bf16 v[2:5], v[182:185], v[214:217], v[2:5]
	v_mfma_f32_16x16x32_bf16 v[54:57], v[178:181], v[194:197], v[54:57]
	v_mfma_f32_16x16x32_bf16 v[50:53], v[186:189], v[194:197], v[50:53]
	v_mfma_f32_16x16x32_bf16 v[38:41], v[178:181], v[202:205], v[38:41]
	v_mfma_f32_16x16x32_bf16 v[34:37], v[186:189], v[202:205], v[34:37]
	v_mfma_f32_16x16x32_bf16 v[22:25], v[178:181], v[210:213], v[22:25]
	v_mfma_f32_16x16x32_bf16 v[18:21], v[186:189], v[210:213], v[18:21]
	v_mfma_f32_16x16x32_bf16 v[6:9], v[178:181], v[218:221], v[6:9]
	v_mfma_f32_16x16x32_bf16 v[2:5], v[186:189], v[218:221], v[2:5]
	s_barrier
	v_add_u32_e32 v138, s60, v161
	ds_read_b128 v[152:155], v138
	ds_read_b128 v[156:159], v138 offset:1024
	ds_read_b128 v[166:169], v138 offset:2048
	ds_read_b128 v[170:173], v138 offset:3072
	v_add_u32_e32 v138, s61, v161
	ds_read_b128 v[174:177], v138
	ds_read_b128 v[178:181], v138 offset:1024
	ds_read_b128 v[182:185], v138 offset:2048
	ds_read_b128 v[186:189], v138 offset:3072
	s_add_u32 s46, s46, 0x80000
	s_addc_u32 s47, s47, 0
	s_mov_b32 m0, s50
	v_lshl_add_u64 v[222:223], s[46:47], 0, v[136:137]
	ds_read_b128 v[190:193], v165 offset:32768
	ds_read_b128 v[194:197], v165 offset:33792
	ds_read_b128 v[198:201], v165 offset:34816
	ds_read_b128 v[202:205], v165 offset:35840
	ds_read_b128 v[206:209], v165 offset:36864
	ds_read_b128 v[210:213], v165 offset:37888
	ds_read_b128 v[214:217], v165 offset:38912
	ds_read_b128 v[218:221], v165 offset:39936
	global_load_lds_dwordx4 v[222:223], off
	v_lshl_add_u64 v[222:223], s[46:47], 0, v[132:133]
	s_mov_b32 m0, s51
	s_nop 0
	global_load_lds_dwordx4 v[222:223], off
	s_waitcnt vmcnt(8)
	s_waitcnt lgkmcnt(0)
	s_barrier
	v_mfma_f32_16x16x32_bf16 v[126:129], v[152:155], v[190:193], v[126:129]
	v_mfma_f32_16x16x32_bf16 v[122:125], v[166:169], v[190:193], v[122:125]
	v_mfma_f32_16x16x32_bf16 v[110:113], v[152:155], v[198:201], v[110:113]
	v_mfma_f32_16x16x32_bf16 v[106:109], v[166:169], v[198:201], v[106:109]
	v_mfma_f32_16x16x32_bf16 v[94:97], v[152:155], v[206:209], v[94:97]
	v_mfma_f32_16x16x32_bf16 v[90:93], v[166:169], v[206:209], v[90:93]
	v_mfma_f32_16x16x32_bf16 v[78:81], v[152:155], v[214:217], v[78:81]
	v_mfma_f32_16x16x32_bf16 v[74:77], v[166:169], v[214:217], v[74:77]
	v_mfma_f32_16x16x32_bf16 v[126:129], v[156:159], v[194:197], v[126:129]
	v_mfma_f32_16x16x32_bf16 v[122:125], v[170:173], v[194:197], v[122:125]
	v_mfma_f32_16x16x32_bf16 v[110:113], v[156:159], v[202:205], v[110:113]
	v_mfma_f32_16x16x32_bf16 v[106:109], v[170:173], v[202:205], v[106:109]
	v_mfma_f32_16x16x32_bf16 v[94:97], v[156:159], v[210:213], v[94:97]
	v_mfma_f32_16x16x32_bf16 v[90:93], v[170:173], v[210:213], v[90:93]
	v_mfma_f32_16x16x32_bf16 v[78:81], v[156:159], v[218:221], v[78:81]
	v_mfma_f32_16x16x32_bf16 v[74:77], v[170:173], v[218:221], v[74:77]
	v_mfma_f32_16x16x32_bf16 v[118:121], v[174:177], v[190:193], v[118:121]
	v_mfma_f32_16x16x32_bf16 v[114:117], v[182:185], v[190:193], v[114:117]
	v_mfma_f32_16x16x32_bf16 v[102:105], v[174:177], v[198:201], v[102:105]
	v_mfma_f32_16x16x32_bf16 v[98:101], v[182:185], v[198:201], v[98:101]
	v_mfma_f32_16x16x32_bf16 v[86:89], v[174:177], v[206:209], v[86:89]
	v_mfma_f32_16x16x32_bf16 v[82:85], v[182:185], v[206:209], v[82:85]
	v_mfma_f32_16x16x32_bf16 v[70:73], v[174:177], v[214:217], v[70:73]
	v_mfma_f32_16x16x32_bf16 v[66:69], v[182:185], v[214:217], v[66:69]
	v_mfma_f32_16x16x32_bf16 v[118:121], v[178:181], v[194:197], v[118:121]
	v_mfma_f32_16x16x32_bf16 v[114:117], v[186:189], v[194:197], v[114:117]
	v_mfma_f32_16x16x32_bf16 v[102:105], v[178:181], v[202:205], v[102:105]
	v_mfma_f32_16x16x32_bf16 v[98:101], v[186:189], v[202:205], v[98:101]
	v_mfma_f32_16x16x32_bf16 v[86:89], v[178:181], v[210:213], v[86:89]
	v_mfma_f32_16x16x32_bf16 v[82:85], v[186:189], v[210:213], v[82:85]
	v_mfma_f32_16x16x32_bf16 v[70:73], v[178:181], v[218:221], v[70:73]
	v_mfma_f32_16x16x32_bf16 v[66:69], v[186:189], v[218:221], v[66:69]
	s_barrier
; #define PG8_STAGE(bufoff, gbase, voff) do { _Pragma("unroll") for (int _i = 0; _i < 2; ++_i) \
;         __builtin_amdgcn_global_load_lds((const unsigned*)((const char*)(gbase) + (voff)[_i]), (LAS unsigned*)(lds + (bufoff) + ldsw + _i * 8192), 16, 0, 0); } while (0)
; #define PG8_LDA(dst, b, h) do { _Pragma("unroll") for (int m = 0; m < 4; ++m) _Pragma("unroll") for (int k = 0; k < 2; ++k) dst[m][k] = *(const LAS bf16x8*)(lds + PG8_SA(b, h) + aoff + m * 2048 + k * 1024); } while (0)
; #define PG8_MMA(ai, bj, At, Bt) do { __builtin_amdgcn_s_setprio(1); _Pragma("unroll") for (int m = 0; m < 4; ++m) _Pragma("unroll") for (int n = 0; n < 2; ++n) _Pragma("unroll") for (int k = 0; k < 2; ++k) \
;         acc[ai][bj][m][n] = __builtin_amdgcn_mfma_f32_16x16x32_bf16(Bt[n][k], At[m][k], acc[ai][bj][m][n], 0, 0, 0); __builtin_amdgcn_s_setprio(0); } while (0)
; #define PG8_WAIT_V(n) asm volatile("s_waitcnt vmcnt(" #n ")" ::: "memory")
; #define PG8_WAIT_L(n) asm volatile("s_waitcnt lgkmcnt(" #n ")" ::: "memory")
; #define PG8_BAR __builtin_amdgcn_s_barrier()
; #define PG8_SCHED __builtin_amdgcn_sched_barrier(0)
; template <class Epi, class Sched, bool ABLK = false, bool ALIGN_EPI = true, bool SP2 = true, bool BBLK = true>
; __device__ __forceinline__ void gemm_phase(LAS unsigned char* lds, const Gemm g, const Sched& S, const Epi& E) {
;     ...
;             PG8_LDA(At, 1, 1); PG8_STAGE(PG8_SB(1, 0), b3, voffB); PG8_STAGE(PG8_SB(1, 1), b3 + hstepB, voffB); PG8_STAGE(PG8_SA(1, 0), a3, voffA);
;             PG8_WAIT_V(8); PG8_WAIT_L(0); PG8_BAR; PG8_MMA(1, 0, At, B0); PG8_MMA(1, 1, At, B1); PG8_BAR; PG8_SCHED;
;     ...
;         if constexpr (ALIGN_EPI) { if (wr == 0) PG8_BAR; }
	s_add_u32 s46, s44, 0x8000
	s_addc_u32 s47, s45, 0
	s_add_i32 s66, s60, s49
	v_lshl_add_u64 v[222:223], s[46:47], 0, v[134:135]
	s_mov_b32 m0, s66
	ds_read_b128 v[190:193], v165 offset:49152
	ds_read_b128 v[194:197], v165 offset:50176
	ds_read_b128 v[198:201], v165 offset:51200
	ds_read_b128 v[202:205], v165 offset:52224
	ds_read_b128 v[206:209], v165 offset:53248
	ds_read_b128 v[210:213], v165 offset:54272
	ds_read_b128 v[214:217], v165 offset:55296
	ds_read_b128 v[218:221], v165 offset:56320
	global_load_lds_dwordx4 v[222:223], off
	s_add_i32 m0, s66, 0x2000
	s_add_u32 s44, s44, 0xc000
	v_lshl_add_u64 v[222:223], s[46:47], 0, v[130:131]
	s_addc_u32 s45, s45, 0
	s_add_i32 s46, s61, s49
	global_load_lds_dwordx4 v[222:223], off
	v_lshl_add_u64 v[222:223], s[44:45], 0, v[134:135]
	s_mov_b32 m0, s46
	s_nop 0
	global_load_lds_dwordx4 v[222:223], off
	v_lshl_add_u64 v[222:223], s[44:45], 0, v[130:131]
	s_add_i32 m0, s46, 0x2000
	s_nop 0
	global_load_lds_dwordx4 v[222:223], off
	v_lshl_add_u64 v[222:223], s[42:43], 0, v[136:137]
	s_mov_b32 m0, s54
	s_nop 0
	global_load_lds_dwordx4 v[222:223], off
	v_lshl_add_u64 v[222:223], s[42:43], 0, v[132:133]
	s_mov_b32 m0, s55
	s_nop 0
	global_load_lds_dwordx4 v[222:223], off
	s_waitcnt vmcnt(8)
	s_waitcnt lgkmcnt(0)
	s_barrier
	v_mfma_f32_16x16x32_bf16 v[62:65], v[152:155], v[190:193], v[62:65]
	v_mfma_f32_16x16x32_bf16 v[58:61], v[166:169], v[190:193], v[58:61]
	v_mfma_f32_16x16x32_bf16 v[46:49], v[152:155], v[198:201], v[46:49]
	v_mfma_f32_16x16x32_bf16 v[42:45], v[166:169], v[198:201], v[42:45]
	v_mfma_f32_16x16x32_bf16 v[30:33], v[152:155], v[206:209], v[30:33]
	v_mfma_f32_16x16x32_bf16 v[26:29], v[166:169], v[206:209], v[26:29]
	v_mfma_f32_16x16x32_bf16 v[14:17], v[152:155], v[214:217], v[14:17]
	v_mfma_f32_16x16x32_bf16 v[10:13], v[166:169], v[214:217], v[10:13]
	v_mfma_f32_16x16x32_bf16 v[62:65], v[156:159], v[194:197], v[62:65]
	v_mfma_f32_16x16x32_bf16 v[58:61], v[170:173], v[194:197], v[58:61]
	v_mfma_f32_16x16x32_bf16 v[46:49], v[156:159], v[202:205], v[46:49]
	v_mfma_f32_16x16x32_bf16 v[42:45], v[170:173], v[202:205], v[42:45]
	v_mfma_f32_16x16x32_bf16 v[30:33], v[156:159], v[210:213], v[30:33]
	v_mfma_f32_16x16x32_bf16 v[26:29], v[170:173], v[210:213], v[26:29]
	v_mfma_f32_16x16x32_bf16 v[14:17], v[156:159], v[218:221], v[14:17]
	v_mfma_f32_16x16x32_bf16 v[10:13], v[170:173], v[218:221], v[10:13]
	v_mfma_f32_16x16x32_bf16 v[54:57], v[174:177], v[190:193], v[54:57]
	v_mfma_f32_16x16x32_bf16 v[50:53], v[182:185], v[190:193], v[50:53]
	v_mfma_f32_16x16x32_bf16 v[38:41], v[174:177], v[198:201], v[38:41]
	v_mfma_f32_16x16x32_bf16 v[34:37], v[182:185], v[198:201], v[34:37]
	v_mfma_f32_16x16x32_bf16 v[22:25], v[174:177], v[206:209], v[22:25]
	v_mfma_f32_16x16x32_bf16 v[18:21], v[182:185], v[206:209], v[18:21]
	v_mfma_f32_16x16x32_bf16 v[6:9], v[174:177], v[214:217], v[6:9]
	v_mfma_f32_16x16x32_bf16 v[2:5], v[182:185], v[214:217], v[2:5]
	v_mfma_f32_16x16x32_bf16 v[54:57], v[178:181], v[194:197], v[54:57]
	v_mfma_f32_16x16x32_bf16 v[50:53], v[186:189], v[194:197], v[50:53]
	v_mfma_f32_16x16x32_bf16 v[38:41], v[178:181], v[202:205], v[38:41]
	v_mfma_f32_16x16x32_bf16 v[34:37], v[186:189], v[202:205], v[34:37]
	v_mfma_f32_16x16x32_bf16 v[22:25], v[178:181], v[210:213], v[22:25]
	v_mfma_f32_16x16x32_bf16 v[18:21], v[186:189], v[210:213], v[18:21]
	v_mfma_f32_16x16x32_bf16 v[6:9], v[178:181], v[218:221], v[6:9]
	v_mfma_f32_16x16x32_bf16 v[2:5], v[186:189], v[218:221], v[2:5]
	s_barrier
	s_add_i32 s65, s65, 2
	s_add_u32 s40, s40, 0x100
	s_addc_u32 s41, s41, 0
	s_add_u32 s59, s59, 0x10000
	s_addc_u32 s64, s64, 0
	s_cmp_gt_u32 s65, 29
	s_cbranch_scc0 .LBB0_1355
	s_and_b64 vcc, exec, s[12:13]
	s_cbranch_vccz .LBB0_1358
	s_barrier

; #define PG8_STAGE(bufoff, gbase, voff) do { _Pragma("unroll") for (int _i = 0; _i < 2; ++_i) \
;         __builtin_amdgcn_global_load_lds((const unsigned*)((const char*)(gbase) + (voff)[_i]), (LAS unsigned*)(lds + (bufoff) + ldsw + _i * 8192), 16, 0, 0); } while (0)
; #define PG8_LDA(dst, b, h) do { _Pragma("unroll") for (int m = 0; m < 4; ++m) _Pragma("unroll") for (int k = 0; k < 2; ++k) dst[m][k] = *(const LAS bf16x8*)(lds + PG8_SA(b, h) + aoff + m * 2048 + k * 1024); } while (0)
; #define PG8_LDB(dst, b, h) do { _Pragma("unroll") for (int n = 0; n < 2; ++n) _Pragma("unroll") for (int k = 0; k < 2; ++k) dst[n][k] = *(const LAS bf16x8*)(lds + PG8_SB(b, h) + boff + n * 2048 + k * 1024); } while (0)
; #define PG8_MMA(ai, bj, At, Bt) do { __builtin_amdgcn_s_setprio(1); _Pragma("unroll") for (int m = 0; m < 4; ++m) _Pragma("unroll") for (int n = 0; n < 2; ++n) _Pragma("unroll") for (int k = 0; k < 2; ++k) \
;         acc[ai][bj][m][n] = __builtin_amdgcn_mfma_f32_16x16x32_bf16(Bt[n][k], At[m][k], acc[ai][bj][m][n], 0, 0, 0); __builtin_amdgcn_s_setprio(0); } while (0)
; #define PG8_WAIT_V(n) asm volatile("s_waitcnt vmcnt(" #n ")" ::: "memory")
; #define PG8_BAR __builtin_amdgcn_s_barrier()
; template <class Epi, class Sched, bool ABLK = false, bool ALIGN_EPI = true, bool SP2 = true, bool BBLK = true>
; __device__ __forceinline__ void gemm_phase(LAS unsigned char* lds, const Gemm g, const Sched& S, const Epi& E) {
;     ...
;             const bool last = (t == nt - 2);
;             const char* a1 = a_tile(uA, tbA + t + 1);
;             const char* a2 = last ? a_tile(nuA, ntbA) : a_tile(uA, tbA + t + 2); const char* b2 = last ? nB : cB + (size_t)(t + 2) * kstepB;
;             const char* a3 = last ? a_tile(nuA, ntbA + 1) : a_tile(uA, tbA + t + 3); const char* b3 = b2 + kstepB;
;             if (last && has_next) S.a_ready(nxt);
;             if constexpr (SP2) {
;             PG8_LDB(B0, 0, 0); PG8_LDB(B1, 0, 1); PG8_SCHED; PG8_LDA(At, 0, 0); PG8_STAGE(PG8_SA(1, 1), a1 + hstepA, voffA);
;             PG8_WAIT_V(8); PG8_WAIT_L(0); PG8_BAR; PG8_MMA(0, 0, At, B0); PG8_MMA(0, 1, At, B1); PG8_BAR; PG8_SCHED;
;             PG8_LDA(At, 0, 1); PG8_STAGE(PG8_SB(0, 0), b2, voffB); PG8_STAGE(PG8_SB(0, 1), b2 + hstepB, voffB); PG8_STAGE(PG8_SA(0, 0), a2, voffA);
;             PG8_WAIT_V(8); PG8_WAIT_L(0); PG8_BAR; PG8_MMA(1, 0, At, B0); PG8_MMA(1, 1, At, B1); PG8_BAR; PG8_SCHED;
.LBB0_1716:
	ds_read_b128 v[156:159], v152
	ds_read_b128 v[160:163], v152 offset:1024
	ds_read_b128 v[164:167], v152 offset:2048
	ds_read_b128 v[168:171], v152 offset:3072
	ds_read_b128 v[172:175], v153
	ds_read_b128 v[176:179], v153 offset:1024
	ds_read_b128 v[180:183], v153 offset:2048
	ds_read_b128 v[184:187], v153 offset:3072
	s_add_u32 s28, s54, s26
	s_addc_u32 s29, s55, s27
	s_add_u32 s34, s28, 0x100
	s_addc_u32 s35, s29, 0
	s_add_i32 s57, s57, 2
	s_add_u32 s28, s28, 0x180
	s_addc_u32 s29, s29, 0
	s_cmp_eq_u32 s56, s26
	s_cselect_b32 s29, s51, s29
	s_cselect_b32 s28, s50, s28
	s_cselect_b32 s31, s4, s53
	s_cselect_b32 s30, s5, s52
	s_cselect_b32 s35, s49, s35
	s_cselect_b32 s34, s23, s34
	v_lshl_add_u64 v[220:221], v[146:147], 0, s[26:27]
	s_add_i32 m0, s40, 0xc000
	ds_read_b128 v[188:191], v154
	ds_read_b128 v[192:195], v154 offset:1024
	ds_read_b128 v[196:199], v154 offset:2048
	ds_read_b128 v[200:203], v154 offset:3072
	ds_read_b128 v[204:207], v154 offset:4096
	ds_read_b128 v[208:211], v154 offset:5120
	ds_read_b128 v[212:215], v154 offset:6144
	ds_read_b128 v[216:219], v154 offset:7168
	global_load_lds_dwordx4 v[220:221], off
	v_lshl_add_u64 v[220:221], v[148:149], 0, s[26:27]
	s_add_i32 m0, s40, 0xe000
	s_nop 0
	global_load_lds_dwordx4 v[220:221], off
	s_waitcnt vmcnt(8)
	s_waitcnt lgkmcnt(0)
	s_barrier
	v_mfma_f32_16x16x32_bf16 v[126:129], v[156:159], v[188:191], v[126:129]
	v_mfma_f32_16x16x32_bf16 v[122:125], v[164:167], v[188:191], v[122:125]
	v_mfma_f32_16x16x32_bf16 v[110:113], v[156:159], v[196:199], v[110:113]
	v_mfma_f32_16x16x32_bf16 v[106:109], v[164:167], v[196:199], v[106:109]
	v_mfma_f32_16x16x32_bf16 v[94:97], v[156:159], v[204:207], v[94:97]
	v_mfma_f32_16x16x32_bf16 v[90:93], v[164:167], v[204:207], v[90:93]
	v_mfma_f32_16x16x32_bf16 v[78:81], v[156:159], v[212:215], v[78:81]
	v_mfma_f32_16x16x32_bf16 v[74:77], v[164:167], v[212:215], v[74:77]
	v_mfma_f32_16x16x32_bf16 v[126:129], v[160:163], v[192:195], v[126:129]
	v_mfma_f32_16x16x32_bf16 v[122:125], v[168:171], v[192:195], v[122:125]
	v_mfma_f32_16x16x32_bf16 v[110:113], v[160:163], v[200:203], v[110:113]
	v_mfma_f32_16x16x32_bf16 v[106:109], v[168:171], v[200:203], v[106:109]
	v_mfma_f32_16x16x32_bf16 v[94:97], v[160:163], v[208:211], v[94:97]
	v_mfma_f32_16x16x32_bf16 v[90:93], v[168:171], v[208:211], v[90:93]
	v_mfma_f32_16x16x32_bf16 v[78:81], v[160:163], v[216:219], v[78:81]
	v_mfma_f32_16x16x32_bf16 v[74:77], v[168:171], v[216:219], v[74:77]
	v_mfma_f32_16x16x32_bf16 v[118:121], v[172:175], v[188:191], v[118:121]
	v_mfma_f32_16x16x32_bf16 v[114:117], v[180:183], v[188:191], v[114:117]
	v_mfma_f32_16x16x32_bf16 v[102:105], v[172:175], v[196:199], v[102:105]
	v_mfma_f32_16x16x32_bf16 v[98:101], v[180:183], v[196:199], v[98:101]
	v_mfma_f32_16x16x32_bf16 v[86:89], v[172:175], v[204:207], v[86:89]
	v_mfma_f32_16x16x32_bf16 v[82:85], v[180:183], v[204:207], v[82:85]
	v_mfma_f32_16x16x32_bf16 v[70:73], v[172:175], v[212:215], v[70:73]
	v_mfma_f32_16x16x32_bf16 v[66:69], v[180:183], v[212:215], v[66:69]
	v_mfma_f32_16x16x32_bf16 v[118:121], v[176:179], v[192:195], v[118:121]
	v_mfma_f32_16x16x32_bf16 v[114:117], v[184:187], v[192:195], v[114:117]
	v_mfma_f32_16x16x32_bf16 v[102:105], v[176:179], v[200:203], v[102:105]
	v_mfma_f32_16x16x32_bf16 v[98:101], v[184:187], v[200:203], v[98:101]
	v_mfma_f32_16x16x32_bf16 v[86:89], v[176:179], v[208:211], v[86:89]
	v_mfma_f32_16x16x32_bf16 v[82:85], v[184:187], v[208:211], v[82:85]
	v_mfma_f32_16x16x32_bf16 v[70:73], v[176:179], v[216:219], v[70:73]
	v_mfma_f32_16x16x32_bf16 v[66:69], v[184:187], v[216:219], v[66:69]
	s_barrier
	s_add_i32 s58, s72, s39
	v_lshl_add_u64 v[220:221], s[30:31], 0, v[132:133]
	s_mov_b32 m0, s58
	ds_read_b128 v[188:191], v154 offset:16384
	ds_read_b128 v[192:195], v154 offset:17408
	ds_read_b128 v[196:199], v154 offset:18432
	ds_read_b128 v[200:203], v154 offset:19456
	ds_read_b128 v[204:207], v154 offset:20480
	ds_read_b128 v[208:211], v154 offset:21504
	ds_read_b128 v[212:215], v154 offset:22528
	ds_read_b128 v[216:219], v154 offset:23552
	global_load_lds_dwordx4 v[220:221], off
	s_add_i32 m0, s58, 0x2000
	s_add_u32 s58, s30, 0x4000
	v_lshl_add_u64 v[220:221], s[30:31], 0, v[136:137]
	s_addc_u32 s59, s31, 0
	s_add_i32 s64, s73, s39
	global_load_lds_dwordx4 v[220:221], off
	v_lshl_add_u64 v[220:221], s[58:59], 0, v[132:133]
	s_mov_b32 m0, s64
	s_nop 0
	global_load_lds_dwordx4 v[220:221], off
	v_lshl_add_u64 v[220:221], s[58:59], 0, v[136:137]
	s_add_i32 m0, s64, 0x2000
	s_nop 0
	global_load_lds_dwordx4 v[220:221], off
	v_lshl_add_u64 v[220:221], s[34:35], 0, v[130:131]
	s_mov_b32 m0, s40
	s_nop 0
	global_load_lds_dwordx4 v[220:221], off
	v_lshl_add_u64 v[220:221], s[34:35], 0, v[134:135]
	s_mov_b32 m0, s41
	s_nop 0
	global_load_lds_dwordx4 v[220:221], off
	s_waitcnt vmcnt(8)
	s_waitcnt lgkmcnt(0)
	s_barrier
; #define PG8_STAGE(bufoff, gbase, voff) do { _Pragma("unroll") for (int _i = 0; _i < 2; ++_i) \
;         __builtin_amdgcn_global_load_lds((const unsigned*)((const char*)(gbase) + (voff)[_i]), (LAS unsigned*)(lds + (bufoff) + ldsw + _i * 8192), 16, 0, 0); } while (0)
; #define PG8_LDA(dst, b, h) do { _Pragma("unroll") for (int m = 0; m < 4; ++m) _Pragma("unroll") for (int k = 0; k < 2; ++k) dst[m][k] = *(const LAS bf16x8*)(lds + PG8_SA(b, h) + aoff + m * 2048 + k * 1024); } while (0)
; #define PG8_LDB(dst, b, h) do { _Pragma("unroll") for (int n = 0; n < 2; ++n) _Pragma("unroll") for (int k = 0; k < 2; ++k) dst[n][k] = *(const LAS bf16x8*)(lds + PG8_SB(b, h) + boff + n * 2048 + k * 1024); } while (0)
; #define PG8_MMA(ai, bj, At, Bt) do { __builtin_amdgcn_s_setprio(1); _Pragma("unroll") for (int m = 0; m < 4; ++m) _Pragma("unroll") for (int n = 0; n < 2; ++n) _Pragma("unroll") for (int k = 0; k < 2; ++k) \
;         acc[ai][bj][m][n] = __builtin_amdgcn_mfma_f32_16x16x32_bf16(Bt[n][k], At[m][k], acc[ai][bj][m][n], 0, 0, 0); __builtin_amdgcn_s_setprio(0); } while (0)
; #define PG8_WAIT_V(n) asm volatile("s_waitcnt vmcnt(" #n ")" ::: "memory")
; #define PG8_WAIT_L(n) asm volatile("s_waitcnt lgkmcnt(" #n ")" ::: "memory")
; #define PG8_BAR __builtin_amdgcn_s_barrier()
; #define PG8_SCHED __builtin_amdgcn_sched_barrier(0)
; template <class Epi, class Sched, bool ABLK = false, bool ALIGN_EPI = true, bool SP2 = true, bool BBLK = true>
; __device__ __forceinline__ void gemm_phase(LAS unsigned char* lds, const Gemm g, const Sched& S, const Epi& E) {
;     ...
;             PG8_WAIT_V(8); PG8_WAIT_L(0); PG8_BAR; PG8_MMA(1, 0, At, B0); PG8_MMA(1, 1, At, B1); PG8_BAR; PG8_SCHED;
;             PG8_LDB(B0, 1, 0); PG8_LDB(B1, 1, 1); PG8_SCHED; PG8_LDA(At, 1, 0); PG8_STAGE(PG8_SA(0, 1), a2 + hstepA, voffA);
;             PG8_WAIT_V(8); PG8_WAIT_L(0); PG8_BAR; PG8_MMA(0, 0, At, B0); PG8_MMA(0, 1, At, B1); PG8_BAR; PG8_SCHED;
	v_mfma_f32_16x16x32_bf16 v[62:65], v[156:159], v[188:191], v[62:65]
	v_mfma_f32_16x16x32_bf16 v[58:61], v[164:167], v[188:191], v[58:61]
	v_mfma_f32_16x16x32_bf16 v[46:49], v[156:159], v[196:199], v[46:49]
	v_mfma_f32_16x16x32_bf16 v[42:45], v[164:167], v[196:199], v[42:45]
	v_mfma_f32_16x16x32_bf16 v[30:33], v[156:159], v[204:207], v[30:33]
	v_mfma_f32_16x16x32_bf16 v[26:29], v[164:167], v[204:207], v[26:29]
	v_mfma_f32_16x16x32_bf16 v[14:17], v[156:159], v[212:215], v[14:17]
	v_mfma_f32_16x16x32_bf16 v[10:13], v[164:167], v[212:215], v[10:13]
	v_mfma_f32_16x16x32_bf16 v[62:65], v[160:163], v[192:195], v[62:65]
	v_mfma_f32_16x16x32_bf16 v[58:61], v[168:171], v[192:195], v[58:61]
	v_mfma_f32_16x16x32_bf16 v[46:49], v[160:163], v[200:203], v[46:49]
	v_mfma_f32_16x16x32_bf16 v[42:45], v[168:171], v[200:203], v[42:45]
	v_mfma_f32_16x16x32_bf16 v[30:33], v[160:163], v[208:211], v[30:33]
	v_mfma_f32_16x16x32_bf16 v[26:29], v[168:171], v[208:211], v[26:29]
	v_mfma_f32_16x16x32_bf16 v[14:17], v[160:163], v[216:219], v[14:17]
	v_mfma_f32_16x16x32_bf16 v[10:13], v[168:171], v[216:219], v[10:13]
	v_mfma_f32_16x16x32_bf16 v[54:57], v[172:175], v[188:191], v[54:57]
	v_mfma_f32_16x16x32_bf16 v[50:53], v[180:183], v[188:191], v[50:53]
	v_mfma_f32_16x16x32_bf16 v[38:41], v[172:175], v[196:199], v[38:41]
	v_mfma_f32_16x16x32_bf16 v[34:37], v[180:183], v[196:199], v[34:37]
	v_mfma_f32_16x16x32_bf16 v[22:25], v[172:175], v[204:207], v[22:25]
	v_mfma_f32_16x16x32_bf16 v[18:21], v[180:183], v[204:207], v[18:21]
	v_mfma_f32_16x16x32_bf16 v[6:9], v[172:175], v[212:215], v[6:9]
	v_mfma_f32_16x16x32_bf16 v[2:5], v[180:183], v[212:215], v[2:5]
	v_mfma_f32_16x16x32_bf16 v[54:57], v[176:179], v[192:195], v[54:57]
	v_mfma_f32_16x16x32_bf16 v[50:53], v[184:187], v[192:195], v[50:53]
	v_mfma_f32_16x16x32_bf16 v[38:41], v[176:179], v[200:203], v[38:41]
	v_mfma_f32_16x16x32_bf16 v[34:37], v[184:187], v[200:203], v[34:37]
	v_mfma_f32_16x16x32_bf16 v[22:25], v[176:179], v[208:211], v[22:25]
	v_mfma_f32_16x16x32_bf16 v[18:21], v[184:187], v[208:211], v[18:21]
	v_mfma_f32_16x16x32_bf16 v[6:9], v[176:179], v[216:219], v[6:9]
	v_mfma_f32_16x16x32_bf16 v[2:5], v[184:187], v[216:219], v[2:5]
	s_barrier
	v_add_u32_e32 v155, s60, v150
	ds_read_b128 v[156:159], v155
	ds_read_b128 v[160:163], v155 offset:1024
	ds_read_b128 v[164:167], v155 offset:2048
	ds_read_b128 v[168:171], v155 offset:3072
	v_add_u32_e32 v155, s61, v150
	ds_read_b128 v[172:175], v155
	ds_read_b128 v[176:179], v155 offset:1024
	ds_read_b128 v[180:183], v155 offset:2048
	ds_read_b128 v[184:187], v155 offset:3072
	s_add_u32 s34, s34, 0x80000
	s_addc_u32 s35, s35, 0
	s_mov_b32 m0, s42
	v_lshl_add_u64 v[220:221], s[34:35], 0, v[130:131]
	ds_read_b128 v[188:191], v154 offset:32768
	ds_read_b128 v[192:195], v154 offset:33792
	ds_read_b128 v[196:199], v154 offset:34816
	ds_read_b128 v[200:203], v154 offset:35840
	ds_read_b128 v[204:207], v154 offset:36864
	ds_read_b128 v[208:211], v154 offset:37888
	ds_read_b128 v[212:215], v154 offset:38912
	ds_read_b128 v[216:219], v154 offset:39936
	global_load_lds_dwordx4 v[220:221], off
	v_lshl_add_u64 v[220:221], s[34:35], 0, v[134:135]
	s_mov_b32 m0, s43
	s_nop 0
	global_load_lds_dwordx4 v[220:221], off
	s_waitcnt vmcnt(8)
	s_waitcnt lgkmcnt(0)
	s_barrier
	v_mfma_f32_16x16x32_bf16 v[126:129], v[156:159], v[188:191], v[126:129]
	v_mfma_f32_16x16x32_bf16 v[122:125], v[164:167], v[188:191], v[122:125]
	v_mfma_f32_16x16x32_bf16 v[110:113], v[156:159], v[196:199], v[110:113]
	v_mfma_f32_16x16x32_bf16 v[106:109], v[164:167], v[196:199], v[106:109]
	v_mfma_f32_16x16x32_bf16 v[94:97], v[156:159], v[204:207], v[94:97]
	v_mfma_f32_16x16x32_bf16 v[90:93], v[164:167], v[204:207], v[90:93]
	v_mfma_f32_16x16x32_bf16 v[78:81], v[156:159], v[212:215], v[78:81]
	v_mfma_f32_16x16x32_bf16 v[74:77], v[164:167], v[212:215], v[74:77]
	v_mfma_f32_16x16x32_bf16 v[126:129], v[160:163], v[192:195], v[126:129]
	v_mfma_f32_16x16x32_bf16 v[122:125], v[168:171], v[192:195], v[122:125]
	v_mfma_f32_16x16x32_bf16 v[110:113], v[160:163], v[200:203], v[110:113]
	v_mfma_f32_16x16x32_bf16 v[106:109], v[168:171], v[200:203], v[106:109]
	v_mfma_f32_16x16x32_bf16 v[94:97], v[160:163], v[208:211], v[94:97]
	v_mfma_f32_16x16x32_bf16 v[90:93], v[168:171], v[208:211], v[90:93]
	v_mfma_f32_16x16x32_bf16 v[78:81], v[160:163], v[216:219], v[78:81]
	v_mfma_f32_16x16x32_bf16 v[74:77], v[168:171], v[216:219], v[74:77]
	v_mfma_f32_16x16x32_bf16 v[118:121], v[172:175], v[188:191], v[118:121]
	v_mfma_f32_16x16x32_bf16 v[114:117], v[180:183], v[188:191], v[114:117]
	v_mfma_f32_16x16x32_bf16 v[102:105], v[172:175], v[196:199], v[102:105]
	v_mfma_f32_16x16x32_bf16 v[98:101], v[180:183], v[196:199], v[98:101]
	v_mfma_f32_16x16x32_bf16 v[86:89], v[172:175], v[204:207], v[86:89]
	v_mfma_f32_16x16x32_bf16 v[82:85], v[180:183], v[204:207], v[82:85]
	v_mfma_f32_16x16x32_bf16 v[70:73], v[172:175], v[212:215], v[70:73]
	v_mfma_f32_16x16x32_bf16 v[66:69], v[180:183], v[212:215], v[66:69]
	v_mfma_f32_16x16x32_bf16 v[118:121], v[176:179], v[192:195], v[118:121]
	v_mfma_f32_16x16x32_bf16 v[114:117], v[184:187], v[192:195], v[114:117]
	v_mfma_f32_16x16x32_bf16 v[102:105], v[176:179], v[200:203], v[102:105]
	v_mfma_f32_16x16x32_bf16 v[98:101], v[184:187], v[200:203], v[98:101]
	v_mfma_f32_16x16x32_bf16 v[86:89], v[176:179], v[208:211], v[86:89]
	v_mfma_f32_16x16x32_bf16 v[82:85], v[184:187], v[208:211], v[82:85]
	v_mfma_f32_16x16x32_bf16 v[70:73], v[176:179], v[216:219], v[70:73]
	v_mfma_f32_16x16x32_bf16 v[66:69], v[184:187], v[216:219], v[66:69]
	s_barrier
; #define PG8_STAGE(bufoff, gbase, voff) do { _Pragma("unroll") for (int _i = 0; _i < 2; ++_i) \
;         __builtin_amdgcn_global_load_lds((const unsigned*)((const char*)(gbase) + (voff)[_i]), (LAS unsigned*)(lds + (bufoff) + ldsw + _i * 8192), 16, 0, 0); } while (0)
; #define PG8_LDA(dst, b, h) do { _Pragma("unroll") for (int m = 0; m < 4; ++m) _Pragma("unroll") for (int k = 0; k < 2; ++k) dst[m][k] = *(const LAS bf16x8*)(lds + PG8_SA(b, h) + aoff + m * 2048 + k * 1024); } while (0)
; #define PG8_MMA(ai, bj, At, Bt) do { __builtin_amdgcn_s_setprio(1); _Pragma("unroll") for (int m = 0; m < 4; ++m) _Pragma("unroll") for (int n = 0; n < 2; ++n) _Pragma("unroll") for (int k = 0; k < 2; ++k) \
;         acc[ai][bj][m][n] = __builtin_amdgcn_mfma_f32_16x16x32_bf16(Bt[n][k], At[m][k], acc[ai][bj][m][n], 0, 0, 0); __builtin_amdgcn_s_setprio(0); } while (0)
; #define PG8_WAIT_V(n) asm volatile("s_waitcnt vmcnt(" #n ")" ::: "memory")
; #define PG8_WAIT_L(n) asm volatile("s_waitcnt lgkmcnt(" #n ")" ::: "memory")
; #define PG8_BAR __builtin_amdgcn_s_barrier()
; #define PG8_SCHED __builtin_amdgcn_sched_barrier(0)
; template <class Epi, class Sched, bool ABLK = false, bool ALIGN_EPI = true, bool SP2 = true, bool BBLK = true>
; __device__ __forceinline__ void gemm_phase(LAS unsigned char* lds, const Gemm g, const Sched& S, const Epi& E) {
;     ...
;             PG8_LDA(At, 1, 1); PG8_STAGE(PG8_SB(1, 0), b3, voffB); PG8_STAGE(PG8_SB(1, 1), b3 + hstepB, voffB); PG8_STAGE(PG8_SA(1, 0), a3, voffA);
;             PG8_WAIT_V(8); PG8_WAIT_L(0); PG8_BAR; PG8_MMA(1, 0, At, B0); PG8_MMA(1, 1, At, B1); PG8_BAR; PG8_SCHED;
;     ...
;         if constexpr (ALIGN_EPI) { if (wr == 0) PG8_BAR; }
	s_add_u32 s34, s30, 0x8000
	s_addc_u32 s35, s31, 0
	s_add_i32 s58, s60, s39
	v_lshl_add_u64 v[220:221], s[34:35], 0, v[132:133]
	s_mov_b32 m0, s58
	ds_read_b128 v[188:191], v154 offset:49152
	ds_read_b128 v[192:195], v154 offset:50176
	ds_read_b128 v[196:199], v154 offset:51200
	ds_read_b128 v[200:203], v154 offset:52224
	ds_read_b128 v[204:207], v154 offset:53248
	ds_read_b128 v[208:211], v154 offset:54272
	ds_read_b128 v[212:215], v154 offset:55296
	ds_read_b128 v[216:219], v154 offset:56320
	global_load_lds_dwordx4 v[220:221], off
	s_add_i32 m0, s58, 0x2000
	s_add_u32 s30, s30, 0xc000
	v_lshl_add_u64 v[220:221], s[34:35], 0, v[136:137]
	s_addc_u32 s31, s31, 0
	s_add_i32 s34, s61, s39
	global_load_lds_dwordx4 v[220:221], off
	v_lshl_add_u64 v[220:221], s[30:31], 0, v[132:133]
	s_mov_b32 m0, s34
	s_nop 0
	global_load_lds_dwordx4 v[220:221], off
	v_lshl_add_u64 v[220:221], s[30:31], 0, v[136:137]
	s_add_i32 m0, s34, 0x2000
	s_nop 0
	global_load_lds_dwordx4 v[220:221], off
	v_lshl_add_u64 v[220:221], s[28:29], 0, v[130:131]
	s_mov_b32 m0, s44
	s_nop 0
	global_load_lds_dwordx4 v[220:221], off
	v_lshl_add_u64 v[220:221], s[28:29], 0, v[134:135]
	s_mov_b32 m0, s45
	s_nop 0
	global_load_lds_dwordx4 v[220:221], off
	s_waitcnt vmcnt(8)
	s_waitcnt lgkmcnt(0)
	s_barrier
	v_mfma_f32_16x16x32_bf16 v[62:65], v[156:159], v[188:191], v[62:65]
	v_mfma_f32_16x16x32_bf16 v[58:61], v[164:167], v[188:191], v[58:61]
	v_mfma_f32_16x16x32_bf16 v[46:49], v[156:159], v[196:199], v[46:49]
	v_mfma_f32_16x16x32_bf16 v[42:45], v[164:167], v[196:199], v[42:45]
	v_mfma_f32_16x16x32_bf16 v[30:33], v[156:159], v[204:207], v[30:33]
	v_mfma_f32_16x16x32_bf16 v[26:29], v[164:167], v[204:207], v[26:29]
	v_mfma_f32_16x16x32_bf16 v[14:17], v[156:159], v[212:215], v[14:17]
	v_mfma_f32_16x16x32_bf16 v[10:13], v[164:167], v[212:215], v[10:13]
	v_mfma_f32_16x16x32_bf16 v[62:65], v[160:163], v[192:195], v[62:65]
	v_mfma_f32_16x16x32_bf16 v[58:61], v[168:171], v[192:195], v[58:61]
	v_mfma_f32_16x16x32_bf16 v[46:49], v[160:163], v[200:203], v[46:49]
	v_mfma_f32_16x16x32_bf16 v[42:45], v[168:171], v[200:203], v[42:45]
	v_mfma_f32_16x16x32_bf16 v[30:33], v[160:163], v[208:211], v[30:33]
	v_mfma_f32_16x16x32_bf16 v[26:29], v[168:171], v[208:211], v[26:29]
	v_mfma_f32_16x16x32_bf16 v[14:17], v[160:163], v[216:219], v[14:17]
	v_mfma_f32_16x16x32_bf16 v[10:13], v[168:171], v[216:219], v[10:13]
	v_mfma_f32_16x16x32_bf16 v[54:57], v[172:175], v[188:191], v[54:57]
	v_mfma_f32_16x16x32_bf16 v[50:53], v[180:183], v[188:191], v[50:53]
	v_mfma_f32_16x16x32_bf16 v[38:41], v[172:175], v[196:199], v[38:41]
	v_mfma_f32_16x16x32_bf16 v[34:37], v[180:183], v[196:199], v[34:37]
	v_mfma_f32_16x16x32_bf16 v[22:25], v[172:175], v[204:207], v[22:25]
	v_mfma_f32_16x16x32_bf16 v[18:21], v[180:183], v[204:207], v[18:21]
	v_mfma_f32_16x16x32_bf16 v[6:9], v[172:175], v[212:215], v[6:9]
	v_mfma_f32_16x16x32_bf16 v[2:5], v[180:183], v[212:215], v[2:5]
	v_mfma_f32_16x16x32_bf16 v[54:57], v[176:179], v[192:195], v[54:57]
	v_mfma_f32_16x16x32_bf16 v[50:53], v[184:187], v[192:195], v[50:53]
	v_mfma_f32_16x16x32_bf16 v[38:41], v[176:179], v[200:203], v[38:41]
	v_mfma_f32_16x16x32_bf16 v[34:37], v[184:187], v[200:203], v[34:37]
	v_mfma_f32_16x16x32_bf16 v[22:25], v[176:179], v[208:211], v[22:25]
	v_mfma_f32_16x16x32_bf16 v[18:21], v[184:187], v[208:211], v[18:21]
	v_mfma_f32_16x16x32_bf16 v[6:9], v[176:179], v[216:219], v[6:9]
	v_mfma_f32_16x16x32_bf16 v[2:5], v[184:187], v[216:219], v[2:5]
	s_barrier
	s_add_u32 s52, s52, 0x10000
	s_addc_u32 s53, s53, 0
	s_add_u32 s26, s26, 0x100
	s_addc_u32 s27, s27, 0
	s_cmp_ge_u32 s57, s47
	s_cbranch_scc0 .LBB0_1716
	s_and_b64 vcc, exec, s[6:7]
	s_cbranch_vccz .LBB0_1719
	s_barrier

; #define PG8_STAGE(bufoff, gbase, voff) do { _Pragma("unroll") for (int _i = 0; _i < 2; ++_i) \
;         __builtin_amdgcn_global_load_lds((const unsigned*)((const char*)(gbase) + (voff)[_i]), (LAS unsigned*)(lds + (bufoff) + ldsw + _i * 8192), 16, 0, 0); } while (0)
; #define PG8_LDA(dst, b, h) do { _Pragma("unroll") for (int m = 0; m < 4; ++m) _Pragma("unroll") for (int k = 0; k < 2; ++k) dst[m][k] = *(const LAS bf16x8*)(lds + PG8_SA(b, h) + aoff + m * 2048 + k * 1024); } while (0)
; #define PG8_LDB(dst, b, h) do { _Pragma("unroll") for (int n = 0; n < 2; ++n) _Pragma("unroll") for (int k = 0; k < 2; ++k) dst[n][k] = *(const LAS bf16x8*)(lds + PG8_SB(b, h) + boff + n * 2048 + k * 1024); } while (0)
; #define PG8_MMA(ai, bj, At, Bt) do { __builtin_amdgcn_s_setprio(1); _Pragma("unroll") for (int m = 0; m < 4; ++m) _Pragma("unroll") for (int n = 0; n < 2; ++n) _Pragma("unroll") for (int k = 0; k < 2; ++k) \
;         acc[ai][bj][m][n] = __builtin_amdgcn_mfma_f32_16x16x32_bf16(Bt[n][k], At[m][k], acc[ai][bj][m][n], 0, 0, 0); __builtin_amdgcn_s_setprio(0); } while (0)
; #define PG8_WAIT_V(n) asm volatile("s_waitcnt vmcnt(" #n ")" ::: "memory")
; #define PG8_BAR __builtin_amdgcn_s_barrier()
; template <class Epi, class Sched, bool ABLK = false, bool ALIGN_EPI = true, bool SP2 = true, bool BBLK = true>
; __device__ __forceinline__ void gemm_phase(LAS unsigned char* lds, const Gemm g, const Sched& S, const Epi& E) {
;     ...
;             const bool last = (t == nt - 2);
;             const char* a1 = a_tile(uA, tbA + t + 1);
;             const char* a2 = last ? a_tile(nuA, ntbA) : a_tile(uA, tbA + t + 2); const char* b2 = last ? nB : cB + (size_t)(t + 2) * kstepB;
;             const char* a3 = last ? a_tile(nuA, ntbA + 1) : a_tile(uA, tbA + t + 3); const char* b3 = b2 + kstepB;
;             if (last && has_next) S.a_ready(nxt);
;             if constexpr (SP2) {
;             PG8_LDB(B0, 0, 0); PG8_LDB(B1, 0, 1); PG8_SCHED; PG8_LDA(At, 0, 0); PG8_STAGE(PG8_SA(1, 1), a1 + hstepA, voffA);
;             PG8_WAIT_V(8); PG8_WAIT_L(0); PG8_BAR; PG8_MMA(0, 0, At, B0); PG8_MMA(0, 1, At, B1); PG8_BAR; PG8_SCHED;
;             PG8_LDA(At, 0, 1); PG8_STAGE(PG8_SB(0, 0), b2, voffB); PG8_STAGE(PG8_SB(0, 1), b2 + hstepB, voffB); PG8_STAGE(PG8_SA(0, 0), a2, voffA);
;             PG8_WAIT_V(8); PG8_WAIT_L(0); PG8_BAR; PG8_MMA(1, 0, At, B0); PG8_MMA(1, 1, At, B1); PG8_BAR; PG8_SCHED;
.LBB0_1842:
	ds_read_b128 v[172:175], v168
	ds_read_b128 v[176:179], v168 offset:1024
	ds_read_b128 v[180:183], v168 offset:2048
	ds_read_b128 v[184:187], v168 offset:3072
	ds_read_b128 v[188:191], v169
	ds_read_b128 v[192:195], v169 offset:1024
	ds_read_b128 v[196:199], v169 offset:2048
	ds_read_b128 v[200:203], v169 offset:3072
	s_add_u32 s30, s26, s28
	s_addc_u32 s31, s27, s29
	s_add_u32 s36, s30, 0x100
	s_addc_u32 s37, s31, 0
	s_add_u32 s30, s30, 0x180
	s_addc_u32 s31, s31, 0
	s_cmpk_eq_i32 s28, 0xf00
	s_cselect_b32 s31, s51, s31
	s_cselect_b32 s30, s23, s30
	s_cselect_b32 s35, s11, s53
	s_cselect_b32 s34, s15, s52
	s_cselect_b32 s37, s4, s37
	s_cselect_b32 s36, s5, s36
	s_mov_b32 m0, s47
	v_lshl_add_u64 v[236:237], v[164:165], 0, s[28:29]
	ds_read_b128 v[204:207], v170
	ds_read_b128 v[208:211], v170 offset:1024
	ds_read_b128 v[212:215], v170 offset:2048
	ds_read_b128 v[216:219], v170 offset:3072
	ds_read_b128 v[220:223], v170 offset:4096
	ds_read_b128 v[224:227], v170 offset:5120
	ds_read_b128 v[228:231], v170 offset:6144
	ds_read_b128 v[232:235], v170 offset:7168
	global_load_lds_dwordx4 v[236:237], off
	v_lshl_add_u64 v[236:237], v[166:167], 0, s[28:29]
	s_mov_b32 m0, s48
	s_nop 0
	global_load_lds_dwordx4 v[236:237], off
	s_waitcnt vmcnt(8)
	s_waitcnt lgkmcnt(0)
	s_barrier
	v_mfma_f32_16x16x32_bf16 v[126:129], v[172:175], v[204:207], v[126:129]
	v_mfma_f32_16x16x32_bf16 v[122:125], v[180:183], v[204:207], v[122:125]
	v_mfma_f32_16x16x32_bf16 v[110:113], v[172:175], v[212:215], v[110:113]
	v_mfma_f32_16x16x32_bf16 v[106:109], v[180:183], v[212:215], v[106:109]
	v_mfma_f32_16x16x32_bf16 v[94:97], v[172:175], v[220:223], v[94:97]
	v_mfma_f32_16x16x32_bf16 v[90:93], v[180:183], v[220:223], v[90:93]
	v_mfma_f32_16x16x32_bf16 v[78:81], v[172:175], v[228:231], v[78:81]
	v_mfma_f32_16x16x32_bf16 v[74:77], v[180:183], v[228:231], v[74:77]
	v_mfma_f32_16x16x32_bf16 v[126:129], v[176:179], v[208:211], v[126:129]
	v_mfma_f32_16x16x32_bf16 v[122:125], v[184:187], v[208:211], v[122:125]
	v_mfma_f32_16x16x32_bf16 v[110:113], v[176:179], v[216:219], v[110:113]
	v_mfma_f32_16x16x32_bf16 v[106:109], v[184:187], v[216:219], v[106:109]
	v_mfma_f32_16x16x32_bf16 v[94:97], v[176:179], v[224:227], v[94:97]
	v_mfma_f32_16x16x32_bf16 v[90:93], v[184:187], v[224:227], v[90:93]
	v_mfma_f32_16x16x32_bf16 v[78:81], v[176:179], v[232:235], v[78:81]
	v_mfma_f32_16x16x32_bf16 v[74:77], v[184:187], v[232:235], v[74:77]
	v_mfma_f32_16x16x32_bf16 v[118:121], v[188:191], v[204:207], v[118:121]
	v_mfma_f32_16x16x32_bf16 v[114:117], v[196:199], v[204:207], v[114:117]
	v_mfma_f32_16x16x32_bf16 v[102:105], v[188:191], v[212:215], v[102:105]
	v_mfma_f32_16x16x32_bf16 v[98:101], v[196:199], v[212:215], v[98:101]
	v_mfma_f32_16x16x32_bf16 v[86:89], v[188:191], v[220:223], v[86:89]
	v_mfma_f32_16x16x32_bf16 v[82:85], v[196:199], v[220:223], v[82:85]
	v_mfma_f32_16x16x32_bf16 v[70:73], v[188:191], v[228:231], v[70:73]
	v_mfma_f32_16x16x32_bf16 v[66:69], v[196:199], v[228:231], v[66:69]
	v_mfma_f32_16x16x32_bf16 v[118:121], v[192:195], v[208:211], v[118:121]
	v_mfma_f32_16x16x32_bf16 v[114:117], v[200:203], v[208:211], v[114:117]
	v_mfma_f32_16x16x32_bf16 v[102:105], v[192:195], v[216:219], v[102:105]
	v_mfma_f32_16x16x32_bf16 v[98:101], v[200:203], v[216:219], v[98:101]
	v_mfma_f32_16x16x32_bf16 v[86:89], v[192:195], v[224:227], v[86:89]
	v_mfma_f32_16x16x32_bf16 v[82:85], v[200:203], v[224:227], v[82:85]
	v_mfma_f32_16x16x32_bf16 v[70:73], v[192:195], v[232:235], v[70:73]
	v_mfma_f32_16x16x32_bf16 v[66:69], v[200:203], v[232:235], v[66:69]
	s_barrier
	s_mov_b32 m0, s49
	v_lshl_add_u64 v[236:237], s[34:35], 0, v[134:135]
	s_add_u32 s56, s34, 0x4000
	ds_read_b128 v[204:207], v170 offset:16384
	ds_read_b128 v[208:211], v170 offset:17408
	ds_read_b128 v[212:215], v170 offset:18432
	ds_read_b128 v[216:219], v170 offset:19456
	ds_read_b128 v[220:223], v170 offset:20480
	ds_read_b128 v[224:227], v170 offset:21504
	ds_read_b128 v[228:231], v170 offset:22528
	ds_read_b128 v[232:235], v170 offset:23552
	global_load_lds_dwordx4 v[236:237], off
	v_lshl_add_u64 v[236:237], s[34:35], 0, v[130:131]
	s_mov_b32 m0, s50
	s_addc_u32 s57, s35, 0
	s_add_i32 s55, s73, s39
	global_load_lds_dwordx4 v[236:237], off
	v_lshl_add_u64 v[236:237], s[56:57], 0, v[134:135]
	s_mov_b32 m0, s55
	s_nop 0
	global_load_lds_dwordx4 v[236:237], off
	v_lshl_add_u64 v[236:237], s[56:57], 0, v[130:131]
	s_add_i32 m0, s55, 0x2000
	s_nop 0
	global_load_lds_dwordx4 v[236:237], off
	v_lshl_add_u64 v[236:237], s[36:37], 0, v[136:137]
	s_mov_b32 m0, s25
	s_nop 0
	global_load_lds_dwordx4 v[236:237], off
	v_lshl_add_u64 v[236:237], s[36:37], 0, v[132:133]
	s_mov_b32 m0, s40
	s_nop 0
	global_load_lds_dwordx4 v[236:237], off
	s_waitcnt vmcnt(8)
	s_waitcnt lgkmcnt(0)
	s_barrier
; #define PG8_STAGE(bufoff, gbase, voff) do { _Pragma("unroll") for (int _i = 0; _i < 2; ++_i) \
;         __builtin_amdgcn_global_load_lds((const unsigned*)((const char*)(gbase) + (voff)[_i]), (LAS unsigned*)(lds + (bufoff) + ldsw + _i * 8192), 16, 0, 0); } while (0)
; #define PG8_LDA(dst, b, h) do { _Pragma("unroll") for (int m = 0; m < 4; ++m) _Pragma("unroll") for (int k = 0; k < 2; ++k) dst[m][k] = *(const LAS bf16x8*)(lds + PG8_SA(b, h) + aoff + m * 2048 + k * 1024); } while (0)
; #define PG8_LDB(dst, b, h) do { _Pragma("unroll") for (int n = 0; n < 2; ++n) _Pragma("unroll") for (int k = 0; k < 2; ++k) dst[n][k] = *(const LAS bf16x8*)(lds + PG8_SB(b, h) + boff + n * 2048 + k * 1024); } while (0)
; #define PG8_MMA(ai, bj, At, Bt) do { __builtin_amdgcn_s_setprio(1); _Pragma("unroll") for (int m = 0; m < 4; ++m) _Pragma("unroll") for (int n = 0; n < 2; ++n) _Pragma("unroll") for (int k = 0; k < 2; ++k) \
;         acc[ai][bj][m][n] = __builtin_amdgcn_mfma_f32_16x16x32_bf16(Bt[n][k], At[m][k], acc[ai][bj][m][n], 0, 0, 0); __builtin_amdgcn_s_setprio(0); } while (0)
; #define PG8_WAIT_V(n) asm volatile("s_waitcnt vmcnt(" #n ")" ::: "memory")
; #define PG8_WAIT_L(n) asm volatile("s_waitcnt lgkmcnt(" #n ")" ::: "memory")
; #define PG8_BAR __builtin_amdgcn_s_barrier()
; #define PG8_SCHED __builtin_amdgcn_sched_barrier(0)
; template <class Epi, class Sched, bool ABLK = false, bool ALIGN_EPI = true, bool SP2 = true, bool BBLK = true>
; __device__ __forceinline__ void gemm_phase(LAS unsigned char* lds, const Gemm g, const Sched& S, const Epi& E) {
;     ...
;             PG8_WAIT_V(8); PG8_WAIT_L(0); PG8_BAR; PG8_MMA(1, 0, At, B0); PG8_MMA(1, 1, At, B1); PG8_BAR; PG8_SCHED;
;             PG8_LDB(B0, 1, 0); PG8_LDB(B1, 1, 1); PG8_SCHED; PG8_LDA(At, 1, 0); PG8_STAGE(PG8_SA(0, 1), a2 + hstepA, voffA);
;             PG8_WAIT_V(8); PG8_WAIT_L(0); PG8_BAR; PG8_MMA(0, 0, At, B0); PG8_MMA(0, 1, At, B1); PG8_BAR; PG8_SCHED;
	v_mfma_f32_16x16x32_bf16 v[62:65], v[172:175], v[204:207], v[62:65]
	v_mfma_f32_16x16x32_bf16 v[58:61], v[180:183], v[204:207], v[58:61]
	v_mfma_f32_16x16x32_bf16 v[46:49], v[172:175], v[212:215], v[46:49]
	v_mfma_f32_16x16x32_bf16 v[42:45], v[180:183], v[212:215], v[42:45]
	v_mfma_f32_16x16x32_bf16 v[30:33], v[172:175], v[220:223], v[30:33]
	v_mfma_f32_16x16x32_bf16 v[26:29], v[180:183], v[220:223], v[26:29]
	v_mfma_f32_16x16x32_bf16 v[14:17], v[172:175], v[228:231], v[14:17]
	v_mfma_f32_16x16x32_bf16 v[10:13], v[180:183], v[228:231], v[10:13]
	v_mfma_f32_16x16x32_bf16 v[62:65], v[176:179], v[208:211], v[62:65]
	v_mfma_f32_16x16x32_bf16 v[58:61], v[184:187], v[208:211], v[58:61]
	v_mfma_f32_16x16x32_bf16 v[46:49], v[176:179], v[216:219], v[46:49]
	v_mfma_f32_16x16x32_bf16 v[42:45], v[184:187], v[216:219], v[42:45]
	v_mfma_f32_16x16x32_bf16 v[30:33], v[176:179], v[224:227], v[30:33]
	v_mfma_f32_16x16x32_bf16 v[26:29], v[184:187], v[224:227], v[26:29]
	v_mfma_f32_16x16x32_bf16 v[14:17], v[176:179], v[232:235], v[14:17]
	v_mfma_f32_16x16x32_bf16 v[10:13], v[184:187], v[232:235], v[10:13]
	v_mfma_f32_16x16x32_bf16 v[54:57], v[188:191], v[204:207], v[54:57]
	v_mfma_f32_16x16x32_bf16 v[50:53], v[196:199], v[204:207], v[50:53]
	v_mfma_f32_16x16x32_bf16 v[38:41], v[188:191], v[212:215], v[38:41]
	v_mfma_f32_16x16x32_bf16 v[34:37], v[196:199], v[212:215], v[34:37]
	v_mfma_f32_16x16x32_bf16 v[22:25], v[188:191], v[220:223], v[22:25]
	v_mfma_f32_16x16x32_bf16 v[18:21], v[196:199], v[220:223], v[18:21]
	v_mfma_f32_16x16x32_bf16 v[6:9], v[188:191], v[228:231], v[6:9]
	v_mfma_f32_16x16x32_bf16 v[2:5], v[196:199], v[228:231], v[2:5]
	v_mfma_f32_16x16x32_bf16 v[54:57], v[192:195], v[208:211], v[54:57]
	v_mfma_f32_16x16x32_bf16 v[50:53], v[200:203], v[208:211], v[50:53]
	v_mfma_f32_16x16x32_bf16 v[38:41], v[192:195], v[216:219], v[38:41]
	v_mfma_f32_16x16x32_bf16 v[34:37], v[200:203], v[216:219], v[34:37]
	v_mfma_f32_16x16x32_bf16 v[22:25], v[192:195], v[224:227], v[22:25]
	v_mfma_f32_16x16x32_bf16 v[18:21], v[200:203], v[224:227], v[18:21]
	v_mfma_f32_16x16x32_bf16 v[6:9], v[192:195], v[232:235], v[6:9]
	v_mfma_f32_16x16x32_bf16 v[2:5], v[200:203], v[232:235], v[2:5]
	s_barrier
	v_add_u32_e32 v171, s60, v1
	ds_read_b128 v[172:175], v171
	ds_read_b128 v[176:179], v171 offset:1024
	ds_read_b128 v[180:183], v171 offset:2048
	ds_read_b128 v[184:187], v171 offset:3072
	v_add_u32_e32 v171, s61, v1
	ds_read_b128 v[188:191], v171
	ds_read_b128 v[192:195], v171 offset:1024
	ds_read_b128 v[196:199], v171 offset:2048
	ds_read_b128 v[200:203], v171 offset:3072
	s_add_u32 s36, s36, 0x80000
	s_addc_u32 s37, s37, 0
	s_mov_b32 m0, s41
	v_lshl_add_u64 v[236:237], s[36:37], 0, v[136:137]
	ds_read_b128 v[204:207], v170 offset:32768
	ds_read_b128 v[208:211], v170 offset:33792
	ds_read_b128 v[212:215], v170 offset:34816
	ds_read_b128 v[216:219], v170 offset:35840
	ds_read_b128 v[220:223], v170 offset:36864
	ds_read_b128 v[224:227], v170 offset:37888
	ds_read_b128 v[228:231], v170 offset:38912
	ds_read_b128 v[232:235], v170 offset:39936
	global_load_lds_dwordx4 v[236:237], off
	v_lshl_add_u64 v[236:237], s[36:37], 0, v[132:133]
	s_mov_b32 m0, s42
	s_nop 0
	global_load_lds_dwordx4 v[236:237], off
	s_waitcnt vmcnt(8)
	s_waitcnt lgkmcnt(0)
	s_barrier
	v_mfma_f32_16x16x32_bf16 v[126:129], v[172:175], v[204:207], v[126:129]
	v_mfma_f32_16x16x32_bf16 v[122:125], v[180:183], v[204:207], v[122:125]
	v_mfma_f32_16x16x32_bf16 v[110:113], v[172:175], v[212:215], v[110:113]
	v_mfma_f32_16x16x32_bf16 v[106:109], v[180:183], v[212:215], v[106:109]
	v_mfma_f32_16x16x32_bf16 v[94:97], v[172:175], v[220:223], v[94:97]
	v_mfma_f32_16x16x32_bf16 v[90:93], v[180:183], v[220:223], v[90:93]
	v_mfma_f32_16x16x32_bf16 v[78:81], v[172:175], v[228:231], v[78:81]
	v_mfma_f32_16x16x32_bf16 v[74:77], v[180:183], v[228:231], v[74:77]
	v_mfma_f32_16x16x32_bf16 v[126:129], v[176:179], v[208:211], v[126:129]
	v_mfma_f32_16x16x32_bf16 v[122:125], v[184:187], v[208:211], v[122:125]
	v_mfma_f32_16x16x32_bf16 v[110:113], v[176:179], v[216:219], v[110:113]
	v_mfma_f32_16x16x32_bf16 v[106:109], v[184:187], v[216:219], v[106:109]
	v_mfma_f32_16x16x32_bf16 v[94:97], v[176:179], v[224:227], v[94:97]
	v_mfma_f32_16x16x32_bf16 v[90:93], v[184:187], v[224:227], v[90:93]
	v_mfma_f32_16x16x32_bf16 v[78:81], v[176:179], v[232:235], v[78:81]
	v_mfma_f32_16x16x32_bf16 v[74:77], v[184:187], v[232:235], v[74:77]
	v_mfma_f32_16x16x32_bf16 v[118:121], v[188:191], v[204:207], v[118:121]
	v_mfma_f32_16x16x32_bf16 v[114:117], v[196:199], v[204:207], v[114:117]
	v_mfma_f32_16x16x32_bf16 v[102:105], v[188:191], v[212:215], v[102:105]
	v_mfma_f32_16x16x32_bf16 v[98:101], v[196:199], v[212:215], v[98:101]
	v_mfma_f32_16x16x32_bf16 v[86:89], v[188:191], v[220:223], v[86:89]
	v_mfma_f32_16x16x32_bf16 v[82:85], v[196:199], v[220:223], v[82:85]
	v_mfma_f32_16x16x32_bf16 v[70:73], v[188:191], v[228:231], v[70:73]
	v_mfma_f32_16x16x32_bf16 v[66:69], v[196:199], v[228:231], v[66:69]
	v_mfma_f32_16x16x32_bf16 v[118:121], v[192:195], v[208:211], v[118:121]
	v_mfma_f32_16x16x32_bf16 v[114:117], v[200:203], v[208:211], v[114:117]
	v_mfma_f32_16x16x32_bf16 v[102:105], v[192:195], v[216:219], v[102:105]
	v_mfma_f32_16x16x32_bf16 v[98:101], v[200:203], v[216:219], v[98:101]
	v_mfma_f32_16x16x32_bf16 v[86:89], v[192:195], v[224:227], v[86:89]
	v_mfma_f32_16x16x32_bf16 v[82:85], v[200:203], v[224:227], v[82:85]
	v_mfma_f32_16x16x32_bf16 v[70:73], v[192:195], v[232:235], v[70:73]
	v_mfma_f32_16x16x32_bf16 v[66:69], v[200:203], v[232:235], v[66:69]
	s_barrier
; #define PG8_STAGE(bufoff, gbase, voff) do { _Pragma("unroll") for (int _i = 0; _i < 2; ++_i) \
;         __builtin_amdgcn_global_load_lds((const unsigned*)((const char*)(gbase) + (voff)[_i]), (LAS unsigned*)(lds + (bufoff) + ldsw + _i * 8192), 16, 0, 0); } while (0)
; #define PG8_LDA(dst, b, h) do { _Pragma("unroll") for (int m = 0; m < 4; ++m) _Pragma("unroll") for (int k = 0; k < 2; ++k) dst[m][k] = *(const LAS bf16x8*)(lds + PG8_SA(b, h) + aoff + m * 2048 + k * 1024); } while (0)
; #define PG8_MMA(ai, bj, At, Bt) do { __builtin_amdgcn_s_setprio(1); _Pragma("unroll") for (int m = 0; m < 4; ++m) _Pragma("unroll") for (int n = 0; n < 2; ++n) _Pragma("unroll") for (int k = 0; k < 2; ++k) \
;         acc[ai][bj][m][n] = __builtin_amdgcn_mfma_f32_16x16x32_bf16(Bt[n][k], At[m][k], acc[ai][bj][m][n], 0, 0, 0); __builtin_amdgcn_s_setprio(0); } while (0)
; #define PG8_WAIT_V(n) asm volatile("s_waitcnt vmcnt(" #n ")" ::: "memory")
; #define PG8_WAIT_L(n) asm volatile("s_waitcnt lgkmcnt(" #n ")" ::: "memory")
; #define PG8_BAR __builtin_amdgcn_s_barrier()
; #define PG8_SCHED __builtin_amdgcn_sched_barrier(0)
; template <class Epi, class Sched, bool ABLK = false, bool ALIGN_EPI = true, bool SP2 = true, bool BBLK = true>
; __device__ __forceinline__ void gemm_phase(LAS unsigned char* lds, const Gemm g, const Sched& S, const Epi& E) {
;     ...
;             PG8_LDA(At, 1, 1); PG8_STAGE(PG8_SB(1, 0), b3, voffB); PG8_STAGE(PG8_SB(1, 1), b3 + hstepB, voffB); PG8_STAGE(PG8_SA(1, 0), a3, voffA);
;             PG8_WAIT_V(8); PG8_WAIT_L(0); PG8_BAR; PG8_MMA(1, 0, At, B0); PG8_MMA(1, 1, At, B1); PG8_BAR; PG8_SCHED;
;     ...
;         if constexpr (ALIGN_EPI) { if (wr == 0) PG8_BAR; }
	s_add_u32 s36, s34, 0x8000
	s_addc_u32 s37, s35, 0
	s_add_i32 s55, s60, s39
	v_lshl_add_u64 v[236:237], s[36:37], 0, v[134:135]
	s_mov_b32 m0, s55
	ds_read_b128 v[204:207], v170 offset:49152
	ds_read_b128 v[208:211], v170 offset:50176
	ds_read_b128 v[212:215], v170 offset:51200
	ds_read_b128 v[216:219], v170 offset:52224
	ds_read_b128 v[220:223], v170 offset:53248
	ds_read_b128 v[224:227], v170 offset:54272
	ds_read_b128 v[228:231], v170 offset:55296
	ds_read_b128 v[232:235], v170 offset:56320
	global_load_lds_dwordx4 v[236:237], off
	s_add_i32 m0, s55, 0x2000
	s_add_u32 s34, s34, 0xc000
	v_lshl_add_u64 v[236:237], s[36:37], 0, v[130:131]
	s_addc_u32 s35, s35, 0
	s_add_i32 s36, s61, s39
	global_load_lds_dwordx4 v[236:237], off
	v_lshl_add_u64 v[236:237], s[34:35], 0, v[134:135]
	s_mov_b32 m0, s36
	s_nop 0
	global_load_lds_dwordx4 v[236:237], off
	v_lshl_add_u64 v[236:237], s[34:35], 0, v[130:131]
	s_add_i32 m0, s36, 0x2000
	s_nop 0
	global_load_lds_dwordx4 v[236:237], off
	v_lshl_add_u64 v[236:237], s[30:31], 0, v[136:137]
	s_mov_b32 m0, s45
	s_nop 0
	global_load_lds_dwordx4 v[236:237], off
	v_lshl_add_u64 v[236:237], s[30:31], 0, v[132:133]
	s_mov_b32 m0, s46
	s_nop 0
	global_load_lds_dwordx4 v[236:237], off
	s_waitcnt vmcnt(8)
	s_waitcnt lgkmcnt(0)
	s_barrier
	v_mfma_f32_16x16x32_bf16 v[62:65], v[172:175], v[204:207], v[62:65]
	v_mfma_f32_16x16x32_bf16 v[58:61], v[180:183], v[204:207], v[58:61]
	v_mfma_f32_16x16x32_bf16 v[46:49], v[172:175], v[212:215], v[46:49]
	v_mfma_f32_16x16x32_bf16 v[42:45], v[180:183], v[212:215], v[42:45]
	v_mfma_f32_16x16x32_bf16 v[30:33], v[172:175], v[220:223], v[30:33]
	v_mfma_f32_16x16x32_bf16 v[26:29], v[180:183], v[220:223], v[26:29]
	v_mfma_f32_16x16x32_bf16 v[14:17], v[172:175], v[228:231], v[14:17]
	v_mfma_f32_16x16x32_bf16 v[10:13], v[180:183], v[228:231], v[10:13]
	v_mfma_f32_16x16x32_bf16 v[62:65], v[176:179], v[208:211], v[62:65]
	v_mfma_f32_16x16x32_bf16 v[58:61], v[184:187], v[208:211], v[58:61]
	v_mfma_f32_16x16x32_bf16 v[46:49], v[176:179], v[216:219], v[46:49]
	v_mfma_f32_16x16x32_bf16 v[42:45], v[184:187], v[216:219], v[42:45]
	v_mfma_f32_16x16x32_bf16 v[30:33], v[176:179], v[224:227], v[30:33]
	v_mfma_f32_16x16x32_bf16 v[26:29], v[184:187], v[224:227], v[26:29]
	v_mfma_f32_16x16x32_bf16 v[14:17], v[176:179], v[232:235], v[14:17]
	v_mfma_f32_16x16x32_bf16 v[10:13], v[184:187], v[232:235], v[10:13]
	v_mfma_f32_16x16x32_bf16 v[54:57], v[188:191], v[204:207], v[54:57]
	v_mfma_f32_16x16x32_bf16 v[50:53], v[196:199], v[204:207], v[50:53]
	v_mfma_f32_16x16x32_bf16 v[38:41], v[188:191], v[212:215], v[38:41]
	v_mfma_f32_16x16x32_bf16 v[34:37], v[196:199], v[212:215], v[34:37]
	v_mfma_f32_16x16x32_bf16 v[22:25], v[188:191], v[220:223], v[22:25]
	v_mfma_f32_16x16x32_bf16 v[18:21], v[196:199], v[220:223], v[18:21]
	v_mfma_f32_16x16x32_bf16 v[6:9], v[188:191], v[228:231], v[6:9]
	v_mfma_f32_16x16x32_bf16 v[2:5], v[196:199], v[228:231], v[2:5]
	v_mfma_f32_16x16x32_bf16 v[54:57], v[192:195], v[208:211], v[54:57]
	v_mfma_f32_16x16x32_bf16 v[50:53], v[200:203], v[208:211], v[50:53]
	v_mfma_f32_16x16x32_bf16 v[38:41], v[192:195], v[216:219], v[38:41]
	v_mfma_f32_16x16x32_bf16 v[34:37], v[200:203], v[216:219], v[34:37]
	v_mfma_f32_16x16x32_bf16 v[22:25], v[192:195], v[224:227], v[22:25]
	v_mfma_f32_16x16x32_bf16 v[18:21], v[200:203], v[224:227], v[18:21]
	v_mfma_f32_16x16x32_bf16 v[6:9], v[192:195], v[232:235], v[6:9]
	v_mfma_f32_16x16x32_bf16 v[2:5], v[200:203], v[232:235], v[2:5]
	s_barrier
	s_add_i32 s54, s54, 2
	s_add_u32 s28, s28, 0x100
	s_addc_u32 s29, s29, 0
	s_add_u32 s52, s52, 0x10000
	s_addc_u32 s53, s53, 0
	s_cmp_gt_u32 s54, 29
	s_cbranch_scc0 .LBB0_1842
	s_and_b64 vcc, exec, s[6:7]
	s_cbranch_vccz .LBB0_1845
	s_barrier

; #define PG8_STAGE(bufoff, gbase, voff) do { _Pragma("unroll") for (int _i = 0; _i < 2; ++_i) \
;         __builtin_amdgcn_global_load_lds((const unsigned*)((const char*)(gbase) + (voff)[_i]), (LAS unsigned*)(lds + (bufoff) + ldsw + _i * 8192), 16, 0, 0); } while (0)
; #define PG8_LDA(dst, b, h) do { _Pragma("unroll") for (int m = 0; m < 4; ++m) _Pragma("unroll") for (int k = 0; k < 2; ++k) dst[m][k] = *(const LAS bf16x8*)(lds + PG8_SA(b, h) + aoff + m * 2048 + k * 1024); } while (0)
; #define PG8_LDB(dst, b, h) do { _Pragma("unroll") for (int n = 0; n < 2; ++n) _Pragma("unroll") for (int k = 0; k < 2; ++k) dst[n][k] = *(const LAS bf16x8*)(lds + PG8_SB(b, h) + boff + n * 2048 + k * 1024); } while (0)
; #define PG8_MMA(ai, bj, At, Bt) do { __builtin_amdgcn_s_setprio(1); _Pragma("unroll") for (int m = 0; m < 4; ++m) _Pragma("unroll") for (int n = 0; n < 2; ++n) _Pragma("unroll") for (int k = 0; k < 2; ++k) \
;         acc[ai][bj][m][n] = __builtin_amdgcn_mfma_f32_16x16x32_bf16(Bt[n][k], At[m][k], acc[ai][bj][m][n], 0, 0, 0); __builtin_amdgcn_s_setprio(0); } while (0)
; #define PG8_WAIT_V(n) asm volatile("s_waitcnt vmcnt(" #n ")" ::: "memory")
; #define PG8_BAR __builtin_amdgcn_s_barrier()
; template <class Epi, class Sched, bool ABLK = false, bool ALIGN_EPI = true, bool SP2 = true, bool BBLK = true>
; __device__ __forceinline__ void gemm_phase(LAS unsigned char* lds, const Gemm g, const Sched& S, const Epi& E) {
;     ...
;             const bool last = (t == nt - 2);
;             const char* a1 = a_tile(uA, tbA + t + 1);
;             const char* a2 = last ? a_tile(nuA, ntbA) : a_tile(uA, tbA + t + 2); const char* b2 = last ? nB : cB + (size_t)(t + 2) * kstepB;
;             const char* a3 = last ? a_tile(nuA, ntbA + 1) : a_tile(uA, tbA + t + 3); const char* b3 = b2 + kstepB;
;             if (last && has_next) S.a_ready(nxt);
;             if constexpr (SP2) {
;             PG8_LDB(B0, 0, 0); PG8_LDB(B1, 0, 1); PG8_SCHED; PG8_LDA(At, 0, 0); PG8_STAGE(PG8_SA(1, 1), a1 + hstepA, voffA);
;             PG8_WAIT_V(8); PG8_WAIT_L(0); PG8_BAR; PG8_MMA(0, 0, At, B0); PG8_MMA(0, 1, At, B1); PG8_BAR; PG8_SCHED;
;             PG8_LDA(At, 0, 1); PG8_STAGE(PG8_SB(0, 0), b2, voffB); PG8_STAGE(PG8_SB(0, 1), b2 + hstepB, voffB); PG8_STAGE(PG8_SA(0, 0), a2, voffA);
;             PG8_WAIT_V(8); PG8_WAIT_L(0); PG8_BAR; PG8_MMA(1, 0, At, B0); PG8_MMA(1, 1, At, B1); PG8_BAR; PG8_SCHED;
.LBB0_1907:
	ds_read_b128 v[152:155], v148
	ds_read_b128 v[156:159], v148 offset:1024
	ds_read_b128 v[160:163], v148 offset:2048
	ds_read_b128 v[164:167], v148 offset:3072
	ds_read_b128 v[168:171], v149
	ds_read_b128 v[172:175], v149 offset:1024
	ds_read_b128 v[176:179], v149 offset:2048
	ds_read_b128 v[180:183], v149 offset:3072
	s_add_u32 s34, s55, s30
	s_addc_u32 s35, s56, s31
	s_add_u32 s38, s34, 0x10000
	s_addc_u32 s39, s35, 0
	s_add_i32 s58, s58, 2
	s_add_u32 s36, s53, s30
	s_addc_u32 s37, s54, s31
	s_add_u32 s34, s34, 0x18000
	s_addc_u32 s35, s35, 0
	s_cmp_eq_u32 s57, s30
	s_cselect_b32 s35, s52, s35
	s_cselect_b32 s34, s51, s34
	s_cselect_b32 s37, s4, s37
	s_cselect_b32 s36, s5, s36
	s_cselect_b32 s39, s50, s39
	s_cselect_b32 s38, s27, s38
	v_lshl_add_u64 v[216:217], v[142:143], 0, s[30:31]
	s_add_i32 m0, s41, 0xc000
	ds_read_b128 v[184:187], v150
	ds_read_b128 v[188:191], v150 offset:1024
	ds_read_b128 v[192:195], v150 offset:2048
	ds_read_b128 v[196:199], v150 offset:3072
	ds_read_b128 v[200:203], v150 offset:4096
	ds_read_b128 v[204:207], v150 offset:5120
	ds_read_b128 v[208:211], v150 offset:6144
	ds_read_b128 v[212:215], v150 offset:7168
	global_load_lds_dwordx4 v[216:217], off
	v_lshl_add_u64 v[216:217], v[144:145], 0, s[30:31]
	s_add_i32 m0, s41, 0xe000
	s_nop 0
	global_load_lds_dwordx4 v[216:217], off
	s_waitcnt vmcnt(8)
	s_waitcnt lgkmcnt(0)
	s_barrier
	v_mfma_f32_16x16x32_bf16 v[126:129], v[152:155], v[184:187], v[126:129]
	v_mfma_f32_16x16x32_bf16 v[122:125], v[160:163], v[184:187], v[122:125]
	v_mfma_f32_16x16x32_bf16 v[110:113], v[152:155], v[192:195], v[110:113]
	v_mfma_f32_16x16x32_bf16 v[106:109], v[160:163], v[192:195], v[106:109]
	v_mfma_f32_16x16x32_bf16 v[94:97], v[152:155], v[200:203], v[94:97]
	v_mfma_f32_16x16x32_bf16 v[90:93], v[160:163], v[200:203], v[90:93]
	v_mfma_f32_16x16x32_bf16 v[78:81], v[152:155], v[208:211], v[78:81]
	v_mfma_f32_16x16x32_bf16 v[74:77], v[160:163], v[208:211], v[74:77]
	v_mfma_f32_16x16x32_bf16 v[126:129], v[156:159], v[188:191], v[126:129]
	v_mfma_f32_16x16x32_bf16 v[122:125], v[164:167], v[188:191], v[122:125]
	v_mfma_f32_16x16x32_bf16 v[110:113], v[156:159], v[196:199], v[110:113]
	v_mfma_f32_16x16x32_bf16 v[106:109], v[164:167], v[196:199], v[106:109]
	v_mfma_f32_16x16x32_bf16 v[94:97], v[156:159], v[204:207], v[94:97]
	v_mfma_f32_16x16x32_bf16 v[90:93], v[164:167], v[204:207], v[90:93]
	v_mfma_f32_16x16x32_bf16 v[78:81], v[156:159], v[212:215], v[78:81]
	v_mfma_f32_16x16x32_bf16 v[74:77], v[164:167], v[212:215], v[74:77]
	v_mfma_f32_16x16x32_bf16 v[118:121], v[168:171], v[184:187], v[118:121]
	v_mfma_f32_16x16x32_bf16 v[114:117], v[176:179], v[184:187], v[114:117]
	v_mfma_f32_16x16x32_bf16 v[102:105], v[168:171], v[192:195], v[102:105]
	v_mfma_f32_16x16x32_bf16 v[98:101], v[176:179], v[192:195], v[98:101]
	v_mfma_f32_16x16x32_bf16 v[86:89], v[168:171], v[200:203], v[86:89]
	v_mfma_f32_16x16x32_bf16 v[82:85], v[176:179], v[200:203], v[82:85]
	v_mfma_f32_16x16x32_bf16 v[70:73], v[168:171], v[208:211], v[70:73]
	v_mfma_f32_16x16x32_bf16 v[66:69], v[176:179], v[208:211], v[66:69]
	v_mfma_f32_16x16x32_bf16 v[118:121], v[172:175], v[188:191], v[118:121]
	v_mfma_f32_16x16x32_bf16 v[114:117], v[180:183], v[188:191], v[114:117]
	v_mfma_f32_16x16x32_bf16 v[102:105], v[172:175], v[196:199], v[102:105]
	v_mfma_f32_16x16x32_bf16 v[98:101], v[180:183], v[196:199], v[98:101]
	v_mfma_f32_16x16x32_bf16 v[86:89], v[172:175], v[204:207], v[86:89]
	v_mfma_f32_16x16x32_bf16 v[82:85], v[180:183], v[204:207], v[82:85]
	v_mfma_f32_16x16x32_bf16 v[70:73], v[172:175], v[212:215], v[70:73]
	v_mfma_f32_16x16x32_bf16 v[66:69], v[180:183], v[212:215], v[66:69]
	s_barrier
	s_add_i32 s59, s72, s40
	v_lshl_add_u64 v[216:217], s[36:37], 0, v[130:131]
	s_mov_b32 m0, s59
	ds_read_b128 v[184:187], v150 offset:16384
	ds_read_b128 v[188:191], v150 offset:17408
	ds_read_b128 v[192:195], v150 offset:18432
	ds_read_b128 v[196:199], v150 offset:19456
	ds_read_b128 v[200:203], v150 offset:20480
	ds_read_b128 v[204:207], v150 offset:21504
	ds_read_b128 v[208:211], v150 offset:22528
	ds_read_b128 v[212:215], v150 offset:23552
	global_load_lds_dwordx4 v[216:217], off
	s_add_i32 m0, s59, 0x2000
	s_add_u32 s64, s36, 0x4000
	v_lshl_add_u64 v[216:217], s[36:37], 0, v[132:133]
	s_addc_u32 s65, s37, 0
	s_add_i32 s59, s73, s40
	global_load_lds_dwordx4 v[216:217], off
	v_lshl_add_u64 v[216:217], s[64:65], 0, v[130:131]
	s_mov_b32 m0, s59
	s_nop 0
	global_load_lds_dwordx4 v[216:217], off
	v_lshl_add_u64 v[216:217], s[64:65], 0, v[132:133]
	s_add_i32 m0, s59, 0x2000
	s_nop 0
	global_load_lds_dwordx4 v[216:217], off
	v_lshl_add_u64 v[216:217], s[38:39], 0, v[130:131]
	s_mov_b32 m0, s41
	s_nop 0
	global_load_lds_dwordx4 v[216:217], off
	v_lshl_add_u64 v[216:217], s[38:39], 0, v[132:133]
	s_mov_b32 m0, s42
	s_nop 0
	global_load_lds_dwordx4 v[216:217], off
	s_waitcnt vmcnt(8)
	s_waitcnt lgkmcnt(0)
	s_barrier
; #define PG8_STAGE(bufoff, gbase, voff) do { _Pragma("unroll") for (int _i = 0; _i < 2; ++_i) \
;         __builtin_amdgcn_global_load_lds((const unsigned*)((const char*)(gbase) + (voff)[_i]), (LAS unsigned*)(lds + (bufoff) + ldsw + _i * 8192), 16, 0, 0); } while (0)
; #define PG8_LDA(dst, b, h) do { _Pragma("unroll") for (int m = 0; m < 4; ++m) _Pragma("unroll") for (int k = 0; k < 2; ++k) dst[m][k] = *(const LAS bf16x8*)(lds + PG8_SA(b, h) + aoff + m * 2048 + k * 1024); } while (0)
; #define PG8_LDB(dst, b, h) do { _Pragma("unroll") for (int n = 0; n < 2; ++n) _Pragma("unroll") for (int k = 0; k < 2; ++k) dst[n][k] = *(const LAS bf16x8*)(lds + PG8_SB(b, h) + boff + n * 2048 + k * 1024); } while (0)
; #define PG8_MMA(ai, bj, At, Bt) do { __builtin_amdgcn_s_setprio(1); _Pragma("unroll") for (int m = 0; m < 4; ++m) _Pragma("unroll") for (int n = 0; n < 2; ++n) _Pragma("unroll") for (int k = 0; k < 2; ++k) \
;         acc[ai][bj][m][n] = __builtin_amdgcn_mfma_f32_16x16x32_bf16(Bt[n][k], At[m][k], acc[ai][bj][m][n], 0, 0, 0); __builtin_amdgcn_s_setprio(0); } while (0)
; #define PG8_WAIT_V(n) asm volatile("s_waitcnt vmcnt(" #n ")" ::: "memory")
; #define PG8_WAIT_L(n) asm volatile("s_waitcnt lgkmcnt(" #n ")" ::: "memory")
; #define PG8_BAR __builtin_amdgcn_s_barrier()
; #define PG8_SCHED __builtin_amdgcn_sched_barrier(0)
; template <class Epi, class Sched, bool ABLK = false, bool ALIGN_EPI = true, bool SP2 = true, bool BBLK = true>
; __device__ __forceinline__ void gemm_phase(LAS unsigned char* lds, const Gemm g, const Sched& S, const Epi& E) {
;     ...
;             PG8_WAIT_V(8); PG8_WAIT_L(0); PG8_BAR; PG8_MMA(1, 0, At, B0); PG8_MMA(1, 1, At, B1); PG8_BAR; PG8_SCHED;
;             PG8_LDB(B0, 1, 0); PG8_LDB(B1, 1, 1); PG8_SCHED; PG8_LDA(At, 1, 0); PG8_STAGE(PG8_SA(0, 1), a2 + hstepA, voffA);
;             PG8_WAIT_V(8); PG8_WAIT_L(0); PG8_BAR; PG8_MMA(0, 0, At, B0); PG8_MMA(0, 1, At, B1); PG8_BAR; PG8_SCHED;
	v_mfma_f32_16x16x32_bf16 v[62:65], v[152:155], v[184:187], v[62:65]
	v_mfma_f32_16x16x32_bf16 v[58:61], v[160:163], v[184:187], v[58:61]
	v_mfma_f32_16x16x32_bf16 v[46:49], v[152:155], v[192:195], v[46:49]
	v_mfma_f32_16x16x32_bf16 v[42:45], v[160:163], v[192:195], v[42:45]
	v_mfma_f32_16x16x32_bf16 v[30:33], v[152:155], v[200:203], v[30:33]
	v_mfma_f32_16x16x32_bf16 v[26:29], v[160:163], v[200:203], v[26:29]
	v_mfma_f32_16x16x32_bf16 v[14:17], v[152:155], v[208:211], v[14:17]
	v_mfma_f32_16x16x32_bf16 v[10:13], v[160:163], v[208:211], v[10:13]
	v_mfma_f32_16x16x32_bf16 v[62:65], v[156:159], v[188:191], v[62:65]
	v_mfma_f32_16x16x32_bf16 v[58:61], v[164:167], v[188:191], v[58:61]
	v_mfma_f32_16x16x32_bf16 v[46:49], v[156:159], v[196:199], v[46:49]
	v_mfma_f32_16x16x32_bf16 v[42:45], v[164:167], v[196:199], v[42:45]
	v_mfma_f32_16x16x32_bf16 v[30:33], v[156:159], v[204:207], v[30:33]
	v_mfma_f32_16x16x32_bf16 v[26:29], v[164:167], v[204:207], v[26:29]
	v_mfma_f32_16x16x32_bf16 v[14:17], v[156:159], v[212:215], v[14:17]
	v_mfma_f32_16x16x32_bf16 v[10:13], v[164:167], v[212:215], v[10:13]
	v_mfma_f32_16x16x32_bf16 v[54:57], v[168:171], v[184:187], v[54:57]
	v_mfma_f32_16x16x32_bf16 v[50:53], v[176:179], v[184:187], v[50:53]
	v_mfma_f32_16x16x32_bf16 v[38:41], v[168:171], v[192:195], v[38:41]
	v_mfma_f32_16x16x32_bf16 v[34:37], v[176:179], v[192:195], v[34:37]
	v_mfma_f32_16x16x32_bf16 v[22:25], v[168:171], v[200:203], v[22:25]
	v_mfma_f32_16x16x32_bf16 v[18:21], v[176:179], v[200:203], v[18:21]
	v_mfma_f32_16x16x32_bf16 v[6:9], v[168:171], v[208:211], v[6:9]
	v_mfma_f32_16x16x32_bf16 v[2:5], v[176:179], v[208:211], v[2:5]
	v_mfma_f32_16x16x32_bf16 v[54:57], v[172:175], v[188:191], v[54:57]
	v_mfma_f32_16x16x32_bf16 v[50:53], v[180:183], v[188:191], v[50:53]
	v_mfma_f32_16x16x32_bf16 v[38:41], v[172:175], v[196:199], v[38:41]
	v_mfma_f32_16x16x32_bf16 v[34:37], v[180:183], v[196:199], v[34:37]
	v_mfma_f32_16x16x32_bf16 v[22:25], v[172:175], v[204:207], v[22:25]
	v_mfma_f32_16x16x32_bf16 v[18:21], v[180:183], v[204:207], v[18:21]
	v_mfma_f32_16x16x32_bf16 v[6:9], v[172:175], v[212:215], v[6:9]
	v_mfma_f32_16x16x32_bf16 v[2:5], v[180:183], v[212:215], v[2:5]
	s_barrier
	v_add_u32_e32 v151, s60, v146
	ds_read_b128 v[152:155], v151
	ds_read_b128 v[156:159], v151 offset:1024
	ds_read_b128 v[160:163], v151 offset:2048
	ds_read_b128 v[164:167], v151 offset:3072
	v_add_u32_e32 v151, s61, v146
	ds_read_b128 v[168:171], v151
	ds_read_b128 v[172:175], v151 offset:1024
	ds_read_b128 v[176:179], v151 offset:2048
	ds_read_b128 v[180:183], v151 offset:3072
	s_add_u32 s38, s38, 0x4000
	s_addc_u32 s39, s39, 0
	s_mov_b32 m0, s43
	v_lshl_add_u64 v[216:217], s[38:39], 0, v[130:131]
	ds_read_b128 v[184:187], v150 offset:32768
	ds_read_b128 v[188:191], v150 offset:33792
	ds_read_b128 v[192:195], v150 offset:34816
	ds_read_b128 v[196:199], v150 offset:35840
	ds_read_b128 v[200:203], v150 offset:36864
	ds_read_b128 v[204:207], v150 offset:37888
	ds_read_b128 v[208:211], v150 offset:38912
	ds_read_b128 v[212:215], v150 offset:39936
	global_load_lds_dwordx4 v[216:217], off
	v_lshl_add_u64 v[216:217], s[38:39], 0, v[132:133]
	s_mov_b32 m0, s44
	s_nop 0
	global_load_lds_dwordx4 v[216:217], off
	s_waitcnt vmcnt(8)
	s_waitcnt lgkmcnt(0)
	s_barrier
	v_mfma_f32_16x16x32_bf16 v[126:129], v[152:155], v[184:187], v[126:129]
	v_mfma_f32_16x16x32_bf16 v[122:125], v[160:163], v[184:187], v[122:125]
	v_mfma_f32_16x16x32_bf16 v[110:113], v[152:155], v[192:195], v[110:113]
	v_mfma_f32_16x16x32_bf16 v[106:109], v[160:163], v[192:195], v[106:109]
	v_mfma_f32_16x16x32_bf16 v[94:97], v[152:155], v[200:203], v[94:97]
	v_mfma_f32_16x16x32_bf16 v[90:93], v[160:163], v[200:203], v[90:93]
	v_mfma_f32_16x16x32_bf16 v[78:81], v[152:155], v[208:211], v[78:81]
	v_mfma_f32_16x16x32_bf16 v[74:77], v[160:163], v[208:211], v[74:77]
	v_mfma_f32_16x16x32_bf16 v[126:129], v[156:159], v[188:191], v[126:129]
	v_mfma_f32_16x16x32_bf16 v[122:125], v[164:167], v[188:191], v[122:125]
	v_mfma_f32_16x16x32_bf16 v[110:113], v[156:159], v[196:199], v[110:113]
	v_mfma_f32_16x16x32_bf16 v[106:109], v[164:167], v[196:199], v[106:109]
	v_mfma_f32_16x16x32_bf16 v[94:97], v[156:159], v[204:207], v[94:97]
	v_mfma_f32_16x16x32_bf16 v[90:93], v[164:167], v[204:207], v[90:93]
	v_mfma_f32_16x16x32_bf16 v[78:81], v[156:159], v[212:215], v[78:81]
	v_mfma_f32_16x16x32_bf16 v[74:77], v[164:167], v[212:215], v[74:77]
	v_mfma_f32_16x16x32_bf16 v[118:121], v[168:171], v[184:187], v[118:121]
	v_mfma_f32_16x16x32_bf16 v[114:117], v[176:179], v[184:187], v[114:117]
	v_mfma_f32_16x16x32_bf16 v[102:105], v[168:171], v[192:195], v[102:105]
	v_mfma_f32_16x16x32_bf16 v[98:101], v[176:179], v[192:195], v[98:101]
	v_mfma_f32_16x16x32_bf16 v[86:89], v[168:171], v[200:203], v[86:89]
	v_mfma_f32_16x16x32_bf16 v[82:85], v[176:179], v[200:203], v[82:85]
	v_mfma_f32_16x16x32_bf16 v[70:73], v[168:171], v[208:211], v[70:73]
	v_mfma_f32_16x16x32_bf16 v[66:69], v[176:179], v[208:211], v[66:69]
	v_mfma_f32_16x16x32_bf16 v[118:121], v[172:175], v[188:191], v[118:121]
	v_mfma_f32_16x16x32_bf16 v[114:117], v[180:183], v[188:191], v[114:117]
	v_mfma_f32_16x16x32_bf16 v[102:105], v[172:175], v[196:199], v[102:105]
	v_mfma_f32_16x16x32_bf16 v[98:101], v[180:183], v[196:199], v[98:101]
	v_mfma_f32_16x16x32_bf16 v[86:89], v[172:175], v[204:207], v[86:89]
	v_mfma_f32_16x16x32_bf16 v[82:85], v[180:183], v[204:207], v[82:85]
	v_mfma_f32_16x16x32_bf16 v[70:73], v[172:175], v[212:215], v[70:73]
	v_mfma_f32_16x16x32_bf16 v[66:69], v[180:183], v[212:215], v[66:69]
	s_barrier
; #define PG8_STAGE(bufoff, gbase, voff) do { _Pragma("unroll") for (int _i = 0; _i < 2; ++_i) \
;         __builtin_amdgcn_global_load_lds((const unsigned*)((const char*)(gbase) + (voff)[_i]), (LAS unsigned*)(lds + (bufoff) + ldsw + _i * 8192), 16, 0, 0); } while (0)
; #define PG8_LDA(dst, b, h) do { _Pragma("unroll") for (int m = 0; m < 4; ++m) _Pragma("unroll") for (int k = 0; k < 2; ++k) dst[m][k] = *(const LAS bf16x8*)(lds + PG8_SA(b, h) + aoff + m * 2048 + k * 1024); } while (0)
; #define PG8_MMA(ai, bj, At, Bt) do { __builtin_amdgcn_s_setprio(1); _Pragma("unroll") for (int m = 0; m < 4; ++m) _Pragma("unroll") for (int n = 0; n < 2; ++n) _Pragma("unroll") for (int k = 0; k < 2; ++k) \
;         acc[ai][bj][m][n] = __builtin_amdgcn_mfma_f32_16x16x32_bf16(Bt[n][k], At[m][k], acc[ai][bj][m][n], 0, 0, 0); __builtin_amdgcn_s_setprio(0); } while (0)
; #define PG8_WAIT_V(n) asm volatile("s_waitcnt vmcnt(" #n ")" ::: "memory")
; #define PG8_WAIT_L(n) asm volatile("s_waitcnt lgkmcnt(" #n ")" ::: "memory")
; #define PG8_BAR __builtin_amdgcn_s_barrier()
; #define PG8_SCHED __builtin_amdgcn_sched_barrier(0)
; template <class Epi, class Sched, bool ABLK = false, bool ALIGN_EPI = true, bool SP2 = true, bool BBLK = true>
; __device__ __forceinline__ void gemm_phase(LAS unsigned char* lds, const Gemm g, const Sched& S, const Epi& E) {
;     ...
;             PG8_LDA(At, 1, 1); PG8_STAGE(PG8_SB(1, 0), b3, voffB); PG8_STAGE(PG8_SB(1, 1), b3 + hstepB, voffB); PG8_STAGE(PG8_SA(1, 0), a3, voffA);
;             PG8_WAIT_V(8); PG8_WAIT_L(0); PG8_BAR; PG8_MMA(1, 0, At, B0); PG8_MMA(1, 1, At, B1); PG8_BAR; PG8_SCHED;
;     ...
;         if constexpr (ALIGN_EPI) { if (wr == 0) PG8_BAR; }
	s_add_u32 s38, s36, 0x8000
	s_addc_u32 s39, s37, 0
	s_add_i32 s59, s60, s40
	v_lshl_add_u64 v[216:217], s[38:39], 0, v[130:131]
	s_mov_b32 m0, s59
	ds_read_b128 v[184:187], v150 offset:49152
	ds_read_b128 v[188:191], v150 offset:50176
	ds_read_b128 v[192:195], v150 offset:51200
	ds_read_b128 v[196:199], v150 offset:52224
	ds_read_b128 v[200:203], v150 offset:53248
	ds_read_b128 v[204:207], v150 offset:54272
	ds_read_b128 v[208:211], v150 offset:55296
	ds_read_b128 v[212:215], v150 offset:56320
	global_load_lds_dwordx4 v[216:217], off
	s_add_i32 m0, s59, 0x2000
	s_add_u32 s36, s36, 0xc000
	v_lshl_add_u64 v[216:217], s[38:39], 0, v[132:133]
	s_addc_u32 s37, s37, 0
	s_add_i32 s38, s61, s40
	global_load_lds_dwordx4 v[216:217], off
	v_lshl_add_u64 v[216:217], s[36:37], 0, v[130:131]
	s_mov_b32 m0, s38
	s_nop 0
	global_load_lds_dwordx4 v[216:217], off
	v_lshl_add_u64 v[216:217], s[36:37], 0, v[132:133]
	s_add_i32 m0, s38, 0x2000
	s_nop 0
	global_load_lds_dwordx4 v[216:217], off
	v_lshl_add_u64 v[216:217], s[34:35], 0, v[130:131]
	s_mov_b32 m0, s45
	s_nop 0
	global_load_lds_dwordx4 v[216:217], off
	v_lshl_add_u64 v[216:217], s[34:35], 0, v[132:133]
	s_mov_b32 m0, s46
	s_nop 0
	global_load_lds_dwordx4 v[216:217], off
	s_waitcnt vmcnt(8)
	s_waitcnt lgkmcnt(0)
	s_barrier
	v_mfma_f32_16x16x32_bf16 v[62:65], v[152:155], v[184:187], v[62:65]
	v_mfma_f32_16x16x32_bf16 v[58:61], v[160:163], v[184:187], v[58:61]
	v_mfma_f32_16x16x32_bf16 v[46:49], v[152:155], v[192:195], v[46:49]
	v_mfma_f32_16x16x32_bf16 v[42:45], v[160:163], v[192:195], v[42:45]
	v_mfma_f32_16x16x32_bf16 v[30:33], v[152:155], v[200:203], v[30:33]
	v_mfma_f32_16x16x32_bf16 v[26:29], v[160:163], v[200:203], v[26:29]
	v_mfma_f32_16x16x32_bf16 v[14:17], v[152:155], v[208:211], v[14:17]
	v_mfma_f32_16x16x32_bf16 v[10:13], v[160:163], v[208:211], v[10:13]
	v_mfma_f32_16x16x32_bf16 v[62:65], v[156:159], v[188:191], v[62:65]
	v_mfma_f32_16x16x32_bf16 v[58:61], v[164:167], v[188:191], v[58:61]
	v_mfma_f32_16x16x32_bf16 v[46:49], v[156:159], v[196:199], v[46:49]
	v_mfma_f32_16x16x32_bf16 v[42:45], v[164:167], v[196:199], v[42:45]
	v_mfma_f32_16x16x32_bf16 v[30:33], v[156:159], v[204:207], v[30:33]
	v_mfma_f32_16x16x32_bf16 v[26:29], v[164:167], v[204:207], v[26:29]
	v_mfma_f32_16x16x32_bf16 v[14:17], v[156:159], v[212:215], v[14:17]
	v_mfma_f32_16x16x32_bf16 v[10:13], v[164:167], v[212:215], v[10:13]
	v_mfma_f32_16x16x32_bf16 v[54:57], v[168:171], v[184:187], v[54:57]
	v_mfma_f32_16x16x32_bf16 v[50:53], v[176:179], v[184:187], v[50:53]
	v_mfma_f32_16x16x32_bf16 v[38:41], v[168:171], v[192:195], v[38:41]
	v_mfma_f32_16x16x32_bf16 v[34:37], v[176:179], v[192:195], v[34:37]
	v_mfma_f32_16x16x32_bf16 v[22:25], v[168:171], v[200:203], v[22:25]
	v_mfma_f32_16x16x32_bf16 v[18:21], v[176:179], v[200:203], v[18:21]
	v_mfma_f32_16x16x32_bf16 v[6:9], v[168:171], v[208:211], v[6:9]
	v_mfma_f32_16x16x32_bf16 v[2:5], v[176:179], v[208:211], v[2:5]
	v_mfma_f32_16x16x32_bf16 v[54:57], v[172:175], v[188:191], v[54:57]
	v_mfma_f32_16x16x32_bf16 v[50:53], v[180:183], v[188:191], v[50:53]
	v_mfma_f32_16x16x32_bf16 v[38:41], v[172:175], v[196:199], v[38:41]
	v_mfma_f32_16x16x32_bf16 v[34:37], v[180:183], v[196:199], v[34:37]
	v_mfma_f32_16x16x32_bf16 v[22:25], v[172:175], v[204:207], v[22:25]
	v_mfma_f32_16x16x32_bf16 v[18:21], v[180:183], v[204:207], v[18:21]
	v_mfma_f32_16x16x32_bf16 v[6:9], v[172:175], v[212:215], v[6:9]
	v_mfma_f32_16x16x32_bf16 v[2:5], v[180:183], v[212:215], v[2:5]
	s_barrier
	s_add_u32 s30, s30, 0x10000
	s_addc_u32 s31, s31, 0
	s_cmp_ge_u32 s58, s48
	s_cbranch_scc0 .LBB0_1907
	s_and_b64 vcc, exec, s[6:7]
	s_cbranch_vccz .LBB0_1910
	s_barrier

; #define PG8_STAGE(bufoff, gbase, voff) do { _Pragma("unroll") for (int _i = 0; _i < 2; ++_i) \
;         __builtin_amdgcn_global_load_lds((const unsigned*)((const char*)(gbase) + (voff)[_i]), (LAS unsigned*)(lds + (bufoff) + ldsw + _i * 8192), 16, 0, 0); } while (0)
; #define PG8_LDA(dst, b, h) do { _Pragma("unroll") for (int m = 0; m < 4; ++m) _Pragma("unroll") for (int k = 0; k < 2; ++k) dst[m][k] = *(const LAS bf16x8*)(lds + PG8_SA(b, h) + aoff + m * 2048 + k * 1024); } while (0)
; #define PG8_LDB(dst, b, h) do { _Pragma("unroll") for (int n = 0; n < 2; ++n) _Pragma("unroll") for (int k = 0; k < 2; ++k) dst[n][k] = *(const LAS bf16x8*)(lds + PG8_SB(b, h) + boff + n * 2048 + k * 1024); } while (0)
; #define PG8_MMA(ai, bj, At, Bt) do { __builtin_amdgcn_s_setprio(1); _Pragma("unroll") for (int m = 0; m < 4; ++m) _Pragma("unroll") for (int n = 0; n < 2; ++n) _Pragma("unroll") for (int k = 0; k < 2; ++k) \
;         acc[ai][bj][m][n] = __builtin_amdgcn_mfma_f32_16x16x32_bf16(Bt[n][k], At[m][k], acc[ai][bj][m][n], 0, 0, 0); __builtin_amdgcn_s_setprio(0); } while (0)
; #define PG8_WAIT_V(n) asm volatile("s_waitcnt vmcnt(" #n ")" ::: "memory")
; #define PG8_BAR __builtin_amdgcn_s_barrier()
; template <class Epi, class Sched, bool ABLK = false, bool ALIGN_EPI = true, bool SP2 = true, bool BBLK = true>
; __device__ __forceinline__ void gemm_phase(LAS unsigned char* lds, const Gemm g, const Sched& S, const Epi& E) {
;     ...
;             const bool last = (t == nt - 2);
;             const char* a1 = a_tile(uA, tbA + t + 1);
;             const char* a2 = last ? a_tile(nuA, ntbA) : a_tile(uA, tbA + t + 2); const char* b2 = last ? nB : cB + (size_t)(t + 2) * kstepB;
;             const char* a3 = last ? a_tile(nuA, ntbA + 1) : a_tile(uA, tbA + t + 3); const char* b3 = b2 + kstepB;
;             if (last && has_next) S.a_ready(nxt);
;             if constexpr (SP2) {
;             PG8_LDB(B0, 0, 0); PG8_LDB(B1, 0, 1); PG8_SCHED; PG8_LDA(At, 0, 0); PG8_STAGE(PG8_SA(1, 1), a1 + hstepA, voffA);
;             PG8_WAIT_V(8); PG8_WAIT_L(0); PG8_BAR; PG8_MMA(0, 0, At, B0); PG8_MMA(0, 1, At, B1); PG8_BAR; PG8_SCHED;
;             PG8_LDA(At, 0, 1); PG8_STAGE(PG8_SB(0, 0), b2, voffB); PG8_STAGE(PG8_SB(0, 1), b2 + hstepB, voffB); PG8_STAGE(PG8_SA(0, 0), a2, voffA);
;             PG8_WAIT_V(8); PG8_WAIT_L(0); PG8_BAR; PG8_MMA(1, 0, At, B0); PG8_MMA(1, 1, At, B1); PG8_BAR; PG8_SCHED;
.LBB0_2138:
	ds_read_b128 v[152:155], v148
	ds_read_b128 v[156:159], v148 offset:1024
	ds_read_b128 v[160:163], v148 offset:2048
	ds_read_b128 v[164:167], v148 offset:3072
	ds_read_b128 v[168:171], v149
	ds_read_b128 v[172:175], v149 offset:1024
	ds_read_b128 v[176:179], v149 offset:2048
	ds_read_b128 v[180:183], v149 offset:3072
	s_add_u32 s28, s24, s26
	s_addc_u32 s29, s25, s27
	s_add_u32 s34, s28, 0x100
	s_addc_u32 s35, s29, 0
	s_add_u32 s28, s28, 0x180
	s_addc_u32 s29, s29, 0
	s_cmpk_eq_i32 s26, 0xf00
	s_cselect_b32 s29, s49, s29
	s_cselect_b32 s28, s48, s28
	s_cselect_b32 s31, s11, s51
	s_cselect_b32 s30, s13, s50
	s_cselect_b32 s35, s4, s35
	s_cselect_b32 s34, s5, s34
	s_mov_b32 m0, s47
	v_lshl_add_u64 v[216:217], v[142:143], 0, s[26:27]
	ds_read_b128 v[184:187], v150
	ds_read_b128 v[188:191], v150 offset:1024
	ds_read_b128 v[192:195], v150 offset:2048
	ds_read_b128 v[196:199], v150 offset:3072
	ds_read_b128 v[200:203], v150 offset:4096
	ds_read_b128 v[204:207], v150 offset:5120
	ds_read_b128 v[208:211], v150 offset:6144
	ds_read_b128 v[212:215], v150 offset:7168
	global_load_lds_dwordx4 v[216:217], off
	v_lshl_add_u64 v[216:217], v[144:145], 0, s[26:27]
	s_add_i32 m0, s21, 0xe000
	s_nop 0
	global_load_lds_dwordx4 v[216:217], off
	s_waitcnt vmcnt(8)
	s_waitcnt lgkmcnt(0)
	s_barrier
	v_mfma_f32_16x16x32_bf16 v[122:125], v[152:155], v[184:187], v[122:125]
	v_mfma_f32_16x16x32_bf16 v[118:121], v[160:163], v[184:187], v[118:121]
	v_mfma_f32_16x16x32_bf16 v[106:109], v[152:155], v[192:195], v[106:109]
	v_mfma_f32_16x16x32_bf16 v[102:105], v[160:163], v[192:195], v[102:105]
	v_mfma_f32_16x16x32_bf16 v[90:93], v[152:155], v[200:203], v[90:93]
	v_mfma_f32_16x16x32_bf16 v[86:89], v[160:163], v[200:203], v[86:89]
	v_mfma_f32_16x16x32_bf16 v[74:77], v[152:155], v[208:211], v[74:77]
	v_mfma_f32_16x16x32_bf16 v[70:73], v[160:163], v[208:211], v[70:73]
	v_mfma_f32_16x16x32_bf16 v[122:125], v[156:159], v[188:191], v[122:125]
	v_mfma_f32_16x16x32_bf16 v[118:121], v[164:167], v[188:191], v[118:121]
	v_mfma_f32_16x16x32_bf16 v[106:109], v[156:159], v[196:199], v[106:109]
	v_mfma_f32_16x16x32_bf16 v[102:105], v[164:167], v[196:199], v[102:105]
	v_mfma_f32_16x16x32_bf16 v[90:93], v[156:159], v[204:207], v[90:93]
	v_mfma_f32_16x16x32_bf16 v[86:89], v[164:167], v[204:207], v[86:89]
	v_mfma_f32_16x16x32_bf16 v[74:77], v[156:159], v[212:215], v[74:77]
	v_mfma_f32_16x16x32_bf16 v[70:73], v[164:167], v[212:215], v[70:73]
	v_mfma_f32_16x16x32_bf16 v[126:129], v[168:171], v[184:187], v[126:129]
	v_mfma_f32_16x16x32_bf16 v[114:117], v[176:179], v[184:187], v[114:117]
	v_mfma_f32_16x16x32_bf16 v[110:113], v[168:171], v[192:195], v[110:113]
	v_mfma_f32_16x16x32_bf16 v[98:101], v[176:179], v[192:195], v[98:101]
	v_mfma_f32_16x16x32_bf16 v[94:97], v[168:171], v[200:203], v[94:97]
	v_mfma_f32_16x16x32_bf16 v[82:85], v[176:179], v[200:203], v[82:85]
	v_mfma_f32_16x16x32_bf16 v[78:81], v[168:171], v[208:211], v[78:81]
	v_mfma_f32_16x16x32_bf16 v[66:69], v[176:179], v[208:211], v[66:69]
	v_mfma_f32_16x16x32_bf16 v[126:129], v[172:175], v[188:191], v[126:129]
	v_mfma_f32_16x16x32_bf16 v[114:117], v[180:183], v[188:191], v[114:117]
	v_mfma_f32_16x16x32_bf16 v[110:113], v[172:175], v[196:199], v[110:113]
	v_mfma_f32_16x16x32_bf16 v[98:101], v[180:183], v[196:199], v[98:101]
	v_mfma_f32_16x16x32_bf16 v[94:97], v[172:175], v[204:207], v[94:97]
	v_mfma_f32_16x16x32_bf16 v[82:85], v[180:183], v[204:207], v[82:85]
	v_mfma_f32_16x16x32_bf16 v[78:81], v[172:175], v[212:215], v[78:81]
	v_mfma_f32_16x16x32_bf16 v[66:69], v[180:183], v[212:215], v[66:69]
	s_barrier
	s_add_i32 s53, s72, s36
	v_lshl_add_u64 v[216:217], s[30:31], 0, v[134:135]
	s_mov_b32 m0, s53
	ds_read_b128 v[184:187], v150 offset:16384
	ds_read_b128 v[188:191], v150 offset:17408
	ds_read_b128 v[192:195], v150 offset:18432
	ds_read_b128 v[196:199], v150 offset:19456
	ds_read_b128 v[200:203], v150 offset:20480
	ds_read_b128 v[204:207], v150 offset:21504
	ds_read_b128 v[208:211], v150 offset:22528
	ds_read_b128 v[212:215], v150 offset:23552
	global_load_lds_dwordx4 v[216:217], off
	s_add_i32 m0, s53, 0x2000
	s_add_u32 s54, s30, 0x4000
	v_lshl_add_u64 v[216:217], s[30:31], 0, v[130:131]
	s_addc_u32 s55, s31, 0
	s_add_i32 s53, s73, s36
	global_load_lds_dwordx4 v[216:217], off
	v_lshl_add_u64 v[216:217], s[54:55], 0, v[134:135]
	s_mov_b32 m0, s53
	s_nop 0
	global_load_lds_dwordx4 v[216:217], off
	v_lshl_add_u64 v[216:217], s[54:55], 0, v[130:131]
	s_add_i32 m0, s53, 0x2000
	s_nop 0
	global_load_lds_dwordx4 v[216:217], off
	v_lshl_add_u64 v[216:217], s[34:35], 0, v[136:137]
	s_mov_b32 m0, s21
	s_nop 0
	global_load_lds_dwordx4 v[216:217], off
	v_lshl_add_u64 v[216:217], s[34:35], 0, v[132:133]
	s_mov_b32 m0, s23
	s_nop 0
	global_load_lds_dwordx4 v[216:217], off
	s_waitcnt vmcnt(8)
	s_waitcnt lgkmcnt(0)
	s_barrier
; #define PG8_STAGE(bufoff, gbase, voff) do { _Pragma("unroll") for (int _i = 0; _i < 2; ++_i) \
;         __builtin_amdgcn_global_load_lds((const unsigned*)((const char*)(gbase) + (voff)[_i]), (LAS unsigned*)(lds + (bufoff) + ldsw + _i * 8192), 16, 0, 0); } while (0)
; #define PG8_LDA(dst, b, h) do { _Pragma("unroll") for (int m = 0; m < 4; ++m) _Pragma("unroll") for (int k = 0; k < 2; ++k) dst[m][k] = *(const LAS bf16x8*)(lds + PG8_SA(b, h) + aoff + m * 2048 + k * 1024); } while (0)
; #define PG8_LDB(dst, b, h) do { _Pragma("unroll") for (int n = 0; n < 2; ++n) _Pragma("unroll") for (int k = 0; k < 2; ++k) dst[n][k] = *(const LAS bf16x8*)(lds + PG8_SB(b, h) + boff + n * 2048 + k * 1024); } while (0)
; #define PG8_MMA(ai, bj, At, Bt) do { __builtin_amdgcn_s_setprio(1); _Pragma("unroll") for (int m = 0; m < 4; ++m) _Pragma("unroll") for (int n = 0; n < 2; ++n) _Pragma("unroll") for (int k = 0; k < 2; ++k) \
;         acc[ai][bj][m][n] = __builtin_amdgcn_mfma_f32_16x16x32_bf16(Bt[n][k], At[m][k], acc[ai][bj][m][n], 0, 0, 0); __builtin_amdgcn_s_setprio(0); } while (0)
; #define PG8_WAIT_V(n) asm volatile("s_waitcnt vmcnt(" #n ")" ::: "memory")
; #define PG8_WAIT_L(n) asm volatile("s_waitcnt lgkmcnt(" #n ")" ::: "memory")
; #define PG8_BAR __builtin_amdgcn_s_barrier()
; #define PG8_SCHED __builtin_amdgcn_sched_barrier(0)
; template <class Epi, class Sched, bool ABLK = false, bool ALIGN_EPI = true, bool SP2 = true, bool BBLK = true>
; __device__ __forceinline__ void gemm_phase(LAS unsigned char* lds, const Gemm g, const Sched& S, const Epi& E) {
;     ...
;             PG8_WAIT_V(8); PG8_WAIT_L(0); PG8_BAR; PG8_MMA(1, 0, At, B0); PG8_MMA(1, 1, At, B1); PG8_BAR; PG8_SCHED;
;             PG8_LDB(B0, 1, 0); PG8_LDB(B1, 1, 1); PG8_SCHED; PG8_LDA(At, 1, 0); PG8_STAGE(PG8_SA(0, 1), a2 + hstepA, voffA);
;             PG8_WAIT_V(8); PG8_WAIT_L(0); PG8_BAR; PG8_MMA(0, 0, At, B0); PG8_MMA(0, 1, At, B1); PG8_BAR; PG8_SCHED;
	v_mfma_f32_16x16x32_bf16 v[58:61], v[152:155], v[184:187], v[58:61]
	v_mfma_f32_16x16x32_bf16 v[54:57], v[160:163], v[184:187], v[54:57]
	v_mfma_f32_16x16x32_bf16 v[42:45], v[152:155], v[192:195], v[42:45]
	v_mfma_f32_16x16x32_bf16 v[38:41], v[160:163], v[192:195], v[38:41]
	v_mfma_f32_16x16x32_bf16 v[26:29], v[152:155], v[200:203], v[26:29]
	v_mfma_f32_16x16x32_bf16 v[22:25], v[160:163], v[200:203], v[22:25]
	v_mfma_f32_16x16x32_bf16 v[10:13], v[152:155], v[208:211], v[10:13]
	v_mfma_f32_16x16x32_bf16 v[6:9], v[160:163], v[208:211], v[6:9]
	v_mfma_f32_16x16x32_bf16 v[58:61], v[156:159], v[188:191], v[58:61]
	v_mfma_f32_16x16x32_bf16 v[54:57], v[164:167], v[188:191], v[54:57]
	v_mfma_f32_16x16x32_bf16 v[42:45], v[156:159], v[196:199], v[42:45]
	v_mfma_f32_16x16x32_bf16 v[38:41], v[164:167], v[196:199], v[38:41]
	v_mfma_f32_16x16x32_bf16 v[26:29], v[156:159], v[204:207], v[26:29]
	v_mfma_f32_16x16x32_bf16 v[22:25], v[164:167], v[204:207], v[22:25]
	v_mfma_f32_16x16x32_bf16 v[10:13], v[156:159], v[212:215], v[10:13]
	v_mfma_f32_16x16x32_bf16 v[6:9], v[164:167], v[212:215], v[6:9]
	v_mfma_f32_16x16x32_bf16 v[62:65], v[168:171], v[184:187], v[62:65]
	v_mfma_f32_16x16x32_bf16 v[50:53], v[176:179], v[184:187], v[50:53]
	v_mfma_f32_16x16x32_bf16 v[46:49], v[168:171], v[192:195], v[46:49]
	v_mfma_f32_16x16x32_bf16 v[34:37], v[176:179], v[192:195], v[34:37]
	v_mfma_f32_16x16x32_bf16 v[30:33], v[168:171], v[200:203], v[30:33]
	v_mfma_f32_16x16x32_bf16 v[18:21], v[176:179], v[200:203], v[18:21]
	v_mfma_f32_16x16x32_bf16 v[14:17], v[168:171], v[208:211], v[14:17]
	v_mfma_f32_16x16x32_bf16 v[2:5], v[176:179], v[208:211], v[2:5]
	v_mfma_f32_16x16x32_bf16 v[62:65], v[172:175], v[188:191], v[62:65]
	v_mfma_f32_16x16x32_bf16 v[50:53], v[180:183], v[188:191], v[50:53]
	v_mfma_f32_16x16x32_bf16 v[46:49], v[172:175], v[196:199], v[46:49]
	v_mfma_f32_16x16x32_bf16 v[34:37], v[180:183], v[196:199], v[34:37]
	v_mfma_f32_16x16x32_bf16 v[30:33], v[172:175], v[204:207], v[30:33]
	v_mfma_f32_16x16x32_bf16 v[18:21], v[180:183], v[204:207], v[18:21]
	v_mfma_f32_16x16x32_bf16 v[14:17], v[172:175], v[212:215], v[14:17]
	v_mfma_f32_16x16x32_bf16 v[2:5], v[180:183], v[212:215], v[2:5]
	s_barrier
	v_add_u32_e32 v151, s60, v146
	ds_read_b128 v[152:155], v151
	ds_read_b128 v[156:159], v151 offset:1024
	ds_read_b128 v[160:163], v151 offset:2048
	ds_read_b128 v[164:167], v151 offset:3072
	v_add_u32_e32 v151, s61, v146
	ds_read_b128 v[168:171], v151
	ds_read_b128 v[172:175], v151 offset:1024
	ds_read_b128 v[176:179], v151 offset:2048
	ds_read_b128 v[180:183], v151 offset:3072
	s_add_u32 s34, s34, 0x80000
	s_addc_u32 s35, s35, 0
	s_mov_b32 m0, s39
	v_lshl_add_u64 v[216:217], s[34:35], 0, v[136:137]
	ds_read_b128 v[184:187], v150 offset:32768
	ds_read_b128 v[188:191], v150 offset:33792
	ds_read_b128 v[192:195], v150 offset:34816
	ds_read_b128 v[196:199], v150 offset:35840
	ds_read_b128 v[200:203], v150 offset:36864
	ds_read_b128 v[204:207], v150 offset:37888
	ds_read_b128 v[208:211], v150 offset:38912
	ds_read_b128 v[212:215], v150 offset:39936
	global_load_lds_dwordx4 v[216:217], off
	v_lshl_add_u64 v[216:217], s[34:35], 0, v[132:133]
	s_mov_b32 m0, s40
	s_nop 0
	global_load_lds_dwordx4 v[216:217], off
	s_waitcnt vmcnt(8)
	s_waitcnt lgkmcnt(0)
	s_barrier
	v_mfma_f32_16x16x32_bf16 v[122:125], v[152:155], v[184:187], v[122:125]
	v_mfma_f32_16x16x32_bf16 v[118:121], v[160:163], v[184:187], v[118:121]
	v_mfma_f32_16x16x32_bf16 v[106:109], v[152:155], v[192:195], v[106:109]
	v_mfma_f32_16x16x32_bf16 v[102:105], v[160:163], v[192:195], v[102:105]
	v_mfma_f32_16x16x32_bf16 v[90:93], v[152:155], v[200:203], v[90:93]
	v_mfma_f32_16x16x32_bf16 v[86:89], v[160:163], v[200:203], v[86:89]
	v_mfma_f32_16x16x32_bf16 v[74:77], v[152:155], v[208:211], v[74:77]
	v_mfma_f32_16x16x32_bf16 v[70:73], v[160:163], v[208:211], v[70:73]
	v_mfma_f32_16x16x32_bf16 v[122:125], v[156:159], v[188:191], v[122:125]
	v_mfma_f32_16x16x32_bf16 v[118:121], v[164:167], v[188:191], v[118:121]
	v_mfma_f32_16x16x32_bf16 v[106:109], v[156:159], v[196:199], v[106:109]
	v_mfma_f32_16x16x32_bf16 v[102:105], v[164:167], v[196:199], v[102:105]
	v_mfma_f32_16x16x32_bf16 v[90:93], v[156:159], v[204:207], v[90:93]
	v_mfma_f32_16x16x32_bf16 v[86:89], v[164:167], v[204:207], v[86:89]
	v_mfma_f32_16x16x32_bf16 v[74:77], v[156:159], v[212:215], v[74:77]
	v_mfma_f32_16x16x32_bf16 v[70:73], v[164:167], v[212:215], v[70:73]
	v_mfma_f32_16x16x32_bf16 v[126:129], v[168:171], v[184:187], v[126:129]
	v_mfma_f32_16x16x32_bf16 v[114:117], v[176:179], v[184:187], v[114:117]
	v_mfma_f32_16x16x32_bf16 v[110:113], v[168:171], v[192:195], v[110:113]
	v_mfma_f32_16x16x32_bf16 v[98:101], v[176:179], v[192:195], v[98:101]
	v_mfma_f32_16x16x32_bf16 v[94:97], v[168:171], v[200:203], v[94:97]
	v_mfma_f32_16x16x32_bf16 v[82:85], v[176:179], v[200:203], v[82:85]
	v_mfma_f32_16x16x32_bf16 v[78:81], v[168:171], v[208:211], v[78:81]
	v_mfma_f32_16x16x32_bf16 v[66:69], v[176:179], v[208:211], v[66:69]
	v_mfma_f32_16x16x32_bf16 v[126:129], v[172:175], v[188:191], v[126:129]
	v_mfma_f32_16x16x32_bf16 v[114:117], v[180:183], v[188:191], v[114:117]
	v_mfma_f32_16x16x32_bf16 v[110:113], v[172:175], v[196:199], v[110:113]
	v_mfma_f32_16x16x32_bf16 v[98:101], v[180:183], v[196:199], v[98:101]
	v_mfma_f32_16x16x32_bf16 v[94:97], v[172:175], v[204:207], v[94:97]
	v_mfma_f32_16x16x32_bf16 v[82:85], v[180:183], v[204:207], v[82:85]
	v_mfma_f32_16x16x32_bf16 v[78:81], v[172:175], v[212:215], v[78:81]
	v_mfma_f32_16x16x32_bf16 v[66:69], v[180:183], v[212:215], v[66:69]
	s_barrier
; #define PG8_STAGE(bufoff, gbase, voff) do { _Pragma("unroll") for (int _i = 0; _i < 2; ++_i) \
;         __builtin_amdgcn_global_load_lds((const unsigned*)((const char*)(gbase) + (voff)[_i]), (LAS unsigned*)(lds + (bufoff) + ldsw + _i * 8192), 16, 0, 0); } while (0)
; #define PG8_LDA(dst, b, h) do { _Pragma("unroll") for (int m = 0; m < 4; ++m) _Pragma("unroll") for (int k = 0; k < 2; ++k) dst[m][k] = *(const LAS bf16x8*)(lds + PG8_SA(b, h) + aoff + m * 2048 + k * 1024); } while (0)
; #define PG8_MMA(ai, bj, At, Bt) do { __builtin_amdgcn_s_setprio(1); _Pragma("unroll") for (int m = 0; m < 4; ++m) _Pragma("unroll") for (int n = 0; n < 2; ++n) _Pragma("unroll") for (int k = 0; k < 2; ++k) \
;         acc[ai][bj][m][n] = __builtin_amdgcn_mfma_f32_16x16x32_bf16(Bt[n][k], At[m][k], acc[ai][bj][m][n], 0, 0, 0); __builtin_amdgcn_s_setprio(0); } while (0)
; #define PG8_WAIT_V(n) asm volatile("s_waitcnt vmcnt(" #n ")" ::: "memory")
; #define PG8_WAIT_L(n) asm volatile("s_waitcnt lgkmcnt(" #n ")" ::: "memory")
; #define PG8_BAR __builtin_amdgcn_s_barrier()
; #define PG8_SCHED __builtin_amdgcn_sched_barrier(0)
; template <class Epi, class Sched, bool ABLK = false, bool ALIGN_EPI = true, bool SP2 = true, bool BBLK = true>
; __device__ __forceinline__ void gemm_phase(LAS unsigned char* lds, const Gemm g, const Sched& S, const Epi& E) {
;     ...
;             PG8_LDA(At, 1, 1); PG8_STAGE(PG8_SB(1, 0), b3, voffB); PG8_STAGE(PG8_SB(1, 1), b3 + hstepB, voffB); PG8_STAGE(PG8_SA(1, 0), a3, voffA);
;             PG8_WAIT_V(8); PG8_WAIT_L(0); PG8_BAR; PG8_MMA(1, 0, At, B0); PG8_MMA(1, 1, At, B1); PG8_BAR; PG8_SCHED;
;     ...
;         if constexpr (ALIGN_EPI) { if (wr == 0) PG8_BAR; }
	s_add_u32 s34, s30, 0x8000
	s_addc_u32 s35, s31, 0
	s_add_i32 s53, s60, s36
	v_lshl_add_u64 v[216:217], s[34:35], 0, v[134:135]
	s_mov_b32 m0, s53
	ds_read_b128 v[184:187], v150 offset:49152
	ds_read_b128 v[188:191], v150 offset:50176
	ds_read_b128 v[192:195], v150 offset:51200
	ds_read_b128 v[196:199], v150 offset:52224
	ds_read_b128 v[200:203], v150 offset:53248
	ds_read_b128 v[204:207], v150 offset:54272
	ds_read_b128 v[208:211], v150 offset:55296
	ds_read_b128 v[212:215], v150 offset:56320
	global_load_lds_dwordx4 v[216:217], off
	s_add_i32 m0, s53, 0x2000
	s_add_u32 s30, s30, 0xc000
	v_lshl_add_u64 v[216:217], s[34:35], 0, v[130:131]
	s_addc_u32 s31, s31, 0
	s_add_i32 s34, s61, s36
	global_load_lds_dwordx4 v[216:217], off
	v_lshl_add_u64 v[216:217], s[30:31], 0, v[134:135]
	s_mov_b32 m0, s34
	s_nop 0
	global_load_lds_dwordx4 v[216:217], off
	v_lshl_add_u64 v[216:217], s[30:31], 0, v[130:131]
	s_add_i32 m0, s34, 0x2000
	s_nop 0
	global_load_lds_dwordx4 v[216:217], off
	v_lshl_add_u64 v[216:217], s[28:29], 0, v[136:137]
	s_mov_b32 m0, s42
	s_nop 0
	global_load_lds_dwordx4 v[216:217], off
	v_lshl_add_u64 v[216:217], s[28:29], 0, v[132:133]
	s_mov_b32 m0, s43
	s_nop 0
	global_load_lds_dwordx4 v[216:217], off
	s_waitcnt vmcnt(8)
	s_waitcnt lgkmcnt(0)
	s_barrier
	v_mfma_f32_16x16x32_bf16 v[58:61], v[152:155], v[184:187], v[58:61]
	v_mfma_f32_16x16x32_bf16 v[54:57], v[160:163], v[184:187], v[54:57]
	v_mfma_f32_16x16x32_bf16 v[42:45], v[152:155], v[192:195], v[42:45]
	v_mfma_f32_16x16x32_bf16 v[38:41], v[160:163], v[192:195], v[38:41]
	v_mfma_f32_16x16x32_bf16 v[26:29], v[152:155], v[200:203], v[26:29]
	v_mfma_f32_16x16x32_bf16 v[22:25], v[160:163], v[200:203], v[22:25]
	v_mfma_f32_16x16x32_bf16 v[10:13], v[152:155], v[208:211], v[10:13]
	v_mfma_f32_16x16x32_bf16 v[6:9], v[160:163], v[208:211], v[6:9]
	v_mfma_f32_16x16x32_bf16 v[58:61], v[156:159], v[188:191], v[58:61]
	v_mfma_f32_16x16x32_bf16 v[54:57], v[164:167], v[188:191], v[54:57]
	v_mfma_f32_16x16x32_bf16 v[42:45], v[156:159], v[196:199], v[42:45]
	v_mfma_f32_16x16x32_bf16 v[38:41], v[164:167], v[196:199], v[38:41]
	v_mfma_f32_16x16x32_bf16 v[26:29], v[156:159], v[204:207], v[26:29]
	v_mfma_f32_16x16x32_bf16 v[22:25], v[164:167], v[204:207], v[22:25]
	v_mfma_f32_16x16x32_bf16 v[10:13], v[156:159], v[212:215], v[10:13]
	v_mfma_f32_16x16x32_bf16 v[6:9], v[164:167], v[212:215], v[6:9]
	v_mfma_f32_16x16x32_bf16 v[62:65], v[168:171], v[184:187], v[62:65]
	v_mfma_f32_16x16x32_bf16 v[50:53], v[176:179], v[184:187], v[50:53]
	v_mfma_f32_16x16x32_bf16 v[46:49], v[168:171], v[192:195], v[46:49]
	v_mfma_f32_16x16x32_bf16 v[34:37], v[176:179], v[192:195], v[34:37]
	v_mfma_f32_16x16x32_bf16 v[30:33], v[168:171], v[200:203], v[30:33]
	v_mfma_f32_16x16x32_bf16 v[18:21], v[176:179], v[200:203], v[18:21]
	v_mfma_f32_16x16x32_bf16 v[14:17], v[168:171], v[208:211], v[14:17]
	v_mfma_f32_16x16x32_bf16 v[2:5], v[176:179], v[208:211], v[2:5]
	v_mfma_f32_16x16x32_bf16 v[62:65], v[172:175], v[188:191], v[62:65]
	v_mfma_f32_16x16x32_bf16 v[50:53], v[180:183], v[188:191], v[50:53]
	v_mfma_f32_16x16x32_bf16 v[46:49], v[172:175], v[196:199], v[46:49]
	v_mfma_f32_16x16x32_bf16 v[34:37], v[180:183], v[196:199], v[34:37]
	v_mfma_f32_16x16x32_bf16 v[30:33], v[172:175], v[204:207], v[30:33]
	v_mfma_f32_16x16x32_bf16 v[18:21], v[180:183], v[204:207], v[18:21]
	v_mfma_f32_16x16x32_bf16 v[14:17], v[172:175], v[212:215], v[14:17]
	v_mfma_f32_16x16x32_bf16 v[2:5], v[180:183], v[212:215], v[2:5]
	s_barrier
	s_add_i32 s52, s52, 2
	s_add_u32 s26, s26, 0x100
	s_addc_u32 s27, s27, 0
	s_add_u32 s50, s50, 0x10000
	s_addc_u32 s51, s51, 0
	s_cmp_gt_u32 s52, 29
	s_cbranch_scc0 .LBB0_2138
	s_and_b64 vcc, exec, s[6:7]
	s_cbranch_vccz .LBB0_2141
	s_barrier

; #define PG8_STAGE(bufoff, gbase, voff) do { _Pragma("unroll") for (int _i = 0; _i < 2; ++_i) \
;         __builtin_amdgcn_global_load_lds((const unsigned*)((const char*)(gbase) + (voff)[_i]), (LAS unsigned*)(lds + (bufoff) + ldsw + _i * 8192), 16, 0, 0); } while (0)
; #define PG8_LDA(dst, b, h) do { _Pragma("unroll") for (int m = 0; m < 4; ++m) _Pragma("unroll") for (int k = 0; k < 2; ++k) dst[m][k] = *(const LAS bf16x8*)(lds + PG8_SA(b, h) + aoff + m * 2048 + k * 1024); } while (0)
; #define PG8_LDB(dst, b, h) do { _Pragma("unroll") for (int n = 0; n < 2; ++n) _Pragma("unroll") for (int k = 0; k < 2; ++k) dst[n][k] = *(const LAS bf16x8*)(lds + PG8_SB(b, h) + boff + n * 2048 + k * 1024); } while (0)
; #define PG8_MMA(ai, bj, At, Bt) do { __builtin_amdgcn_s_setprio(1); _Pragma("unroll") for (int m = 0; m < 4; ++m) _Pragma("unroll") for (int n = 0; n < 2; ++n) _Pragma("unroll") for (int k = 0; k < 2; ++k) \
;         acc[ai][bj][m][n] = __builtin_amdgcn_mfma_f32_16x16x32_bf16(Bt[n][k], At[m][k], acc[ai][bj][m][n], 0, 0, 0); __builtin_amdgcn_s_setprio(0); } while (0)
; #define PG8_WAIT_V(n) asm volatile("s_waitcnt vmcnt(" #n ")" ::: "memory")
; #define PG8_BAR __builtin_amdgcn_s_barrier()
; template <class Epi, class Sched, bool ABLK = false, bool ALIGN_EPI = true, bool SP2 = true, bool BBLK = true>
; __device__ __forceinline__ void gemm_phase(LAS unsigned char* lds, const Gemm g, const Sched& S, const Epi& E) {
;     ...
;             const bool last = (t == nt - 2);
;             const char* a1 = a_tile(uA, tbA + t + 1);
;             const char* a2 = last ? a_tile(nuA, ntbA) : a_tile(uA, tbA + t + 2); const char* b2 = last ? nB : cB + (size_t)(t + 2) * kstepB;
;             const char* a3 = last ? a_tile(nuA, ntbA + 1) : a_tile(uA, tbA + t + 3); const char* b3 = b2 + kstepB;
;             if (last && has_next) S.a_ready(nxt);
;             if constexpr (SP2) {
;             PG8_LDB(B0, 0, 0); PG8_LDB(B1, 0, 1); PG8_SCHED; PG8_LDA(At, 0, 0); PG8_STAGE(PG8_SA(1, 1), a1 + hstepA, voffA);
;             PG8_WAIT_V(8); PG8_WAIT_L(0); PG8_BAR; PG8_MMA(0, 0, At, B0); PG8_MMA(0, 1, At, B1); PG8_BAR; PG8_SCHED;
;             PG8_LDA(At, 0, 1); PG8_STAGE(PG8_SB(0, 0), b2, voffB); PG8_STAGE(PG8_SB(0, 1), b2 + hstepB, voffB); PG8_STAGE(PG8_SA(0, 0), a2, voffA);
;             PG8_WAIT_V(8); PG8_WAIT_L(0); PG8_BAR; PG8_MMA(1, 0, At, B0); PG8_MMA(1, 1, At, B1); PG8_BAR; PG8_SCHED;
.LBB0_2263:
	ds_read_b128 v[172:175], v168
	ds_read_b128 v[176:179], v168 offset:1024
	ds_read_b128 v[180:183], v168 offset:2048
	ds_read_b128 v[184:187], v168 offset:3072
	ds_read_b128 v[188:191], v169
	ds_read_b128 v[192:195], v169 offset:1024
	ds_read_b128 v[196:199], v169 offset:2048
	ds_read_b128 v[200:203], v169 offset:3072
	s_add_u32 s30, s26, s28
	s_addc_u32 s31, s27, s29
	s_add_u32 s36, s30, 0x100
	s_addc_u32 s37, s31, 0
	s_add_u32 s30, s30, 0x180
	s_addc_u32 s31, s31, 0
	s_cmpk_eq_i32 s28, 0xf00
	s_cselect_b32 s31, s54, s31
	s_cselect_b32 s30, s23, s30
	s_cselect_b32 s35, s13, s56
	s_cselect_b32 s34, s15, s55
	s_cselect_b32 s37, s4, s37
	s_cselect_b32 s36, s5, s36
	s_mov_b32 m0, s50
	v_lshl_add_u64 v[236:237], v[164:165], 0, s[28:29]
	ds_read_b128 v[204:207], v170
	ds_read_b128 v[208:211], v170 offset:1024
	ds_read_b128 v[212:215], v170 offset:2048
	ds_read_b128 v[216:219], v170 offset:3072
	ds_read_b128 v[220:223], v170 offset:4096
	ds_read_b128 v[224:227], v170 offset:5120
	ds_read_b128 v[228:231], v170 offset:6144
	ds_read_b128 v[232:235], v170 offset:7168
	global_load_lds_dwordx4 v[236:237], off
	v_lshl_add_u64 v[236:237], v[166:167], 0, s[28:29]
	s_mov_b32 m0, s51
	s_nop 0
	global_load_lds_dwordx4 v[236:237], off
	s_waitcnt vmcnt(8)
	s_waitcnt lgkmcnt(0)
	s_barrier
	v_mfma_f32_16x16x32_bf16 v[126:129], v[172:175], v[204:207], v[126:129]
	v_mfma_f32_16x16x32_bf16 v[122:125], v[180:183], v[204:207], v[122:125]
	v_mfma_f32_16x16x32_bf16 v[110:113], v[172:175], v[212:215], v[110:113]
	v_mfma_f32_16x16x32_bf16 v[106:109], v[180:183], v[212:215], v[106:109]
	v_mfma_f32_16x16x32_bf16 v[94:97], v[172:175], v[220:223], v[94:97]
	v_mfma_f32_16x16x32_bf16 v[90:93], v[180:183], v[220:223], v[90:93]
	v_mfma_f32_16x16x32_bf16 v[78:81], v[172:175], v[228:231], v[78:81]
	v_mfma_f32_16x16x32_bf16 v[74:77], v[180:183], v[228:231], v[74:77]
	v_mfma_f32_16x16x32_bf16 v[126:129], v[176:179], v[208:211], v[126:129]
	v_mfma_f32_16x16x32_bf16 v[122:125], v[184:187], v[208:211], v[122:125]
	v_mfma_f32_16x16x32_bf16 v[110:113], v[176:179], v[216:219], v[110:113]
	v_mfma_f32_16x16x32_bf16 v[106:109], v[184:187], v[216:219], v[106:109]
	v_mfma_f32_16x16x32_bf16 v[94:97], v[176:179], v[224:227], v[94:97]
	v_mfma_f32_16x16x32_bf16 v[90:93], v[184:187], v[224:227], v[90:93]
	v_mfma_f32_16x16x32_bf16 v[78:81], v[176:179], v[232:235], v[78:81]
	v_mfma_f32_16x16x32_bf16 v[74:77], v[184:187], v[232:235], v[74:77]
	v_mfma_f32_16x16x32_bf16 v[118:121], v[188:191], v[204:207], v[118:121]
	v_mfma_f32_16x16x32_bf16 v[114:117], v[196:199], v[204:207], v[114:117]
	v_mfma_f32_16x16x32_bf16 v[102:105], v[188:191], v[212:215], v[102:105]
	v_mfma_f32_16x16x32_bf16 v[98:101], v[196:199], v[212:215], v[98:101]
	v_mfma_f32_16x16x32_bf16 v[86:89], v[188:191], v[220:223], v[86:89]
	v_mfma_f32_16x16x32_bf16 v[82:85], v[196:199], v[220:223], v[82:85]
	v_mfma_f32_16x16x32_bf16 v[70:73], v[188:191], v[228:231], v[70:73]
	v_mfma_f32_16x16x32_bf16 v[66:69], v[196:199], v[228:231], v[66:69]
	v_mfma_f32_16x16x32_bf16 v[118:121], v[192:195], v[208:211], v[118:121]
	v_mfma_f32_16x16x32_bf16 v[114:117], v[200:203], v[208:211], v[114:117]
	v_mfma_f32_16x16x32_bf16 v[102:105], v[192:195], v[216:219], v[102:105]
	v_mfma_f32_16x16x32_bf16 v[98:101], v[200:203], v[216:219], v[98:101]
	v_mfma_f32_16x16x32_bf16 v[86:89], v[192:195], v[224:227], v[86:89]
	v_mfma_f32_16x16x32_bf16 v[82:85], v[200:203], v[224:227], v[82:85]
	v_mfma_f32_16x16x32_bf16 v[70:73], v[192:195], v[232:235], v[70:73]
	v_mfma_f32_16x16x32_bf16 v[66:69], v[200:203], v[232:235], v[66:69]
	s_barrier
	s_mov_b32 m0, s52
	v_lshl_add_u64 v[236:237], s[34:35], 0, v[134:135]
	s_add_u32 s58, s34, 0x4000
	ds_read_b128 v[204:207], v170 offset:16384
	ds_read_b128 v[208:211], v170 offset:17408
	ds_read_b128 v[212:215], v170 offset:18432
	ds_read_b128 v[216:219], v170 offset:19456
	ds_read_b128 v[220:223], v170 offset:20480
	ds_read_b128 v[224:227], v170 offset:21504
	ds_read_b128 v[228:231], v170 offset:22528
	ds_read_b128 v[232:235], v170 offset:23552
	global_load_lds_dwordx4 v[236:237], off
	v_lshl_add_u64 v[236:237], s[34:35], 0, v[130:131]
	s_mov_b32 m0, s53
	s_addc_u32 s59, s35, 0
	s_add_i32 s62, s73, s40
	global_load_lds_dwordx4 v[236:237], off
	v_lshl_add_u64 v[236:237], s[58:59], 0, v[134:135]
	s_mov_b32 m0, s62
	s_nop 0
	global_load_lds_dwordx4 v[236:237], off
	v_lshl_add_u64 v[236:237], s[58:59], 0, v[130:131]
	s_add_i32 m0, s62, 0x2000
	s_nop 0
	global_load_lds_dwordx4 v[236:237], off
	v_lshl_add_u64 v[236:237], s[36:37], 0, v[136:137]
	s_mov_b32 m0, s25
	s_nop 0
	global_load_lds_dwordx4 v[236:237], off
	v_lshl_add_u64 v[236:237], s[36:37], 0, v[132:133]
	s_mov_b32 m0, s43
	s_nop 0
	global_load_lds_dwordx4 v[236:237], off
	s_waitcnt vmcnt(8)
	s_waitcnt lgkmcnt(0)
	s_barrier
; #define PG8_STAGE(bufoff, gbase, voff) do { _Pragma("unroll") for (int _i = 0; _i < 2; ++_i) \
;         __builtin_amdgcn_global_load_lds((const unsigned*)((const char*)(gbase) + (voff)[_i]), (LAS unsigned*)(lds + (bufoff) + ldsw + _i * 8192), 16, 0, 0); } while (0)
; #define PG8_LDA(dst, b, h) do { _Pragma("unroll") for (int m = 0; m < 4; ++m) _Pragma("unroll") for (int k = 0; k < 2; ++k) dst[m][k] = *(const LAS bf16x8*)(lds + PG8_SA(b, h) + aoff + m * 2048 + k * 1024); } while (0)
; #define PG8_LDB(dst, b, h) do { _Pragma("unroll") for (int n = 0; n < 2; ++n) _Pragma("unroll") for (int k = 0; k < 2; ++k) dst[n][k] = *(const LAS bf16x8*)(lds + PG8_SB(b, h) + boff + n * 2048 + k * 1024); } while (0)
; #define PG8_MMA(ai, bj, At, Bt) do { __builtin_amdgcn_s_setprio(1); _Pragma("unroll") for (int m = 0; m < 4; ++m) _Pragma("unroll") for (int n = 0; n < 2; ++n) _Pragma("unroll") for (int k = 0; k < 2; ++k) \
;         acc[ai][bj][m][n] = __builtin_amdgcn_mfma_f32_16x16x32_bf16(Bt[n][k], At[m][k], acc[ai][bj][m][n], 0, 0, 0); __builtin_amdgcn_s_setprio(0); } while (0)
; #define PG8_WAIT_V(n) asm volatile("s_waitcnt vmcnt(" #n ")" ::: "memory")
; #define PG8_WAIT_L(n) asm volatile("s_waitcnt lgkmcnt(" #n ")" ::: "memory")
; #define PG8_BAR __builtin_amdgcn_s_barrier()
; #define PG8_SCHED __builtin_amdgcn_sched_barrier(0)
; template <class Epi, class Sched, bool ABLK = false, bool ALIGN_EPI = true, bool SP2 = true, bool BBLK = true>
; __device__ __forceinline__ void gemm_phase(LAS unsigned char* lds, const Gemm g, const Sched& S, const Epi& E) {
;     ...
;             PG8_WAIT_V(8); PG8_WAIT_L(0); PG8_BAR; PG8_MMA(1, 0, At, B0); PG8_MMA(1, 1, At, B1); PG8_BAR; PG8_SCHED;
;             PG8_LDB(B0, 1, 0); PG8_LDB(B1, 1, 1); PG8_SCHED; PG8_LDA(At, 1, 0); PG8_STAGE(PG8_SA(0, 1), a2 + hstepA, voffA);
;             PG8_WAIT_V(8); PG8_WAIT_L(0); PG8_BAR; PG8_MMA(0, 0, At, B0); PG8_MMA(0, 1, At, B1); PG8_BAR; PG8_SCHED;
	v_mfma_f32_16x16x32_bf16 v[62:65], v[172:175], v[204:207], v[62:65]
	v_mfma_f32_16x16x32_bf16 v[58:61], v[180:183], v[204:207], v[58:61]
	v_mfma_f32_16x16x32_bf16 v[46:49], v[172:175], v[212:215], v[46:49]
	v_mfma_f32_16x16x32_bf16 v[42:45], v[180:183], v[212:215], v[42:45]
	v_mfma_f32_16x16x32_bf16 v[30:33], v[172:175], v[220:223], v[30:33]
	v_mfma_f32_16x16x32_bf16 v[26:29], v[180:183], v[220:223], v[26:29]
	v_mfma_f32_16x16x32_bf16 v[14:17], v[172:175], v[228:231], v[14:17]
	v_mfma_f32_16x16x32_bf16 v[10:13], v[180:183], v[228:231], v[10:13]
	v_mfma_f32_16x16x32_bf16 v[62:65], v[176:179], v[208:211], v[62:65]
	v_mfma_f32_16x16x32_bf16 v[58:61], v[184:187], v[208:211], v[58:61]
	v_mfma_f32_16x16x32_bf16 v[46:49], v[176:179], v[216:219], v[46:49]
	v_mfma_f32_16x16x32_bf16 v[42:45], v[184:187], v[216:219], v[42:45]
	v_mfma_f32_16x16x32_bf16 v[30:33], v[176:179], v[224:227], v[30:33]
	v_mfma_f32_16x16x32_bf16 v[26:29], v[184:187], v[224:227], v[26:29]
	v_mfma_f32_16x16x32_bf16 v[14:17], v[176:179], v[232:235], v[14:17]
	v_mfma_f32_16x16x32_bf16 v[10:13], v[184:187], v[232:235], v[10:13]
	v_mfma_f32_16x16x32_bf16 v[54:57], v[188:191], v[204:207], v[54:57]
	v_mfma_f32_16x16x32_bf16 v[50:53], v[196:199], v[204:207], v[50:53]
	v_mfma_f32_16x16x32_bf16 v[38:41], v[188:191], v[212:215], v[38:41]
	v_mfma_f32_16x16x32_bf16 v[34:37], v[196:199], v[212:215], v[34:37]
	v_mfma_f32_16x16x32_bf16 v[22:25], v[188:191], v[220:223], v[22:25]
	v_mfma_f32_16x16x32_bf16 v[18:21], v[196:199], v[220:223], v[18:21]
	v_mfma_f32_16x16x32_bf16 v[6:9], v[188:191], v[228:231], v[6:9]
	v_mfma_f32_16x16x32_bf16 v[2:5], v[196:199], v[228:231], v[2:5]
	v_mfma_f32_16x16x32_bf16 v[54:57], v[192:195], v[208:211], v[54:57]
	v_mfma_f32_16x16x32_bf16 v[50:53], v[200:203], v[208:211], v[50:53]
	v_mfma_f32_16x16x32_bf16 v[38:41], v[192:195], v[216:219], v[38:41]
	v_mfma_f32_16x16x32_bf16 v[34:37], v[200:203], v[216:219], v[34:37]
	v_mfma_f32_16x16x32_bf16 v[22:25], v[192:195], v[224:227], v[22:25]
	v_mfma_f32_16x16x32_bf16 v[18:21], v[200:203], v[224:227], v[18:21]
	v_mfma_f32_16x16x32_bf16 v[6:9], v[192:195], v[232:235], v[6:9]
	v_mfma_f32_16x16x32_bf16 v[2:5], v[200:203], v[232:235], v[2:5]
	s_barrier
	v_add_u32_e32 v171, s60, v1
	ds_read_b128 v[172:175], v171
	ds_read_b128 v[176:179], v171 offset:1024
	ds_read_b128 v[180:183], v171 offset:2048
	ds_read_b128 v[184:187], v171 offset:3072
	v_add_u32_e32 v171, s61, v1
	ds_read_b128 v[188:191], v171
	ds_read_b128 v[192:195], v171 offset:1024
	ds_read_b128 v[196:199], v171 offset:2048
	ds_read_b128 v[200:203], v171 offset:3072
	s_add_u32 s36, s36, 0x80000
	s_addc_u32 s37, s37, 0
	s_mov_b32 m0, s44
	v_lshl_add_u64 v[236:237], s[36:37], 0, v[136:137]
	ds_read_b128 v[204:207], v170 offset:32768
	ds_read_b128 v[208:211], v170 offset:33792
	ds_read_b128 v[212:215], v170 offset:34816
	ds_read_b128 v[216:219], v170 offset:35840
	ds_read_b128 v[220:223], v170 offset:36864
	ds_read_b128 v[224:227], v170 offset:37888
	ds_read_b128 v[228:231], v170 offset:38912
	ds_read_b128 v[232:235], v170 offset:39936
	global_load_lds_dwordx4 v[236:237], off
	v_lshl_add_u64 v[236:237], s[36:37], 0, v[132:133]
	s_mov_b32 m0, s45
	s_nop 0
	global_load_lds_dwordx4 v[236:237], off
	s_waitcnt vmcnt(8)
	s_waitcnt lgkmcnt(0)
	s_barrier
	v_mfma_f32_16x16x32_bf16 v[126:129], v[172:175], v[204:207], v[126:129]
	v_mfma_f32_16x16x32_bf16 v[122:125], v[180:183], v[204:207], v[122:125]
	v_mfma_f32_16x16x32_bf16 v[110:113], v[172:175], v[212:215], v[110:113]
	v_mfma_f32_16x16x32_bf16 v[106:109], v[180:183], v[212:215], v[106:109]
	v_mfma_f32_16x16x32_bf16 v[94:97], v[172:175], v[220:223], v[94:97]
	v_mfma_f32_16x16x32_bf16 v[90:93], v[180:183], v[220:223], v[90:93]
	v_mfma_f32_16x16x32_bf16 v[78:81], v[172:175], v[228:231], v[78:81]
	v_mfma_f32_16x16x32_bf16 v[74:77], v[180:183], v[228:231], v[74:77]
	v_mfma_f32_16x16x32_bf16 v[126:129], v[176:179], v[208:211], v[126:129]
	v_mfma_f32_16x16x32_bf16 v[122:125], v[184:187], v[208:211], v[122:125]
	v_mfma_f32_16x16x32_bf16 v[110:113], v[176:179], v[216:219], v[110:113]
	v_mfma_f32_16x16x32_bf16 v[106:109], v[184:187], v[216:219], v[106:109]
	v_mfma_f32_16x16x32_bf16 v[94:97], v[176:179], v[224:227], v[94:97]
	v_mfma_f32_16x16x32_bf16 v[90:93], v[184:187], v[224:227], v[90:93]
	v_mfma_f32_16x16x32_bf16 v[78:81], v[176:179], v[232:235], v[78:81]
	v_mfma_f32_16x16x32_bf16 v[74:77], v[184:187], v[232:235], v[74:77]
	v_mfma_f32_16x16x32_bf16 v[118:121], v[188:191], v[204:207], v[118:121]
	v_mfma_f32_16x16x32_bf16 v[114:117], v[196:199], v[204:207], v[114:117]
	v_mfma_f32_16x16x32_bf16 v[102:105], v[188:191], v[212:215], v[102:105]
	v_mfma_f32_16x16x32_bf16 v[98:101], v[196:199], v[212:215], v[98:101]
	v_mfma_f32_16x16x32_bf16 v[86:89], v[188:191], v[220:223], v[86:89]
	v_mfma_f32_16x16x32_bf16 v[82:85], v[196:199], v[220:223], v[82:85]
	v_mfma_f32_16x16x32_bf16 v[70:73], v[188:191], v[228:231], v[70:73]
	v_mfma_f32_16x16x32_bf16 v[66:69], v[196:199], v[228:231], v[66:69]
	v_mfma_f32_16x16x32_bf16 v[118:121], v[192:195], v[208:211], v[118:121]
	v_mfma_f32_16x16x32_bf16 v[114:117], v[200:203], v[208:211], v[114:117]
	v_mfma_f32_16x16x32_bf16 v[102:105], v[192:195], v[216:219], v[102:105]
	v_mfma_f32_16x16x32_bf16 v[98:101], v[200:203], v[216:219], v[98:101]
	v_mfma_f32_16x16x32_bf16 v[86:89], v[192:195], v[224:227], v[86:89]
	v_mfma_f32_16x16x32_bf16 v[82:85], v[200:203], v[224:227], v[82:85]
	v_mfma_f32_16x16x32_bf16 v[70:73], v[192:195], v[232:235], v[70:73]
	v_mfma_f32_16x16x32_bf16 v[66:69], v[200:203], v[232:235], v[66:69]
	s_barrier
; #define PG8_STAGE(bufoff, gbase, voff) do { _Pragma("unroll") for (int _i = 0; _i < 2; ++_i) \
;         __builtin_amdgcn_global_load_lds((const unsigned*)((const char*)(gbase) + (voff)[_i]), (LAS unsigned*)(lds + (bufoff) + ldsw + _i * 8192), 16, 0, 0); } while (0)
; #define PG8_LDA(dst, b, h) do { _Pragma("unroll") for (int m = 0; m < 4; ++m) _Pragma("unroll") for (int k = 0; k < 2; ++k) dst[m][k] = *(const LAS bf16x8*)(lds + PG8_SA(b, h) + aoff + m * 2048 + k * 1024); } while (0)
; #define PG8_MMA(ai, bj, At, Bt) do { __builtin_amdgcn_s_setprio(1); _Pragma("unroll") for (int m = 0; m < 4; ++m) _Pragma("unroll") for (int n = 0; n < 2; ++n) _Pragma("unroll") for (int k = 0; k < 2; ++k) \
;         acc[ai][bj][m][n] = __builtin_amdgcn_mfma_f32_16x16x32_bf16(Bt[n][k], At[m][k], acc[ai][bj][m][n], 0, 0, 0); __builtin_amdgcn_s_setprio(0); } while (0)
; #define PG8_WAIT_V(n) asm volatile("s_waitcnt vmcnt(" #n ")" ::: "memory")
; #define PG8_WAIT_L(n) asm volatile("s_waitcnt lgkmcnt(" #n ")" ::: "memory")
; #define PG8_BAR __builtin_amdgcn_s_barrier()
; #define PG8_SCHED __builtin_amdgcn_sched_barrier(0)
; template <class Epi, class Sched, bool ABLK = false, bool ALIGN_EPI = true, bool SP2 = true, bool BBLK = true>
; __device__ __forceinline__ void gemm_phase(LAS unsigned char* lds, const Gemm g, const Sched& S, const Epi& E) {
;     ...
;             PG8_LDA(At, 1, 1); PG8_STAGE(PG8_SB(1, 0), b3, voffB); PG8_STAGE(PG8_SB(1, 1), b3 + hstepB, voffB); PG8_STAGE(PG8_SA(1, 0), a3, voffA);
;             PG8_WAIT_V(8); PG8_WAIT_L(0); PG8_BAR; PG8_MMA(1, 0, At, B0); PG8_MMA(1, 1, At, B1); PG8_BAR; PG8_SCHED;
;     ...
;         if constexpr (ALIGN_EPI) { if (wr == 0) PG8_BAR; }
	s_add_u32 s36, s34, 0x8000
	s_addc_u32 s37, s35, 0
	s_add_i32 s58, s60, s40
	v_lshl_add_u64 v[236:237], s[36:37], 0, v[134:135]
	s_mov_b32 m0, s58
	ds_read_b128 v[204:207], v170 offset:49152
	ds_read_b128 v[208:211], v170 offset:50176
	ds_read_b128 v[212:215], v170 offset:51200
	ds_read_b128 v[216:219], v170 offset:52224
	ds_read_b128 v[220:223], v170 offset:53248
	ds_read_b128 v[224:227], v170 offset:54272
	ds_read_b128 v[228:231], v170 offset:55296
	ds_read_b128 v[232:235], v170 offset:56320
	global_load_lds_dwordx4 v[236:237], off
	s_add_i32 m0, s58, 0x2000
	s_add_u32 s34, s34, 0xc000
	v_lshl_add_u64 v[236:237], s[36:37], 0, v[130:131]
	s_addc_u32 s35, s35, 0
	s_add_i32 s36, s61, s40
	global_load_lds_dwordx4 v[236:237], off
	v_lshl_add_u64 v[236:237], s[34:35], 0, v[134:135]
	s_mov_b32 m0, s36
	s_nop 0
	global_load_lds_dwordx4 v[236:237], off
	v_lshl_add_u64 v[236:237], s[34:35], 0, v[130:131]
	s_add_i32 m0, s36, 0x2000
	s_nop 0
	global_load_lds_dwordx4 v[236:237], off
	v_lshl_add_u64 v[236:237], s[30:31], 0, v[136:137]
	s_mov_b32 m0, s48
	s_nop 0
	global_load_lds_dwordx4 v[236:237], off
	v_lshl_add_u64 v[236:237], s[30:31], 0, v[132:133]
	s_mov_b32 m0, s49
	s_nop 0
	global_load_lds_dwordx4 v[236:237], off
	s_waitcnt vmcnt(8)
	s_waitcnt lgkmcnt(0)
	s_barrier
	v_mfma_f32_16x16x32_bf16 v[62:65], v[172:175], v[204:207], v[62:65]
	v_mfma_f32_16x16x32_bf16 v[58:61], v[180:183], v[204:207], v[58:61]
	v_mfma_f32_16x16x32_bf16 v[46:49], v[172:175], v[212:215], v[46:49]
	v_mfma_f32_16x16x32_bf16 v[42:45], v[180:183], v[212:215], v[42:45]
	v_mfma_f32_16x16x32_bf16 v[30:33], v[172:175], v[220:223], v[30:33]
	v_mfma_f32_16x16x32_bf16 v[26:29], v[180:183], v[220:223], v[26:29]
	v_mfma_f32_16x16x32_bf16 v[14:17], v[172:175], v[228:231], v[14:17]
	v_mfma_f32_16x16x32_bf16 v[10:13], v[180:183], v[228:231], v[10:13]
	v_mfma_f32_16x16x32_bf16 v[62:65], v[176:179], v[208:211], v[62:65]
	v_mfma_f32_16x16x32_bf16 v[58:61], v[184:187], v[208:211], v[58:61]
	v_mfma_f32_16x16x32_bf16 v[46:49], v[176:179], v[216:219], v[46:49]
	v_mfma_f32_16x16x32_bf16 v[42:45], v[184:187], v[216:219], v[42:45]
	v_mfma_f32_16x16x32_bf16 v[30:33], v[176:179], v[224:227], v[30:33]
	v_mfma_f32_16x16x32_bf16 v[26:29], v[184:187], v[224:227], v[26:29]
	v_mfma_f32_16x16x32_bf16 v[14:17], v[176:179], v[232:235], v[14:17]
	v_mfma_f32_16x16x32_bf16 v[10:13], v[184:187], v[232:235], v[10:13]
	v_mfma_f32_16x16x32_bf16 v[54:57], v[188:191], v[204:207], v[54:57]
	v_mfma_f32_16x16x32_bf16 v[50:53], v[196:199], v[204:207], v[50:53]
	v_mfma_f32_16x16x32_bf16 v[38:41], v[188:191], v[212:215], v[38:41]
	v_mfma_f32_16x16x32_bf16 v[34:37], v[196:199], v[212:215], v[34:37]
	v_mfma_f32_16x16x32_bf16 v[22:25], v[188:191], v[220:223], v[22:25]
	v_mfma_f32_16x16x32_bf16 v[18:21], v[196:199], v[220:223], v[18:21]
	v_mfma_f32_16x16x32_bf16 v[6:9], v[188:191], v[228:231], v[6:9]
	v_mfma_f32_16x16x32_bf16 v[2:5], v[196:199], v[228:231], v[2:5]
	v_mfma_f32_16x16x32_bf16 v[54:57], v[192:195], v[208:211], v[54:57]
	v_mfma_f32_16x16x32_bf16 v[50:53], v[200:203], v[208:211], v[50:53]
	v_mfma_f32_16x16x32_bf16 v[38:41], v[192:195], v[216:219], v[38:41]
	v_mfma_f32_16x16x32_bf16 v[34:37], v[200:203], v[216:219], v[34:37]
	v_mfma_f32_16x16x32_bf16 v[22:25], v[192:195], v[224:227], v[22:25]
	v_mfma_f32_16x16x32_bf16 v[18:21], v[200:203], v[224:227], v[18:21]
	v_mfma_f32_16x16x32_bf16 v[6:9], v[192:195], v[232:235], v[6:9]
	v_mfma_f32_16x16x32_bf16 v[2:5], v[200:203], v[232:235], v[2:5]
	s_barrier
	s_add_i32 s57, s57, 2
	s_add_u32 s28, s28, 0x100
	s_addc_u32 s29, s29, 0
	s_add_u32 s55, s55, 0x10000
	s_addc_u32 s56, s56, 0
	s_cmp_gt_u32 s57, 29
	s_cbranch_scc0 .LBB0_2263
	s_and_b64 vcc, exec, s[10:11]
	s_cbranch_vccz .LBB0_2266
	s_barrier

; #define PG8_STAGE(bufoff, gbase, voff) do { _Pragma("unroll") for (int _i = 0; _i < 2; ++_i) \
;         __builtin_amdgcn_global_load_lds((const unsigned*)((const char*)(gbase) + (voff)[_i]), (LAS unsigned*)(lds + (bufoff) + ldsw + _i * 8192), 16, 0, 0); } while (0)
; #define PG8_LDA(dst, b, h) do { _Pragma("unroll") for (int m = 0; m < 4; ++m) _Pragma("unroll") for (int k = 0; k < 2; ++k) dst[m][k] = *(const LAS bf16x8*)(lds + PG8_SA(b, h) + aoff + m * 2048 + k * 1024); } while (0)
; #define PG8_LDB(dst, b, h) do { _Pragma("unroll") for (int n = 0; n < 2; ++n) _Pragma("unroll") for (int k = 0; k < 2; ++k) dst[n][k] = *(const LAS bf16x8*)(lds + PG8_SB(b, h) + boff + n * 2048 + k * 1024); } while (0)
; #define PG8_MMA(ai, bj, At, Bt) do { __builtin_amdgcn_s_setprio(1); _Pragma("unroll") for (int m = 0; m < 4; ++m) _Pragma("unroll") for (int n = 0; n < 2; ++n) _Pragma("unroll") for (int k = 0; k < 2; ++k) \
;         acc[ai][bj][m][n] = __builtin_amdgcn_mfma_f32_16x16x32_bf16(Bt[n][k], At[m][k], acc[ai][bj][m][n], 0, 0, 0); __builtin_amdgcn_s_setprio(0); } while (0)
; #define PG8_WAIT_V(n) asm volatile("s_waitcnt vmcnt(" #n ")" ::: "memory")
; #define PG8_BAR __builtin_amdgcn_s_barrier()
; template <class Epi, class Sched, bool ABLK = false, bool ALIGN_EPI = true, bool SP2 = true, bool BBLK = true>
; __device__ __forceinline__ void gemm_phase(LAS unsigned char* lds, const Gemm g, const Sched& S, const Epi& E) {
;     ...
;             const bool last = (t == nt - 2);
;             const char* a1 = a_tile(uA, tbA + t + 1);
;             const char* a2 = last ? a_tile(nuA, ntbA) : a_tile(uA, tbA + t + 2); const char* b2 = last ? nB : cB + (size_t)(t + 2) * kstepB;
;             const char* a3 = last ? a_tile(nuA, ntbA + 1) : a_tile(uA, tbA + t + 3); const char* b3 = b2 + kstepB;
;             if (last && has_next) S.a_ready(nxt);
;             if constexpr (SP2) {
;             PG8_LDB(B0, 0, 0); PG8_LDB(B1, 0, 1); PG8_SCHED; PG8_LDA(At, 0, 0); PG8_STAGE(PG8_SA(1, 1), a1 + hstepA, voffA);
;             PG8_WAIT_V(8); PG8_WAIT_L(0); PG8_BAR; PG8_MMA(0, 0, At, B0); PG8_MMA(0, 1, At, B1); PG8_BAR; PG8_SCHED;
;             PG8_LDA(At, 0, 1); PG8_STAGE(PG8_SB(0, 0), b2, voffB); PG8_STAGE(PG8_SB(0, 1), b2 + hstepB, voffB); PG8_STAGE(PG8_SA(0, 0), a2, voffA);
;             PG8_WAIT_V(8); PG8_WAIT_L(0); PG8_BAR; PG8_MMA(1, 0, At, B0); PG8_MMA(1, 1, At, B1); PG8_BAR; PG8_SCHED;
.LBB0_2328:
	ds_read_b128 v[152:155], v148
	ds_read_b128 v[156:159], v148 offset:1024
	ds_read_b128 v[160:163], v148 offset:2048
	ds_read_b128 v[164:167], v148 offset:3072
	ds_read_b128 v[168:171], v149
	ds_read_b128 v[172:175], v149 offset:1024
	ds_read_b128 v[176:179], v149 offset:2048
	ds_read_b128 v[180:183], v149 offset:3072
	s_add_u32 s40, s64, s38
	s_addc_u32 s41, s65, s39
	s_add_u32 s44, s40, 0x10000
	s_addc_u32 s45, s41, 0
	s_add_i32 s67, s67, 2
	s_add_u32 s42, s62, s38
	s_addc_u32 s43, s63, s39
	s_add_u32 s40, s40, 0x18000
	s_addc_u32 s41, s41, 0
	s_cmp_eq_u32 s66, s38
	s_cselect_b32 s41, s59, s41
	s_cselect_b32 s40, s58, s40
	s_cselect_b32 s43, s4, s43
	s_cselect_b32 s42, s5, s42
	s_cselect_b32 s45, s57, s45
	s_cselect_b32 s44, s35, s44
	v_lshl_add_u64 v[216:217], v[142:143], 0, s[38:39]
	s_add_i32 m0, s49, 0xc000
	ds_read_b128 v[184:187], v150
	ds_read_b128 v[188:191], v150 offset:1024
	ds_read_b128 v[192:195], v150 offset:2048
	ds_read_b128 v[196:199], v150 offset:3072
	ds_read_b128 v[200:203], v150 offset:4096
	ds_read_b128 v[204:207], v150 offset:5120
	ds_read_b128 v[208:211], v150 offset:6144
	ds_read_b128 v[212:215], v150 offset:7168
	global_load_lds_dwordx4 v[216:217], off
	v_lshl_add_u64 v[216:217], v[144:145], 0, s[38:39]
	s_add_i32 m0, s49, 0xe000
	s_nop 0
	global_load_lds_dwordx4 v[216:217], off
	s_waitcnt vmcnt(8)
	s_waitcnt lgkmcnt(0)
	s_barrier
	v_mfma_f32_16x16x32_bf16 v[126:129], v[152:155], v[184:187], v[126:129]
	v_mfma_f32_16x16x32_bf16 v[122:125], v[160:163], v[184:187], v[122:125]
	v_mfma_f32_16x16x32_bf16 v[110:113], v[152:155], v[192:195], v[110:113]
	v_mfma_f32_16x16x32_bf16 v[106:109], v[160:163], v[192:195], v[106:109]
	v_mfma_f32_16x16x32_bf16 v[94:97], v[152:155], v[200:203], v[94:97]
	v_mfma_f32_16x16x32_bf16 v[90:93], v[160:163], v[200:203], v[90:93]
	v_mfma_f32_16x16x32_bf16 v[78:81], v[152:155], v[208:211], v[78:81]
	v_mfma_f32_16x16x32_bf16 v[74:77], v[160:163], v[208:211], v[74:77]
	v_mfma_f32_16x16x32_bf16 v[126:129], v[156:159], v[188:191], v[126:129]
	v_mfma_f32_16x16x32_bf16 v[122:125], v[164:167], v[188:191], v[122:125]
	v_mfma_f32_16x16x32_bf16 v[110:113], v[156:159], v[196:199], v[110:113]
	v_mfma_f32_16x16x32_bf16 v[106:109], v[164:167], v[196:199], v[106:109]
	v_mfma_f32_16x16x32_bf16 v[94:97], v[156:159], v[204:207], v[94:97]
	v_mfma_f32_16x16x32_bf16 v[90:93], v[164:167], v[204:207], v[90:93]
	v_mfma_f32_16x16x32_bf16 v[78:81], v[156:159], v[212:215], v[78:81]
	v_mfma_f32_16x16x32_bf16 v[74:77], v[164:167], v[212:215], v[74:77]
	v_mfma_f32_16x16x32_bf16 v[118:121], v[168:171], v[184:187], v[118:121]
	v_mfma_f32_16x16x32_bf16 v[114:117], v[176:179], v[184:187], v[114:117]
	v_mfma_f32_16x16x32_bf16 v[102:105], v[168:171], v[192:195], v[102:105]
	v_mfma_f32_16x16x32_bf16 v[98:101], v[176:179], v[192:195], v[98:101]
	v_mfma_f32_16x16x32_bf16 v[86:89], v[168:171], v[200:203], v[86:89]
	v_mfma_f32_16x16x32_bf16 v[82:85], v[176:179], v[200:203], v[82:85]
	v_mfma_f32_16x16x32_bf16 v[70:73], v[168:171], v[208:211], v[70:73]
	v_mfma_f32_16x16x32_bf16 v[66:69], v[176:179], v[208:211], v[66:69]
	v_mfma_f32_16x16x32_bf16 v[118:121], v[172:175], v[188:191], v[118:121]
	v_mfma_f32_16x16x32_bf16 v[114:117], v[180:183], v[188:191], v[114:117]
	v_mfma_f32_16x16x32_bf16 v[102:105], v[172:175], v[196:199], v[102:105]
	v_mfma_f32_16x16x32_bf16 v[98:101], v[180:183], v[196:199], v[98:101]
	v_mfma_f32_16x16x32_bf16 v[86:89], v[172:175], v[204:207], v[86:89]
	v_mfma_f32_16x16x32_bf16 v[82:85], v[180:183], v[204:207], v[82:85]
	v_mfma_f32_16x16x32_bf16 v[70:73], v[172:175], v[212:215], v[70:73]
	v_mfma_f32_16x16x32_bf16 v[66:69], v[180:183], v[212:215], v[66:69]
	s_barrier
	s_add_i32 s70, s72, s48
	v_lshl_add_u64 v[216:217], s[42:43], 0, v[130:131]
	s_mov_b32 m0, s70
	ds_read_b128 v[184:187], v150 offset:16384
	ds_read_b128 v[188:191], v150 offset:17408
	ds_read_b128 v[192:195], v150 offset:18432
	ds_read_b128 v[196:199], v150 offset:19456
	ds_read_b128 v[200:203], v150 offset:20480
	ds_read_b128 v[204:207], v150 offset:21504
	ds_read_b128 v[208:211], v150 offset:22528
	ds_read_b128 v[212:215], v150 offset:23552
	global_load_lds_dwordx4 v[216:217], off
	s_add_i32 m0, s70, 0x2000
	s_add_u32 s76, s42, 0x4000
	v_lshl_add_u64 v[216:217], s[42:43], 0, v[132:133]
	s_addc_u32 s77, s43, 0
	s_add_i32 s70, s73, s48
	global_load_lds_dwordx4 v[216:217], off
	v_lshl_add_u64 v[216:217], s[76:77], 0, v[130:131]
	s_mov_b32 m0, s70
	s_nop 0
	global_load_lds_dwordx4 v[216:217], off
	v_lshl_add_u64 v[216:217], s[76:77], 0, v[132:133]
	s_add_i32 m0, s70, 0x2000
	s_nop 0
	global_load_lds_dwordx4 v[216:217], off
	v_lshl_add_u64 v[216:217], s[44:45], 0, v[130:131]
	s_mov_b32 m0, s49
	s_nop 0
	global_load_lds_dwordx4 v[216:217], off
	v_lshl_add_u64 v[216:217], s[44:45], 0, v[132:133]
	s_mov_b32 m0, s50
	s_nop 0
	global_load_lds_dwordx4 v[216:217], off
	s_waitcnt vmcnt(8)
	s_waitcnt lgkmcnt(0)
	s_barrier
; #define PG8_STAGE(bufoff, gbase, voff) do { _Pragma("unroll") for (int _i = 0; _i < 2; ++_i) \
;         __builtin_amdgcn_global_load_lds((const unsigned*)((const char*)(gbase) + (voff)[_i]), (LAS unsigned*)(lds + (bufoff) + ldsw + _i * 8192), 16, 0, 0); } while (0)
; #define PG8_LDA(dst, b, h) do { _Pragma("unroll") for (int m = 0; m < 4; ++m) _Pragma("unroll") for (int k = 0; k < 2; ++k) dst[m][k] = *(const LAS bf16x8*)(lds + PG8_SA(b, h) + aoff + m * 2048 + k * 1024); } while (0)
; #define PG8_LDB(dst, b, h) do { _Pragma("unroll") for (int n = 0; n < 2; ++n) _Pragma("unroll") for (int k = 0; k < 2; ++k) dst[n][k] = *(const LAS bf16x8*)(lds + PG8_SB(b, h) + boff + n * 2048 + k * 1024); } while (0)
; #define PG8_MMA(ai, bj, At, Bt) do { __builtin_amdgcn_s_setprio(1); _Pragma("unroll") for (int m = 0; m < 4; ++m) _Pragma("unroll") for (int n = 0; n < 2; ++n) _Pragma("unroll") for (int k = 0; k < 2; ++k) \
;         acc[ai][bj][m][n] = __builtin_amdgcn_mfma_f32_16x16x32_bf16(Bt[n][k], At[m][k], acc[ai][bj][m][n], 0, 0, 0); __builtin_amdgcn_s_setprio(0); } while (0)
; #define PG8_WAIT_V(n) asm volatile("s_waitcnt vmcnt(" #n ")" ::: "memory")
; #define PG8_WAIT_L(n) asm volatile("s_waitcnt lgkmcnt(" #n ")" ::: "memory")
; #define PG8_BAR __builtin_amdgcn_s_barrier()
; #define PG8_SCHED __builtin_amdgcn_sched_barrier(0)
; template <class Epi, class Sched, bool ABLK = false, bool ALIGN_EPI = true, bool SP2 = true, bool BBLK = true>
; __device__ __forceinline__ void gemm_phase(LAS unsigned char* lds, const Gemm g, const Sched& S, const Epi& E) {
;     ...
;             PG8_WAIT_V(8); PG8_WAIT_L(0); PG8_BAR; PG8_MMA(1, 0, At, B0); PG8_MMA(1, 1, At, B1); PG8_BAR; PG8_SCHED;
;             PG8_LDB(B0, 1, 0); PG8_LDB(B1, 1, 1); PG8_SCHED; PG8_LDA(At, 1, 0); PG8_STAGE(PG8_SA(0, 1), a2 + hstepA, voffA);
;             PG8_WAIT_V(8); PG8_WAIT_L(0); PG8_BAR; PG8_MMA(0, 0, At, B0); PG8_MMA(0, 1, At, B1); PG8_BAR; PG8_SCHED;
	v_mfma_f32_16x16x32_bf16 v[62:65], v[152:155], v[184:187], v[62:65]
	v_mfma_f32_16x16x32_bf16 v[58:61], v[160:163], v[184:187], v[58:61]
	v_mfma_f32_16x16x32_bf16 v[46:49], v[152:155], v[192:195], v[46:49]
	v_mfma_f32_16x16x32_bf16 v[42:45], v[160:163], v[192:195], v[42:45]
	v_mfma_f32_16x16x32_bf16 v[30:33], v[152:155], v[200:203], v[30:33]
	v_mfma_f32_16x16x32_bf16 v[26:29], v[160:163], v[200:203], v[26:29]
	v_mfma_f32_16x16x32_bf16 v[14:17], v[152:155], v[208:211], v[14:17]
	v_mfma_f32_16x16x32_bf16 v[10:13], v[160:163], v[208:211], v[10:13]
	v_mfma_f32_16x16x32_bf16 v[62:65], v[156:159], v[188:191], v[62:65]
	v_mfma_f32_16x16x32_bf16 v[58:61], v[164:167], v[188:191], v[58:61]
	v_mfma_f32_16x16x32_bf16 v[46:49], v[156:159], v[196:199], v[46:49]
	v_mfma_f32_16x16x32_bf16 v[42:45], v[164:167], v[196:199], v[42:45]
	v_mfma_f32_16x16x32_bf16 v[30:33], v[156:159], v[204:207], v[30:33]
	v_mfma_f32_16x16x32_bf16 v[26:29], v[164:167], v[204:207], v[26:29]
	v_mfma_f32_16x16x32_bf16 v[14:17], v[156:159], v[212:215], v[14:17]
	v_mfma_f32_16x16x32_bf16 v[10:13], v[164:167], v[212:215], v[10:13]
	v_mfma_f32_16x16x32_bf16 v[54:57], v[168:171], v[184:187], v[54:57]
	v_mfma_f32_16x16x32_bf16 v[50:53], v[176:179], v[184:187], v[50:53]
	v_mfma_f32_16x16x32_bf16 v[38:41], v[168:171], v[192:195], v[38:41]
	v_mfma_f32_16x16x32_bf16 v[34:37], v[176:179], v[192:195], v[34:37]
	v_mfma_f32_16x16x32_bf16 v[22:25], v[168:171], v[200:203], v[22:25]
	v_mfma_f32_16x16x32_bf16 v[18:21], v[176:179], v[200:203], v[18:21]
	v_mfma_f32_16x16x32_bf16 v[6:9], v[168:171], v[208:211], v[6:9]
	v_mfma_f32_16x16x32_bf16 v[2:5], v[176:179], v[208:211], v[2:5]
	v_mfma_f32_16x16x32_bf16 v[54:57], v[172:175], v[188:191], v[54:57]
	v_mfma_f32_16x16x32_bf16 v[50:53], v[180:183], v[188:191], v[50:53]
	v_mfma_f32_16x16x32_bf16 v[38:41], v[172:175], v[196:199], v[38:41]
	v_mfma_f32_16x16x32_bf16 v[34:37], v[180:183], v[196:199], v[34:37]
	v_mfma_f32_16x16x32_bf16 v[22:25], v[172:175], v[204:207], v[22:25]
	v_mfma_f32_16x16x32_bf16 v[18:21], v[180:183], v[204:207], v[18:21]
	v_mfma_f32_16x16x32_bf16 v[6:9], v[172:175], v[212:215], v[6:9]
	v_mfma_f32_16x16x32_bf16 v[2:5], v[180:183], v[212:215], v[2:5]
	s_barrier
	v_add_u32_e32 v151, s60, v146
	ds_read_b128 v[152:155], v151
	ds_read_b128 v[156:159], v151 offset:1024
	ds_read_b128 v[160:163], v151 offset:2048
	ds_read_b128 v[164:167], v151 offset:3072
	v_add_u32_e32 v151, s61, v146
	ds_read_b128 v[168:171], v151
	ds_read_b128 v[172:175], v151 offset:1024
	ds_read_b128 v[176:179], v151 offset:2048
	ds_read_b128 v[180:183], v151 offset:3072
	s_add_u32 s44, s44, 0x4000
	s_addc_u32 s45, s45, 0
	s_mov_b32 m0, s51
	v_lshl_add_u64 v[216:217], s[44:45], 0, v[130:131]
	ds_read_b128 v[184:187], v150 offset:32768
	ds_read_b128 v[188:191], v150 offset:33792
	ds_read_b128 v[192:195], v150 offset:34816
	ds_read_b128 v[196:199], v150 offset:35840
	ds_read_b128 v[200:203], v150 offset:36864
	ds_read_b128 v[204:207], v150 offset:37888
	ds_read_b128 v[208:211], v150 offset:38912
	ds_read_b128 v[212:215], v150 offset:39936
	global_load_lds_dwordx4 v[216:217], off
	v_lshl_add_u64 v[216:217], s[44:45], 0, v[132:133]
	s_mov_b32 m0, s52
	s_nop 0
	global_load_lds_dwordx4 v[216:217], off
	s_waitcnt vmcnt(8)
	s_waitcnt lgkmcnt(0)
	s_barrier
	v_mfma_f32_16x16x32_bf16 v[126:129], v[152:155], v[184:187], v[126:129]
	v_mfma_f32_16x16x32_bf16 v[122:125], v[160:163], v[184:187], v[122:125]
	v_mfma_f32_16x16x32_bf16 v[110:113], v[152:155], v[192:195], v[110:113]
	v_mfma_f32_16x16x32_bf16 v[106:109], v[160:163], v[192:195], v[106:109]
	v_mfma_f32_16x16x32_bf16 v[94:97], v[152:155], v[200:203], v[94:97]
	v_mfma_f32_16x16x32_bf16 v[90:93], v[160:163], v[200:203], v[90:93]
	v_mfma_f32_16x16x32_bf16 v[78:81], v[152:155], v[208:211], v[78:81]
	v_mfma_f32_16x16x32_bf16 v[74:77], v[160:163], v[208:211], v[74:77]
	v_mfma_f32_16x16x32_bf16 v[126:129], v[156:159], v[188:191], v[126:129]
	v_mfma_f32_16x16x32_bf16 v[122:125], v[164:167], v[188:191], v[122:125]
	v_mfma_f32_16x16x32_bf16 v[110:113], v[156:159], v[196:199], v[110:113]
	v_mfma_f32_16x16x32_bf16 v[106:109], v[164:167], v[196:199], v[106:109]
	v_mfma_f32_16x16x32_bf16 v[94:97], v[156:159], v[204:207], v[94:97]
	v_mfma_f32_16x16x32_bf16 v[90:93], v[164:167], v[204:207], v[90:93]
	v_mfma_f32_16x16x32_bf16 v[78:81], v[156:159], v[212:215], v[78:81]
	v_mfma_f32_16x16x32_bf16 v[74:77], v[164:167], v[212:215], v[74:77]
	v_mfma_f32_16x16x32_bf16 v[118:121], v[168:171], v[184:187], v[118:121]
	v_mfma_f32_16x16x32_bf16 v[114:117], v[176:179], v[184:187], v[114:117]
	v_mfma_f32_16x16x32_bf16 v[102:105], v[168:171], v[192:195], v[102:105]
	v_mfma_f32_16x16x32_bf16 v[98:101], v[176:179], v[192:195], v[98:101]
	v_mfma_f32_16x16x32_bf16 v[86:89], v[168:171], v[200:203], v[86:89]
	v_mfma_f32_16x16x32_bf16 v[82:85], v[176:179], v[200:203], v[82:85]
	v_mfma_f32_16x16x32_bf16 v[70:73], v[168:171], v[208:211], v[70:73]
	v_mfma_f32_16x16x32_bf16 v[66:69], v[176:179], v[208:211], v[66:69]
	v_mfma_f32_16x16x32_bf16 v[118:121], v[172:175], v[188:191], v[118:121]
	v_mfma_f32_16x16x32_bf16 v[114:117], v[180:183], v[188:191], v[114:117]
	v_mfma_f32_16x16x32_bf16 v[102:105], v[172:175], v[196:199], v[102:105]
	v_mfma_f32_16x16x32_bf16 v[98:101], v[180:183], v[196:199], v[98:101]
	v_mfma_f32_16x16x32_bf16 v[86:89], v[172:175], v[204:207], v[86:89]
	v_mfma_f32_16x16x32_bf16 v[82:85], v[180:183], v[204:207], v[82:85]
	v_mfma_f32_16x16x32_bf16 v[70:73], v[172:175], v[212:215], v[70:73]
	v_mfma_f32_16x16x32_bf16 v[66:69], v[180:183], v[212:215], v[66:69]
	s_barrier
; #define PG8_STAGE(bufoff, gbase, voff) do { _Pragma("unroll") for (int _i = 0; _i < 2; ++_i) \
;         __builtin_amdgcn_global_load_lds((const unsigned*)((const char*)(gbase) + (voff)[_i]), (LAS unsigned*)(lds + (bufoff) + ldsw + _i * 8192), 16, 0, 0); } while (0)
; #define PG8_LDA(dst, b, h) do { _Pragma("unroll") for (int m = 0; m < 4; ++m) _Pragma("unroll") for (int k = 0; k < 2; ++k) dst[m][k] = *(const LAS bf16x8*)(lds + PG8_SA(b, h) + aoff + m * 2048 + k * 1024); } while (0)
; #define PG8_MMA(ai, bj, At, Bt) do { __builtin_amdgcn_s_setprio(1); _Pragma("unroll") for (int m = 0; m < 4; ++m) _Pragma("unroll") for (int n = 0; n < 2; ++n) _Pragma("unroll") for (int k = 0; k < 2; ++k) \
;         acc[ai][bj][m][n] = __builtin_amdgcn_mfma_f32_16x16x32_bf16(Bt[n][k], At[m][k], acc[ai][bj][m][n], 0, 0, 0); __builtin_amdgcn_s_setprio(0); } while (0)
; #define PG8_WAIT_V(n) asm volatile("s_waitcnt vmcnt(" #n ")" ::: "memory")
; #define PG8_WAIT_L(n) asm volatile("s_waitcnt lgkmcnt(" #n ")" ::: "memory")
; #define PG8_BAR __builtin_amdgcn_s_barrier()
; #define PG8_SCHED __builtin_amdgcn_sched_barrier(0)
; template <class Epi, class Sched, bool ABLK = false, bool ALIGN_EPI = true, bool SP2 = true, bool BBLK = true>
; __device__ __forceinline__ void gemm_phase(LAS unsigned char* lds, const Gemm g, const Sched& S, const Epi& E) {
;     ...
;             PG8_LDA(At, 1, 1); PG8_STAGE(PG8_SB(1, 0), b3, voffB); PG8_STAGE(PG8_SB(1, 1), b3 + hstepB, voffB); PG8_STAGE(PG8_SA(1, 0), a3, voffA);
;             PG8_WAIT_V(8); PG8_WAIT_L(0); PG8_BAR; PG8_MMA(1, 0, At, B0); PG8_MMA(1, 1, At, B1); PG8_BAR; PG8_SCHED;
;     ...
;         if constexpr (ALIGN_EPI) { if (wr == 0) PG8_BAR; }
	s_add_u32 s44, s42, 0x8000
	s_addc_u32 s45, s43, 0
	s_add_i32 s70, s60, s48
	v_lshl_add_u64 v[216:217], s[44:45], 0, v[130:131]
	s_mov_b32 m0, s70
	ds_read_b128 v[184:187], v150 offset:49152
	ds_read_b128 v[188:191], v150 offset:50176
	ds_read_b128 v[192:195], v150 offset:51200
	ds_read_b128 v[196:199], v150 offset:52224
	ds_read_b128 v[200:203], v150 offset:53248
	ds_read_b128 v[204:207], v150 offset:54272
	ds_read_b128 v[208:211], v150 offset:55296
	ds_read_b128 v[212:215], v150 offset:56320
	global_load_lds_dwordx4 v[216:217], off
	s_add_i32 m0, s70, 0x2000
	s_add_u32 s42, s42, 0xc000
	v_lshl_add_u64 v[216:217], s[44:45], 0, v[132:133]
	s_addc_u32 s43, s43, 0
	s_add_i32 s44, s61, s48
	global_load_lds_dwordx4 v[216:217], off
	v_lshl_add_u64 v[216:217], s[42:43], 0, v[130:131]
	s_mov_b32 m0, s44
	s_nop 0
	global_load_lds_dwordx4 v[216:217], off
	v_lshl_add_u64 v[216:217], s[42:43], 0, v[132:133]
	s_add_i32 m0, s44, 0x2000
	s_nop 0
	global_load_lds_dwordx4 v[216:217], off
	v_lshl_add_u64 v[216:217], s[40:41], 0, v[130:131]
	s_mov_b32 m0, s53
	s_nop 0
	global_load_lds_dwordx4 v[216:217], off
	v_lshl_add_u64 v[216:217], s[40:41], 0, v[132:133]
	s_mov_b32 m0, s54
	s_nop 0
	global_load_lds_dwordx4 v[216:217], off
	s_waitcnt vmcnt(8)
	s_waitcnt lgkmcnt(0)
	s_barrier
	v_mfma_f32_16x16x32_bf16 v[62:65], v[152:155], v[184:187], v[62:65]
	v_mfma_f32_16x16x32_bf16 v[58:61], v[160:163], v[184:187], v[58:61]
	v_mfma_f32_16x16x32_bf16 v[46:49], v[152:155], v[192:195], v[46:49]
	v_mfma_f32_16x16x32_bf16 v[42:45], v[160:163], v[192:195], v[42:45]
	v_mfma_f32_16x16x32_bf16 v[30:33], v[152:155], v[200:203], v[30:33]
	v_mfma_f32_16x16x32_bf16 v[26:29], v[160:163], v[200:203], v[26:29]
	v_mfma_f32_16x16x32_bf16 v[14:17], v[152:155], v[208:211], v[14:17]
	v_mfma_f32_16x16x32_bf16 v[10:13], v[160:163], v[208:211], v[10:13]
	v_mfma_f32_16x16x32_bf16 v[62:65], v[156:159], v[188:191], v[62:65]
	v_mfma_f32_16x16x32_bf16 v[58:61], v[164:167], v[188:191], v[58:61]
	v_mfma_f32_16x16x32_bf16 v[46:49], v[156:159], v[196:199], v[46:49]
	v_mfma_f32_16x16x32_bf16 v[42:45], v[164:167], v[196:199], v[42:45]
	v_mfma_f32_16x16x32_bf16 v[30:33], v[156:159], v[204:207], v[30:33]
	v_mfma_f32_16x16x32_bf16 v[26:29], v[164:167], v[204:207], v[26:29]
	v_mfma_f32_16x16x32_bf16 v[14:17], v[156:159], v[212:215], v[14:17]
	v_mfma_f32_16x16x32_bf16 v[10:13], v[164:167], v[212:215], v[10:13]
	v_mfma_f32_16x16x32_bf16 v[54:57], v[168:171], v[184:187], v[54:57]
	v_mfma_f32_16x16x32_bf16 v[50:53], v[176:179], v[184:187], v[50:53]
	v_mfma_f32_16x16x32_bf16 v[38:41], v[168:171], v[192:195], v[38:41]
	v_mfma_f32_16x16x32_bf16 v[34:37], v[176:179], v[192:195], v[34:37]
	v_mfma_f32_16x16x32_bf16 v[22:25], v[168:171], v[200:203], v[22:25]
	v_mfma_f32_16x16x32_bf16 v[18:21], v[176:179], v[200:203], v[18:21]
	v_mfma_f32_16x16x32_bf16 v[6:9], v[168:171], v[208:211], v[6:9]
	v_mfma_f32_16x16x32_bf16 v[2:5], v[176:179], v[208:211], v[2:5]
	v_mfma_f32_16x16x32_bf16 v[54:57], v[172:175], v[188:191], v[54:57]
	v_mfma_f32_16x16x32_bf16 v[50:53], v[180:183], v[188:191], v[50:53]
	v_mfma_f32_16x16x32_bf16 v[38:41], v[172:175], v[196:199], v[38:41]
	v_mfma_f32_16x16x32_bf16 v[34:37], v[180:183], v[196:199], v[34:37]
	v_mfma_f32_16x16x32_bf16 v[22:25], v[172:175], v[204:207], v[22:25]
	v_mfma_f32_16x16x32_bf16 v[18:21], v[180:183], v[204:207], v[18:21]
	v_mfma_f32_16x16x32_bf16 v[6:9], v[172:175], v[212:215], v[6:9]
	v_mfma_f32_16x16x32_bf16 v[2:5], v[180:183], v[212:215], v[2:5]
	s_barrier
	s_add_u32 s38, s38, 0x10000
	s_addc_u32 s39, s39, 0
	s_cmp_ge_u32 s67, s56
	s_cbranch_scc0 .LBB0_2328
	s_and_b64 vcc, exec, s[14:15]
	s_cbranch_vccz .LBB0_2331
	s_barrier
